# GEMM phases: drop the blanket lgkmcnt(0) after the pre-MFMA barrier; MFMAs start behind the compiler's counted per-fragment waits
# speedup vs baseline: 1.0070x; 1.0012x over previous
; #define STAGE(P, BASE, br, kt) do { int _so = ((br) * K + (kt) * BK) * 2; \
;     __builtin_amdgcn_raw_ptr_buffer_load_lds(rs_##BASE, (__attribute__((address_space(3))) void*)((char*)(P) + tx * 16), 16, voff0, _so, 0, 0); \
;     __builtin_amdgcn_raw_ptr_buffer_load_lds(rs_##BASE, (__attribute__((address_space(3))) void*)((char*)(P) + tx * 16 + 8192), 16, voff1, _so, 0, 0); } while (0)
; #define LDA(dst, b, h) _Pragma("unroll") for (int m = 0; m < 4; ++m) _Pragma("unroll") for (int k = 0; k < 2; ++k) \
;     dst[m][k] = *reinterpret_cast<const bf16x8*>((char*)SA(b, h) + lds_byte(wr * 64 + m * 16 + fr, k * 32 + fq * 8))
; #define LDB(dst, b, h) _Pragma("unroll") for (int n = 0; n < 2; ++n) _Pragma("unroll") for (int k = 0; k < 2; ++k) \
;     dst[n][k] = *reinterpret_cast<const bf16x8*>((char*)SB(b, h) + lds_byte(wc * 32 + n * 16 + fr, k * 32 + fq * 8))
; #define MMA(ai, bj, At, Bt_) do { __builtin_amdgcn_s_setprio(1); \
;     _Pragma("unroll") for (int m = 0; m < 4; ++m) _Pragma("unroll") for (int n = 0; n < 2; ++n) _Pragma("unroll") for (int k = 0; k < 2; ++k) \
;       acc[ai][bj][m][n] = __builtin_amdgcn_mfma_f32_16x16x32_bf16(At[m][k], Bt_[n][k], acc[ai][bj][m][n], 0, 0, 0); \
;     __builtin_amdgcn_s_setprio(0); } while (0)
; #define WAIT_V(n) asm volatile("s_waitcnt vmcnt(" #n ")" ::: "memory")
; #define WAIT_L(n) asm volatile("s_waitcnt lgkmcnt(" #n ")" ::: "memory")
; #define BAR __builtin_amdgcn_s_barrier()
; #define SCHED __builtin_amdgcn_sched_barrier(0)
; template <class Epi> ...
;     ...
;     LDB(B0, 0, 0); SCHED; LDA(At, 0, 0); STAGE(SA(1, 1), A, brow + HALF, t + 1);
;     WAIT_L(8); BAR; WAIT_L(0); MMA(0, 0, At, B0); BAR; SCHED;
;     LDB(B1, 0, 1); STAGE(SB(0, 0), Bt, bcol, t + 2);
;     BAR; WAIT_L(0); MMA(0, 1, At, B1); BAR;
;     LDA(At, 0, 1); STAGE(SA(0, 0), A, brow, t + 2);
;     BAR; WAIT_L(0); MMA(1, 0, At, B0); BAR; SCHED;
;     STAGE(SB(0, 1), Bt, bcol + HALF, t + 2);
;     WAIT_V(6); BAR; MMA(1, 1, At, B1); BAR;
.Lpk0:
	ds_read_b128 v[156:159], v155
	ds_read_b128 v[166:169], v155 offset:1024
	ds_read_b128 v[170:173], v155 offset:2048
	ds_read_b128 v[186:189], v155 offset:3072
	s_add_i32 s35, s21, s34
	v_readfirstlane_b32 s37, v152
	s_add_i32 s36, s35, 0x40080
	s_mov_b32 m0, s37
	v_readfirstlane_b32 s37, v151
	ds_read_b128 v[190:193], v143
	ds_read_b128 v[194:197], v143 offset:1024
	ds_read_b128 v[198:201], v142
	ds_read_b128 v[202:205], v142 offset:1024
	ds_read_b128 v[206:209], v141
	ds_read_b128 v[210:213], v141 offset:1024
	ds_read_b128 v[214:217], v140
	ds_read_b128 v[218:221], v140 offset:1024
	buffer_load_dwordx4 v32, s[4:7], s36 offen lds
	s_mov_b32 m0, s37
	s_nop 0
	buffer_load_dwordx4 v130, s[4:7], s36 offen lds
	s_waitcnt lgkmcnt(8)
	s_barrier
	s_setprio 1
	s_waitcnt lgkmcnt(7)
	v_mfma_f32_16x16x32_bf16 v[126:129], v[190:193], v[156:159], 0
	v_mfma_f32_16x16x32_bf16 v[122:125], v[190:193], v[170:173], 0
	s_waitcnt lgkmcnt(5)
	v_mfma_f32_16x16x32_bf16 v[118:121], v[198:201], v[156:159], 0
	v_mfma_f32_16x16x32_bf16 v[114:117], v[198:201], v[170:173], 0
	s_waitcnt lgkmcnt(3)
	v_mfma_f32_16x16x32_bf16 v[110:113], v[206:209], v[156:159], 0
	v_mfma_f32_16x16x32_bf16 v[106:109], v[206:209], v[170:173], 0
	s_waitcnt lgkmcnt(1)
	v_mfma_f32_16x16x32_bf16 v[102:105], v[214:217], v[156:159], 0
	v_mfma_f32_16x16x32_bf16 v[98:101], v[214:217], v[170:173], 0
	v_mfma_f32_16x16x32_bf16 v[126:129], v[194:197], v[166:169], v[126:129]
	v_mfma_f32_16x16x32_bf16 v[122:125], v[194:197], v[186:189], v[122:125]
	v_mfma_f32_16x16x32_bf16 v[118:121], v[202:205], v[166:169], v[118:121]
	v_mfma_f32_16x16x32_bf16 v[114:117], v[202:205], v[186:189], v[114:117]
	v_mfma_f32_16x16x32_bf16 v[110:113], v[210:213], v[166:169], v[110:113]
	v_mfma_f32_16x16x32_bf16 v[106:109], v[210:213], v[186:189], v[106:109]
	s_waitcnt lgkmcnt(0)
	v_mfma_f32_16x16x32_bf16 v[102:105], v[218:221], v[166:169], v[102:105]
	v_mfma_f32_16x16x32_bf16 v[98:101], v[218:221], v[186:189], v[98:101]
	s_setprio 0
	s_barrier
	s_add_i32 s36, s20, s34
	v_readfirstlane_b32 s38, v137
	s_add_i32 s37, s36, 0x100
	s_mov_b32 m0, s38
	v_readfirstlane_b32 s38, v139
	ds_read_b128 v[222:225], v149
	ds_read_b128 v[226:229], v149 offset:1024
	ds_read_b128 v[230:233], v149 offset:2048
	ds_read_b128 v[234:237], v149 offset:3072
	buffer_load_dwordx4 v32, s[76:79], s37 offen lds
	s_mov_b32 m0, s38
	s_nop 0
	buffer_load_dwordx4 v130, s[76:79], s37 offen lds
	s_barrier
	s_setprio 1
	s_waitcnt lgkmcnt(3)
	v_mfma_f32_16x16x32_bf16 v[94:97], v[190:193], v[222:225], 0
	s_waitcnt lgkmcnt(1)
	v_mfma_f32_16x16x32_bf16 v[90:93], v[190:193], v[230:233], 0
	v_mfma_f32_16x16x32_bf16 v[86:89], v[198:201], v[222:225], 0
	v_mfma_f32_16x16x32_bf16 v[82:85], v[198:201], v[230:233], 0
	v_mfma_f32_16x16x32_bf16 v[78:81], v[206:209], v[222:225], 0
	v_mfma_f32_16x16x32_bf16 v[74:77], v[206:209], v[230:233], 0
	v_mfma_f32_16x16x32_bf16 v[70:73], v[214:217], v[222:225], 0
	v_mfma_f32_16x16x32_bf16 v[66:69], v[214:217], v[230:233], 0
	v_mfma_f32_16x16x32_bf16 v[94:97], v[194:197], v[226:229], v[94:97]
	s_waitcnt lgkmcnt(0)
	v_mfma_f32_16x16x32_bf16 v[90:93], v[194:197], v[234:237], v[90:93]
	v_mfma_f32_16x16x32_bf16 v[86:89], v[202:205], v[226:229], v[86:89]
	v_mfma_f32_16x16x32_bf16 v[82:85], v[202:205], v[234:237], v[82:85]
	v_mfma_f32_16x16x32_bf16 v[78:81], v[210:213], v[226:229], v[78:81]
	v_mfma_f32_16x16x32_bf16 v[74:77], v[210:213], v[234:237], v[74:77]
	v_mfma_f32_16x16x32_bf16 v[70:73], v[218:221], v[226:229], v[70:73]
	v_mfma_f32_16x16x32_bf16 v[66:69], v[218:221], v[234:237], v[66:69]
	s_setprio 0
	v_readfirstlane_b32 s38, v136
	s_add_i32 s37, s35, 0x100
	s_mov_b32 m0, s38
	v_readfirstlane_b32 s38, v135
	s_barrier
	ds_read_b128 v[190:193], v143 offset:16384
	ds_read_b128 v[194:197], v143 offset:17408
	ds_read_b128 v[198:201], v142 offset:16384
	ds_read_b128 v[202:205], v142 offset:17408
	ds_read_b128 v[206:209], v141 offset:16384
	ds_read_b128 v[210:213], v141 offset:17408
	ds_read_b128 v[214:217], v140 offset:16384
	ds_read_b128 v[218:221], v140 offset:17408
	buffer_load_dwordx4 v32, s[4:7], s37 offen lds
	s_mov_b32 m0, s38
	s_nop 0
	buffer_load_dwordx4 v130, s[4:7], s37 offen lds
	s_barrier
	s_setprio 1
	s_waitcnt lgkmcnt(7)
	v_mfma_f32_16x16x32_bf16 v[62:65], v[190:193], v[156:159], 0
	v_mfma_f32_16x16x32_bf16 v[58:61], v[190:193], v[170:173], 0
	s_waitcnt lgkmcnt(5)
	v_mfma_f32_16x16x32_bf16 v[54:57], v[198:201], v[156:159], 0
	v_mfma_f32_16x16x32_bf16 v[50:53], v[198:201], v[170:173], 0
	s_waitcnt lgkmcnt(3)
	v_mfma_f32_16x16x32_bf16 v[46:49], v[206:209], v[156:159], 0
	v_mfma_f32_16x16x32_bf16 v[42:45], v[206:209], v[170:173], 0
	s_waitcnt lgkmcnt(1)
	v_mfma_f32_16x16x32_bf16 v[38:41], v[214:217], v[156:159], 0
	v_mfma_f32_16x16x32_bf16 v[34:37], v[214:217], v[170:173], 0
	v_mfma_f32_16x16x32_bf16 v[62:65], v[194:197], v[166:169], v[62:65]
	v_mfma_f32_16x16x32_bf16 v[58:61], v[194:197], v[186:189], v[58:61]
	v_mfma_f32_16x16x32_bf16 v[54:57], v[202:205], v[166:169], v[54:57]
	v_mfma_f32_16x16x32_bf16 v[50:53], v[202:205], v[186:189], v[50:53]
	v_mfma_f32_16x16x32_bf16 v[46:49], v[210:213], v[166:169], v[46:49]
	v_mfma_f32_16x16x32_bf16 v[42:45], v[210:213], v[186:189], v[42:45]
	s_waitcnt lgkmcnt(0)
	v_mfma_f32_16x16x32_bf16 v[38:41], v[218:221], v[166:169], v[38:41]
	v_mfma_f32_16x16x32_bf16 v[34:37], v[218:221], v[186:189], v[34:37]
	s_setprio 0
	s_barrier
	v_readfirstlane_b32 s38, v134
	s_add_i32 s37, s36, 0x40100
	s_mov_b32 m0, s38
	v_readfirstlane_b32 s38, v138
	buffer_load_dwordx4 v32, s[76:79], s37 offen lds
	s_mov_b32 m0, s38
	s_nop 0
	buffer_load_dwordx4 v130, s[76:79], s37 offen lds
	s_waitcnt vmcnt(6)
	s_barrier
; #define STAGE(P, BASE, br, kt) do { int _so = ((br) * K + (kt) * BK) * 2; \
;     __builtin_amdgcn_raw_ptr_buffer_load_lds(rs_##BASE, (__attribute__((address_space(3))) void*)((char*)(P) + tx * 16), 16, voff0, _so, 0, 0); \
;     __builtin_amdgcn_raw_ptr_buffer_load_lds(rs_##BASE, (__attribute__((address_space(3))) void*)((char*)(P) + tx * 16 + 8192), 16, voff1, _so, 0, 0); } while (0)
; #define LDA(dst, b, h) _Pragma("unroll") for (int m = 0; m < 4; ++m) _Pragma("unroll") for (int k = 0; k < 2; ++k) \
;     dst[m][k] = *reinterpret_cast<const bf16x8*>((char*)SA(b, h) + lds_byte(wr * 64 + m * 16 + fr, k * 32 + fq * 8))
; #define LDB(dst, b, h) _Pragma("unroll") for (int n = 0; n < 2; ++n) _Pragma("unroll") for (int k = 0; k < 2; ++k) \
;     dst[n][k] = *reinterpret_cast<const bf16x8*>((char*)SB(b, h) + lds_byte(wc * 32 + n * 16 + fr, k * 32 + fq * 8))
; #define MMA(ai, bj, At, Bt_) do { __builtin_amdgcn_s_setprio(1); \
;     _Pragma("unroll") for (int m = 0; m < 4; ++m) _Pragma("unroll") for (int n = 0; n < 2; ++n) _Pragma("unroll") for (int k = 0; k < 2; ++k) \
;       acc[ai][bj][m][n] = __builtin_amdgcn_mfma_f32_16x16x32_bf16(At[m][k], Bt_[n][k], acc[ai][bj][m][n], 0, 0, 0); \
;     __builtin_amdgcn_s_setprio(0); } while (0)
; #define WAIT_V(n) asm volatile("s_waitcnt vmcnt(" #n ")" ::: "memory")
; #define WAIT_L(n) asm volatile("s_waitcnt lgkmcnt(" #n ")" ::: "memory")
; #define BAR __builtin_amdgcn_s_barrier()
; #define SCHED __builtin_amdgcn_sched_barrier(0)
; template <class Epi> ...
;     ...
;     WAIT_V(6); BAR; MMA(1, 1, At, B1); BAR;
;     LDB(B0, 1, 0); SCHED; LDA(At, 1, 0); STAGE(SA(0, 1), A, brow + HALF, t + 2);
;     WAIT_L(8); BAR; WAIT_L(0); MMA(0, 0, At, B0); BAR; SCHED;
;     LDB(B1, 1, 1); STAGE(SB(1, 0), Bt, bcol, t + 3);
;     BAR; WAIT_L(0); MMA(0, 1, At, B1); BAR;
;     LDA(At, 1, 1); STAGE(SA(1, 0), A, brow, t + 3);
;     BAR; WAIT_L(0); MMA(1, 0, At, B0); BAR; SCHED;
	s_setprio 1
	v_mfma_f32_16x16x32_bf16 v[28:31], v[190:193], v[222:225], 0
	v_mfma_f32_16x16x32_bf16 v[24:27], v[190:193], v[230:233], 0
	v_mfma_f32_16x16x32_bf16 v[20:23], v[198:201], v[222:225], 0
	v_mfma_f32_16x16x32_bf16 v[16:19], v[198:201], v[230:233], 0
	v_mfma_f32_16x16x32_bf16 v[12:15], v[206:209], v[222:225], 0
	v_mfma_f32_16x16x32_bf16 v[8:11], v[206:209], v[230:233], 0
	v_mfma_f32_16x16x32_bf16 v[4:7], v[214:217], v[222:225], 0
	v_mfma_f32_16x16x32_bf16 v[0:3], v[214:217], v[230:233], 0
	v_mfma_f32_16x16x32_bf16 v[28:31], v[194:197], v[226:229], v[28:31]
	v_mfma_f32_16x16x32_bf16 v[24:27], v[194:197], v[234:237], v[24:27]
	v_mfma_f32_16x16x32_bf16 v[20:23], v[202:205], v[226:229], v[20:23]
	v_mfma_f32_16x16x32_bf16 v[16:19], v[202:205], v[234:237], v[16:19]
	v_mfma_f32_16x16x32_bf16 v[12:15], v[210:213], v[226:229], v[12:15]
	v_mfma_f32_16x16x32_bf16 v[8:11], v[210:213], v[234:237], v[8:11]
	v_mfma_f32_16x16x32_bf16 v[4:7], v[218:221], v[226:229], v[4:7]
	v_mfma_f32_16x16x32_bf16 v[0:3], v[218:221], v[234:237], v[0:3]
	s_setprio 0
	s_barrier
	ds_read_b128 v[156:159], v145
	ds_read_b128 v[166:169], v145 offset:1024
	ds_read_b128 v[170:173], v145 offset:2048
	ds_read_b128 v[186:189], v145 offset:3072
	v_readfirstlane_b32 s38, v132
	s_add_i32 s37, s35, 0x40100
	s_mov_b32 m0, s38
	v_readfirstlane_b32 s38, v131
	ds_read_b128 v[190:193], v143 offset:32768
	ds_read_b128 v[194:197], v143 offset:33792
	ds_read_b128 v[198:201], v142 offset:32768
	ds_read_b128 v[202:205], v142 offset:33792
	ds_read_b128 v[206:209], v141 offset:32768
	ds_read_b128 v[210:213], v141 offset:33792
	ds_read_b128 v[214:217], v140 offset:32768
	ds_read_b128 v[218:221], v140 offset:33792
	buffer_load_dwordx4 v32, s[4:7], s37 offen lds
	s_mov_b32 m0, s38
	s_nop 0
	buffer_load_dwordx4 v130, s[4:7], s37 offen lds
	s_waitcnt lgkmcnt(8)
	s_barrier
	s_setprio 1
	s_waitcnt lgkmcnt(7)
	v_mfma_f32_16x16x32_bf16 v[126:129], v[190:193], v[156:159], v[126:129]
	v_mfma_f32_16x16x32_bf16 v[122:125], v[190:193], v[170:173], v[122:125]
	s_waitcnt lgkmcnt(5)
	v_mfma_f32_16x16x32_bf16 v[118:121], v[198:201], v[156:159], v[118:121]
	v_mfma_f32_16x16x32_bf16 v[114:117], v[198:201], v[170:173], v[114:117]
	s_waitcnt lgkmcnt(3)
	v_mfma_f32_16x16x32_bf16 v[110:113], v[206:209], v[156:159], v[110:113]
	v_mfma_f32_16x16x32_bf16 v[106:109], v[206:209], v[170:173], v[106:109]
	s_waitcnt lgkmcnt(1)
	v_mfma_f32_16x16x32_bf16 v[102:105], v[214:217], v[156:159], v[102:105]
	v_mfma_f32_16x16x32_bf16 v[98:101], v[214:217], v[170:173], v[98:101]
	v_mfma_f32_16x16x32_bf16 v[126:129], v[194:197], v[166:169], v[126:129]
	v_mfma_f32_16x16x32_bf16 v[122:125], v[194:197], v[186:189], v[122:125]
	v_mfma_f32_16x16x32_bf16 v[118:121], v[202:205], v[166:169], v[118:121]
	v_mfma_f32_16x16x32_bf16 v[114:117], v[202:205], v[186:189], v[114:117]
	v_mfma_f32_16x16x32_bf16 v[110:113], v[210:213], v[166:169], v[110:113]
	v_mfma_f32_16x16x32_bf16 v[106:109], v[210:213], v[186:189], v[106:109]
	s_waitcnt lgkmcnt(0)
	v_mfma_f32_16x16x32_bf16 v[102:105], v[218:221], v[166:169], v[102:105]
	v_mfma_f32_16x16x32_bf16 v[98:101], v[218:221], v[186:189], v[98:101]
	s_setprio 0
	s_barrier
	v_readfirstlane_b32 s38, v146
	s_add_i32 s37, s36, 0x180
	s_mov_b32 m0, s38
	v_readfirstlane_b32 s38, v147
	ds_read_b128 v[222:225], v144
	ds_read_b128 v[226:229], v144 offset:1024
	ds_read_b128 v[230:233], v144 offset:2048
	ds_read_b128 v[234:237], v144 offset:3072
	buffer_load_dwordx4 v32, s[76:79], s37 offen lds
	s_mov_b32 m0, s38
	s_nop 0
	buffer_load_dwordx4 v130, s[76:79], s37 offen lds
	s_barrier
	s_setprio 1
	s_waitcnt lgkmcnt(3)
	v_mfma_f32_16x16x32_bf16 v[94:97], v[190:193], v[222:225], v[94:97]
	s_waitcnt lgkmcnt(1)
	v_mfma_f32_16x16x32_bf16 v[90:93], v[190:193], v[230:233], v[90:93]
	v_mfma_f32_16x16x32_bf16 v[86:89], v[198:201], v[222:225], v[86:89]
	v_mfma_f32_16x16x32_bf16 v[82:85], v[198:201], v[230:233], v[82:85]
	v_mfma_f32_16x16x32_bf16 v[78:81], v[206:209], v[222:225], v[78:81]
	v_mfma_f32_16x16x32_bf16 v[74:77], v[206:209], v[230:233], v[74:77]
	v_mfma_f32_16x16x32_bf16 v[70:73], v[214:217], v[222:225], v[70:73]
	v_mfma_f32_16x16x32_bf16 v[66:69], v[214:217], v[230:233], v[66:69]
	v_mfma_f32_16x16x32_bf16 v[94:97], v[194:197], v[226:229], v[94:97]
	s_waitcnt lgkmcnt(0)
	v_mfma_f32_16x16x32_bf16 v[90:93], v[194:197], v[234:237], v[90:93]
	v_mfma_f32_16x16x32_bf16 v[86:89], v[202:205], v[226:229], v[86:89]
	v_mfma_f32_16x16x32_bf16 v[82:85], v[202:205], v[234:237], v[82:85]
	v_mfma_f32_16x16x32_bf16 v[78:81], v[210:213], v[226:229], v[78:81]
	v_mfma_f32_16x16x32_bf16 v[74:77], v[210:213], v[234:237], v[74:77]
	v_mfma_f32_16x16x32_bf16 v[70:73], v[218:221], v[226:229], v[70:73]
	v_mfma_f32_16x16x32_bf16 v[66:69], v[218:221], v[234:237], v[66:69]
	s_setprio 0
	v_readfirstlane_b32 s37, v148
	s_addk_i32 s35, 0x180
	s_mov_b32 m0, s37
	v_readfirstlane_b32 s37, v150
	s_barrier
	ds_read_b128 v[190:193], v143 offset:49152
	ds_read_b128 v[194:197], v143 offset:50176
	ds_read_b128 v[198:201], v142 offset:49152
	ds_read_b128 v[202:205], v142 offset:50176
	ds_read_b128 v[206:209], v141 offset:49152
	ds_read_b128 v[210:213], v141 offset:50176
	ds_read_b128 v[214:217], v140 offset:49152
	ds_read_b128 v[218:221], v140 offset:50176
	buffer_load_dwordx4 v32, s[4:7], s35 offen lds
	s_mov_b32 m0, s37
	s_nop 0
	buffer_load_dwordx4 v130, s[4:7], s35 offen lds
	s_barrier
; #define STAGE(P, BASE, br, kt) do { int _so = ((br) * K + (kt) * BK) * 2; \
;     __builtin_amdgcn_raw_ptr_buffer_load_lds(rs_##BASE, (__attribute__((address_space(3))) void*)((char*)(P) + tx * 16), 16, voff0, _so, 0, 0); \
;     __builtin_amdgcn_raw_ptr_buffer_load_lds(rs_##BASE, (__attribute__((address_space(3))) void*)((char*)(P) + tx * 16 + 8192), 16, voff1, _so, 0, 0); } while (0)
; #define LDA(dst, b, h) _Pragma("unroll") for (int m = 0; m < 4; ++m) _Pragma("unroll") for (int k = 0; k < 2; ++k) \
;     dst[m][k] = *reinterpret_cast<const bf16x8*>((char*)SA(b, h) + lds_byte(wr * 64 + m * 16 + fr, k * 32 + fq * 8))
; #define LDB(dst, b, h) _Pragma("unroll") for (int n = 0; n < 2; ++n) _Pragma("unroll") for (int k = 0; k < 2; ++k) \
;     dst[n][k] = *reinterpret_cast<const bf16x8*>((char*)SB(b, h) + lds_byte(wc * 32 + n * 16 + fr, k * 32 + fq * 8))
; #define MMA(ai, bj, At, Bt_) do { __builtin_amdgcn_s_setprio(1); \
;     _Pragma("unroll") for (int m = 0; m < 4; ++m) _Pragma("unroll") for (int n = 0; n < 2; ++n) _Pragma("unroll") for (int k = 0; k < 2; ++k) \
;       acc[ai][bj][m][n] = __builtin_amdgcn_mfma_f32_16x16x32_bf16(At[m][k], Bt_[n][k], acc[ai][bj][m][n], 0, 0, 0); \
;     __builtin_amdgcn_s_setprio(0); } while (0)
; #define WAIT_V(n) asm volatile("s_waitcnt vmcnt(" #n ")" ::: "memory")
; #define WAIT_L(n) asm volatile("s_waitcnt lgkmcnt(" #n ")" ::: "memory")
; template <class Epi> ...
;     ...
;   for (int t = 0; t < nt - 2; t += 2) {
;     LDB(B0, 0, 0); SCHED; LDA(At, 0, 0); STAGE(SA(1, 1), A, brow + HALF, t + 1);
;     WAIT_L(8); BAR; WAIT_L(0); MMA(0, 0, At, B0); BAR; SCHED;
;     LDB(B1, 0, 1); STAGE(SB(0, 0), Bt, bcol, t + 2);
;     BAR; WAIT_L(0); MMA(0, 1, At, B1); BAR;
;     LDA(At, 0, 1); STAGE(SA(0, 0), A, brow, t + 2);
;     BAR; WAIT_L(0); MMA(1, 0, At, B0); BAR; SCHED;
;     STAGE(SB(0, 1), Bt, bcol + HALF, t + 2);
;     WAIT_V(6); BAR; MMA(1, 1, At, B1); BAR;
;     LDB(B0, 1, 0); SCHED; LDA(At, 1, 0); STAGE(SA(0, 1), A, brow + HALF, t + 2);
;     WAIT_L(8); BAR; WAIT_L(0); MMA(0, 0, At, B0); BAR; SCHED;
;     LDB(B1, 1, 1); STAGE(SB(1, 0), Bt, bcol, t + 3);
;     BAR; WAIT_L(0); MMA(0, 1, At, B1); BAR;
;     LDA(At, 1, 1); STAGE(SA(1, 0), A, brow, t + 3);
;     BAR; WAIT_L(0); MMA(1, 0, At, B0); BAR; SCHED;
;     STAGE(SB(1, 1), Bt, bcol + HALF, t + 3);
;     WAIT_V(6); BAR; MMA(1, 1, At, B1); BAR;
;   }
	s_setprio 1
	s_waitcnt lgkmcnt(7)
	v_mfma_f32_16x16x32_bf16 v[62:65], v[190:193], v[156:159], v[62:65]
	v_mfma_f32_16x16x32_bf16 v[58:61], v[190:193], v[170:173], v[58:61]
	s_waitcnt lgkmcnt(5)
	v_mfma_f32_16x16x32_bf16 v[54:57], v[198:201], v[156:159], v[54:57]
	v_mfma_f32_16x16x32_bf16 v[50:53], v[198:201], v[170:173], v[50:53]
	s_waitcnt lgkmcnt(3)
	v_mfma_f32_16x16x32_bf16 v[46:49], v[206:209], v[156:159], v[46:49]
	v_mfma_f32_16x16x32_bf16 v[42:45], v[206:209], v[170:173], v[42:45]
	s_waitcnt lgkmcnt(1)
	v_mfma_f32_16x16x32_bf16 v[38:41], v[214:217], v[156:159], v[38:41]
	v_mfma_f32_16x16x32_bf16 v[34:37], v[214:217], v[170:173], v[34:37]
	v_mfma_f32_16x16x32_bf16 v[62:65], v[194:197], v[166:169], v[62:65]
	v_mfma_f32_16x16x32_bf16 v[58:61], v[194:197], v[186:189], v[58:61]
	v_mfma_f32_16x16x32_bf16 v[54:57], v[202:205], v[166:169], v[54:57]
	v_mfma_f32_16x16x32_bf16 v[50:53], v[202:205], v[186:189], v[50:53]
	v_mfma_f32_16x16x32_bf16 v[46:49], v[210:213], v[166:169], v[46:49]
	v_mfma_f32_16x16x32_bf16 v[42:45], v[210:213], v[186:189], v[42:45]
	s_waitcnt lgkmcnt(0)
	v_mfma_f32_16x16x32_bf16 v[38:41], v[218:221], v[166:169], v[38:41]
	v_mfma_f32_16x16x32_bf16 v[34:37], v[218:221], v[186:189], v[34:37]
	s_setprio 0
	s_barrier
	v_readfirstlane_b32 s35, v153
	s_add_i32 s36, s36, 0x40180
	s_mov_b32 m0, s35
	v_readfirstlane_b32 s35, v154
	buffer_load_dwordx4 v32, s[76:79], s36 offen lds
	s_mov_b32 m0, s35
	s_nop 0
	buffer_load_dwordx4 v130, s[76:79], s36 offen lds
	s_waitcnt vmcnt(6)
	s_barrier
	s_setprio 1
	v_mfma_f32_16x16x32_bf16 v[28:31], v[190:193], v[222:225], v[28:31]
	v_mfma_f32_16x16x32_bf16 v[24:27], v[190:193], v[230:233], v[24:27]
	v_mfma_f32_16x16x32_bf16 v[20:23], v[198:201], v[222:225], v[20:23]
	v_mfma_f32_16x16x32_bf16 v[16:19], v[198:201], v[230:233], v[16:19]
	v_mfma_f32_16x16x32_bf16 v[12:15], v[206:209], v[222:225], v[12:15]
	v_mfma_f32_16x16x32_bf16 v[8:11], v[206:209], v[230:233], v[8:11]
	v_mfma_f32_16x16x32_bf16 v[4:7], v[214:217], v[222:225], v[4:7]
	v_mfma_f32_16x16x32_bf16 v[0:3], v[214:217], v[230:233], v[0:3]
	v_mfma_f32_16x16x32_bf16 v[28:31], v[194:197], v[226:229], v[28:31]
	v_mfma_f32_16x16x32_bf16 v[24:27], v[194:197], v[234:237], v[24:27]
	v_mfma_f32_16x16x32_bf16 v[20:23], v[202:205], v[226:229], v[20:23]
	v_mfma_f32_16x16x32_bf16 v[16:19], v[202:205], v[234:237], v[16:19]
	v_mfma_f32_16x16x32_bf16 v[12:15], v[210:213], v[226:229], v[12:15]
	v_mfma_f32_16x16x32_bf16 v[8:11], v[210:213], v[234:237], v[8:11]
	v_mfma_f32_16x16x32_bf16 v[4:7], v[218:221], v[226:229], v[4:7]
	v_mfma_f32_16x16x32_bf16 v[0:3], v[218:221], v[234:237], v[0:3]
	s_setprio 0
	s_add_i32 s31, s31, 2
	s_addk_i32 s34, 0x100
	s_cmp_lt_u32 s31, 12
	s_barrier
	s_cbranch_scc1 .LBB0_74
	s_branch .Lpx0
.LBB0_74:
	ds_read_b128 v[156:159], v155
	ds_read_b128 v[166:169], v155 offset:1024
	ds_read_b128 v[170:173], v155 offset:2048
	ds_read_b128 v[186:189], v155 offset:3072
	s_add_i32 s35, s21, s34
	v_readfirstlane_b32 s37, v152
	s_add_i32 s36, s35, 0x40080
	s_mov_b32 m0, s37
	v_readfirstlane_b32 s37, v151
	ds_read_b128 v[190:193], v143
	ds_read_b128 v[194:197], v143 offset:1024
	ds_read_b128 v[198:201], v142
	ds_read_b128 v[202:205], v142 offset:1024
	ds_read_b128 v[206:209], v141
	ds_read_b128 v[210:213], v141 offset:1024
	ds_read_b128 v[214:217], v140
	ds_read_b128 v[218:221], v140 offset:1024
	buffer_load_dwordx4 v32, s[4:7], s36 offen lds
	s_mov_b32 m0, s37
	s_nop 0
	buffer_load_dwordx4 v130, s[4:7], s36 offen lds
	s_waitcnt lgkmcnt(8)
	s_barrier
	s_setprio 1
	s_waitcnt lgkmcnt(7)
	v_mfma_f32_16x16x32_bf16 v[126:129], v[190:193], v[156:159], v[126:129]
	v_mfma_f32_16x16x32_bf16 v[122:125], v[190:193], v[170:173], v[122:125]
	s_waitcnt lgkmcnt(5)
	v_mfma_f32_16x16x32_bf16 v[118:121], v[198:201], v[156:159], v[118:121]
	v_mfma_f32_16x16x32_bf16 v[114:117], v[198:201], v[170:173], v[114:117]
	s_waitcnt lgkmcnt(3)
	v_mfma_f32_16x16x32_bf16 v[110:113], v[206:209], v[156:159], v[110:113]
	v_mfma_f32_16x16x32_bf16 v[106:109], v[206:209], v[170:173], v[106:109]
	s_waitcnt lgkmcnt(1)
	v_mfma_f32_16x16x32_bf16 v[102:105], v[214:217], v[156:159], v[102:105]
	v_mfma_f32_16x16x32_bf16 v[98:101], v[214:217], v[170:173], v[98:101]
	v_mfma_f32_16x16x32_bf16 v[126:129], v[194:197], v[166:169], v[126:129]
	v_mfma_f32_16x16x32_bf16 v[122:125], v[194:197], v[186:189], v[122:125]
	v_mfma_f32_16x16x32_bf16 v[118:121], v[202:205], v[166:169], v[118:121]
	v_mfma_f32_16x16x32_bf16 v[114:117], v[202:205], v[186:189], v[114:117]
	v_mfma_f32_16x16x32_bf16 v[110:113], v[210:213], v[166:169], v[110:113]
	v_mfma_f32_16x16x32_bf16 v[106:109], v[210:213], v[186:189], v[106:109]
	s_waitcnt lgkmcnt(0)
	v_mfma_f32_16x16x32_bf16 v[102:105], v[218:221], v[166:169], v[102:105]
	v_mfma_f32_16x16x32_bf16 v[98:101], v[218:221], v[186:189], v[98:101]
	s_setprio 0
	s_barrier
	s_add_i32 s36, s20, s34
	v_readfirstlane_b32 s38, v137
	s_add_i32 s37, s36, 0x100
	s_mov_b32 m0, s38
	v_readfirstlane_b32 s38, v139
	ds_read_b128 v[222:225], v149
	ds_read_b128 v[226:229], v149 offset:1024
	ds_read_b128 v[230:233], v149 offset:2048
	ds_read_b128 v[234:237], v149 offset:3072
	buffer_load_dwordx4 v32, s[76:79], s37 offen lds
	s_mov_b32 m0, s38
	s_nop 0
	buffer_load_dwordx4 v130, s[76:79], s37 offen lds
	s_barrier
; #define STAGE(P, BASE, br, kt) do { int _so = ((br) * K + (kt) * BK) * 2; \
;     __builtin_amdgcn_raw_ptr_buffer_load_lds(rs_##BASE, (__attribute__((address_space(3))) void*)((char*)(P) + tx * 16), 16, voff0, _so, 0, 0); \
;     __builtin_amdgcn_raw_ptr_buffer_load_lds(rs_##BASE, (__attribute__((address_space(3))) void*)((char*)(P) + tx * 16 + 8192), 16, voff1, _so, 0, 0); } while (0)
; #define LDA(dst, b, h) _Pragma("unroll") for (int m = 0; m < 4; ++m) _Pragma("unroll") for (int k = 0; k < 2; ++k) \
;     dst[m][k] = *reinterpret_cast<const bf16x8*>((char*)SA(b, h) + lds_byte(wr * 64 + m * 16 + fr, k * 32 + fq * 8))
; #define LDB(dst, b, h) _Pragma("unroll") for (int n = 0; n < 2; ++n) _Pragma("unroll") for (int k = 0; k < 2; ++k) \
;     dst[n][k] = *reinterpret_cast<const bf16x8*>((char*)SB(b, h) + lds_byte(wc * 32 + n * 16 + fr, k * 32 + fq * 8))
; #define MMA(ai, bj, At, Bt_) do { __builtin_amdgcn_s_setprio(1); \
;     _Pragma("unroll") for (int m = 0; m < 4; ++m) _Pragma("unroll") for (int n = 0; n < 2; ++n) _Pragma("unroll") for (int k = 0; k < 2; ++k) \
;       acc[ai][bj][m][n] = __builtin_amdgcn_mfma_f32_16x16x32_bf16(At[m][k], Bt_[n][k], acc[ai][bj][m][n], 0, 0, 0); \
;     __builtin_amdgcn_s_setprio(0); } while (0)
; #define WAIT_V(n) asm volatile("s_waitcnt vmcnt(" #n ")" ::: "memory")
; #define WAIT_L(n) asm volatile("s_waitcnt lgkmcnt(" #n ")" ::: "memory")
; template <class Epi> ...
;     ...
;   for (int t = 0; t < nt - 2; t += 2) {
;     LDB(B0, 0, 0); SCHED; LDA(At, 0, 0); STAGE(SA(1, 1), A, brow + HALF, t + 1);
;     WAIT_L(8); BAR; WAIT_L(0); MMA(0, 0, At, B0); BAR; SCHED;
;     LDB(B1, 0, 1); STAGE(SB(0, 0), Bt, bcol, t + 2);
;     BAR; WAIT_L(0); MMA(0, 1, At, B1); BAR;
;     LDA(At, 0, 1); STAGE(SA(0, 0), A, brow, t + 2);
;     BAR; WAIT_L(0); MMA(1, 0, At, B0); BAR; SCHED;
;     STAGE(SB(0, 1), Bt, bcol + HALF, t + 2);
;     WAIT_V(6); BAR; MMA(1, 1, At, B1); BAR;
;     LDB(B0, 1, 0); SCHED; LDA(At, 1, 0); STAGE(SA(0, 1), A, brow + HALF, t + 2);
;     WAIT_L(8); BAR; WAIT_L(0); MMA(0, 0, At, B0); BAR; SCHED;
;     LDB(B1, 1, 1); STAGE(SB(1, 0), Bt, bcol, t + 3);
;     BAR; WAIT_L(0); MMA(0, 1, At, B1); BAR;
;     LDA(At, 1, 1); STAGE(SA(1, 0), A, brow, t + 3);
;     BAR; WAIT_L(0); MMA(1, 0, At, B0); BAR; SCHED;
;     STAGE(SB(1, 1), Bt, bcol + HALF, t + 3);
;     WAIT_V(6); BAR; MMA(1, 1, At, B1); BAR;
;   }
	s_setprio 1
	s_waitcnt lgkmcnt(3)
	v_mfma_f32_16x16x32_bf16 v[94:97], v[190:193], v[222:225], v[94:97]
	s_waitcnt lgkmcnt(1)
	v_mfma_f32_16x16x32_bf16 v[90:93], v[190:193], v[230:233], v[90:93]
	v_mfma_f32_16x16x32_bf16 v[86:89], v[198:201], v[222:225], v[86:89]
	v_mfma_f32_16x16x32_bf16 v[82:85], v[198:201], v[230:233], v[82:85]
	v_mfma_f32_16x16x32_bf16 v[78:81], v[206:209], v[222:225], v[78:81]
	v_mfma_f32_16x16x32_bf16 v[74:77], v[206:209], v[230:233], v[74:77]
	v_mfma_f32_16x16x32_bf16 v[70:73], v[214:217], v[222:225], v[70:73]
	v_mfma_f32_16x16x32_bf16 v[66:69], v[214:217], v[230:233], v[66:69]
	v_mfma_f32_16x16x32_bf16 v[94:97], v[194:197], v[226:229], v[94:97]
	s_waitcnt lgkmcnt(0)
	v_mfma_f32_16x16x32_bf16 v[90:93], v[194:197], v[234:237], v[90:93]
	v_mfma_f32_16x16x32_bf16 v[86:89], v[202:205], v[226:229], v[86:89]
	v_mfma_f32_16x16x32_bf16 v[82:85], v[202:205], v[234:237], v[82:85]
	v_mfma_f32_16x16x32_bf16 v[78:81], v[210:213], v[226:229], v[78:81]
	v_mfma_f32_16x16x32_bf16 v[74:77], v[210:213], v[234:237], v[74:77]
	v_mfma_f32_16x16x32_bf16 v[70:73], v[218:221], v[226:229], v[70:73]
	v_mfma_f32_16x16x32_bf16 v[66:69], v[218:221], v[234:237], v[66:69]
	s_setprio 0
	v_readfirstlane_b32 s38, v136
	s_add_i32 s37, s35, 0x100
	s_mov_b32 m0, s38
	v_readfirstlane_b32 s38, v135
	s_barrier
	ds_read_b128 v[190:193], v143 offset:16384
	ds_read_b128 v[194:197], v143 offset:17408
	ds_read_b128 v[198:201], v142 offset:16384
	ds_read_b128 v[202:205], v142 offset:17408
	ds_read_b128 v[206:209], v141 offset:16384
	ds_read_b128 v[210:213], v141 offset:17408
	ds_read_b128 v[214:217], v140 offset:16384
	ds_read_b128 v[218:221], v140 offset:17408
	buffer_load_dwordx4 v32, s[4:7], s37 offen lds
	s_mov_b32 m0, s38
	s_nop 0
	buffer_load_dwordx4 v130, s[4:7], s37 offen lds
	s_barrier
	s_setprio 1
	s_waitcnt lgkmcnt(7)
	v_mfma_f32_16x16x32_bf16 v[62:65], v[190:193], v[156:159], v[62:65]
	v_mfma_f32_16x16x32_bf16 v[58:61], v[190:193], v[170:173], v[58:61]
	s_waitcnt lgkmcnt(5)
	v_mfma_f32_16x16x32_bf16 v[54:57], v[198:201], v[156:159], v[54:57]
	v_mfma_f32_16x16x32_bf16 v[50:53], v[198:201], v[170:173], v[50:53]
	s_waitcnt lgkmcnt(3)
	v_mfma_f32_16x16x32_bf16 v[46:49], v[206:209], v[156:159], v[46:49]
	v_mfma_f32_16x16x32_bf16 v[42:45], v[206:209], v[170:173], v[42:45]
	s_waitcnt lgkmcnt(1)
	v_mfma_f32_16x16x32_bf16 v[38:41], v[214:217], v[156:159], v[38:41]
	v_mfma_f32_16x16x32_bf16 v[34:37], v[214:217], v[170:173], v[34:37]
	v_mfma_f32_16x16x32_bf16 v[62:65], v[194:197], v[166:169], v[62:65]
	v_mfma_f32_16x16x32_bf16 v[58:61], v[194:197], v[186:189], v[58:61]
	v_mfma_f32_16x16x32_bf16 v[54:57], v[202:205], v[166:169], v[54:57]
	v_mfma_f32_16x16x32_bf16 v[50:53], v[202:205], v[186:189], v[50:53]
	v_mfma_f32_16x16x32_bf16 v[46:49], v[210:213], v[166:169], v[46:49]
	v_mfma_f32_16x16x32_bf16 v[42:45], v[210:213], v[186:189], v[42:45]
	s_waitcnt lgkmcnt(0)
	v_mfma_f32_16x16x32_bf16 v[38:41], v[218:221], v[166:169], v[38:41]
	v_mfma_f32_16x16x32_bf16 v[34:37], v[218:221], v[186:189], v[34:37]
	s_setprio 0
	s_barrier
	v_readfirstlane_b32 s38, v134
	s_add_i32 s37, s36, 0x40100
	s_mov_b32 m0, s38
	v_readfirstlane_b32 s38, v138
	buffer_load_dwordx4 v32, s[76:79], s37 offen lds
	s_mov_b32 m0, s38
	s_nop 0
	buffer_load_dwordx4 v130, s[76:79], s37 offen lds
	s_waitcnt vmcnt(6)
	s_barrier
	s_setprio 1
	v_mfma_f32_16x16x32_bf16 v[28:31], v[190:193], v[222:225], v[28:31]
	v_mfma_f32_16x16x32_bf16 v[24:27], v[190:193], v[230:233], v[24:27]
	v_mfma_f32_16x16x32_bf16 v[20:23], v[198:201], v[222:225], v[20:23]
	v_mfma_f32_16x16x32_bf16 v[16:19], v[198:201], v[230:233], v[16:19]
	v_mfma_f32_16x16x32_bf16 v[12:15], v[206:209], v[222:225], v[12:15]
	v_mfma_f32_16x16x32_bf16 v[8:11], v[206:209], v[230:233], v[8:11]
	v_mfma_f32_16x16x32_bf16 v[4:7], v[214:217], v[222:225], v[4:7]
	v_mfma_f32_16x16x32_bf16 v[0:3], v[214:217], v[230:233], v[0:3]
	v_mfma_f32_16x16x32_bf16 v[28:31], v[194:197], v[226:229], v[28:31]
	v_mfma_f32_16x16x32_bf16 v[24:27], v[194:197], v[234:237], v[24:27]
	v_mfma_f32_16x16x32_bf16 v[20:23], v[202:205], v[226:229], v[20:23]
	v_mfma_f32_16x16x32_bf16 v[16:19], v[202:205], v[234:237], v[16:19]
	v_mfma_f32_16x16x32_bf16 v[12:15], v[210:213], v[226:229], v[12:15]
	v_mfma_f32_16x16x32_bf16 v[8:11], v[210:213], v[234:237], v[8:11]
	v_mfma_f32_16x16x32_bf16 v[4:7], v[218:221], v[226:229], v[4:7]
	v_mfma_f32_16x16x32_bf16 v[0:3], v[218:221], v[234:237], v[0:3]
	s_setprio 0
	s_barrier
	ds_read_b128 v[156:159], v145
	ds_read_b128 v[166:169], v145 offset:1024
	ds_read_b128 v[170:173], v145 offset:2048
	ds_read_b128 v[186:189], v145 offset:3072
	v_readfirstlane_b32 s38, v132
	s_add_i32 s37, s35, 0x40100
	s_mov_b32 m0, s38
	v_readfirstlane_b32 s38, v131
	ds_read_b128 v[190:193], v143 offset:32768
	ds_read_b128 v[194:197], v143 offset:33792
	ds_read_b128 v[198:201], v142 offset:32768
	ds_read_b128 v[202:205], v142 offset:33792
	ds_read_b128 v[206:209], v141 offset:32768
	ds_read_b128 v[210:213], v141 offset:33792
	ds_read_b128 v[214:217], v140 offset:32768
	ds_read_b128 v[218:221], v140 offset:33792
	buffer_load_dwordx4 v32, s[4:7], s37 offen lds
	s_mov_b32 m0, s38
	s_nop 0
	buffer_load_dwordx4 v130, s[4:7], s37 offen lds
	s_waitcnt lgkmcnt(8)
	s_barrier
; #define STAGE(P, BASE, br, kt) do { int _so = ((br) * K + (kt) * BK) * 2; \
;     __builtin_amdgcn_raw_ptr_buffer_load_lds(rs_##BASE, (__attribute__((address_space(3))) void*)((char*)(P) + tx * 16), 16, voff0, _so, 0, 0); \
;     __builtin_amdgcn_raw_ptr_buffer_load_lds(rs_##BASE, (__attribute__((address_space(3))) void*)((char*)(P) + tx * 16 + 8192), 16, voff1, _so, 0, 0); } while (0)
; #define LDA(dst, b, h) _Pragma("unroll") for (int m = 0; m < 4; ++m) _Pragma("unroll") for (int k = 0; k < 2; ++k) \
;     dst[m][k] = *reinterpret_cast<const bf16x8*>((char*)SA(b, h) + lds_byte(wr * 64 + m * 16 + fr, k * 32 + fq * 8))
; #define LDB(dst, b, h) _Pragma("unroll") for (int n = 0; n < 2; ++n) _Pragma("unroll") for (int k = 0; k < 2; ++k) \
;     dst[n][k] = *reinterpret_cast<const bf16x8*>((char*)SB(b, h) + lds_byte(wc * 32 + n * 16 + fr, k * 32 + fq * 8))
; #define MMA(ai, bj, At, Bt_) do { __builtin_amdgcn_s_setprio(1); \
;     _Pragma("unroll") for (int m = 0; m < 4; ++m) _Pragma("unroll") for (int n = 0; n < 2; ++n) _Pragma("unroll") for (int k = 0; k < 2; ++k) \
;       acc[ai][bj][m][n] = __builtin_amdgcn_mfma_f32_16x16x32_bf16(At[m][k], Bt_[n][k], acc[ai][bj][m][n], 0, 0, 0); \
;     __builtin_amdgcn_s_setprio(0); } while (0)
; #define WAIT_V(n) asm volatile("s_waitcnt vmcnt(" #n ")" ::: "memory")
; #define WAIT_L(n) asm volatile("s_waitcnt lgkmcnt(" #n ")" ::: "memory")
; template <class Epi> ...
;     ...
;   for (int t = 0; t < nt - 2; t += 2) {
;     LDB(B0, 0, 0); SCHED; LDA(At, 0, 0); STAGE(SA(1, 1), A, brow + HALF, t + 1);
;     WAIT_L(8); BAR; WAIT_L(0); MMA(0, 0, At, B0); BAR; SCHED;
;     LDB(B1, 0, 1); STAGE(SB(0, 0), Bt, bcol, t + 2);
;     BAR; WAIT_L(0); MMA(0, 1, At, B1); BAR;
;     LDA(At, 0, 1); STAGE(SA(0, 0), A, brow, t + 2);
;     BAR; WAIT_L(0); MMA(1, 0, At, B0); BAR; SCHED;
;     STAGE(SB(0, 1), Bt, bcol + HALF, t + 2);
;     WAIT_V(6); BAR; MMA(1, 1, At, B1); BAR;
;     LDB(B0, 1, 0); SCHED; LDA(At, 1, 0); STAGE(SA(0, 1), A, brow + HALF, t + 2);
;     WAIT_L(8); BAR; WAIT_L(0); MMA(0, 0, At, B0); BAR; SCHED;
;     LDB(B1, 1, 1); STAGE(SB(1, 0), Bt, bcol, t + 3);
;     BAR; WAIT_L(0); MMA(0, 1, At, B1); BAR;
;     LDA(At, 1, 1); STAGE(SA(1, 0), A, brow, t + 3);
;     BAR; WAIT_L(0); MMA(1, 0, At, B0); BAR; SCHED;
;     STAGE(SB(1, 1), Bt, bcol + HALF, t + 3);
;     WAIT_V(6); BAR; MMA(1, 1, At, B1); BAR;
;   }
	s_setprio 1
	s_waitcnt lgkmcnt(7)
	v_mfma_f32_16x16x32_bf16 v[126:129], v[190:193], v[156:159], v[126:129]
	v_mfma_f32_16x16x32_bf16 v[122:125], v[190:193], v[170:173], v[122:125]
	s_waitcnt lgkmcnt(5)
	v_mfma_f32_16x16x32_bf16 v[118:121], v[198:201], v[156:159], v[118:121]
	v_mfma_f32_16x16x32_bf16 v[114:117], v[198:201], v[170:173], v[114:117]
	s_waitcnt lgkmcnt(3)
	v_mfma_f32_16x16x32_bf16 v[110:113], v[206:209], v[156:159], v[110:113]
	v_mfma_f32_16x16x32_bf16 v[106:109], v[206:209], v[170:173], v[106:109]
	s_waitcnt lgkmcnt(1)
	v_mfma_f32_16x16x32_bf16 v[102:105], v[214:217], v[156:159], v[102:105]
	v_mfma_f32_16x16x32_bf16 v[98:101], v[214:217], v[170:173], v[98:101]
	v_mfma_f32_16x16x32_bf16 v[126:129], v[194:197], v[166:169], v[126:129]
	v_mfma_f32_16x16x32_bf16 v[122:125], v[194:197], v[186:189], v[122:125]
	v_mfma_f32_16x16x32_bf16 v[118:121], v[202:205], v[166:169], v[118:121]
	v_mfma_f32_16x16x32_bf16 v[114:117], v[202:205], v[186:189], v[114:117]
	v_mfma_f32_16x16x32_bf16 v[110:113], v[210:213], v[166:169], v[110:113]
	v_mfma_f32_16x16x32_bf16 v[106:109], v[210:213], v[186:189], v[106:109]
	s_waitcnt lgkmcnt(0)
	v_mfma_f32_16x16x32_bf16 v[102:105], v[218:221], v[166:169], v[102:105]
	v_mfma_f32_16x16x32_bf16 v[98:101], v[218:221], v[186:189], v[98:101]
	s_setprio 0
	s_barrier
	v_readfirstlane_b32 s38, v146
	s_add_i32 s37, s36, 0x180
	s_mov_b32 m0, s38
	v_readfirstlane_b32 s38, v147
	ds_read_b128 v[222:225], v144
	ds_read_b128 v[226:229], v144 offset:1024
	ds_read_b128 v[230:233], v144 offset:2048
	ds_read_b128 v[234:237], v144 offset:3072
	buffer_load_dwordx4 v32, s[76:79], s37 offen lds
	s_mov_b32 m0, s38
	s_nop 0
	buffer_load_dwordx4 v130, s[76:79], s37 offen lds
	s_barrier
	s_setprio 1
	s_waitcnt lgkmcnt(3)
	v_mfma_f32_16x16x32_bf16 v[94:97], v[190:193], v[222:225], v[94:97]
	s_waitcnt lgkmcnt(1)
	v_mfma_f32_16x16x32_bf16 v[90:93], v[190:193], v[230:233], v[90:93]
	v_mfma_f32_16x16x32_bf16 v[86:89], v[198:201], v[222:225], v[86:89]
	v_mfma_f32_16x16x32_bf16 v[82:85], v[198:201], v[230:233], v[82:85]
	v_mfma_f32_16x16x32_bf16 v[78:81], v[206:209], v[222:225], v[78:81]
	v_mfma_f32_16x16x32_bf16 v[74:77], v[206:209], v[230:233], v[74:77]
	v_mfma_f32_16x16x32_bf16 v[70:73], v[214:217], v[222:225], v[70:73]
	v_mfma_f32_16x16x32_bf16 v[66:69], v[214:217], v[230:233], v[66:69]
	v_mfma_f32_16x16x32_bf16 v[94:97], v[194:197], v[226:229], v[94:97]
	s_waitcnt lgkmcnt(0)
	v_mfma_f32_16x16x32_bf16 v[90:93], v[194:197], v[234:237], v[90:93]
	v_mfma_f32_16x16x32_bf16 v[86:89], v[202:205], v[226:229], v[86:89]
	v_mfma_f32_16x16x32_bf16 v[82:85], v[202:205], v[234:237], v[82:85]
	v_mfma_f32_16x16x32_bf16 v[78:81], v[210:213], v[226:229], v[78:81]
	v_mfma_f32_16x16x32_bf16 v[74:77], v[210:213], v[234:237], v[74:77]
	v_mfma_f32_16x16x32_bf16 v[70:73], v[218:221], v[226:229], v[70:73]
	v_mfma_f32_16x16x32_bf16 v[66:69], v[218:221], v[234:237], v[66:69]
	s_setprio 0
	v_readfirstlane_b32 s37, v148
	s_addk_i32 s35, 0x180
	s_mov_b32 m0, s37
	v_readfirstlane_b32 s37, v150
	s_barrier
	ds_read_b128 v[190:193], v143 offset:49152
	ds_read_b128 v[194:197], v143 offset:50176
	ds_read_b128 v[198:201], v142 offset:49152
	ds_read_b128 v[202:205], v142 offset:50176
	ds_read_b128 v[206:209], v141 offset:49152
	ds_read_b128 v[210:213], v141 offset:50176
	ds_read_b128 v[214:217], v140 offset:49152
	ds_read_b128 v[218:221], v140 offset:50176
	buffer_load_dwordx4 v32, s[4:7], s35 offen lds
	s_mov_b32 m0, s37
	s_nop 0
	buffer_load_dwordx4 v130, s[4:7], s35 offen lds
	s_barrier
	s_setprio 1
	s_waitcnt lgkmcnt(7)
	v_mfma_f32_16x16x32_bf16 v[62:65], v[190:193], v[156:159], v[62:65]
	v_mfma_f32_16x16x32_bf16 v[58:61], v[190:193], v[170:173], v[58:61]
	s_waitcnt lgkmcnt(5)
	v_mfma_f32_16x16x32_bf16 v[54:57], v[198:201], v[156:159], v[54:57]
	v_mfma_f32_16x16x32_bf16 v[50:53], v[198:201], v[170:173], v[50:53]
	s_waitcnt lgkmcnt(3)
	v_mfma_f32_16x16x32_bf16 v[46:49], v[206:209], v[156:159], v[46:49]
	v_mfma_f32_16x16x32_bf16 v[42:45], v[206:209], v[170:173], v[42:45]
	s_waitcnt lgkmcnt(1)
	v_mfma_f32_16x16x32_bf16 v[38:41], v[214:217], v[156:159], v[38:41]
	v_mfma_f32_16x16x32_bf16 v[34:37], v[214:217], v[170:173], v[34:37]
	v_mfma_f32_16x16x32_bf16 v[62:65], v[194:197], v[166:169], v[62:65]
	v_mfma_f32_16x16x32_bf16 v[58:61], v[194:197], v[186:189], v[58:61]
	v_mfma_f32_16x16x32_bf16 v[54:57], v[202:205], v[166:169], v[54:57]
	v_mfma_f32_16x16x32_bf16 v[50:53], v[202:205], v[186:189], v[50:53]
	v_mfma_f32_16x16x32_bf16 v[46:49], v[210:213], v[166:169], v[46:49]
	v_mfma_f32_16x16x32_bf16 v[42:45], v[210:213], v[186:189], v[42:45]
	s_waitcnt lgkmcnt(0)
	v_mfma_f32_16x16x32_bf16 v[38:41], v[218:221], v[166:169], v[38:41]
	v_mfma_f32_16x16x32_bf16 v[34:37], v[218:221], v[186:189], v[34:37]
	s_setprio 0
	s_barrier
	v_readfirstlane_b32 s35, v153
	s_add_i32 s36, s36, 0x40180
	s_mov_b32 m0, s35
	v_readfirstlane_b32 s35, v154
	buffer_load_dwordx4 v32, s[76:79], s36 offen lds
	s_mov_b32 m0, s35
	s_nop 0
	buffer_load_dwordx4 v130, s[76:79], s36 offen lds
	s_waitcnt vmcnt(6)
	s_barrier
	s_setprio 1
	v_mfma_f32_16x16x32_bf16 v[28:31], v[190:193], v[222:225], v[28:31]
	v_mfma_f32_16x16x32_bf16 v[24:27], v[190:193], v[230:233], v[24:27]
	v_mfma_f32_16x16x32_bf16 v[20:23], v[198:201], v[222:225], v[20:23]
	v_mfma_f32_16x16x32_bf16 v[16:19], v[198:201], v[230:233], v[16:19]
	v_mfma_f32_16x16x32_bf16 v[12:15], v[206:209], v[222:225], v[12:15]
	v_mfma_f32_16x16x32_bf16 v[8:11], v[206:209], v[230:233], v[8:11]
	v_mfma_f32_16x16x32_bf16 v[4:7], v[214:217], v[222:225], v[4:7]
	v_mfma_f32_16x16x32_bf16 v[0:3], v[214:217], v[230:233], v[0:3]
	v_mfma_f32_16x16x32_bf16 v[28:31], v[194:197], v[226:229], v[28:31]
	v_mfma_f32_16x16x32_bf16 v[24:27], v[194:197], v[234:237], v[24:27]
	v_mfma_f32_16x16x32_bf16 v[20:23], v[202:205], v[226:229], v[20:23]
	v_mfma_f32_16x16x32_bf16 v[16:19], v[202:205], v[234:237], v[16:19]
	v_mfma_f32_16x16x32_bf16 v[12:15], v[210:213], v[226:229], v[12:15]
	v_mfma_f32_16x16x32_bf16 v[8:11], v[210:213], v[234:237], v[8:11]
	v_mfma_f32_16x16x32_bf16 v[4:7], v[218:221], v[226:229], v[4:7]
	v_mfma_f32_16x16x32_bf16 v[0:3], v[218:221], v[234:237], v[0:3]
	s_setprio 0
	s_add_i32 s31, s31, 2
	s_addk_i32 s34, 0x100
	s_cmp_lt_u32 s31, 12
	s_barrier
	s_cbranch_scc1 .LBB0_74
; #define STAGE(P, BASE, br, kt) do { int _so = ((br) * K + (kt) * BK) * 2; \
;     __builtin_amdgcn_raw_ptr_buffer_load_lds(rs_##BASE, (__attribute__((address_space(3))) void*)((char*)(P) + tx * 16), 16, voff0, _so, 0, 0); \
;     __builtin_amdgcn_raw_ptr_buffer_load_lds(rs_##BASE, (__attribute__((address_space(3))) void*)((char*)(P) + tx * 16 + 8192), 16, voff1, _so, 0, 0); } while (0)
; #define LDA(dst, b, h) _Pragma("unroll") for (int m = 0; m < 4; ++m) _Pragma("unroll") for (int k = 0; k < 2; ++k) \
;     dst[m][k] = *reinterpret_cast<const bf16x8*>((char*)SA(b, h) + lds_byte(wr * 64 + m * 16 + fr, k * 32 + fq * 8))
; #define LDB(dst, b, h) _Pragma("unroll") for (int n = 0; n < 2; ++n) _Pragma("unroll") for (int k = 0; k < 2; ++k) \
;     dst[n][k] = *reinterpret_cast<const bf16x8*>((char*)SB(b, h) + lds_byte(wc * 32 + n * 16 + fr, k * 32 + fq * 8))
; #define MMA(ai, bj, At, Bt_) do { __builtin_amdgcn_s_setprio(1); \
;     _Pragma("unroll") for (int m = 0; m < 4; ++m) _Pragma("unroll") for (int n = 0; n < 2; ++n) _Pragma("unroll") for (int k = 0; k < 2; ++k) \
;       acc[ai][bj][m][n] = __builtin_amdgcn_mfma_f32_16x16x32_bf16(At[m][k], Bt_[n][k], acc[ai][bj][m][n], 0, 0, 0); \
;     __builtin_amdgcn_s_setprio(0); } while (0)
; #define WAIT_V(n) asm volatile("s_waitcnt vmcnt(" #n ")" ::: "memory")
; #define WAIT_L(n) asm volatile("s_waitcnt lgkmcnt(" #n ")" ::: "memory")
; #define BAR __builtin_amdgcn_s_barrier()
; template <class Epi> ...
;     ...
;   { LDB(B0, 0, 0); LDA(At, 0, 0); STAGE(SA(1, 1), A, brow + HALF, nt - 1);
;     BAR; WAIT_L(0); MMA(0, 0, At, B0); BAR;
;     LDB(B1, 0, 1); BAR; WAIT_L(0); MMA(0, 1, At, B1); BAR;
;     LDA(At, 0, 1); WAIT_V(4); BAR; WAIT_L(0); MMA(1, 0, At, B0); MMA(1, 1, At, B1); BAR; }
;   { LDB(B0, 1, 0); LDA(At, 1, 0); WAIT_V(2); BAR; WAIT_L(0); MMA(0, 0, At, B0); BAR;
.Lpx0:
	v_readfirstlane_b32 s20, v152
	s_add_i32 s21, s21, 0x40780
	s_mov_b32 s6, s78
	s_mov_b32 s7, s79
	s_mov_b32 m0, s20
	v_readfirstlane_b32 s20, v151
	ds_read_b128 v[156:159], v155
	ds_read_b128 v[166:169], v155 offset:1024
	ds_read_b128 v[170:173], v155 offset:2048
	ds_read_b128 v[186:189], v155 offset:3072
	ds_read_b128 v[190:193], v143
	ds_read_b128 v[194:197], v143 offset:1024
	ds_read_b128 v[198:201], v142
	ds_read_b128 v[202:205], v142 offset:1024
	ds_read_b128 v[206:209], v141
	ds_read_b128 v[210:213], v141 offset:1024
	ds_read_b128 v[214:217], v140
	ds_read_b128 v[218:221], v140 offset:1024
	buffer_load_dwordx4 v32, s[4:7], s21 offen lds
	s_mov_b32 m0, s20
	s_nop 0
	buffer_load_dwordx4 v130, s[4:7], s21 offen lds
	s_barrier
	s_setprio 1
	s_waitcnt lgkmcnt(7)
	v_mfma_f32_16x16x32_bf16 v[126:129], v[190:193], v[156:159], v[126:129]
	v_mfma_f32_16x16x32_bf16 v[122:125], v[190:193], v[170:173], v[122:125]
	s_waitcnt lgkmcnt(5)
	v_mfma_f32_16x16x32_bf16 v[118:121], v[198:201], v[156:159], v[118:121]
	v_mfma_f32_16x16x32_bf16 v[114:117], v[198:201], v[170:173], v[114:117]
	s_waitcnt lgkmcnt(3)
	v_mfma_f32_16x16x32_bf16 v[110:113], v[206:209], v[156:159], v[110:113]
	v_mfma_f32_16x16x32_bf16 v[106:109], v[206:209], v[170:173], v[106:109]
	s_waitcnt lgkmcnt(1)
	v_mfma_f32_16x16x32_bf16 v[102:105], v[214:217], v[156:159], v[102:105]
	v_mfma_f32_16x16x32_bf16 v[98:101], v[214:217], v[170:173], v[98:101]
	v_mfma_f32_16x16x32_bf16 v[126:129], v[194:197], v[166:169], v[126:129]
	v_mfma_f32_16x16x32_bf16 v[122:125], v[194:197], v[186:189], v[122:125]
	v_mfma_f32_16x16x32_bf16 v[118:121], v[202:205], v[166:169], v[118:121]
	v_mfma_f32_16x16x32_bf16 v[114:117], v[202:205], v[186:189], v[114:117]
	v_mfma_f32_16x16x32_bf16 v[110:113], v[210:213], v[166:169], v[110:113]
	v_mfma_f32_16x16x32_bf16 v[106:109], v[210:213], v[186:189], v[106:109]
	s_waitcnt lgkmcnt(0)
	v_mfma_f32_16x16x32_bf16 v[102:105], v[218:221], v[166:169], v[102:105]
	v_mfma_f32_16x16x32_bf16 v[98:101], v[218:221], v[186:189], v[98:101]
	s_setprio 0
	s_barrier
	ds_read_b128 v[150:153], v149
	ds_read_b128 v[222:225], v149 offset:1024
	ds_read_b128 v[226:229], v149 offset:2048
	ds_read_b128 v[146:149], v149 offset:3072
	s_barrier
	s_setprio 1
	s_waitcnt lgkmcnt(3)
	v_mfma_f32_16x16x32_bf16 v[78:81], v[206:209], v[150:153], v[78:81]
	s_waitcnt lgkmcnt(1)
	v_mfma_f32_16x16x32_bf16 v[74:77], v[206:209], v[226:229], v[74:77]
	v_mfma_f32_16x16x32_bf16 v[70:73], v[214:217], v[150:153], v[70:73]
	v_mfma_f32_16x16x32_bf16 v[66:69], v[214:217], v[226:229], v[66:69]
	v_mfma_f32_16x16x32_bf16 v[94:97], v[190:193], v[150:153], v[94:97]
	v_mfma_f32_16x16x32_bf16 v[90:93], v[190:193], v[226:229], v[90:93]
	v_mfma_f32_16x16x32_bf16 v[86:89], v[198:201], v[150:153], v[86:89]
	v_mfma_f32_16x16x32_bf16 v[82:85], v[198:201], v[226:229], v[82:85]
	v_mfma_f32_16x16x32_bf16 v[78:81], v[210:213], v[222:225], v[78:81]
	s_waitcnt lgkmcnt(0)
	v_mfma_f32_16x16x32_bf16 v[74:77], v[210:213], v[146:149], v[74:77]
	v_mfma_f32_16x16x32_bf16 v[70:73], v[218:221], v[222:225], v[70:73]
	v_mfma_f32_16x16x32_bf16 v[66:69], v[218:221], v[146:149], v[66:69]
	v_mfma_f32_16x16x32_bf16 v[230:233], v[194:197], v[222:225], v[94:97]
	v_mfma_f32_16x16x32_bf16 v[190:193], v[194:197], v[146:149], v[90:93]
	v_mfma_f32_16x16x32_bf16 v[194:197], v[202:205], v[222:225], v[86:89]
	v_mfma_f32_16x16x32_bf16 v[198:201], v[202:205], v[146:149], v[82:85]
	s_setprio 0
	s_barrier
	s_nop 0
	ds_read_b128 v[82:85], v143 offset:16384
	ds_read_b128 v[86:89], v143 offset:17408
	ds_read_b128 v[90:93], v142 offset:16384
	ds_read_b128 v[94:97], v142 offset:17408
	ds_read_b128 v[202:205], v141 offset:16384
	ds_read_b128 v[206:209], v141 offset:17408
	ds_read_b128 v[210:213], v140 offset:16384
	ds_read_b128 v[214:217], v140 offset:17408
	s_waitcnt vmcnt(4)
	s_barrier
	s_setprio 1
	s_waitcnt lgkmcnt(3)
	v_mfma_f32_16x16x32_bf16 v[46:49], v[202:205], v[156:159], v[46:49]
	v_mfma_f32_16x16x32_bf16 v[42:45], v[202:205], v[170:173], v[42:45]
	s_waitcnt lgkmcnt(1)
	v_mfma_f32_16x16x32_bf16 v[38:41], v[210:213], v[156:159], v[38:41]
	v_mfma_f32_16x16x32_bf16 v[34:37], v[210:213], v[170:173], v[34:37]
	v_mfma_f32_16x16x32_bf16 v[62:65], v[82:85], v[156:159], v[62:65]
	v_mfma_f32_16x16x32_bf16 v[58:61], v[82:85], v[170:173], v[58:61]
	v_mfma_f32_16x16x32_bf16 v[54:57], v[90:93], v[156:159], v[54:57]
	v_mfma_f32_16x16x32_bf16 v[50:53], v[90:93], v[170:173], v[50:53]
	v_mfma_f32_16x16x32_bf16 v[46:49], v[206:209], v[166:169], v[46:49]
	v_mfma_f32_16x16x32_bf16 v[42:45], v[206:209], v[186:189], v[42:45]
	s_waitcnt lgkmcnt(0)
	v_mfma_f32_16x16x32_bf16 v[38:41], v[214:217], v[166:169], v[38:41]
	v_mfma_f32_16x16x32_bf16 v[34:37], v[214:217], v[186:189], v[34:37]
	v_mfma_f32_16x16x32_bf16 v[218:221], v[86:89], v[166:169], v[62:65]
	v_mfma_f32_16x16x32_bf16 v[234:237], v[86:89], v[186:189], v[58:61]
	v_mfma_f32_16x16x32_bf16 v[238:241], v[94:97], v[166:169], v[54:57]
	v_mfma_f32_16x16x32_bf16 v[242:245], v[94:97], v[186:189], v[50:53]
	s_setprio 0
	s_setprio 1
	v_mfma_f32_16x16x32_bf16 v[0:3], v[210:213], v[226:229], v[0:3]
	v_mfma_f32_16x16x32_bf16 v[28:31], v[82:85], v[150:153], v[28:31]
	v_mfma_f32_16x16x32_bf16 v[24:27], v[82:85], v[226:229], v[24:27]
	v_mfma_f32_16x16x32_bf16 v[20:23], v[90:93], v[150:153], v[20:23]
	v_mfma_f32_16x16x32_bf16 v[16:19], v[90:93], v[226:229], v[16:19]
	v_mfma_f32_16x16x32_bf16 v[12:15], v[202:205], v[150:153], v[12:15]
	v_mfma_f32_16x16x32_bf16 v[8:11], v[202:205], v[226:229], v[8:11]
	v_mfma_f32_16x16x32_bf16 v[4:7], v[210:213], v[150:153], v[4:7]
	v_mfma_f32_16x16x32_bf16 v[0:3], v[214:217], v[146:149], v[0:3]
	v_mfma_f32_16x16x32_bf16 v[154:157], v[86:89], v[222:225], v[28:31]
	v_mfma_f32_16x16x32_bf16 v[158:161], v[86:89], v[146:149], v[24:27]
	v_mfma_f32_16x16x32_bf16 v[166:169], v[94:97], v[222:225], v[20:23]
	v_mfma_f32_16x16x32_bf16 v[170:173], v[94:97], v[146:149], v[16:19]
	v_mfma_f32_16x16x32_bf16 v[186:189], v[206:209], v[222:225], v[12:15]
	v_mfma_f32_16x16x32_bf16 v[202:205], v[206:209], v[146:149], v[8:11]
	v_mfma_f32_16x16x32_bf16 v[150:153], v[214:217], v[222:225], v[4:7]
	s_setprio 0
	s_barrier
; #define LDA(dst, b, h) _Pragma("unroll") for (int m = 0; m < 4; ++m) _Pragma("unroll") for (int k = 0; k < 2; ++k) \
;     dst[m][k] = *reinterpret_cast<const bf16x8*>((char*)SA(b, h) + lds_byte(wr * 64 + m * 16 + fr, k * 32 + fq * 8))
; #define LDB(dst, b, h) _Pragma("unroll") for (int n = 0; n < 2; ++n) _Pragma("unroll") for (int k = 0; k < 2; ++k) \
;     dst[n][k] = *reinterpret_cast<const bf16x8*>((char*)SB(b, h) + lds_byte(wc * 32 + n * 16 + fr, k * 32 + fq * 8))
; #define MMA(ai, bj, At, Bt_) do { __builtin_amdgcn_s_setprio(1); \
;     _Pragma("unroll") for (int m = 0; m < 4; ++m) _Pragma("unroll") for (int n = 0; n < 2; ++n) _Pragma("unroll") for (int k = 0; k < 2; ++k) \
;       acc[ai][bj][m][n] = __builtin_amdgcn_mfma_f32_16x16x32_bf16(At[m][k], Bt_[n][k], acc[ai][bj][m][n], 0, 0, 0); \
;     __builtin_amdgcn_s_setprio(0); } while (0)
; #define WAIT_V(n) asm volatile("s_waitcnt vmcnt(" #n ")" ::: "memory")
; #define WAIT_L(n) asm volatile("s_waitcnt lgkmcnt(" #n ")" ::: "memory")
; #define BAR __builtin_amdgcn_s_barrier()
; template <class Epi> ...
;     ...
;   { LDB(B0, 1, 0); LDA(At, 1, 0); WAIT_V(2); BAR; WAIT_L(0); MMA(0, 0, At, B0); BAR;
;     LDB(B1, 1, 1); WAIT_V(0); BAR; WAIT_L(0); MMA(0, 1, At, B1); BAR;
;     LDA(At, 1, 1); BAR; WAIT_L(0); MMA(1, 0, At, B0); MMA(1, 1, At, B1); BAR; }
;   if (wr == 0) BAR;
	s_nop 0
	ds_read_b128 v[4:7], v145
	ds_read_b128 v[8:11], v145 offset:1024
	ds_read_b128 v[12:15], v145 offset:2048
	ds_read_b128 v[146:149], v145 offset:3072
	ds_read_b128 v[16:19], v143 offset:32768
	ds_read_b128 v[20:23], v143 offset:33792
	ds_read_b128 v[24:27], v142 offset:32768
	ds_read_b128 v[50:53], v142 offset:33792
	ds_read_b128 v[206:209], v141 offset:32768
	ds_read_b128 v[210:213], v141 offset:33792
	ds_read_b128 v[214:217], v140 offset:32768
	ds_read_b128 v[222:225], v140 offset:33792
	s_waitcnt vmcnt(2)
	s_barrier
	s_setprio 1
	s_waitcnt lgkmcnt(7)
	v_mfma_f32_16x16x32_bf16 v[28:31], v[16:19], v[4:7], v[126:129]
	s_waitcnt lgkmcnt(6)
	v_mfma_f32_16x16x32_bf16 v[126:129], v[20:23], v[8:11], v[28:31]
	v_mfma_f32_16x16x32_bf16 v[28:31], v[16:19], v[12:15], v[122:125]
	v_mfma_f32_16x16x32_bf16 v[94:97], v[20:23], v[146:149], v[28:31]
	s_waitcnt lgkmcnt(5)
	v_mfma_f32_16x16x32_bf16 v[28:31], v[24:27], v[4:7], v[118:121]
	s_waitcnt lgkmcnt(4)
	v_mfma_f32_16x16x32_bf16 v[122:125], v[50:53], v[8:11], v[28:31]
	v_mfma_f32_16x16x32_bf16 v[28:31], v[24:27], v[12:15], v[114:117]
	v_mfma_f32_16x16x32_bf16 v[90:93], v[50:53], v[146:149], v[28:31]
	s_waitcnt lgkmcnt(3)
	v_mfma_f32_16x16x32_bf16 v[28:31], v[206:209], v[4:7], v[110:113]
	s_waitcnt lgkmcnt(2)
	v_mfma_f32_16x16x32_bf16 v[118:121], v[210:213], v[8:11], v[28:31]
	v_mfma_f32_16x16x32_bf16 v[28:31], v[206:209], v[12:15], v[106:109]
	v_mfma_f32_16x16x32_bf16 v[86:89], v[210:213], v[146:149], v[28:31]
	s_waitcnt lgkmcnt(1)
	v_mfma_f32_16x16x32_bf16 v[28:31], v[214:217], v[4:7], v[102:105]
	s_waitcnt lgkmcnt(0)
	v_mfma_f32_16x16x32_bf16 v[114:117], v[222:225], v[8:11], v[28:31]
	v_mfma_f32_16x16x32_bf16 v[28:31], v[214:217], v[12:15], v[98:101]
	v_mfma_f32_16x16x32_bf16 v[82:85], v[222:225], v[146:149], v[28:31]
	s_setprio 0
	s_barrier
	ds_read_b128 v[226:229], v144
	ds_read_b128 v[246:249], v144 offset:1024
	ds_read_b128 v[250:253], v144 offset:2048
	ds_read_b128 v[174:177], v144 offset:3072
	s_waitcnt vmcnt(0)
	s_barrier
	s_setprio 1
	s_waitcnt lgkmcnt(3)
	v_mfma_f32_16x16x32_bf16 v[28:31], v[16:19], v[226:229], v[230:233]
	s_waitcnt lgkmcnt(1)
	v_mfma_f32_16x16x32_bf16 v[16:19], v[16:19], v[250:253], v[190:193]
	v_mfma_f32_16x16x32_bf16 v[62:65], v[20:23], v[246:249], v[28:31]
	s_waitcnt lgkmcnt(0)
	v_mfma_f32_16x16x32_bf16 v[28:31], v[20:23], v[174:177], v[16:19]
	v_mfma_f32_16x16x32_bf16 v[16:19], v[24:27], v[226:229], v[194:197]
	v_mfma_f32_16x16x32_bf16 v[58:61], v[50:53], v[246:249], v[16:19]
	v_mfma_f32_16x16x32_bf16 v[16:19], v[24:27], v[250:253], v[198:201]
	v_mfma_f32_16x16x32_bf16 v[24:27], v[50:53], v[174:177], v[16:19]
	v_mfma_f32_16x16x32_bf16 v[16:19], v[206:209], v[226:229], v[78:81]
	v_mfma_f32_16x16x32_bf16 v[54:57], v[210:213], v[246:249], v[16:19]
	v_mfma_f32_16x16x32_bf16 v[16:19], v[206:209], v[250:253], v[74:77]
	v_mfma_f32_16x16x32_bf16 v[20:23], v[210:213], v[174:177], v[16:19]
	v_mfma_f32_16x16x32_bf16 v[16:19], v[214:217], v[226:229], v[70:73]
	v_mfma_f32_16x16x32_bf16 v[50:53], v[222:225], v[246:249], v[16:19]
	v_mfma_f32_16x16x32_bf16 v[16:19], v[214:217], v[250:253], v[66:69]
	v_mfma_f32_16x16x32_bf16 v[16:19], v[222:225], v[174:177], v[16:19]
	s_setprio 0
	s_barrier
	ds_read_b128 v[190:193], v143 offset:49152
	ds_read_b128 v[194:197], v143 offset:50176
	ds_read_b128 v[198:201], v142 offset:49152
	ds_read_b128 v[142:145], v142 offset:50176
	ds_read_b128 v[206:209], v141 offset:49152
	ds_read_b128 v[210:213], v141 offset:50176
	ds_read_b128 v[214:217], v140 offset:49152
	ds_read_b128 v[222:225], v140 offset:50176
	s_barrier
	s_setprio 1
	s_waitcnt lgkmcnt(7)
	v_mfma_f32_16x16x32_bf16 v[66:69], v[190:193], v[4:7], v[218:221]
	s_waitcnt lgkmcnt(6)
	v_mfma_f32_16x16x32_bf16 v[110:113], v[194:197], v[8:11], v[66:69]
	v_mfma_f32_16x16x32_bf16 v[66:69], v[190:193], v[12:15], v[234:237]
	v_mfma_f32_16x16x32_bf16 v[78:81], v[194:197], v[146:149], v[66:69]
	s_waitcnt lgkmcnt(5)
	v_mfma_f32_16x16x32_bf16 v[66:69], v[198:201], v[4:7], v[238:241]
	s_waitcnt lgkmcnt(3)
	v_mfma_f32_16x16x32_bf16 v[46:49], v[206:209], v[4:7], v[46:49]
	s_waitcnt lgkmcnt(1)
	v_mfma_f32_16x16x32_bf16 v[4:7], v[214:217], v[4:7], v[38:41]
	v_mfma_f32_16x16x32_bf16 v[106:109], v[142:145], v[8:11], v[66:69]
	v_mfma_f32_16x16x32_bf16 v[66:69], v[198:201], v[12:15], v[242:245]
	v_mfma_f32_16x16x32_bf16 v[42:45], v[206:209], v[12:15], v[42:45]
	s_waitcnt lgkmcnt(0)
	v_mfma_f32_16x16x32_bf16 v[98:101], v[222:225], v[8:11], v[4:7]
	v_mfma_f32_16x16x32_bf16 v[4:7], v[214:217], v[12:15], v[34:37]
	v_mfma_f32_16x16x32_bf16 v[74:77], v[142:145], v[146:149], v[66:69]
	v_mfma_f32_16x16x32_bf16 v[102:105], v[210:213], v[8:11], v[46:49]
	v_mfma_f32_16x16x32_bf16 v[70:73], v[210:213], v[146:149], v[42:45]
	v_mfma_f32_16x16x32_bf16 v[66:69], v[222:225], v[146:149], v[4:7]
	s_setprio 0
	s_setprio 1
	v_mfma_f32_16x16x32_bf16 v[4:7], v[190:193], v[226:229], v[154:157]
	v_mfma_f32_16x16x32_bf16 v[46:49], v[194:197], v[246:249], v[4:7]
	v_mfma_f32_16x16x32_bf16 v[4:7], v[190:193], v[250:253], v[158:161]
	v_mfma_f32_16x16x32_bf16 v[12:15], v[194:197], v[174:177], v[4:7]
	v_mfma_f32_16x16x32_bf16 v[4:7], v[198:201], v[226:229], v[166:169]
	v_mfma_f32_16x16x32_bf16 v[42:45], v[142:145], v[246:249], v[4:7]
	v_mfma_f32_16x16x32_bf16 v[4:7], v[198:201], v[250:253], v[170:173]
	v_mfma_f32_16x16x32_bf16 v[8:11], v[142:145], v[174:177], v[4:7]
	v_mfma_f32_16x16x32_bf16 v[4:7], v[206:209], v[226:229], v[186:189]
	v_mfma_f32_16x16x32_bf16 v[38:41], v[210:213], v[246:249], v[4:7]
	v_mfma_f32_16x16x32_bf16 v[4:7], v[206:209], v[250:253], v[202:205]
	v_mfma_f32_16x16x32_bf16 v[34:37], v[214:217], v[226:229], v[150:153]
	v_mfma_f32_16x16x32_bf16 v[0:3], v[214:217], v[250:253], v[0:3]
	v_mfma_f32_16x16x32_bf16 v[4:7], v[210:213], v[174:177], v[4:7]
	v_mfma_f32_16x16x32_bf16 v[34:37], v[222:225], v[246:249], v[34:37]
	v_mfma_f32_16x16x32_bf16 v[0:3], v[222:225], v[174:177], v[0:3]
	s_setprio 0
	v_cmp_gt_u32_e32 vcc, s59, v133
	s_barrier
	s_and_saveexec_b64 s[4:5], vcc
	s_cbranch_execz .LBB0_77
	s_barrier

; #define STAGE(P, BASE, br, kt) do { int _so = ((br) * K + (kt) * BK) * 2; \
;     __builtin_amdgcn_raw_ptr_buffer_load_lds(rs_##BASE, (__attribute__((address_space(3))) void*)((char*)(P) + tx * 16), 16, voff0, _so, 0, 0); \
;     __builtin_amdgcn_raw_ptr_buffer_load_lds(rs_##BASE, (__attribute__((address_space(3))) void*)((char*)(P) + tx * 16 + 8192), 16, voff1, _so, 0, 0); } while (0)
; #define LDA(dst, b, h) _Pragma("unroll") for (int m = 0; m < 4; ++m) _Pragma("unroll") for (int k = 0; k < 2; ++k) \
;     dst[m][k] = *reinterpret_cast<const bf16x8*>((char*)SA(b, h) + lds_byte(wr * 64 + m * 16 + fr, k * 32 + fq * 8))
; #define LDB(dst, b, h) _Pragma("unroll") for (int n = 0; n < 2; ++n) _Pragma("unroll") for (int k = 0; k < 2; ++k) \
;     dst[n][k] = *reinterpret_cast<const bf16x8*>((char*)SB(b, h) + lds_byte(wc * 32 + n * 16 + fr, k * 32 + fq * 8))
; #define MMA(ai, bj, At, Bt_) do { __builtin_amdgcn_s_setprio(1); \
;     _Pragma("unroll") for (int m = 0; m < 4; ++m) _Pragma("unroll") for (int n = 0; n < 2; ++n) _Pragma("unroll") for (int k = 0; k < 2; ++k) \
;       acc[ai][bj][m][n] = __builtin_amdgcn_mfma_f32_16x16x32_bf16(At[m][k], Bt_[n][k], acc[ai][bj][m][n], 0, 0, 0); \
;     __builtin_amdgcn_s_setprio(0); } while (0)
; #define WAIT_V(n) asm volatile("s_waitcnt vmcnt(" #n ")" ::: "memory")
; #define WAIT_L(n) asm volatile("s_waitcnt lgkmcnt(" #n ")" ::: "memory")
; #define BAR __builtin_amdgcn_s_barrier()
; template <class Epi> ...
;     ...
;   { LDB(B0, 0, 0); LDA(At, 0, 0); STAGE(SA(1, 1), A, brow + HALF, nt - 1);
;     BAR; WAIT_L(0); MMA(0, 0, At, B0); BAR;
;     LDB(B1, 0, 1); BAR; WAIT_L(0); MMA(0, 1, At, B1); BAR;
;     LDA(At, 0, 1); WAIT_V(4); BAR; WAIT_L(0); MMA(1, 0, At, B0); MMA(1, 1, At, B1); BAR; }
;   { LDB(B0, 1, 0); LDA(At, 1, 0); WAIT_V(2); BAR; WAIT_L(0); MMA(0, 0, At, B0); BAR;
.Lpx1:
	v_readfirstlane_b32 s20, v152
	s_add_i32 s21, s21, 0x40780
	s_mov_b32 s6, s78
	s_mov_b32 s7, s79
	s_mov_b32 m0, s20
	v_readfirstlane_b32 s20, v151
	ds_read_b128 v[156:159], v155
	ds_read_b128 v[166:169], v155 offset:1024
	ds_read_b128 v[170:173], v155 offset:2048
	ds_read_b128 v[186:189], v155 offset:3072
	ds_read_b128 v[190:193], v143
	ds_read_b128 v[194:197], v143 offset:1024
	ds_read_b128 v[198:201], v142
	ds_read_b128 v[202:205], v142 offset:1024
	ds_read_b128 v[206:209], v141
	ds_read_b128 v[210:213], v141 offset:1024
	ds_read_b128 v[214:217], v140
	ds_read_b128 v[218:221], v140 offset:1024
	buffer_load_dwordx4 v32, s[4:7], s21 offen lds
	s_mov_b32 m0, s20
	s_nop 0
	buffer_load_dwordx4 v130, s[4:7], s21 offen lds
	s_barrier
	s_setprio 1
	s_waitcnt lgkmcnt(7)
	v_mfma_f32_16x16x32_bf16 v[126:129], v[190:193], v[156:159], v[126:129]
	v_mfma_f32_16x16x32_bf16 v[122:125], v[190:193], v[170:173], v[122:125]
	s_waitcnt lgkmcnt(5)
	v_mfma_f32_16x16x32_bf16 v[114:117], v[198:201], v[170:173], v[114:117]
	s_waitcnt lgkmcnt(3)
	v_mfma_f32_16x16x32_bf16 v[106:109], v[206:209], v[170:173], v[106:109]
	s_waitcnt lgkmcnt(1)
	v_mfma_f32_16x16x32_bf16 v[102:105], v[214:217], v[156:159], v[102:105]
	v_mfma_f32_16x16x32_bf16 v[126:129], v[194:197], v[166:169], v[126:129]
	v_mfma_f32_16x16x32_bf16 v[122:125], v[194:197], v[186:189], v[122:125]
	v_mfma_f32_16x16x32_bf16 v[118:121], v[198:201], v[156:159], v[118:121]
	v_mfma_f32_16x16x32_bf16 v[114:117], v[202:205], v[186:189], v[114:117]
	v_mfma_f32_16x16x32_bf16 v[110:113], v[206:209], v[156:159], v[110:113]
	v_mfma_f32_16x16x32_bf16 v[106:109], v[210:213], v[186:189], v[106:109]
	s_waitcnt lgkmcnt(0)
	v_mfma_f32_16x16x32_bf16 v[102:105], v[218:221], v[166:169], v[102:105]
	v_mfma_f32_16x16x32_bf16 v[98:101], v[214:217], v[170:173], v[98:101]
	v_mfma_f32_16x16x32_bf16 v[150:153], v[202:205], v[166:169], v[118:121]
	v_mfma_f32_16x16x32_bf16 v[222:225], v[210:213], v[166:169], v[110:113]
	v_mfma_f32_16x16x32_bf16 v[226:229], v[218:221], v[186:189], v[98:101]
	s_setprio 0
	s_barrier
	s_nop 2
	ds_read_b128 v[98:101], v149
	ds_read_b128 v[110:113], v149 offset:1024
	ds_read_b128 v[118:121], v149 offset:2048
	ds_read_b128 v[146:149], v149 offset:3072
	s_barrier
	s_setprio 1
	s_waitcnt lgkmcnt(1)
	v_mfma_f32_16x16x32_bf16 v[90:93], v[190:193], v[118:121], v[90:93]
	v_mfma_f32_16x16x32_bf16 v[86:89], v[198:201], v[98:101], v[86:89]
	v_mfma_f32_16x16x32_bf16 v[74:77], v[206:209], v[118:121], v[74:77]
	v_mfma_f32_16x16x32_bf16 v[70:73], v[214:217], v[98:101], v[70:73]
	v_mfma_f32_16x16x32_bf16 v[94:97], v[190:193], v[98:101], v[94:97]
	s_waitcnt lgkmcnt(0)
	v_mfma_f32_16x16x32_bf16 v[90:93], v[194:197], v[146:149], v[90:93]
	v_mfma_f32_16x16x32_bf16 v[86:89], v[202:205], v[110:113], v[86:89]
	v_mfma_f32_16x16x32_bf16 v[82:85], v[198:201], v[118:121], v[82:85]
	v_mfma_f32_16x16x32_bf16 v[78:81], v[206:209], v[98:101], v[78:81]
	v_mfma_f32_16x16x32_bf16 v[74:77], v[210:213], v[146:149], v[74:77]
	v_mfma_f32_16x16x32_bf16 v[70:73], v[218:221], v[110:113], v[70:73]
	v_mfma_f32_16x16x32_bf16 v[66:69], v[214:217], v[118:121], v[66:69]
	v_mfma_f32_16x16x32_bf16 v[230:233], v[194:197], v[110:113], v[94:97]
	v_mfma_f32_16x16x32_bf16 v[190:193], v[202:205], v[146:149], v[82:85]
	v_mfma_f32_16x16x32_bf16 v[194:197], v[210:213], v[110:113], v[78:81]
	v_mfma_f32_16x16x32_bf16 v[198:201], v[218:221], v[146:149], v[66:69]
	s_setprio 0
	s_barrier
	s_nop 1
	ds_read_b128 v[66:69], v143 offset:16384
	ds_read_b128 v[78:81], v143 offset:17408
	ds_read_b128 v[82:85], v142 offset:16384
	ds_read_b128 v[94:97], v142 offset:17408
	ds_read_b128 v[202:205], v141 offset:16384
	ds_read_b128 v[206:209], v141 offset:17408
	ds_read_b128 v[210:213], v140 offset:16384
	ds_read_b128 v[214:217], v140 offset:17408
	s_waitcnt vmcnt(4)
	s_barrier
	s_setprio 1
	s_waitcnt lgkmcnt(7)
	v_mfma_f32_16x16x32_bf16 v[62:65], v[66:69], v[156:159], v[62:65]
	v_mfma_f32_16x16x32_bf16 v[58:61], v[66:69], v[170:173], v[58:61]
	s_waitcnt lgkmcnt(5)
	v_mfma_f32_16x16x32_bf16 v[54:57], v[82:85], v[156:159], v[54:57]
	v_mfma_f32_16x16x32_bf16 v[50:53], v[82:85], v[170:173], v[50:53]
	s_waitcnt lgkmcnt(3)
	v_mfma_f32_16x16x32_bf16 v[42:45], v[202:205], v[170:173], v[42:45]
	s_waitcnt lgkmcnt(1)
	v_mfma_f32_16x16x32_bf16 v[34:37], v[210:213], v[170:173], v[34:37]
	v_mfma_f32_16x16x32_bf16 v[62:65], v[78:81], v[166:169], v[62:65]
	v_mfma_f32_16x16x32_bf16 v[58:61], v[78:81], v[186:189], v[58:61]
	v_mfma_f32_16x16x32_bf16 v[54:57], v[94:97], v[166:169], v[54:57]
	v_mfma_f32_16x16x32_bf16 v[50:53], v[94:97], v[186:189], v[50:53]
	v_mfma_f32_16x16x32_bf16 v[46:49], v[202:205], v[156:159], v[46:49]
	v_mfma_f32_16x16x32_bf16 v[42:45], v[206:209], v[186:189], v[42:45]
	v_mfma_f32_16x16x32_bf16 v[38:41], v[210:213], v[156:159], v[38:41]
	s_waitcnt lgkmcnt(0)
	v_mfma_f32_16x16x32_bf16 v[34:37], v[214:217], v[186:189], v[34:37]
	v_mfma_f32_16x16x32_bf16 v[218:221], v[206:209], v[166:169], v[46:49]
	v_mfma_f32_16x16x32_bf16 v[154:157], v[214:217], v[166:169], v[38:41]
	s_setprio 0
	s_setprio 1
	v_mfma_f32_16x16x32_bf16 v[24:27], v[66:69], v[118:121], v[24:27]
	v_mfma_f32_16x16x32_bf16 v[16:19], v[82:85], v[118:121], v[16:19]
	v_mfma_f32_16x16x32_bf16 v[8:11], v[202:205], v[118:121], v[8:11]
	v_mfma_f32_16x16x32_bf16 v[0:3], v[210:213], v[118:121], v[0:3]
	v_mfma_f32_16x16x32_bf16 v[28:31], v[66:69], v[98:101], v[28:31]
	v_mfma_f32_16x16x32_bf16 v[24:27], v[78:81], v[146:149], v[24:27]
	v_mfma_f32_16x16x32_bf16 v[20:23], v[82:85], v[98:101], v[20:23]
	v_mfma_f32_16x16x32_bf16 v[16:19], v[94:97], v[146:149], v[16:19]
	v_mfma_f32_16x16x32_bf16 v[12:15], v[202:205], v[98:101], v[12:15]
	v_mfma_f32_16x16x32_bf16 v[8:11], v[206:209], v[146:149], v[8:11]
	v_mfma_f32_16x16x32_bf16 v[4:7], v[210:213], v[98:101], v[4:7]
	v_mfma_f32_16x16x32_bf16 v[0:3], v[214:217], v[146:149], v[0:3]
	v_mfma_f32_16x16x32_bf16 v[158:161], v[78:81], v[110:113], v[28:31]
	v_mfma_f32_16x16x32_bf16 v[166:169], v[94:97], v[110:113], v[20:23]
	v_mfma_f32_16x16x32_bf16 v[170:173], v[206:209], v[110:113], v[12:15]
	v_mfma_f32_16x16x32_bf16 v[186:189], v[214:217], v[110:113], v[4:7]
	s_setprio 0
	s_barrier
; #define LDA(dst, b, h) _Pragma("unroll") for (int m = 0; m < 4; ++m) _Pragma("unroll") for (int k = 0; k < 2; ++k) \
;     dst[m][k] = *reinterpret_cast<const bf16x8*>((char*)SA(b, h) + lds_byte(wr * 64 + m * 16 + fr, k * 32 + fq * 8))
; #define LDB(dst, b, h) _Pragma("unroll") for (int n = 0; n < 2; ++n) _Pragma("unroll") for (int k = 0; k < 2; ++k) \
;     dst[n][k] = *reinterpret_cast<const bf16x8*>((char*)SB(b, h) + lds_byte(wc * 32 + n * 16 + fr, k * 32 + fq * 8))
; #define MMA(ai, bj, At, Bt_) do { __builtin_amdgcn_s_setprio(1); \
;     _Pragma("unroll") for (int m = 0; m < 4; ++m) _Pragma("unroll") for (int n = 0; n < 2; ++n) _Pragma("unroll") for (int k = 0; k < 2; ++k) \
;       acc[ai][bj][m][n] = __builtin_amdgcn_mfma_f32_16x16x32_bf16(At[m][k], Bt_[n][k], acc[ai][bj][m][n], 0, 0, 0); \
;     __builtin_amdgcn_s_setprio(0); } while (0)
; #define WAIT_V(n) asm volatile("s_waitcnt vmcnt(" #n ")" ::: "memory")
; #define WAIT_L(n) asm volatile("s_waitcnt lgkmcnt(" #n ")" ::: "memory")
; #define BAR __builtin_amdgcn_s_barrier()
; template <class Epi> ...
;     ...
;   { LDB(B0, 1, 0); LDA(At, 1, 0); WAIT_V(2); BAR; WAIT_L(0); MMA(0, 0, At, B0); BAR;
;     LDB(B1, 1, 1); WAIT_V(0); BAR; WAIT_L(0); MMA(0, 1, At, B1); BAR;
;     LDA(At, 1, 1); BAR; WAIT_L(0); MMA(1, 0, At, B0); MMA(1, 1, At, B1); BAR; }
;   if (wr == 0) BAR;
	s_nop 0
	ds_read_b128 v[4:7], v145
	ds_read_b128 v[12:15], v145 offset:1024
	ds_read_b128 v[146:149], v145 offset:2048
	ds_read_b128 v[202:205], v145 offset:3072
	ds_read_b128 v[20:23], v143 offset:32768
	ds_read_b128 v[28:31], v143 offset:33792
	ds_read_b128 v[38:41], v142 offset:32768
	ds_read_b128 v[46:49], v142 offset:33792
	ds_read_b128 v[206:209], v141 offset:32768
	ds_read_b128 v[210:213], v141 offset:33792
	ds_read_b128 v[214:217], v140 offset:32768
	ds_read_b128 v[234:237], v140 offset:33792
	s_waitcnt vmcnt(2)
	s_barrier
	s_setprio 1
	s_waitcnt lgkmcnt(7)
	v_mfma_f32_16x16x32_bf16 v[66:69], v[20:23], v[4:7], v[126:129]
	s_waitcnt lgkmcnt(6)
	v_mfma_f32_16x16x32_bf16 v[126:129], v[28:31], v[12:15], v[66:69]
	v_mfma_f32_16x16x32_bf16 v[66:69], v[20:23], v[146:149], v[122:125]
	v_mfma_f32_16x16x32_bf16 v[118:121], v[28:31], v[202:205], v[66:69]
	s_waitcnt lgkmcnt(5)
	v_mfma_f32_16x16x32_bf16 v[66:69], v[38:41], v[4:7], v[150:153]
	s_waitcnt lgkmcnt(4)
	v_mfma_f32_16x16x32_bf16 v[110:113], v[46:49], v[12:15], v[66:69]
	v_mfma_f32_16x16x32_bf16 v[66:69], v[38:41], v[146:149], v[114:117]
	v_mfma_f32_16x16x32_bf16 v[98:101], v[46:49], v[202:205], v[66:69]
	s_waitcnt lgkmcnt(3)
	v_mfma_f32_16x16x32_bf16 v[66:69], v[206:209], v[4:7], v[222:225]
	s_waitcnt lgkmcnt(2)
	v_mfma_f32_16x16x32_bf16 v[94:97], v[210:213], v[12:15], v[66:69]
	v_mfma_f32_16x16x32_bf16 v[66:69], v[206:209], v[146:149], v[106:109]
	v_mfma_f32_16x16x32_bf16 v[82:85], v[210:213], v[202:205], v[66:69]
	s_waitcnt lgkmcnt(1)
	v_mfma_f32_16x16x32_bf16 v[66:69], v[214:217], v[4:7], v[102:105]
	s_waitcnt lgkmcnt(0)
	v_mfma_f32_16x16x32_bf16 v[78:81], v[234:237], v[12:15], v[66:69]
	v_mfma_f32_16x16x32_bf16 v[66:69], v[214:217], v[146:149], v[226:229]
	v_mfma_f32_16x16x32_bf16 v[66:69], v[234:237], v[202:205], v[66:69]
	s_setprio 0
	s_barrier
	ds_read_b128 v[150:153], v144
	ds_read_b128 v[222:225], v144 offset:1024
	ds_read_b128 v[226:229], v144 offset:2048
	ds_read_b128 v[238:241], v144 offset:3072
	s_waitcnt vmcnt(0)
	s_barrier
	s_setprio 1
	s_waitcnt lgkmcnt(3)
	v_mfma_f32_16x16x32_bf16 v[102:105], v[20:23], v[150:153], v[230:233]
	s_waitcnt lgkmcnt(1)
	v_mfma_f32_16x16x32_bf16 v[20:23], v[20:23], v[226:229], v[90:93]
	s_waitcnt lgkmcnt(0)
	v_mfma_f32_16x16x32_bf16 v[114:117], v[28:31], v[238:241], v[20:23]
	v_mfma_f32_16x16x32_bf16 v[20:23], v[38:41], v[150:153], v[86:89]
	v_mfma_f32_16x16x32_bf16 v[106:109], v[46:49], v[222:225], v[20:23]
	v_mfma_f32_16x16x32_bf16 v[20:23], v[38:41], v[226:229], v[190:193]
	v_mfma_f32_16x16x32_bf16 v[122:125], v[28:31], v[222:225], v[102:105]
	v_mfma_f32_16x16x32_bf16 v[102:105], v[46:49], v[238:241], v[20:23]
	v_mfma_f32_16x16x32_bf16 v[20:23], v[206:209], v[150:153], v[194:197]
	v_mfma_f32_16x16x32_bf16 v[90:93], v[210:213], v[222:225], v[20:23]
	v_mfma_f32_16x16x32_bf16 v[20:23], v[206:209], v[226:229], v[74:77]
	v_mfma_f32_16x16x32_bf16 v[86:89], v[210:213], v[238:241], v[20:23]
	v_mfma_f32_16x16x32_bf16 v[20:23], v[214:217], v[150:153], v[70:73]
	v_mfma_f32_16x16x32_bf16 v[74:77], v[234:237], v[222:225], v[20:23]
	v_mfma_f32_16x16x32_bf16 v[20:23], v[214:217], v[226:229], v[198:201]
	v_mfma_f32_16x16x32_bf16 v[70:73], v[234:237], v[238:241], v[20:23]
	s_setprio 0
	s_barrier
	ds_read_b128 v[190:193], v143 offset:49152
	ds_read_b128 v[194:197], v143 offset:50176
	ds_read_b128 v[198:201], v142 offset:49152
	ds_read_b128 v[142:145], v142 offset:50176
	ds_read_b128 v[206:209], v141 offset:49152
	ds_read_b128 v[210:213], v141 offset:50176
	ds_read_b128 v[214:217], v140 offset:49152
	ds_read_b128 v[230:233], v140 offset:50176
	s_barrier
	s_setprio 1
	s_waitcnt lgkmcnt(7)
	v_mfma_f32_16x16x32_bf16 v[20:23], v[190:193], v[4:7], v[62:65]
	s_waitcnt lgkmcnt(6)
	v_mfma_f32_16x16x32_bf16 v[62:65], v[194:197], v[12:15], v[20:23]
	v_mfma_f32_16x16x32_bf16 v[20:23], v[190:193], v[146:149], v[58:61]
	v_mfma_f32_16x16x32_bf16 v[58:61], v[194:197], v[202:205], v[20:23]
	s_waitcnt lgkmcnt(5)
	v_mfma_f32_16x16x32_bf16 v[20:23], v[198:201], v[4:7], v[54:57]
	s_waitcnt lgkmcnt(4)
	v_mfma_f32_16x16x32_bf16 v[46:49], v[142:145], v[12:15], v[20:23]
	v_mfma_f32_16x16x32_bf16 v[20:23], v[198:201], v[146:149], v[50:53]
	v_mfma_f32_16x16x32_bf16 v[38:41], v[142:145], v[202:205], v[20:23]
	s_waitcnt lgkmcnt(3)
	v_mfma_f32_16x16x32_bf16 v[20:23], v[206:209], v[4:7], v[218:221]
	s_waitcnt lgkmcnt(1)
	v_mfma_f32_16x16x32_bf16 v[4:7], v[214:217], v[4:7], v[154:157]
	v_mfma_f32_16x16x32_bf16 v[28:31], v[210:213], v[12:15], v[20:23]
	v_mfma_f32_16x16x32_bf16 v[20:23], v[206:209], v[146:149], v[42:45]
	s_waitcnt lgkmcnt(0)
	v_mfma_f32_16x16x32_bf16 v[12:15], v[230:233], v[12:15], v[4:7]
	v_mfma_f32_16x16x32_bf16 v[4:7], v[214:217], v[146:149], v[34:37]
	v_mfma_f32_16x16x32_bf16 v[20:23], v[210:213], v[202:205], v[20:23]
	v_mfma_f32_16x16x32_bf16 v[4:7], v[230:233], v[202:205], v[4:7]
	s_setprio 0
	s_setprio 1
	v_mfma_f32_16x16x32_bf16 v[34:37], v[190:193], v[150:153], v[158:161]
	v_mfma_f32_16x16x32_bf16 v[24:27], v[190:193], v[226:229], v[24:27]
	v_mfma_f32_16x16x32_bf16 v[16:19], v[198:201], v[226:229], v[16:19]
	v_mfma_f32_16x16x32_bf16 v[54:57], v[194:197], v[222:225], v[34:37]
	v_mfma_f32_16x16x32_bf16 v[50:53], v[194:197], v[238:241], v[24:27]
	v_mfma_f32_16x16x32_bf16 v[24:27], v[198:201], v[150:153], v[166:169]
	v_mfma_f32_16x16x32_bf16 v[34:37], v[142:145], v[238:241], v[16:19]
	v_mfma_f32_16x16x32_bf16 v[16:19], v[206:209], v[150:153], v[170:173]
	v_mfma_f32_16x16x32_bf16 v[8:11], v[206:209], v[226:229], v[8:11]
	v_mfma_f32_16x16x32_bf16 v[42:45], v[142:145], v[222:225], v[24:27]
	v_mfma_f32_16x16x32_bf16 v[24:27], v[210:213], v[222:225], v[16:19]
	v_mfma_f32_16x16x32_bf16 v[16:19], v[210:213], v[238:241], v[8:11]
	v_mfma_f32_16x16x32_bf16 v[8:11], v[214:217], v[150:153], v[186:189]
	v_mfma_f32_16x16x32_bf16 v[0:3], v[214:217], v[226:229], v[0:3]
	v_mfma_f32_16x16x32_bf16 v[8:11], v[230:233], v[222:225], v[8:11]
	v_mfma_f32_16x16x32_bf16 v[0:3], v[230:233], v[238:241], v[0:3]
	s_setprio 0
	v_cmp_gt_u32_e32 vcc, s59, v133
	s_barrier
	s_and_saveexec_b64 s[4:5], vcc
	s_cbranch_execz .LBB0_1370
	s_barrier

; #define STAGE(P, BASE, br, kt) do { int _so = ((br) * K + (kt) * BK) * 2; \
;     __builtin_amdgcn_raw_ptr_buffer_load_lds(rs_##BASE, (__attribute__((address_space(3))) void*)((char*)(P) + tx * 16), 16, voff0, _so, 0, 0); \
;     __builtin_amdgcn_raw_ptr_buffer_load_lds(rs_##BASE, (__attribute__((address_space(3))) void*)((char*)(P) + tx * 16 + 8192), 16, voff1, _so, 0, 0); } while (0)
; #define LDA(dst, b, h) _Pragma("unroll") for (int m = 0; m < 4; ++m) _Pragma("unroll") for (int k = 0; k < 2; ++k) \
;     dst[m][k] = *reinterpret_cast<const bf16x8*>((char*)SA(b, h) + lds_byte(wr * 64 + m * 16 + fr, k * 32 + fq * 8))
; #define LDB(dst, b, h) _Pragma("unroll") for (int n = 0; n < 2; ++n) _Pragma("unroll") for (int k = 0; k < 2; ++k) \
;     dst[n][k] = *reinterpret_cast<const bf16x8*>((char*)SB(b, h) + lds_byte(wc * 32 + n * 16 + fr, k * 32 + fq * 8))
; #define MMA(ai, bj, At, Bt_) do { __builtin_amdgcn_s_setprio(1); \
;     _Pragma("unroll") for (int m = 0; m < 4; ++m) _Pragma("unroll") for (int n = 0; n < 2; ++n) _Pragma("unroll") for (int k = 0; k < 2; ++k) \
;       acc[ai][bj][m][n] = __builtin_amdgcn_mfma_f32_16x16x32_bf16(At[m][k], Bt_[n][k], acc[ai][bj][m][n], 0, 0, 0); \
;     __builtin_amdgcn_s_setprio(0); } while (0)
; #define WAIT_V(n) asm volatile("s_waitcnt vmcnt(" #n ")" ::: "memory")
; #define WAIT_L(n) asm volatile("s_waitcnt lgkmcnt(" #n ")" ::: "memory")
; #define BAR __builtin_amdgcn_s_barrier()
; #define SCHED __builtin_amdgcn_sched_barrier(0)
; template <class Epi> ...
;     ...
;     STAGE(SB(0, 0), Bt, bcol, 0); STAGE(SA(0, 0), A, brow, 0);
;     STAGE(SB(0, 1), Bt, bcol + HALF, 0); STAGE(SA(0, 1), A, brow + HALF, 0);
;   }
;   if (wr == 1) BAR;
;   if (pre) { WAIT_V(0); } else { WAIT_V(4); }
;   BAR;
;   STAGE(SB(1, 0), Bt, bcol, 1); STAGE(SA(1, 0), A, brow, 1); STAGE(SB(1, 1), Bt, bcol + HALF, 1);
;   WAIT_V(6); BAR;
;   for (int t = 0; t < nt - 2; t += 2) {
;     LDB(B0, 0, 0); SCHED; LDA(At, 0, 0); STAGE(SA(1, 1), A, brow + HALF, t + 1);
;     WAIT_L(8); BAR; WAIT_L(0); MMA(0, 0, At, B0); BAR; SCHED;
;     LDB(B1, 0, 1); STAGE(SB(0, 0), Bt, bcol, t + 2);
;     BAR; WAIT_L(0); MMA(0, 1, At, B1); BAR;
;     LDA(At, 0, 1); STAGE(SA(0, 0), A, brow, t + 2);
;     BAR; WAIT_L(0); MMA(1, 0, At, B0); BAR; SCHED;
;     STAGE(SB(0, 1), Bt, bcol + HALF, t + 2);
;     WAIT_V(6); BAR; MMA(1, 1, At, B1); BAR;
.Lpk2:
	ds_read_b128 v[156:159], v153
	ds_read_b128 v[166:169], v153 offset:1024
	ds_read_b128 v[170:173], v153 offset:2048
	ds_read_b128 v[186:189], v153 offset:3072
	s_add_i32 s28, s24, s27
	v_readfirstlane_b32 s30, v155
	s_add_i32 s29, s28, 0x40080
	s_mov_b32 m0, s30
	v_readfirstlane_b32 s30, v154
	ds_read_b128 v[190:193], v133
	ds_read_b128 v[194:197], v133 offset:1024
	ds_read_b128 v[198:201], v132
	ds_read_b128 v[202:205], v132 offset:1024
	ds_read_b128 v[206:209], v131
	ds_read_b128 v[210:213], v131 offset:1024
	ds_read_b128 v[214:217], v130
	ds_read_b128 v[218:221], v130 offset:1024
	buffer_load_dwordx4 v134, s[4:7], s29 offen lds
	s_mov_b32 m0, s30
	s_nop 0
	buffer_load_dwordx4 v135, s[4:7], s29 offen lds
	s_waitcnt lgkmcnt(8)
	s_barrier
	s_setprio 1
	s_waitcnt lgkmcnt(7)
	v_mfma_f32_16x16x32_bf16 v[126:129], v[190:193], v[156:159], 0
	v_mfma_f32_16x16x32_bf16 v[122:125], v[190:193], v[170:173], 0
	s_waitcnt lgkmcnt(5)
	v_mfma_f32_16x16x32_bf16 v[118:121], v[198:201], v[156:159], 0
	v_mfma_f32_16x16x32_bf16 v[114:117], v[198:201], v[170:173], 0
	s_waitcnt lgkmcnt(3)
	v_mfma_f32_16x16x32_bf16 v[110:113], v[206:209], v[156:159], 0
	v_mfma_f32_16x16x32_bf16 v[106:109], v[206:209], v[170:173], 0
	s_waitcnt lgkmcnt(1)
	v_mfma_f32_16x16x32_bf16 v[102:105], v[214:217], v[156:159], 0
	v_mfma_f32_16x16x32_bf16 v[98:101], v[214:217], v[170:173], 0
	v_mfma_f32_16x16x32_bf16 v[126:129], v[194:197], v[166:169], v[126:129]
	v_mfma_f32_16x16x32_bf16 v[122:125], v[194:197], v[186:189], v[122:125]
	v_mfma_f32_16x16x32_bf16 v[118:121], v[202:205], v[166:169], v[118:121]
	v_mfma_f32_16x16x32_bf16 v[114:117], v[202:205], v[186:189], v[114:117]
	v_mfma_f32_16x16x32_bf16 v[110:113], v[210:213], v[166:169], v[110:113]
	v_mfma_f32_16x16x32_bf16 v[106:109], v[210:213], v[186:189], v[106:109]
	s_waitcnt lgkmcnt(0)
	v_mfma_f32_16x16x32_bf16 v[102:105], v[218:221], v[166:169], v[102:105]
	v_mfma_f32_16x16x32_bf16 v[98:101], v[218:221], v[186:189], v[98:101]
	s_setprio 0
	s_barrier
	s_add_i32 s29, s25, s27
	v_readfirstlane_b32 s31, v138
	s_add_i32 s30, s29, 0x100
	s_mov_b32 m0, s31
	v_readfirstlane_b32 s31, v139
	ds_read_b128 v[222:225], v149
	ds_read_b128 v[226:229], v149 offset:1024
	ds_read_b128 v[230:233], v149 offset:2048
	ds_read_b128 v[234:237], v149 offset:3072
	buffer_load_dwordx4 v134, s[76:79], s30 offen lds
	s_mov_b32 m0, s31
	s_nop 0
	buffer_load_dwordx4 v135, s[76:79], s30 offen lds
	s_barrier
	s_setprio 1
	s_waitcnt lgkmcnt(3)
	v_mfma_f32_16x16x32_bf16 v[94:97], v[190:193], v[222:225], 0
	s_waitcnt lgkmcnt(1)
	v_mfma_f32_16x16x32_bf16 v[90:93], v[190:193], v[230:233], 0
	v_mfma_f32_16x16x32_bf16 v[86:89], v[198:201], v[222:225], 0
	v_mfma_f32_16x16x32_bf16 v[82:85], v[198:201], v[230:233], 0
	v_mfma_f32_16x16x32_bf16 v[78:81], v[206:209], v[222:225], 0
	v_mfma_f32_16x16x32_bf16 v[74:77], v[206:209], v[230:233], 0
	v_mfma_f32_16x16x32_bf16 v[70:73], v[214:217], v[222:225], 0
	v_mfma_f32_16x16x32_bf16 v[66:69], v[214:217], v[230:233], 0
	v_mfma_f32_16x16x32_bf16 v[94:97], v[194:197], v[226:229], v[94:97]
	s_waitcnt lgkmcnt(0)
	v_mfma_f32_16x16x32_bf16 v[90:93], v[194:197], v[234:237], v[90:93]
	v_mfma_f32_16x16x32_bf16 v[86:89], v[202:205], v[226:229], v[86:89]
	v_mfma_f32_16x16x32_bf16 v[82:85], v[202:205], v[234:237], v[82:85]
	v_mfma_f32_16x16x32_bf16 v[78:81], v[210:213], v[226:229], v[78:81]
	v_mfma_f32_16x16x32_bf16 v[74:77], v[210:213], v[234:237], v[74:77]
	v_mfma_f32_16x16x32_bf16 v[70:73], v[218:221], v[226:229], v[70:73]
	v_mfma_f32_16x16x32_bf16 v[66:69], v[218:221], v[234:237], v[66:69]
	s_setprio 0
	v_readfirstlane_b32 s31, v140
	s_add_i32 s30, s28, 0x100
	s_mov_b32 m0, s31
	v_readfirstlane_b32 s31, v141
	s_barrier
	ds_read_b128 v[190:193], v133 offset:16384
	ds_read_b128 v[194:197], v133 offset:17408
	ds_read_b128 v[198:201], v132 offset:16384
	ds_read_b128 v[202:205], v132 offset:17408
	ds_read_b128 v[206:209], v131 offset:16384
	ds_read_b128 v[210:213], v131 offset:17408
	ds_read_b128 v[214:217], v130 offset:16384
	ds_read_b128 v[218:221], v130 offset:17408
	buffer_load_dwordx4 v134, s[4:7], s30 offen lds
	s_mov_b32 m0, s31
	s_nop 0
	buffer_load_dwordx4 v135, s[4:7], s30 offen lds
	s_barrier
	s_setprio 1
	s_waitcnt lgkmcnt(7)
	v_mfma_f32_16x16x32_bf16 v[62:65], v[190:193], v[156:159], 0
	v_mfma_f32_16x16x32_bf16 v[58:61], v[190:193], v[170:173], 0
	s_waitcnt lgkmcnt(5)
	v_mfma_f32_16x16x32_bf16 v[54:57], v[198:201], v[156:159], 0
	v_mfma_f32_16x16x32_bf16 v[50:53], v[198:201], v[170:173], 0
	s_waitcnt lgkmcnt(3)
	v_mfma_f32_16x16x32_bf16 v[46:49], v[206:209], v[156:159], 0
	v_mfma_f32_16x16x32_bf16 v[42:45], v[206:209], v[170:173], 0
	s_waitcnt lgkmcnt(1)
	v_mfma_f32_16x16x32_bf16 v[38:41], v[214:217], v[156:159], 0
	v_mfma_f32_16x16x32_bf16 v[34:37], v[214:217], v[170:173], 0
	v_mfma_f32_16x16x32_bf16 v[62:65], v[194:197], v[166:169], v[62:65]
	v_mfma_f32_16x16x32_bf16 v[58:61], v[194:197], v[186:189], v[58:61]
	v_mfma_f32_16x16x32_bf16 v[54:57], v[202:205], v[166:169], v[54:57]
	v_mfma_f32_16x16x32_bf16 v[50:53], v[202:205], v[186:189], v[50:53]
	v_mfma_f32_16x16x32_bf16 v[46:49], v[210:213], v[166:169], v[46:49]
	v_mfma_f32_16x16x32_bf16 v[42:45], v[210:213], v[186:189], v[42:45]
	s_waitcnt lgkmcnt(0)
	v_mfma_f32_16x16x32_bf16 v[38:41], v[218:221], v[166:169], v[38:41]
	v_mfma_f32_16x16x32_bf16 v[34:37], v[218:221], v[186:189], v[34:37]
	s_setprio 0
	s_barrier
	v_readfirstlane_b32 s31, v142
	s_add_i32 s30, s29, 0x40100
	s_mov_b32 m0, s31
	v_readfirstlane_b32 s31, v143
	buffer_load_dwordx4 v134, s[76:79], s30 offen lds
	s_mov_b32 m0, s31
	s_nop 0
	buffer_load_dwordx4 v135, s[76:79], s30 offen lds
	s_waitcnt vmcnt(6)
	s_barrier
; #define STAGE(P, BASE, br, kt) do { int _so = ((br) * K + (kt) * BK) * 2; \
;     __builtin_amdgcn_raw_ptr_buffer_load_lds(rs_##BASE, (__attribute__((address_space(3))) void*)((char*)(P) + tx * 16), 16, voff0, _so, 0, 0); \
;     __builtin_amdgcn_raw_ptr_buffer_load_lds(rs_##BASE, (__attribute__((address_space(3))) void*)((char*)(P) + tx * 16 + 8192), 16, voff1, _so, 0, 0); } while (0)
; #define LDA(dst, b, h) _Pragma("unroll") for (int m = 0; m < 4; ++m) _Pragma("unroll") for (int k = 0; k < 2; ++k) \
;     dst[m][k] = *reinterpret_cast<const bf16x8*>((char*)SA(b, h) + lds_byte(wr * 64 + m * 16 + fr, k * 32 + fq * 8))
; #define LDB(dst, b, h) _Pragma("unroll") for (int n = 0; n < 2; ++n) _Pragma("unroll") for (int k = 0; k < 2; ++k) \
;     dst[n][k] = *reinterpret_cast<const bf16x8*>((char*)SB(b, h) + lds_byte(wc * 32 + n * 16 + fr, k * 32 + fq * 8))
; #define MMA(ai, bj, At, Bt_) do { __builtin_amdgcn_s_setprio(1); \
;     _Pragma("unroll") for (int m = 0; m < 4; ++m) _Pragma("unroll") for (int n = 0; n < 2; ++n) _Pragma("unroll") for (int k = 0; k < 2; ++k) \
;       acc[ai][bj][m][n] = __builtin_amdgcn_mfma_f32_16x16x32_bf16(At[m][k], Bt_[n][k], acc[ai][bj][m][n], 0, 0, 0); \
;     __builtin_amdgcn_s_setprio(0); } while (0)
; #define WAIT_V(n) asm volatile("s_waitcnt vmcnt(" #n ")" ::: "memory")
; #define WAIT_L(n) asm volatile("s_waitcnt lgkmcnt(" #n ")" ::: "memory")
; #define BAR __builtin_amdgcn_s_barrier()
; #define SCHED __builtin_amdgcn_sched_barrier(0)
; template <class Epi> ...
;     ...
;     WAIT_V(6); BAR; MMA(1, 1, At, B1); BAR;
;     LDB(B0, 1, 0); SCHED; LDA(At, 1, 0); STAGE(SA(0, 1), A, brow + HALF, t + 2);
;     WAIT_L(8); BAR; WAIT_L(0); MMA(0, 0, At, B0); BAR; SCHED;
;     LDB(B1, 1, 1); STAGE(SB(1, 0), Bt, bcol, t + 3);
;     BAR; WAIT_L(0); MMA(0, 1, At, B1); BAR;
;     LDA(At, 1, 1); STAGE(SA(1, 0), A, brow, t + 3);
;     BAR; WAIT_L(0); MMA(1, 0, At, B0); BAR; SCHED;
;     STAGE(SB(1, 1), Bt, bcol + HALF, t + 3);
;     WAIT_V(6); BAR; MMA(1, 1, At, B1); BAR;
	s_setprio 1
	v_mfma_f32_16x16x32_bf16 v[28:31], v[190:193], v[222:225], 0
	v_mfma_f32_16x16x32_bf16 v[24:27], v[190:193], v[230:233], 0
	v_mfma_f32_16x16x32_bf16 v[20:23], v[198:201], v[222:225], 0
	v_mfma_f32_16x16x32_bf16 v[16:19], v[198:201], v[230:233], 0
	v_mfma_f32_16x16x32_bf16 v[12:15], v[206:209], v[222:225], 0
	v_mfma_f32_16x16x32_bf16 v[8:11], v[206:209], v[230:233], 0
	v_mfma_f32_16x16x32_bf16 v[4:7], v[214:217], v[222:225], 0
	v_mfma_f32_16x16x32_bf16 v[0:3], v[214:217], v[230:233], 0
	v_mfma_f32_16x16x32_bf16 v[28:31], v[194:197], v[226:229], v[28:31]
	v_mfma_f32_16x16x32_bf16 v[24:27], v[194:197], v[234:237], v[24:27]
	v_mfma_f32_16x16x32_bf16 v[20:23], v[202:205], v[226:229], v[20:23]
	v_mfma_f32_16x16x32_bf16 v[16:19], v[202:205], v[234:237], v[16:19]
	v_mfma_f32_16x16x32_bf16 v[12:15], v[210:213], v[226:229], v[12:15]
	v_mfma_f32_16x16x32_bf16 v[8:11], v[210:213], v[234:237], v[8:11]
	v_mfma_f32_16x16x32_bf16 v[4:7], v[218:221], v[226:229], v[4:7]
	v_mfma_f32_16x16x32_bf16 v[0:3], v[218:221], v[234:237], v[0:3]
	s_setprio 0
	s_barrier
	ds_read_b128 v[156:159], v137
	ds_read_b128 v[166:169], v137 offset:1024
	ds_read_b128 v[170:173], v137 offset:2048
	ds_read_b128 v[186:189], v137 offset:3072
	v_readfirstlane_b32 s31, v144
	s_add_i32 s30, s28, 0x40100
	s_mov_b32 m0, s31
	v_readfirstlane_b32 s31, v145
	ds_read_b128 v[190:193], v133 offset:32768
	ds_read_b128 v[194:197], v133 offset:33792
	ds_read_b128 v[198:201], v132 offset:32768
	ds_read_b128 v[202:205], v132 offset:33792
	ds_read_b128 v[206:209], v131 offset:32768
	ds_read_b128 v[210:213], v131 offset:33792
	ds_read_b128 v[214:217], v130 offset:32768
	ds_read_b128 v[218:221], v130 offset:33792
	buffer_load_dwordx4 v134, s[4:7], s30 offen lds
	s_mov_b32 m0, s31
	s_nop 0
	buffer_load_dwordx4 v135, s[4:7], s30 offen lds
	s_waitcnt lgkmcnt(8)
	s_barrier
	s_setprio 1
	s_waitcnt lgkmcnt(7)
	v_mfma_f32_16x16x32_bf16 v[126:129], v[190:193], v[156:159], v[126:129]
	v_mfma_f32_16x16x32_bf16 v[122:125], v[190:193], v[170:173], v[122:125]
	s_waitcnt lgkmcnt(5)
	v_mfma_f32_16x16x32_bf16 v[118:121], v[198:201], v[156:159], v[118:121]
	v_mfma_f32_16x16x32_bf16 v[114:117], v[198:201], v[170:173], v[114:117]
	s_waitcnt lgkmcnt(3)
	v_mfma_f32_16x16x32_bf16 v[110:113], v[206:209], v[156:159], v[110:113]
	v_mfma_f32_16x16x32_bf16 v[106:109], v[206:209], v[170:173], v[106:109]
	s_waitcnt lgkmcnt(1)
	v_mfma_f32_16x16x32_bf16 v[102:105], v[214:217], v[156:159], v[102:105]
	v_mfma_f32_16x16x32_bf16 v[98:101], v[214:217], v[170:173], v[98:101]
	v_mfma_f32_16x16x32_bf16 v[126:129], v[194:197], v[166:169], v[126:129]
	v_mfma_f32_16x16x32_bf16 v[122:125], v[194:197], v[186:189], v[122:125]
	v_mfma_f32_16x16x32_bf16 v[118:121], v[202:205], v[166:169], v[118:121]
	v_mfma_f32_16x16x32_bf16 v[114:117], v[202:205], v[186:189], v[114:117]
	v_mfma_f32_16x16x32_bf16 v[110:113], v[210:213], v[166:169], v[110:113]
	v_mfma_f32_16x16x32_bf16 v[106:109], v[210:213], v[186:189], v[106:109]
	s_waitcnt lgkmcnt(0)
	v_mfma_f32_16x16x32_bf16 v[102:105], v[218:221], v[166:169], v[102:105]
	v_mfma_f32_16x16x32_bf16 v[98:101], v[218:221], v[186:189], v[98:101]
	s_setprio 0
	s_barrier
	v_readfirstlane_b32 s31, v146
	s_add_i32 s30, s29, 0x180
	s_mov_b32 m0, s31
	v_readfirstlane_b32 s31, v147
	ds_read_b128 v[222:225], v136
	ds_read_b128 v[226:229], v136 offset:1024
	ds_read_b128 v[230:233], v136 offset:2048
	ds_read_b128 v[234:237], v136 offset:3072
	buffer_load_dwordx4 v134, s[76:79], s30 offen lds
	s_mov_b32 m0, s31
	s_nop 0
	buffer_load_dwordx4 v135, s[76:79], s30 offen lds
	s_barrier
	s_setprio 1
	s_waitcnt lgkmcnt(3)
	v_mfma_f32_16x16x32_bf16 v[94:97], v[190:193], v[222:225], v[94:97]
	s_waitcnt lgkmcnt(1)
	v_mfma_f32_16x16x32_bf16 v[90:93], v[190:193], v[230:233], v[90:93]
	v_mfma_f32_16x16x32_bf16 v[86:89], v[198:201], v[222:225], v[86:89]
	v_mfma_f32_16x16x32_bf16 v[82:85], v[198:201], v[230:233], v[82:85]
	v_mfma_f32_16x16x32_bf16 v[78:81], v[206:209], v[222:225], v[78:81]
	v_mfma_f32_16x16x32_bf16 v[74:77], v[206:209], v[230:233], v[74:77]
	v_mfma_f32_16x16x32_bf16 v[70:73], v[214:217], v[222:225], v[70:73]
	v_mfma_f32_16x16x32_bf16 v[66:69], v[214:217], v[230:233], v[66:69]
	v_mfma_f32_16x16x32_bf16 v[94:97], v[194:197], v[226:229], v[94:97]
	s_waitcnt lgkmcnt(0)
	v_mfma_f32_16x16x32_bf16 v[90:93], v[194:197], v[234:237], v[90:93]
	v_mfma_f32_16x16x32_bf16 v[86:89], v[202:205], v[226:229], v[86:89]
	v_mfma_f32_16x16x32_bf16 v[82:85], v[202:205], v[234:237], v[82:85]
	v_mfma_f32_16x16x32_bf16 v[78:81], v[210:213], v[226:229], v[78:81]
	v_mfma_f32_16x16x32_bf16 v[74:77], v[210:213], v[234:237], v[74:77]
	v_mfma_f32_16x16x32_bf16 v[70:73], v[218:221], v[226:229], v[70:73]
	v_mfma_f32_16x16x32_bf16 v[66:69], v[218:221], v[234:237], v[66:69]
	s_setprio 0
	v_readfirstlane_b32 s30, v148
	s_addk_i32 s28, 0x180
	s_mov_b32 m0, s30
	v_readfirstlane_b32 s30, v150
	s_barrier
	ds_read_b128 v[190:193], v133 offset:49152
	ds_read_b128 v[194:197], v133 offset:50176
	ds_read_b128 v[198:201], v132 offset:49152
	ds_read_b128 v[202:205], v132 offset:50176
	ds_read_b128 v[206:209], v131 offset:49152
	ds_read_b128 v[210:213], v131 offset:50176
	ds_read_b128 v[214:217], v130 offset:49152
	ds_read_b128 v[218:221], v130 offset:50176
	buffer_load_dwordx4 v134, s[4:7], s28 offen lds
	s_mov_b32 m0, s30
	s_nop 0
	buffer_load_dwordx4 v135, s[4:7], s28 offen lds
	s_barrier
; #define STAGE(P, BASE, br, kt) do { int _so = ((br) * K + (kt) * BK) * 2; \
;     __builtin_amdgcn_raw_ptr_buffer_load_lds(rs_##BASE, (__attribute__((address_space(3))) void*)((char*)(P) + tx * 16), 16, voff0, _so, 0, 0); \
;     __builtin_amdgcn_raw_ptr_buffer_load_lds(rs_##BASE, (__attribute__((address_space(3))) void*)((char*)(P) + tx * 16 + 8192), 16, voff1, _so, 0, 0); } while (0)
; #define LDA(dst, b, h) _Pragma("unroll") for (int m = 0; m < 4; ++m) _Pragma("unroll") for (int k = 0; k < 2; ++k) \
;     dst[m][k] = *reinterpret_cast<const bf16x8*>((char*)SA(b, h) + lds_byte(wr * 64 + m * 16 + fr, k * 32 + fq * 8))
; #define LDB(dst, b, h) _Pragma("unroll") for (int n = 0; n < 2; ++n) _Pragma("unroll") for (int k = 0; k < 2; ++k) \
;     dst[n][k] = *reinterpret_cast<const bf16x8*>((char*)SB(b, h) + lds_byte(wc * 32 + n * 16 + fr, k * 32 + fq * 8))
; #define MMA(ai, bj, At, Bt_) do { __builtin_amdgcn_s_setprio(1); \
;     _Pragma("unroll") for (int m = 0; m < 4; ++m) _Pragma("unroll") for (int n = 0; n < 2; ++n) _Pragma("unroll") for (int k = 0; k < 2; ++k) \
;       acc[ai][bj][m][n] = __builtin_amdgcn_mfma_f32_16x16x32_bf16(At[m][k], Bt_[n][k], acc[ai][bj][m][n], 0, 0, 0); \
;     __builtin_amdgcn_s_setprio(0); } while (0)
; #define WAIT_V(n) asm volatile("s_waitcnt vmcnt(" #n ")" ::: "memory")
; #define WAIT_L(n) asm volatile("s_waitcnt lgkmcnt(" #n ")" ::: "memory")
; template <class Epi> ...
;     ...
;   for (int t = 0; t < nt - 2; t += 2) {
;     LDB(B0, 0, 0); SCHED; LDA(At, 0, 0); STAGE(SA(1, 1), A, brow + HALF, t + 1);
;     WAIT_L(8); BAR; WAIT_L(0); MMA(0, 0, At, B0); BAR; SCHED;
;     LDB(B1, 0, 1); STAGE(SB(0, 0), Bt, bcol, t + 2);
;     BAR; WAIT_L(0); MMA(0, 1, At, B1); BAR;
;     LDA(At, 0, 1); STAGE(SA(0, 0), A, brow, t + 2);
;     BAR; WAIT_L(0); MMA(1, 0, At, B0); BAR; SCHED;
;     STAGE(SB(0, 1), Bt, bcol + HALF, t + 2);
;     WAIT_V(6); BAR; MMA(1, 1, At, B1); BAR;
;     LDB(B0, 1, 0); SCHED; LDA(At, 1, 0); STAGE(SA(0, 1), A, brow + HALF, t + 2);
;     WAIT_L(8); BAR; WAIT_L(0); MMA(0, 0, At, B0); BAR; SCHED;
;     LDB(B1, 1, 1); STAGE(SB(1, 0), Bt, bcol, t + 3);
;     BAR; WAIT_L(0); MMA(0, 1, At, B1); BAR;
;     LDA(At, 1, 1); STAGE(SA(1, 0), A, brow, t + 3);
;     BAR; WAIT_L(0); MMA(1, 0, At, B0); BAR; SCHED;
;     STAGE(SB(1, 1), Bt, bcol + HALF, t + 3);
;     WAIT_V(6); BAR; MMA(1, 1, At, B1); BAR;
;   }
	s_setprio 1
	s_waitcnt lgkmcnt(7)
	v_mfma_f32_16x16x32_bf16 v[62:65], v[190:193], v[156:159], v[62:65]
	v_mfma_f32_16x16x32_bf16 v[58:61], v[190:193], v[170:173], v[58:61]
	s_waitcnt lgkmcnt(5)
	v_mfma_f32_16x16x32_bf16 v[54:57], v[198:201], v[156:159], v[54:57]
	v_mfma_f32_16x16x32_bf16 v[50:53], v[198:201], v[170:173], v[50:53]
	s_waitcnt lgkmcnt(3)
	v_mfma_f32_16x16x32_bf16 v[46:49], v[206:209], v[156:159], v[46:49]
	v_mfma_f32_16x16x32_bf16 v[42:45], v[206:209], v[170:173], v[42:45]
	s_waitcnt lgkmcnt(1)
	v_mfma_f32_16x16x32_bf16 v[38:41], v[214:217], v[156:159], v[38:41]
	v_mfma_f32_16x16x32_bf16 v[34:37], v[214:217], v[170:173], v[34:37]
	v_mfma_f32_16x16x32_bf16 v[62:65], v[194:197], v[166:169], v[62:65]
	v_mfma_f32_16x16x32_bf16 v[58:61], v[194:197], v[186:189], v[58:61]
	v_mfma_f32_16x16x32_bf16 v[54:57], v[202:205], v[166:169], v[54:57]
	v_mfma_f32_16x16x32_bf16 v[50:53], v[202:205], v[186:189], v[50:53]
	v_mfma_f32_16x16x32_bf16 v[46:49], v[210:213], v[166:169], v[46:49]
	v_mfma_f32_16x16x32_bf16 v[42:45], v[210:213], v[186:189], v[42:45]
	s_waitcnt lgkmcnt(0)
	v_mfma_f32_16x16x32_bf16 v[38:41], v[218:221], v[166:169], v[38:41]
	v_mfma_f32_16x16x32_bf16 v[34:37], v[218:221], v[186:189], v[34:37]
	s_setprio 0
	s_barrier
	v_readfirstlane_b32 s28, v151
	s_add_i32 s29, s29, 0x40180
	s_mov_b32 m0, s28
	v_readfirstlane_b32 s28, v152
	buffer_load_dwordx4 v134, s[76:79], s29 offen lds
	s_mov_b32 m0, s28
	s_nop 0
	buffer_load_dwordx4 v135, s[76:79], s29 offen lds
	s_waitcnt vmcnt(6)
	s_barrier
	s_setprio 1
	v_mfma_f32_16x16x32_bf16 v[28:31], v[190:193], v[222:225], v[28:31]
	v_mfma_f32_16x16x32_bf16 v[24:27], v[190:193], v[230:233], v[24:27]
	v_mfma_f32_16x16x32_bf16 v[20:23], v[198:201], v[222:225], v[20:23]
	v_mfma_f32_16x16x32_bf16 v[16:19], v[198:201], v[230:233], v[16:19]
	v_mfma_f32_16x16x32_bf16 v[12:15], v[206:209], v[222:225], v[12:15]
	v_mfma_f32_16x16x32_bf16 v[8:11], v[206:209], v[230:233], v[8:11]
	v_mfma_f32_16x16x32_bf16 v[4:7], v[214:217], v[222:225], v[4:7]
	v_mfma_f32_16x16x32_bf16 v[0:3], v[214:217], v[230:233], v[0:3]
	v_mfma_f32_16x16x32_bf16 v[28:31], v[194:197], v[226:229], v[28:31]
	v_mfma_f32_16x16x32_bf16 v[24:27], v[194:197], v[234:237], v[24:27]
	v_mfma_f32_16x16x32_bf16 v[20:23], v[202:205], v[226:229], v[20:23]
	v_mfma_f32_16x16x32_bf16 v[16:19], v[202:205], v[234:237], v[16:19]
	v_mfma_f32_16x16x32_bf16 v[12:15], v[210:213], v[226:229], v[12:15]
	v_mfma_f32_16x16x32_bf16 v[8:11], v[210:213], v[234:237], v[8:11]
	v_mfma_f32_16x16x32_bf16 v[4:7], v[218:221], v[226:229], v[4:7]
	v_mfma_f32_16x16x32_bf16 v[0:3], v[218:221], v[234:237], v[0:3]
	s_setprio 0
	s_add_i32 s26, s26, 2
	s_addk_i32 s27, 0x100
	s_cmp_lt_u32 s26, 12
	s_barrier
	s_cbranch_scc1 .LBB0_1657
	s_branch .Lpx2
.LBB0_1657:
	ds_read_b128 v[156:159], v153
	ds_read_b128 v[166:169], v153 offset:1024
	ds_read_b128 v[170:173], v153 offset:2048
	ds_read_b128 v[186:189], v153 offset:3072
	s_add_i32 s28, s24, s27
	v_readfirstlane_b32 s30, v155
	s_add_i32 s29, s28, 0x40080
	s_mov_b32 m0, s30
	v_readfirstlane_b32 s30, v154
	ds_read_b128 v[190:193], v133
	ds_read_b128 v[194:197], v133 offset:1024
	ds_read_b128 v[198:201], v132
	ds_read_b128 v[202:205], v132 offset:1024
	ds_read_b128 v[206:209], v131
	ds_read_b128 v[210:213], v131 offset:1024
	ds_read_b128 v[214:217], v130
	ds_read_b128 v[218:221], v130 offset:1024
	buffer_load_dwordx4 v134, s[4:7], s29 offen lds
	s_mov_b32 m0, s30
	s_nop 0
	buffer_load_dwordx4 v135, s[4:7], s29 offen lds
	s_waitcnt lgkmcnt(8)
	s_barrier
	s_setprio 1
	s_waitcnt lgkmcnt(7)
	v_mfma_f32_16x16x32_bf16 v[126:129], v[190:193], v[156:159], v[126:129]
	v_mfma_f32_16x16x32_bf16 v[122:125], v[190:193], v[170:173], v[122:125]
	s_waitcnt lgkmcnt(5)
	v_mfma_f32_16x16x32_bf16 v[118:121], v[198:201], v[156:159], v[118:121]
	v_mfma_f32_16x16x32_bf16 v[114:117], v[198:201], v[170:173], v[114:117]
	s_waitcnt lgkmcnt(3)
	v_mfma_f32_16x16x32_bf16 v[110:113], v[206:209], v[156:159], v[110:113]
	v_mfma_f32_16x16x32_bf16 v[106:109], v[206:209], v[170:173], v[106:109]
	s_waitcnt lgkmcnt(1)
	v_mfma_f32_16x16x32_bf16 v[102:105], v[214:217], v[156:159], v[102:105]
	v_mfma_f32_16x16x32_bf16 v[98:101], v[214:217], v[170:173], v[98:101]
	v_mfma_f32_16x16x32_bf16 v[126:129], v[194:197], v[166:169], v[126:129]
	v_mfma_f32_16x16x32_bf16 v[122:125], v[194:197], v[186:189], v[122:125]
	v_mfma_f32_16x16x32_bf16 v[118:121], v[202:205], v[166:169], v[118:121]
	v_mfma_f32_16x16x32_bf16 v[114:117], v[202:205], v[186:189], v[114:117]
	v_mfma_f32_16x16x32_bf16 v[110:113], v[210:213], v[166:169], v[110:113]
	v_mfma_f32_16x16x32_bf16 v[106:109], v[210:213], v[186:189], v[106:109]
	s_waitcnt lgkmcnt(0)
	v_mfma_f32_16x16x32_bf16 v[102:105], v[218:221], v[166:169], v[102:105]
	v_mfma_f32_16x16x32_bf16 v[98:101], v[218:221], v[186:189], v[98:101]
	s_setprio 0
	s_barrier
	s_add_i32 s29, s25, s27
	v_readfirstlane_b32 s31, v138
	s_add_i32 s30, s29, 0x100
	s_mov_b32 m0, s31
	v_readfirstlane_b32 s31, v139
	ds_read_b128 v[222:225], v149
	ds_read_b128 v[226:229], v149 offset:1024
	ds_read_b128 v[230:233], v149 offset:2048
	ds_read_b128 v[234:237], v149 offset:3072
	buffer_load_dwordx4 v134, s[76:79], s30 offen lds
	s_mov_b32 m0, s31
	s_nop 0
	buffer_load_dwordx4 v135, s[76:79], s30 offen lds
	s_barrier
; #define STAGE(P, BASE, br, kt) do { int _so = ((br) * K + (kt) * BK) * 2; \
;     __builtin_amdgcn_raw_ptr_buffer_load_lds(rs_##BASE, (__attribute__((address_space(3))) void*)((char*)(P) + tx * 16), 16, voff0, _so, 0, 0); \
;     __builtin_amdgcn_raw_ptr_buffer_load_lds(rs_##BASE, (__attribute__((address_space(3))) void*)((char*)(P) + tx * 16 + 8192), 16, voff1, _so, 0, 0); } while (0)
; #define LDA(dst, b, h) _Pragma("unroll") for (int m = 0; m < 4; ++m) _Pragma("unroll") for (int k = 0; k < 2; ++k) \
;     dst[m][k] = *reinterpret_cast<const bf16x8*>((char*)SA(b, h) + lds_byte(wr * 64 + m * 16 + fr, k * 32 + fq * 8))
; #define LDB(dst, b, h) _Pragma("unroll") for (int n = 0; n < 2; ++n) _Pragma("unroll") for (int k = 0; k < 2; ++k) \
;     dst[n][k] = *reinterpret_cast<const bf16x8*>((char*)SB(b, h) + lds_byte(wc * 32 + n * 16 + fr, k * 32 + fq * 8))
; #define MMA(ai, bj, At, Bt_) do { __builtin_amdgcn_s_setprio(1); \
;     _Pragma("unroll") for (int m = 0; m < 4; ++m) _Pragma("unroll") for (int n = 0; n < 2; ++n) _Pragma("unroll") for (int k = 0; k < 2; ++k) \
;       acc[ai][bj][m][n] = __builtin_amdgcn_mfma_f32_16x16x32_bf16(At[m][k], Bt_[n][k], acc[ai][bj][m][n], 0, 0, 0); \
;     __builtin_amdgcn_s_setprio(0); } while (0)
; #define WAIT_V(n) asm volatile("s_waitcnt vmcnt(" #n ")" ::: "memory")
; #define WAIT_L(n) asm volatile("s_waitcnt lgkmcnt(" #n ")" ::: "memory")
; template <class Epi> ...
;     ...
;   for (int t = 0; t < nt - 2; t += 2) {
;     LDB(B0, 0, 0); SCHED; LDA(At, 0, 0); STAGE(SA(1, 1), A, brow + HALF, t + 1);
;     WAIT_L(8); BAR; WAIT_L(0); MMA(0, 0, At, B0); BAR; SCHED;
;     LDB(B1, 0, 1); STAGE(SB(0, 0), Bt, bcol, t + 2);
;     BAR; WAIT_L(0); MMA(0, 1, At, B1); BAR;
;     LDA(At, 0, 1); STAGE(SA(0, 0), A, brow, t + 2);
;     BAR; WAIT_L(0); MMA(1, 0, At, B0); BAR; SCHED;
;     STAGE(SB(0, 1), Bt, bcol + HALF, t + 2);
;     WAIT_V(6); BAR; MMA(1, 1, At, B1); BAR;
;     LDB(B0, 1, 0); SCHED; LDA(At, 1, 0); STAGE(SA(0, 1), A, brow + HALF, t + 2);
;     WAIT_L(8); BAR; WAIT_L(0); MMA(0, 0, At, B0); BAR; SCHED;
;     LDB(B1, 1, 1); STAGE(SB(1, 0), Bt, bcol, t + 3);
;     BAR; WAIT_L(0); MMA(0, 1, At, B1); BAR;
;     LDA(At, 1, 1); STAGE(SA(1, 0), A, brow, t + 3);
;     BAR; WAIT_L(0); MMA(1, 0, At, B0); BAR; SCHED;
;     STAGE(SB(1, 1), Bt, bcol + HALF, t + 3);
;     WAIT_V(6); BAR; MMA(1, 1, At, B1); BAR;
;   }
	s_setprio 1
	s_waitcnt lgkmcnt(3)
	v_mfma_f32_16x16x32_bf16 v[94:97], v[190:193], v[222:225], v[94:97]
	s_waitcnt lgkmcnt(1)
	v_mfma_f32_16x16x32_bf16 v[90:93], v[190:193], v[230:233], v[90:93]
	v_mfma_f32_16x16x32_bf16 v[86:89], v[198:201], v[222:225], v[86:89]
	v_mfma_f32_16x16x32_bf16 v[82:85], v[198:201], v[230:233], v[82:85]
	v_mfma_f32_16x16x32_bf16 v[78:81], v[206:209], v[222:225], v[78:81]
	v_mfma_f32_16x16x32_bf16 v[74:77], v[206:209], v[230:233], v[74:77]
	v_mfma_f32_16x16x32_bf16 v[70:73], v[214:217], v[222:225], v[70:73]
	v_mfma_f32_16x16x32_bf16 v[66:69], v[214:217], v[230:233], v[66:69]
	v_mfma_f32_16x16x32_bf16 v[94:97], v[194:197], v[226:229], v[94:97]
	s_waitcnt lgkmcnt(0)
	v_mfma_f32_16x16x32_bf16 v[90:93], v[194:197], v[234:237], v[90:93]
	v_mfma_f32_16x16x32_bf16 v[86:89], v[202:205], v[226:229], v[86:89]
	v_mfma_f32_16x16x32_bf16 v[82:85], v[202:205], v[234:237], v[82:85]
	v_mfma_f32_16x16x32_bf16 v[78:81], v[210:213], v[226:229], v[78:81]
	v_mfma_f32_16x16x32_bf16 v[74:77], v[210:213], v[234:237], v[74:77]
	v_mfma_f32_16x16x32_bf16 v[70:73], v[218:221], v[226:229], v[70:73]
	v_mfma_f32_16x16x32_bf16 v[66:69], v[218:221], v[234:237], v[66:69]
	s_setprio 0
	v_readfirstlane_b32 s31, v140
	s_add_i32 s30, s28, 0x100
	s_mov_b32 m0, s31
	v_readfirstlane_b32 s31, v141
	s_barrier
	ds_read_b128 v[190:193], v133 offset:16384
	ds_read_b128 v[194:197], v133 offset:17408
	ds_read_b128 v[198:201], v132 offset:16384
	ds_read_b128 v[202:205], v132 offset:17408
	ds_read_b128 v[206:209], v131 offset:16384
	ds_read_b128 v[210:213], v131 offset:17408
	ds_read_b128 v[214:217], v130 offset:16384
	ds_read_b128 v[218:221], v130 offset:17408
	buffer_load_dwordx4 v134, s[4:7], s30 offen lds
	s_mov_b32 m0, s31
	s_nop 0
	buffer_load_dwordx4 v135, s[4:7], s30 offen lds
	s_barrier
	s_setprio 1
	s_waitcnt lgkmcnt(7)
	v_mfma_f32_16x16x32_bf16 v[62:65], v[190:193], v[156:159], v[62:65]
	v_mfma_f32_16x16x32_bf16 v[58:61], v[190:193], v[170:173], v[58:61]
	s_waitcnt lgkmcnt(5)
	v_mfma_f32_16x16x32_bf16 v[54:57], v[198:201], v[156:159], v[54:57]
	v_mfma_f32_16x16x32_bf16 v[50:53], v[198:201], v[170:173], v[50:53]
	s_waitcnt lgkmcnt(3)
	v_mfma_f32_16x16x32_bf16 v[46:49], v[206:209], v[156:159], v[46:49]
	v_mfma_f32_16x16x32_bf16 v[42:45], v[206:209], v[170:173], v[42:45]
	s_waitcnt lgkmcnt(1)
	v_mfma_f32_16x16x32_bf16 v[38:41], v[214:217], v[156:159], v[38:41]
	v_mfma_f32_16x16x32_bf16 v[34:37], v[214:217], v[170:173], v[34:37]
	v_mfma_f32_16x16x32_bf16 v[62:65], v[194:197], v[166:169], v[62:65]
	v_mfma_f32_16x16x32_bf16 v[58:61], v[194:197], v[186:189], v[58:61]
	v_mfma_f32_16x16x32_bf16 v[54:57], v[202:205], v[166:169], v[54:57]
	v_mfma_f32_16x16x32_bf16 v[50:53], v[202:205], v[186:189], v[50:53]
	v_mfma_f32_16x16x32_bf16 v[46:49], v[210:213], v[166:169], v[46:49]
	v_mfma_f32_16x16x32_bf16 v[42:45], v[210:213], v[186:189], v[42:45]
	s_waitcnt lgkmcnt(0)
	v_mfma_f32_16x16x32_bf16 v[38:41], v[218:221], v[166:169], v[38:41]
	v_mfma_f32_16x16x32_bf16 v[34:37], v[218:221], v[186:189], v[34:37]
	s_setprio 0
	s_barrier
	v_readfirstlane_b32 s31, v142
	s_add_i32 s30, s29, 0x40100
	s_mov_b32 m0, s31
	v_readfirstlane_b32 s31, v143
	buffer_load_dwordx4 v134, s[76:79], s30 offen lds
	s_mov_b32 m0, s31
	s_nop 0
	buffer_load_dwordx4 v135, s[76:79], s30 offen lds
	s_waitcnt vmcnt(6)
	s_barrier
	s_setprio 1
	v_mfma_f32_16x16x32_bf16 v[28:31], v[190:193], v[222:225], v[28:31]
	v_mfma_f32_16x16x32_bf16 v[24:27], v[190:193], v[230:233], v[24:27]
	v_mfma_f32_16x16x32_bf16 v[20:23], v[198:201], v[222:225], v[20:23]
	v_mfma_f32_16x16x32_bf16 v[16:19], v[198:201], v[230:233], v[16:19]
	v_mfma_f32_16x16x32_bf16 v[12:15], v[206:209], v[222:225], v[12:15]
	v_mfma_f32_16x16x32_bf16 v[8:11], v[206:209], v[230:233], v[8:11]
	v_mfma_f32_16x16x32_bf16 v[4:7], v[214:217], v[222:225], v[4:7]
	v_mfma_f32_16x16x32_bf16 v[0:3], v[214:217], v[230:233], v[0:3]
	v_mfma_f32_16x16x32_bf16 v[28:31], v[194:197], v[226:229], v[28:31]
	v_mfma_f32_16x16x32_bf16 v[24:27], v[194:197], v[234:237], v[24:27]
	v_mfma_f32_16x16x32_bf16 v[20:23], v[202:205], v[226:229], v[20:23]
	v_mfma_f32_16x16x32_bf16 v[16:19], v[202:205], v[234:237], v[16:19]
	v_mfma_f32_16x16x32_bf16 v[12:15], v[210:213], v[226:229], v[12:15]
	v_mfma_f32_16x16x32_bf16 v[8:11], v[210:213], v[234:237], v[8:11]
	v_mfma_f32_16x16x32_bf16 v[4:7], v[218:221], v[226:229], v[4:7]
	v_mfma_f32_16x16x32_bf16 v[0:3], v[218:221], v[234:237], v[0:3]
	s_setprio 0
	s_barrier
	ds_read_b128 v[156:159], v137
	ds_read_b128 v[166:169], v137 offset:1024
	ds_read_b128 v[170:173], v137 offset:2048
	ds_read_b128 v[186:189], v137 offset:3072
	v_readfirstlane_b32 s31, v144
	s_add_i32 s30, s28, 0x40100
	s_mov_b32 m0, s31
	v_readfirstlane_b32 s31, v145
	ds_read_b128 v[190:193], v133 offset:32768
	ds_read_b128 v[194:197], v133 offset:33792
	ds_read_b128 v[198:201], v132 offset:32768
	ds_read_b128 v[202:205], v132 offset:33792
	ds_read_b128 v[206:209], v131 offset:32768
	ds_read_b128 v[210:213], v131 offset:33792
	ds_read_b128 v[214:217], v130 offset:32768
	ds_read_b128 v[218:221], v130 offset:33792
	buffer_load_dwordx4 v134, s[4:7], s30 offen lds
	s_mov_b32 m0, s31
	s_nop 0
	buffer_load_dwordx4 v135, s[4:7], s30 offen lds
	s_waitcnt lgkmcnt(8)
	s_barrier
; #define STAGE(P, BASE, br, kt) do { int _so = ((br) * K + (kt) * BK) * 2; \
;     __builtin_amdgcn_raw_ptr_buffer_load_lds(rs_##BASE, (__attribute__((address_space(3))) void*)((char*)(P) + tx * 16), 16, voff0, _so, 0, 0); \
;     __builtin_amdgcn_raw_ptr_buffer_load_lds(rs_##BASE, (__attribute__((address_space(3))) void*)((char*)(P) + tx * 16 + 8192), 16, voff1, _so, 0, 0); } while (0)
; #define LDA(dst, b, h) _Pragma("unroll") for (int m = 0; m < 4; ++m) _Pragma("unroll") for (int k = 0; k < 2; ++k) \
;     dst[m][k] = *reinterpret_cast<const bf16x8*>((char*)SA(b, h) + lds_byte(wr * 64 + m * 16 + fr, k * 32 + fq * 8))
; #define LDB(dst, b, h) _Pragma("unroll") for (int n = 0; n < 2; ++n) _Pragma("unroll") for (int k = 0; k < 2; ++k) \
;     dst[n][k] = *reinterpret_cast<const bf16x8*>((char*)SB(b, h) + lds_byte(wc * 32 + n * 16 + fr, k * 32 + fq * 8))
; #define MMA(ai, bj, At, Bt_) do { __builtin_amdgcn_s_setprio(1); \
;     _Pragma("unroll") for (int m = 0; m < 4; ++m) _Pragma("unroll") for (int n = 0; n < 2; ++n) _Pragma("unroll") for (int k = 0; k < 2; ++k) \
;       acc[ai][bj][m][n] = __builtin_amdgcn_mfma_f32_16x16x32_bf16(At[m][k], Bt_[n][k], acc[ai][bj][m][n], 0, 0, 0); \
;     __builtin_amdgcn_s_setprio(0); } while (0)
; #define WAIT_V(n) asm volatile("s_waitcnt vmcnt(" #n ")" ::: "memory")
; #define WAIT_L(n) asm volatile("s_waitcnt lgkmcnt(" #n ")" ::: "memory")
; #define BAR __builtin_amdgcn_s_barrier()
; #define SCHED __builtin_amdgcn_sched_barrier(0)
; template <class Epi> ...
;     ...
;     LDB(B0, 1, 0); SCHED; LDA(At, 1, 0); STAGE(SA(0, 1), A, brow + HALF, t + 2);
;     WAIT_L(8); BAR; WAIT_L(0); MMA(0, 0, At, B0); BAR; SCHED;
;     LDB(B1, 1, 1); STAGE(SB(1, 0), Bt, bcol, t + 3);
;     BAR; WAIT_L(0); MMA(0, 1, At, B1); BAR;
;     LDA(At, 1, 1); STAGE(SA(1, 0), A, brow, t + 3);
;     BAR; WAIT_L(0); MMA(1, 0, At, B0); BAR; SCHED;
;     STAGE(SB(1, 1), Bt, bcol + HALF, t + 3);
;     WAIT_V(6); BAR; MMA(1, 1, At, B1); BAR;
;   }
	s_setprio 1
	s_waitcnt lgkmcnt(7)
	v_mfma_f32_16x16x32_bf16 v[126:129], v[190:193], v[156:159], v[126:129]
	v_mfma_f32_16x16x32_bf16 v[122:125], v[190:193], v[170:173], v[122:125]
	s_waitcnt lgkmcnt(5)
	v_mfma_f32_16x16x32_bf16 v[118:121], v[198:201], v[156:159], v[118:121]
	v_mfma_f32_16x16x32_bf16 v[114:117], v[198:201], v[170:173], v[114:117]
	s_waitcnt lgkmcnt(3)
	v_mfma_f32_16x16x32_bf16 v[110:113], v[206:209], v[156:159], v[110:113]
	v_mfma_f32_16x16x32_bf16 v[106:109], v[206:209], v[170:173], v[106:109]
	s_waitcnt lgkmcnt(1)
	v_mfma_f32_16x16x32_bf16 v[102:105], v[214:217], v[156:159], v[102:105]
	v_mfma_f32_16x16x32_bf16 v[98:101], v[214:217], v[170:173], v[98:101]
	v_mfma_f32_16x16x32_bf16 v[126:129], v[194:197], v[166:169], v[126:129]
	v_mfma_f32_16x16x32_bf16 v[122:125], v[194:197], v[186:189], v[122:125]
	v_mfma_f32_16x16x32_bf16 v[118:121], v[202:205], v[166:169], v[118:121]
	v_mfma_f32_16x16x32_bf16 v[114:117], v[202:205], v[186:189], v[114:117]
	v_mfma_f32_16x16x32_bf16 v[110:113], v[210:213], v[166:169], v[110:113]
	v_mfma_f32_16x16x32_bf16 v[106:109], v[210:213], v[186:189], v[106:109]
	s_waitcnt lgkmcnt(0)
	v_mfma_f32_16x16x32_bf16 v[102:105], v[218:221], v[166:169], v[102:105]
	v_mfma_f32_16x16x32_bf16 v[98:101], v[218:221], v[186:189], v[98:101]
	s_setprio 0
	s_barrier
	v_readfirstlane_b32 s31, v146
	s_add_i32 s30, s29, 0x180
	s_mov_b32 m0, s31
	v_readfirstlane_b32 s31, v147
	ds_read_b128 v[222:225], v136
	ds_read_b128 v[226:229], v136 offset:1024
	ds_read_b128 v[230:233], v136 offset:2048
	ds_read_b128 v[234:237], v136 offset:3072
	buffer_load_dwordx4 v134, s[76:79], s30 offen lds
	s_mov_b32 m0, s31
	s_nop 0
	buffer_load_dwordx4 v135, s[76:79], s30 offen lds
	s_barrier
	s_setprio 1
	s_waitcnt lgkmcnt(3)
	v_mfma_f32_16x16x32_bf16 v[94:97], v[190:193], v[222:225], v[94:97]
	s_waitcnt lgkmcnt(1)
	v_mfma_f32_16x16x32_bf16 v[90:93], v[190:193], v[230:233], v[90:93]
	v_mfma_f32_16x16x32_bf16 v[86:89], v[198:201], v[222:225], v[86:89]
	v_mfma_f32_16x16x32_bf16 v[82:85], v[198:201], v[230:233], v[82:85]
	v_mfma_f32_16x16x32_bf16 v[78:81], v[206:209], v[222:225], v[78:81]
	v_mfma_f32_16x16x32_bf16 v[74:77], v[206:209], v[230:233], v[74:77]
	v_mfma_f32_16x16x32_bf16 v[70:73], v[214:217], v[222:225], v[70:73]
	v_mfma_f32_16x16x32_bf16 v[66:69], v[214:217], v[230:233], v[66:69]
	v_mfma_f32_16x16x32_bf16 v[94:97], v[194:197], v[226:229], v[94:97]
	s_waitcnt lgkmcnt(0)
	v_mfma_f32_16x16x32_bf16 v[90:93], v[194:197], v[234:237], v[90:93]
	v_mfma_f32_16x16x32_bf16 v[86:89], v[202:205], v[226:229], v[86:89]
	v_mfma_f32_16x16x32_bf16 v[82:85], v[202:205], v[234:237], v[82:85]
	v_mfma_f32_16x16x32_bf16 v[78:81], v[210:213], v[226:229], v[78:81]
	v_mfma_f32_16x16x32_bf16 v[74:77], v[210:213], v[234:237], v[74:77]
	v_mfma_f32_16x16x32_bf16 v[70:73], v[218:221], v[226:229], v[70:73]
	v_mfma_f32_16x16x32_bf16 v[66:69], v[218:221], v[234:237], v[66:69]
	s_setprio 0
	v_readfirstlane_b32 s30, v148
	s_addk_i32 s28, 0x180
	s_mov_b32 m0, s30
	v_readfirstlane_b32 s30, v150
	s_barrier
	ds_read_b128 v[190:193], v133 offset:49152
	ds_read_b128 v[194:197], v133 offset:50176
	ds_read_b128 v[198:201], v132 offset:49152
	ds_read_b128 v[202:205], v132 offset:50176
	ds_read_b128 v[206:209], v131 offset:49152
	ds_read_b128 v[210:213], v131 offset:50176
	ds_read_b128 v[214:217], v130 offset:49152
	ds_read_b128 v[218:221], v130 offset:50176
	buffer_load_dwordx4 v134, s[4:7], s28 offen lds
	s_mov_b32 m0, s30
	s_nop 0
	buffer_load_dwordx4 v135, s[4:7], s28 offen lds
	s_barrier
	s_setprio 1
	s_waitcnt lgkmcnt(7)
	v_mfma_f32_16x16x32_bf16 v[62:65], v[190:193], v[156:159], v[62:65]
	v_mfma_f32_16x16x32_bf16 v[58:61], v[190:193], v[170:173], v[58:61]
	s_waitcnt lgkmcnt(5)
	v_mfma_f32_16x16x32_bf16 v[54:57], v[198:201], v[156:159], v[54:57]
	v_mfma_f32_16x16x32_bf16 v[50:53], v[198:201], v[170:173], v[50:53]
	s_waitcnt lgkmcnt(3)
	v_mfma_f32_16x16x32_bf16 v[46:49], v[206:209], v[156:159], v[46:49]
	v_mfma_f32_16x16x32_bf16 v[42:45], v[206:209], v[170:173], v[42:45]
	s_waitcnt lgkmcnt(1)
	v_mfma_f32_16x16x32_bf16 v[38:41], v[214:217], v[156:159], v[38:41]
	v_mfma_f32_16x16x32_bf16 v[34:37], v[214:217], v[170:173], v[34:37]
	v_mfma_f32_16x16x32_bf16 v[62:65], v[194:197], v[166:169], v[62:65]
	v_mfma_f32_16x16x32_bf16 v[58:61], v[194:197], v[186:189], v[58:61]
	v_mfma_f32_16x16x32_bf16 v[54:57], v[202:205], v[166:169], v[54:57]
	v_mfma_f32_16x16x32_bf16 v[50:53], v[202:205], v[186:189], v[50:53]
	v_mfma_f32_16x16x32_bf16 v[46:49], v[210:213], v[166:169], v[46:49]
	v_mfma_f32_16x16x32_bf16 v[42:45], v[210:213], v[186:189], v[42:45]
	s_waitcnt lgkmcnt(0)
	v_mfma_f32_16x16x32_bf16 v[38:41], v[218:221], v[166:169], v[38:41]
	v_mfma_f32_16x16x32_bf16 v[34:37], v[218:221], v[186:189], v[34:37]
	s_setprio 0
	s_barrier
	v_readfirstlane_b32 s28, v151
	s_add_i32 s29, s29, 0x40180
	s_mov_b32 m0, s28
	v_readfirstlane_b32 s28, v152
	buffer_load_dwordx4 v134, s[76:79], s29 offen lds
	s_mov_b32 m0, s28
	s_nop 0
	buffer_load_dwordx4 v135, s[76:79], s29 offen lds
	s_waitcnt vmcnt(6)
	s_barrier
	s_setprio 1
	v_mfma_f32_16x16x32_bf16 v[28:31], v[190:193], v[222:225], v[28:31]
	v_mfma_f32_16x16x32_bf16 v[24:27], v[190:193], v[230:233], v[24:27]
	v_mfma_f32_16x16x32_bf16 v[20:23], v[198:201], v[222:225], v[20:23]
	v_mfma_f32_16x16x32_bf16 v[16:19], v[198:201], v[230:233], v[16:19]
	v_mfma_f32_16x16x32_bf16 v[12:15], v[206:209], v[222:225], v[12:15]
	v_mfma_f32_16x16x32_bf16 v[8:11], v[206:209], v[230:233], v[8:11]
	v_mfma_f32_16x16x32_bf16 v[4:7], v[214:217], v[222:225], v[4:7]
	v_mfma_f32_16x16x32_bf16 v[0:3], v[214:217], v[230:233], v[0:3]
	v_mfma_f32_16x16x32_bf16 v[28:31], v[194:197], v[226:229], v[28:31]
	v_mfma_f32_16x16x32_bf16 v[24:27], v[194:197], v[234:237], v[24:27]
	v_mfma_f32_16x16x32_bf16 v[20:23], v[202:205], v[226:229], v[20:23]
	v_mfma_f32_16x16x32_bf16 v[16:19], v[202:205], v[234:237], v[16:19]
	v_mfma_f32_16x16x32_bf16 v[12:15], v[210:213], v[226:229], v[12:15]
	v_mfma_f32_16x16x32_bf16 v[8:11], v[210:213], v[234:237], v[8:11]
	v_mfma_f32_16x16x32_bf16 v[4:7], v[218:221], v[226:229], v[4:7]
	v_mfma_f32_16x16x32_bf16 v[0:3], v[218:221], v[234:237], v[0:3]
	s_setprio 0
	s_add_i32 s26, s26, 2
	s_addk_i32 s27, 0x100
	s_cmp_lt_u32 s26, 12
	s_barrier
	s_cbranch_scc1 .LBB0_1657
; #define STAGE(P, BASE, br, kt) do { int _so = ((br) * K + (kt) * BK) * 2; \
;     __builtin_amdgcn_raw_ptr_buffer_load_lds(rs_##BASE, (__attribute__((address_space(3))) void*)((char*)(P) + tx * 16), 16, voff0, _so, 0, 0); \
;     __builtin_amdgcn_raw_ptr_buffer_load_lds(rs_##BASE, (__attribute__((address_space(3))) void*)((char*)(P) + tx * 16 + 8192), 16, voff1, _so, 0, 0); } while (0)
; #define LDA(dst, b, h) _Pragma("unroll") for (int m = 0; m < 4; ++m) _Pragma("unroll") for (int k = 0; k < 2; ++k) \
;     dst[m][k] = *reinterpret_cast<const bf16x8*>((char*)SA(b, h) + lds_byte(wr * 64 + m * 16 + fr, k * 32 + fq * 8))
; #define LDB(dst, b, h) _Pragma("unroll") for (int n = 0; n < 2; ++n) _Pragma("unroll") for (int k = 0; k < 2; ++k) \
;     dst[n][k] = *reinterpret_cast<const bf16x8*>((char*)SB(b, h) + lds_byte(wc * 32 + n * 16 + fr, k * 32 + fq * 8))
; #define MMA(ai, bj, At, Bt_) do { __builtin_amdgcn_s_setprio(1); \
;     _Pragma("unroll") for (int m = 0; m < 4; ++m) _Pragma("unroll") for (int n = 0; n < 2; ++n) _Pragma("unroll") for (int k = 0; k < 2; ++k) \
;       acc[ai][bj][m][n] = __builtin_amdgcn_mfma_f32_16x16x32_bf16(At[m][k], Bt_[n][k], acc[ai][bj][m][n], 0, 0, 0); \
;     __builtin_amdgcn_s_setprio(0); } while (0)
; #define WAIT_V(n) asm volatile("s_waitcnt vmcnt(" #n ")" ::: "memory")
; #define WAIT_L(n) asm volatile("s_waitcnt lgkmcnt(" #n ")" ::: "memory")
; #define BAR __builtin_amdgcn_s_barrier()
; template <class Epi> ...
;     ...
;   { LDB(B0, 0, 0); LDA(At, 0, 0); STAGE(SA(1, 1), A, brow + HALF, nt - 1);
;     BAR; WAIT_L(0); MMA(0, 0, At, B0); BAR;
;     LDB(B1, 0, 1); BAR; WAIT_L(0); MMA(0, 1, At, B1); BAR;
;     LDA(At, 0, 1); WAIT_V(4); BAR; WAIT_L(0); MMA(1, 0, At, B0); MMA(1, 1, At, B1); BAR; }
;   { LDB(B0, 1, 0); LDA(At, 1, 0); WAIT_V(2); BAR; WAIT_L(0); MMA(0, 0, At, B0); BAR;
.Lpx2:
	v_readfirstlane_b32 s25, v155
	s_or_b32 s24, s24, 0x40780
	s_mov_b32 s6, s78
	s_mov_b32 s7, s79
	s_mov_b32 m0, s25
	v_readfirstlane_b32 s25, v154
	ds_read_b128 v[138:141], v153
	ds_read_b128 v[142:145], v153 offset:1024
	ds_read_b128 v[156:159], v153 offset:2048
	ds_read_b128 v[150:153], v153 offset:3072
	ds_read_b128 v[166:169], v133
	ds_read_b128 v[170:173], v133 offset:1024
	ds_read_b128 v[186:189], v132
	ds_read_b128 v[190:193], v132 offset:1024
	ds_read_b128 v[194:197], v131
	ds_read_b128 v[198:201], v131 offset:1024
	ds_read_b128 v[202:205], v130
	ds_read_b128 v[206:209], v130 offset:1024
	buffer_load_dwordx4 v134, s[4:7], s24 offen lds
	s_mov_b32 m0, s25
	s_nop 0
	buffer_load_dwordx4 v135, s[4:7], s24 offen lds
	s_barrier
	s_setprio 1
	s_waitcnt lgkmcnt(7)
	v_mfma_f32_16x16x32_bf16 v[126:129], v[166:169], v[138:141], v[126:129]
	v_mfma_f32_16x16x32_bf16 v[122:125], v[166:169], v[156:159], v[122:125]
	s_waitcnt lgkmcnt(5)
	v_mfma_f32_16x16x32_bf16 v[118:121], v[186:189], v[138:141], v[118:121]
	v_mfma_f32_16x16x32_bf16 v[114:117], v[186:189], v[156:159], v[114:117]
	s_waitcnt lgkmcnt(3)
	v_mfma_f32_16x16x32_bf16 v[110:113], v[194:197], v[138:141], v[110:113]
	v_mfma_f32_16x16x32_bf16 v[106:109], v[194:197], v[156:159], v[106:109]
	s_waitcnt lgkmcnt(1)
	v_mfma_f32_16x16x32_bf16 v[102:105], v[202:205], v[138:141], v[102:105]
	v_mfma_f32_16x16x32_bf16 v[98:101], v[202:205], v[156:159], v[98:101]
	v_mfma_f32_16x16x32_bf16 v[126:129], v[170:173], v[142:145], v[126:129]
	v_mfma_f32_16x16x32_bf16 v[122:125], v[170:173], v[150:153], v[122:125]
	v_mfma_f32_16x16x32_bf16 v[118:121], v[190:193], v[142:145], v[118:121]
	v_mfma_f32_16x16x32_bf16 v[114:117], v[190:193], v[150:153], v[114:117]
	v_mfma_f32_16x16x32_bf16 v[110:113], v[198:201], v[142:145], v[110:113]
	v_mfma_f32_16x16x32_bf16 v[106:109], v[198:201], v[150:153], v[106:109]
	s_waitcnt lgkmcnt(0)
	v_mfma_f32_16x16x32_bf16 v[102:105], v[206:209], v[142:145], v[102:105]
	v_mfma_f32_16x16x32_bf16 v[98:101], v[206:209], v[150:153], v[98:101]
	s_setprio 0
	s_barrier
	ds_read_b128 v[210:213], v149
	ds_read_b128 v[214:217], v149 offset:1024
	ds_read_b128 v[218:221], v149 offset:2048
	ds_read_b128 v[146:149], v149 offset:3072
	s_barrier
	s_setprio 1
	s_waitcnt lgkmcnt(3)
	v_mfma_f32_16x16x32_bf16 v[94:97], v[166:169], v[210:213], v[94:97]
	s_waitcnt lgkmcnt(1)
	v_mfma_f32_16x16x32_bf16 v[90:93], v[166:169], v[218:221], v[90:93]
	v_mfma_f32_16x16x32_bf16 v[82:85], v[186:189], v[218:221], v[82:85]
	v_mfma_f32_16x16x32_bf16 v[78:81], v[194:197], v[210:213], v[78:81]
	v_mfma_f32_16x16x32_bf16 v[66:69], v[202:205], v[218:221], v[66:69]
	v_mfma_f32_16x16x32_bf16 v[94:97], v[170:173], v[214:217], v[94:97]
	s_waitcnt lgkmcnt(0)
	v_mfma_f32_16x16x32_bf16 v[90:93], v[170:173], v[146:149], v[90:93]
	v_mfma_f32_16x16x32_bf16 v[86:89], v[186:189], v[210:213], v[86:89]
	v_mfma_f32_16x16x32_bf16 v[82:85], v[190:193], v[146:149], v[82:85]
	v_mfma_f32_16x16x32_bf16 v[78:81], v[198:201], v[214:217], v[78:81]
	v_mfma_f32_16x16x32_bf16 v[74:77], v[194:197], v[218:221], v[74:77]
	v_mfma_f32_16x16x32_bf16 v[70:73], v[202:205], v[210:213], v[70:73]
	v_mfma_f32_16x16x32_bf16 v[66:69], v[206:209], v[146:149], v[66:69]
	v_mfma_f32_16x16x32_bf16 v[166:169], v[190:193], v[214:217], v[86:89]
	v_mfma_f32_16x16x32_bf16 v[170:173], v[198:201], v[146:149], v[74:77]
	v_mfma_f32_16x16x32_bf16 v[186:189], v[206:209], v[214:217], v[70:73]
	s_setprio 0
	s_barrier
	s_nop 1
	ds_read_b128 v[70:73], v133 offset:16384
	ds_read_b128 v[74:77], v133 offset:17408
	ds_read_b128 v[86:89], v132 offset:16384
	ds_read_b128 v[190:193], v132 offset:17408
	ds_read_b128 v[194:197], v131 offset:16384
	ds_read_b128 v[198:201], v131 offset:17408
	ds_read_b128 v[202:205], v130 offset:16384
	ds_read_b128 v[206:209], v130 offset:17408
	s_waitcnt vmcnt(4)
	s_barrier
	s_setprio 1
	s_waitcnt lgkmcnt(7)
	v_mfma_f32_16x16x32_bf16 v[62:65], v[70:73], v[138:141], v[62:65]
	s_waitcnt lgkmcnt(5)
	v_mfma_f32_16x16x32_bf16 v[50:53], v[86:89], v[156:159], v[50:53]
	s_waitcnt lgkmcnt(3)
	v_mfma_f32_16x16x32_bf16 v[46:49], v[194:197], v[138:141], v[46:49]
	v_mfma_f32_16x16x32_bf16 v[62:65], v[74:77], v[142:145], v[62:65]
	v_mfma_f32_16x16x32_bf16 v[58:61], v[70:73], v[156:159], v[58:61]
	v_mfma_f32_16x16x32_bf16 v[54:57], v[86:89], v[138:141], v[54:57]
	v_mfma_f32_16x16x32_bf16 v[50:53], v[190:193], v[150:153], v[50:53]
	s_waitcnt lgkmcnt(2)
	v_mfma_f32_16x16x32_bf16 v[46:49], v[198:201], v[142:145], v[46:49]
	v_mfma_f32_16x16x32_bf16 v[42:45], v[194:197], v[156:159], v[42:45]
	s_waitcnt lgkmcnt(1)
	v_mfma_f32_16x16x32_bf16 v[38:41], v[202:205], v[138:141], v[38:41]
	v_mfma_f32_16x16x32_bf16 v[34:37], v[202:205], v[156:159], v[34:37]
	v_mfma_f32_16x16x32_bf16 v[222:225], v[74:77], v[150:153], v[58:61]
	v_mfma_f32_16x16x32_bf16 v[226:229], v[190:193], v[142:145], v[54:57]
	v_mfma_f32_16x16x32_bf16 v[230:233], v[198:201], v[150:153], v[42:45]
	s_waitcnt lgkmcnt(0)
	v_mfma_f32_16x16x32_bf16 v[138:141], v[206:209], v[142:145], v[38:41]
	v_mfma_f32_16x16x32_bf16 v[142:145], v[206:209], v[150:153], v[34:37]
	s_setprio 0
	s_setprio 1
	v_mfma_f32_16x16x32_bf16 v[0:3], v[202:205], v[218:221], v[0:3]
	v_mfma_f32_16x16x32_bf16 v[28:31], v[70:73], v[210:213], v[28:31]
	v_mfma_f32_16x16x32_bf16 v[24:27], v[70:73], v[218:221], v[24:27]
	v_mfma_f32_16x16x32_bf16 v[20:23], v[86:89], v[210:213], v[20:23]
	v_mfma_f32_16x16x32_bf16 v[16:19], v[86:89], v[218:221], v[16:19]
	v_mfma_f32_16x16x32_bf16 v[12:15], v[194:197], v[210:213], v[12:15]
	v_mfma_f32_16x16x32_bf16 v[8:11], v[194:197], v[218:221], v[8:11]
	v_mfma_f32_16x16x32_bf16 v[4:7], v[202:205], v[210:213], v[4:7]
	v_mfma_f32_16x16x32_bf16 v[0:3], v[206:209], v[146:149], v[0:3]
	v_mfma_f32_16x16x32_bf16 v[150:153], v[74:77], v[214:217], v[28:31]
	v_mfma_f32_16x16x32_bf16 v[154:157], v[74:77], v[146:149], v[24:27]
	v_mfma_f32_16x16x32_bf16 v[158:161], v[190:193], v[214:217], v[20:23]
	v_mfma_f32_16x16x32_bf16 v[190:193], v[190:193], v[146:149], v[16:19]
	v_mfma_f32_16x16x32_bf16 v[234:237], v[198:201], v[214:217], v[12:15]
	v_mfma_f32_16x16x32_bf16 v[194:197], v[198:201], v[146:149], v[8:11]
	v_mfma_f32_16x16x32_bf16 v[198:201], v[206:209], v[214:217], v[4:7]
	s_setprio 0
	s_barrier
; #define LDA(dst, b, h) _Pragma("unroll") for (int m = 0; m < 4; ++m) _Pragma("unroll") for (int k = 0; k < 2; ++k) \
;     dst[m][k] = *reinterpret_cast<const bf16x8*>((char*)SA(b, h) + lds_byte(wr * 64 + m * 16 + fr, k * 32 + fq * 8))
; #define LDB(dst, b, h) _Pragma("unroll") for (int n = 0; n < 2; ++n) _Pragma("unroll") for (int k = 0; k < 2; ++k) \
;     dst[n][k] = *reinterpret_cast<const bf16x8*>((char*)SB(b, h) + lds_byte(wc * 32 + n * 16 + fr, k * 32 + fq * 8))
; #define MMA(ai, bj, At, Bt_) do { __builtin_amdgcn_s_setprio(1); \
;     _Pragma("unroll") for (int m = 0; m < 4; ++m) _Pragma("unroll") for (int n = 0; n < 2; ++n) _Pragma("unroll") for (int k = 0; k < 2; ++k) \
;       acc[ai][bj][m][n] = __builtin_amdgcn_mfma_f32_16x16x32_bf16(At[m][k], Bt_[n][k], acc[ai][bj][m][n], 0, 0, 0); \
;     __builtin_amdgcn_s_setprio(0); } while (0)
; #define WAIT_V(n) asm volatile("s_waitcnt vmcnt(" #n ")" ::: "memory")
; #define WAIT_L(n) asm volatile("s_waitcnt lgkmcnt(" #n ")" ::: "memory")
; #define BAR __builtin_amdgcn_s_barrier()
; template <class Epi> ...
;     ...
;   { LDB(B0, 1, 0); LDA(At, 1, 0); WAIT_V(2); BAR; WAIT_L(0); MMA(0, 0, At, B0); BAR;
;     LDB(B1, 1, 1); WAIT_V(0); BAR; WAIT_L(0); MMA(0, 1, At, B1); BAR;
;     LDA(At, 1, 1); BAR; WAIT_L(0); MMA(1, 0, At, B0); MMA(1, 1, At, B1); BAR; }
;   if (wr == 0) BAR;
	ds_read_b128 v[146:149], v137
	ds_read_b128 v[202:205], v137 offset:1024
	ds_read_b128 v[206:209], v137 offset:2048
	ds_read_b128 v[210:213], v137 offset:3072
	ds_read_b128 v[38:41], v133 offset:32768
	ds_read_b128 v[42:45], v133 offset:33792
	ds_read_b128 v[54:57], v132 offset:32768
	ds_read_b128 v[58:61], v132 offset:33792
	ds_read_b128 v[214:217], v131 offset:32768
	ds_read_b128 v[218:221], v131 offset:33792
	ds_read_b128 v[238:241], v130 offset:32768
	ds_read_b128 v[242:245], v130 offset:33792
	s_waitcnt vmcnt(2)
	s_barrier
	s_setprio 1
	s_waitcnt lgkmcnt(7)
	v_mfma_f32_16x16x32_bf16 v[4:7], v[38:41], v[146:149], v[126:129]
	s_waitcnt lgkmcnt(6)
	v_mfma_f32_16x16x32_bf16 v[28:31], v[42:45], v[202:205], v[4:7]
	v_mfma_f32_16x16x32_bf16 v[4:7], v[38:41], v[206:209], v[122:125]
	v_mfma_f32_16x16x32_bf16 v[34:37], v[42:45], v[210:213], v[4:7]
	s_waitcnt lgkmcnt(5)
	v_mfma_f32_16x16x32_bf16 v[4:7], v[54:57], v[146:149], v[118:121]
	s_waitcnt lgkmcnt(4)
	v_mfma_f32_16x16x32_bf16 v[20:23], v[58:61], v[202:205], v[4:7]
	v_mfma_f32_16x16x32_bf16 v[4:7], v[54:57], v[206:209], v[114:117]
	v_mfma_f32_16x16x32_bf16 v[24:27], v[58:61], v[210:213], v[4:7]
	s_waitcnt lgkmcnt(3)
	v_mfma_f32_16x16x32_bf16 v[4:7], v[214:217], v[146:149], v[110:113]
	s_waitcnt lgkmcnt(2)
	v_mfma_f32_16x16x32_bf16 v[12:15], v[218:221], v[202:205], v[4:7]
	v_mfma_f32_16x16x32_bf16 v[4:7], v[214:217], v[206:209], v[106:109]
	v_mfma_f32_16x16x32_bf16 v[16:19], v[218:221], v[210:213], v[4:7]
	s_waitcnt lgkmcnt(1)
	v_mfma_f32_16x16x32_bf16 v[4:7], v[238:241], v[146:149], v[102:105]
	v_mfma_f32_16x16x32_bf16 v[8:11], v[238:241], v[206:209], v[98:101]
	s_waitcnt lgkmcnt(0)
	v_mfma_f32_16x16x32_bf16 v[4:7], v[242:245], v[202:205], v[4:7]
	v_mfma_f32_16x16x32_bf16 v[8:11], v[242:245], v[210:213], v[8:11]
	s_setprio 0
	s_barrier
	ds_read_b128 v[102:105], v136
	ds_read_b128 v[246:249], v136 offset:1024
	ds_read_b128 v[250:253], v136 offset:2048
	ds_read_b128 v[134:137], v136 offset:3072
	s_waitcnt vmcnt(0)
	s_barrier
	s_setprio 1
	s_waitcnt lgkmcnt(3)
	v_mfma_f32_16x16x32_bf16 v[70:73], v[38:41], v[102:105], v[94:97]
	s_waitcnt lgkmcnt(1)
	v_mfma_f32_16x16x32_bf16 v[38:41], v[38:41], v[250:253], v[90:93]
	s_waitcnt lgkmcnt(0)
	v_mfma_f32_16x16x32_bf16 v[90:93], v[42:45], v[134:137], v[38:41]
	v_mfma_f32_16x16x32_bf16 v[38:41], v[54:57], v[102:105], v[166:169]
	v_mfma_f32_16x16x32_bf16 v[86:89], v[42:45], v[246:249], v[70:73]
	v_mfma_f32_16x16x32_bf16 v[70:73], v[58:61], v[246:249], v[38:41]
	v_mfma_f32_16x16x32_bf16 v[38:41], v[54:57], v[250:253], v[82:85]
	v_mfma_f32_16x16x32_bf16 v[74:77], v[58:61], v[134:137], v[38:41]
	v_mfma_f32_16x16x32_bf16 v[38:41], v[214:217], v[102:105], v[78:81]
	v_mfma_f32_16x16x32_bf16 v[54:57], v[218:221], v[246:249], v[38:41]
	v_mfma_f32_16x16x32_bf16 v[38:41], v[214:217], v[250:253], v[170:173]
	v_mfma_f32_16x16x32_bf16 v[58:61], v[218:221], v[134:137], v[38:41]
	v_mfma_f32_16x16x32_bf16 v[38:41], v[238:241], v[102:105], v[186:189]
	v_mfma_f32_16x16x32_bf16 v[42:45], v[238:241], v[250:253], v[66:69]
	v_mfma_f32_16x16x32_bf16 v[38:41], v[242:245], v[246:249], v[38:41]
	v_mfma_f32_16x16x32_bf16 v[42:45], v[242:245], v[134:137], v[42:45]
	s_setprio 0
	s_barrier
	ds_read_b128 v[106:109], v133 offset:49152
	ds_read_b128 v[110:113], v133 offset:50176
	ds_read_b128 v[118:121], v132 offset:49152
	ds_read_b128 v[166:169], v132 offset:50176
	ds_read_b128 v[170:173], v131 offset:49152
	ds_read_b128 v[186:189], v131 offset:50176
	ds_read_b128 v[214:217], v130 offset:49152
	ds_read_b128 v[130:133], v130 offset:50176
	s_barrier
	s_setprio 1
	s_waitcnt lgkmcnt(7)
	v_mfma_f32_16x16x32_bf16 v[62:65], v[106:109], v[146:149], v[62:65]
	s_waitcnt lgkmcnt(6)
	v_mfma_f32_16x16x32_bf16 v[94:97], v[110:113], v[202:205], v[62:65]
	v_mfma_f32_16x16x32_bf16 v[62:65], v[106:109], v[206:209], v[222:225]
	v_mfma_f32_16x16x32_bf16 v[98:101], v[110:113], v[210:213], v[62:65]
	s_waitcnt lgkmcnt(5)
	v_mfma_f32_16x16x32_bf16 v[62:65], v[118:121], v[146:149], v[226:229]
	s_waitcnt lgkmcnt(3)
	v_mfma_f32_16x16x32_bf16 v[46:49], v[170:173], v[146:149], v[46:49]
	v_mfma_f32_16x16x32_bf16 v[78:81], v[166:169], v[202:205], v[62:65]
	v_mfma_f32_16x16x32_bf16 v[50:53], v[118:121], v[206:209], v[50:53]
	s_waitcnt lgkmcnt(2)
	v_mfma_f32_16x16x32_bf16 v[62:65], v[186:189], v[202:205], v[46:49]
	v_mfma_f32_16x16x32_bf16 v[46:49], v[170:173], v[206:209], v[230:233]
	v_mfma_f32_16x16x32_bf16 v[82:85], v[166:169], v[210:213], v[50:53]
	v_mfma_f32_16x16x32_bf16 v[66:69], v[186:189], v[210:213], v[46:49]
	s_waitcnt lgkmcnt(1)
	v_mfma_f32_16x16x32_bf16 v[46:49], v[214:217], v[146:149], v[138:141]
	v_mfma_f32_16x16x32_bf16 v[50:53], v[214:217], v[206:209], v[142:145]
	s_waitcnt lgkmcnt(0)
	v_mfma_f32_16x16x32_bf16 v[46:49], v[130:133], v[202:205], v[46:49]
	v_mfma_f32_16x16x32_bf16 v[50:53], v[130:133], v[210:213], v[50:53]
	s_setprio 0
	s_setprio 1
	v_mfma_f32_16x16x32_bf16 v[114:117], v[106:109], v[102:105], v[150:153]
	v_mfma_f32_16x16x32_bf16 v[106:109], v[106:109], v[250:253], v[154:157]
	v_mfma_f32_16x16x32_bf16 v[126:129], v[110:113], v[134:137], v[106:109]
	v_mfma_f32_16x16x32_bf16 v[106:109], v[118:121], v[102:105], v[158:161]
	v_mfma_f32_16x16x32_bf16 v[122:125], v[110:113], v[246:249], v[114:117]
	v_mfma_f32_16x16x32_bf16 v[114:117], v[166:169], v[246:249], v[106:109]
	v_mfma_f32_16x16x32_bf16 v[106:109], v[118:121], v[250:253], v[190:193]
	v_mfma_f32_16x16x32_bf16 v[118:121], v[166:169], v[134:137], v[106:109]
	v_mfma_f32_16x16x32_bf16 v[106:109], v[170:173], v[102:105], v[234:237]
	v_mfma_f32_16x16x32_bf16 v[110:113], v[170:173], v[250:253], v[194:197]
	v_mfma_f32_16x16x32_bf16 v[102:105], v[214:217], v[102:105], v[198:201]
	v_mfma_f32_16x16x32_bf16 v[0:3], v[214:217], v[250:253], v[0:3]
	v_mfma_f32_16x16x32_bf16 v[106:109], v[186:189], v[246:249], v[106:109]
	v_mfma_f32_16x16x32_bf16 v[110:113], v[186:189], v[134:137], v[110:113]
	v_mfma_f32_16x16x32_bf16 v[102:105], v[130:133], v[246:249], v[102:105]
	v_mfma_f32_16x16x32_bf16 v[0:3], v[130:133], v[134:137], v[0:3]
	s_setprio 0
	v_cmp_gt_u32_e32 vcc, s59, v32
	s_barrier
	s_and_saveexec_b64 s[4:5], vcc
	s_cbranch_execz .LBB0_1660
	s_barrier

; #define STAGE(P, BASE, br, kt) do { int _so = ((br) * K + (kt) * BK) * 2; \
;     __builtin_amdgcn_raw_ptr_buffer_load_lds(rs_##BASE, (__attribute__((address_space(3))) void*)((char*)(P) + tx * 16), 16, voff0, _so, 0, 0); \
;     __builtin_amdgcn_raw_ptr_buffer_load_lds(rs_##BASE, (__attribute__((address_space(3))) void*)((char*)(P) + tx * 16 + 8192), 16, voff1, _so, 0, 0); } while (0)
; #define LDA(dst, b, h) _Pragma("unroll") for (int m = 0; m < 4; ++m) _Pragma("unroll") for (int k = 0; k < 2; ++k) \
;     dst[m][k] = *reinterpret_cast<const bf16x8*>((char*)SA(b, h) + lds_byte(wr * 64 + m * 16 + fr, k * 32 + fq * 8))
; #define LDB(dst, b, h) _Pragma("unroll") for (int n = 0; n < 2; ++n) _Pragma("unroll") for (int k = 0; k < 2; ++k) \
;     dst[n][k] = *reinterpret_cast<const bf16x8*>((char*)SB(b, h) + lds_byte(wc * 32 + n * 16 + fr, k * 32 + fq * 8))
; #define MMA(ai, bj, At, Bt_) do { __builtin_amdgcn_s_setprio(1); \
;     _Pragma("unroll") for (int m = 0; m < 4; ++m) _Pragma("unroll") for (int n = 0; n < 2; ++n) _Pragma("unroll") for (int k = 0; k < 2; ++k) \
;       acc[ai][bj][m][n] = __builtin_amdgcn_mfma_f32_16x16x32_bf16(At[m][k], Bt_[n][k], acc[ai][bj][m][n], 0, 0, 0); \
;     __builtin_amdgcn_s_setprio(0); } while (0)
; #define WAIT_V(n) asm volatile("s_waitcnt vmcnt(" #n ")" ::: "memory")
; #define WAIT_L(n) asm volatile("s_waitcnt lgkmcnt(" #n ")" ::: "memory")
; #define BAR __builtin_amdgcn_s_barrier()
; #define SCHED __builtin_amdgcn_sched_barrier(0)
; template <class Epi> ...
;     ...
;     STAGE(SB(0, 0), Bt, bcol, 0); STAGE(SA(0, 0), A, brow, 0);
;     STAGE(SB(0, 1), Bt, bcol + HALF, 0); STAGE(SA(0, 1), A, brow + HALF, 0);
;   }
;   if (wr == 1) BAR;
;   if (pre) { WAIT_V(0); } else { WAIT_V(4); }
;   BAR;
;   STAGE(SB(1, 0), Bt, bcol, 1); STAGE(SA(1, 0), A, brow, 1); STAGE(SB(1, 1), Bt, bcol + HALF, 1);
;   WAIT_V(6); BAR;
;   for (int t = 0; t < nt - 2; t += 2) {
;     LDB(B0, 0, 0); SCHED; LDA(At, 0, 0); STAGE(SA(1, 1), A, brow + HALF, t + 1);
;     WAIT_L(8); BAR; WAIT_L(0); MMA(0, 0, At, B0); BAR; SCHED;
;     LDB(B1, 0, 1); STAGE(SB(0, 0), Bt, bcol, t + 2);
;     BAR; WAIT_L(0); MMA(0, 1, At, B1); BAR;
;     LDA(At, 0, 1); STAGE(SA(0, 0), A, brow, t + 2);
;     BAR; WAIT_L(0); MMA(1, 0, At, B0); BAR; SCHED;
;     STAGE(SB(0, 1), Bt, bcol + HALF, t + 2);
;     WAIT_V(6); BAR; MMA(1, 1, At, B1); BAR;
.Lpk3:
	ds_read_b128 v[156:159], v155
	ds_read_b128 v[166:169], v155 offset:1024
	ds_read_b128 v[170:173], v155 offset:2048
	ds_read_b128 v[186:189], v155 offset:3072
	s_add_i32 s29, s19, s28
	v_readfirstlane_b32 s31, v152
	s_add_i32 s30, s29, 0x40080
	s_mov_b32 m0, s31
	v_readfirstlane_b32 s31, v151
	ds_read_b128 v[190:193], v143
	ds_read_b128 v[194:197], v143 offset:1024
	ds_read_b128 v[198:201], v142
	ds_read_b128 v[202:205], v142 offset:1024
	ds_read_b128 v[206:209], v141
	ds_read_b128 v[210:213], v141 offset:1024
	ds_read_b128 v[214:217], v140
	ds_read_b128 v[218:221], v140 offset:1024
	buffer_load_dwordx4 v32, s[4:7], s30 offen lds
	s_mov_b32 m0, s31
	s_nop 0
	buffer_load_dwordx4 v130, s[4:7], s30 offen lds
	s_waitcnt lgkmcnt(8)
	s_barrier
	s_setprio 1
	s_waitcnt lgkmcnt(7)
	v_mfma_f32_16x16x32_bf16 v[126:129], v[190:193], v[156:159], 0
	v_mfma_f32_16x16x32_bf16 v[122:125], v[190:193], v[170:173], 0
	s_waitcnt lgkmcnt(5)
	v_mfma_f32_16x16x32_bf16 v[118:121], v[198:201], v[156:159], 0
	v_mfma_f32_16x16x32_bf16 v[114:117], v[198:201], v[170:173], 0
	s_waitcnt lgkmcnt(3)
	v_mfma_f32_16x16x32_bf16 v[110:113], v[206:209], v[156:159], 0
	v_mfma_f32_16x16x32_bf16 v[106:109], v[206:209], v[170:173], 0
	s_waitcnt lgkmcnt(1)
	v_mfma_f32_16x16x32_bf16 v[102:105], v[214:217], v[156:159], 0
	v_mfma_f32_16x16x32_bf16 v[98:101], v[214:217], v[170:173], 0
	v_mfma_f32_16x16x32_bf16 v[126:129], v[194:197], v[166:169], v[126:129]
	v_mfma_f32_16x16x32_bf16 v[122:125], v[194:197], v[186:189], v[122:125]
	v_mfma_f32_16x16x32_bf16 v[118:121], v[202:205], v[166:169], v[118:121]
	v_mfma_f32_16x16x32_bf16 v[114:117], v[202:205], v[186:189], v[114:117]
	v_mfma_f32_16x16x32_bf16 v[110:113], v[210:213], v[166:169], v[110:113]
	v_mfma_f32_16x16x32_bf16 v[106:109], v[210:213], v[186:189], v[106:109]
	s_waitcnt lgkmcnt(0)
	v_mfma_f32_16x16x32_bf16 v[102:105], v[218:221], v[166:169], v[102:105]
	v_mfma_f32_16x16x32_bf16 v[98:101], v[218:221], v[186:189], v[98:101]
	s_setprio 0
	s_barrier
	s_add_i32 s30, s18, s28
	v_readfirstlane_b32 s34, v137
	s_add_i32 s31, s30, 0x100
	s_mov_b32 m0, s34
	v_readfirstlane_b32 s34, v139
	ds_read_b128 v[222:225], v149
	ds_read_b128 v[226:229], v149 offset:1024
	ds_read_b128 v[230:233], v149 offset:2048
	ds_read_b128 v[234:237], v149 offset:3072
	buffer_load_dwordx4 v32, s[76:79], s31 offen lds
	s_mov_b32 m0, s34
	s_nop 0
	buffer_load_dwordx4 v130, s[76:79], s31 offen lds
	s_barrier
	s_setprio 1
	s_waitcnt lgkmcnt(3)
	v_mfma_f32_16x16x32_bf16 v[94:97], v[190:193], v[222:225], 0
	s_waitcnt lgkmcnt(1)
	v_mfma_f32_16x16x32_bf16 v[90:93], v[190:193], v[230:233], 0
	v_mfma_f32_16x16x32_bf16 v[86:89], v[198:201], v[222:225], 0
	v_mfma_f32_16x16x32_bf16 v[82:85], v[198:201], v[230:233], 0
	v_mfma_f32_16x16x32_bf16 v[78:81], v[206:209], v[222:225], 0
	v_mfma_f32_16x16x32_bf16 v[74:77], v[206:209], v[230:233], 0
	v_mfma_f32_16x16x32_bf16 v[70:73], v[214:217], v[222:225], 0
	v_mfma_f32_16x16x32_bf16 v[66:69], v[214:217], v[230:233], 0
	v_mfma_f32_16x16x32_bf16 v[94:97], v[194:197], v[226:229], v[94:97]
	s_waitcnt lgkmcnt(0)
	v_mfma_f32_16x16x32_bf16 v[90:93], v[194:197], v[234:237], v[90:93]
	v_mfma_f32_16x16x32_bf16 v[86:89], v[202:205], v[226:229], v[86:89]
	v_mfma_f32_16x16x32_bf16 v[82:85], v[202:205], v[234:237], v[82:85]
	v_mfma_f32_16x16x32_bf16 v[78:81], v[210:213], v[226:229], v[78:81]
	v_mfma_f32_16x16x32_bf16 v[74:77], v[210:213], v[234:237], v[74:77]
	v_mfma_f32_16x16x32_bf16 v[70:73], v[218:221], v[226:229], v[70:73]
	v_mfma_f32_16x16x32_bf16 v[66:69], v[218:221], v[234:237], v[66:69]
	s_setprio 0
	v_readfirstlane_b32 s34, v136
	s_add_i32 s31, s29, 0x100
	s_mov_b32 m0, s34
	v_readfirstlane_b32 s34, v135
	s_barrier
	ds_read_b128 v[190:193], v143 offset:16384
	ds_read_b128 v[194:197], v143 offset:17408
	ds_read_b128 v[198:201], v142 offset:16384
	ds_read_b128 v[202:205], v142 offset:17408
	ds_read_b128 v[206:209], v141 offset:16384
	ds_read_b128 v[210:213], v141 offset:17408
	ds_read_b128 v[214:217], v140 offset:16384
	ds_read_b128 v[218:221], v140 offset:17408
	buffer_load_dwordx4 v32, s[4:7], s31 offen lds
	s_mov_b32 m0, s34
	s_nop 0
	buffer_load_dwordx4 v130, s[4:7], s31 offen lds
	s_barrier
	s_setprio 1
	s_waitcnt lgkmcnt(7)
	v_mfma_f32_16x16x32_bf16 v[62:65], v[190:193], v[156:159], 0
	v_mfma_f32_16x16x32_bf16 v[58:61], v[190:193], v[170:173], 0
	s_waitcnt lgkmcnt(5)
	v_mfma_f32_16x16x32_bf16 v[54:57], v[198:201], v[156:159], 0
	v_mfma_f32_16x16x32_bf16 v[50:53], v[198:201], v[170:173], 0
	s_waitcnt lgkmcnt(3)
	v_mfma_f32_16x16x32_bf16 v[46:49], v[206:209], v[156:159], 0
	v_mfma_f32_16x16x32_bf16 v[42:45], v[206:209], v[170:173], 0
	s_waitcnt lgkmcnt(1)
	v_mfma_f32_16x16x32_bf16 v[38:41], v[214:217], v[156:159], 0
	v_mfma_f32_16x16x32_bf16 v[34:37], v[214:217], v[170:173], 0
	v_mfma_f32_16x16x32_bf16 v[62:65], v[194:197], v[166:169], v[62:65]
	v_mfma_f32_16x16x32_bf16 v[58:61], v[194:197], v[186:189], v[58:61]
	v_mfma_f32_16x16x32_bf16 v[54:57], v[202:205], v[166:169], v[54:57]
	v_mfma_f32_16x16x32_bf16 v[50:53], v[202:205], v[186:189], v[50:53]
	v_mfma_f32_16x16x32_bf16 v[46:49], v[210:213], v[166:169], v[46:49]
	v_mfma_f32_16x16x32_bf16 v[42:45], v[210:213], v[186:189], v[42:45]
	s_waitcnt lgkmcnt(0)
	v_mfma_f32_16x16x32_bf16 v[38:41], v[218:221], v[166:169], v[38:41]
	v_mfma_f32_16x16x32_bf16 v[34:37], v[218:221], v[186:189], v[34:37]
	s_setprio 0
	s_barrier
	v_readfirstlane_b32 s34, v134
	s_add_i32 s31, s30, 0x40100
	s_mov_b32 m0, s34
	v_readfirstlane_b32 s34, v138
	buffer_load_dwordx4 v32, s[76:79], s31 offen lds
	s_mov_b32 m0, s34
	s_nop 0
	buffer_load_dwordx4 v130, s[76:79], s31 offen lds
	s_waitcnt vmcnt(6)
	s_barrier
; #define STAGE(P, BASE, br, kt) do { int _so = ((br) * K + (kt) * BK) * 2; \
;     __builtin_amdgcn_raw_ptr_buffer_load_lds(rs_##BASE, (__attribute__((address_space(3))) void*)((char*)(P) + tx * 16), 16, voff0, _so, 0, 0); \
;     __builtin_amdgcn_raw_ptr_buffer_load_lds(rs_##BASE, (__attribute__((address_space(3))) void*)((char*)(P) + tx * 16 + 8192), 16, voff1, _so, 0, 0); } while (0)
; #define LDA(dst, b, h) _Pragma("unroll") for (int m = 0; m < 4; ++m) _Pragma("unroll") for (int k = 0; k < 2; ++k) \
;     dst[m][k] = *reinterpret_cast<const bf16x8*>((char*)SA(b, h) + lds_byte(wr * 64 + m * 16 + fr, k * 32 + fq * 8))
; #define LDB(dst, b, h) _Pragma("unroll") for (int n = 0; n < 2; ++n) _Pragma("unroll") for (int k = 0; k < 2; ++k) \
;     dst[n][k] = *reinterpret_cast<const bf16x8*>((char*)SB(b, h) + lds_byte(wc * 32 + n * 16 + fr, k * 32 + fq * 8))
; #define MMA(ai, bj, At, Bt_) do { __builtin_amdgcn_s_setprio(1); \
;     _Pragma("unroll") for (int m = 0; m < 4; ++m) _Pragma("unroll") for (int n = 0; n < 2; ++n) _Pragma("unroll") for (int k = 0; k < 2; ++k) \
;       acc[ai][bj][m][n] = __builtin_amdgcn_mfma_f32_16x16x32_bf16(At[m][k], Bt_[n][k], acc[ai][bj][m][n], 0, 0, 0); \
;     __builtin_amdgcn_s_setprio(0); } while (0)
; #define WAIT_V(n) asm volatile("s_waitcnt vmcnt(" #n ")" ::: "memory")
; #define WAIT_L(n) asm volatile("s_waitcnt lgkmcnt(" #n ")" ::: "memory")
; #define BAR __builtin_amdgcn_s_barrier()
; #define SCHED __builtin_amdgcn_sched_barrier(0)
; template <class Epi> ...
;     ...
;     WAIT_V(6); BAR; MMA(1, 1, At, B1); BAR;
;     LDB(B0, 1, 0); SCHED; LDA(At, 1, 0); STAGE(SA(0, 1), A, brow + HALF, t + 2);
;     WAIT_L(8); BAR; WAIT_L(0); MMA(0, 0, At, B0); BAR; SCHED;
;     LDB(B1, 1, 1); STAGE(SB(1, 0), Bt, bcol, t + 3);
;     BAR; WAIT_L(0); MMA(0, 1, At, B1); BAR;
;     LDA(At, 1, 1); STAGE(SA(1, 0), A, brow, t + 3);
;     BAR; WAIT_L(0); MMA(1, 0, At, B0); BAR; SCHED;
;     STAGE(SB(1, 1), Bt, bcol + HALF, t + 3);
;     WAIT_V(6); BAR; MMA(1, 1, At, B1); BAR;
	s_setprio 1
	v_mfma_f32_16x16x32_bf16 v[28:31], v[190:193], v[222:225], 0
	v_mfma_f32_16x16x32_bf16 v[24:27], v[190:193], v[230:233], 0
	v_mfma_f32_16x16x32_bf16 v[20:23], v[198:201], v[222:225], 0
	v_mfma_f32_16x16x32_bf16 v[16:19], v[198:201], v[230:233], 0
	v_mfma_f32_16x16x32_bf16 v[12:15], v[206:209], v[222:225], 0
	v_mfma_f32_16x16x32_bf16 v[8:11], v[206:209], v[230:233], 0
	v_mfma_f32_16x16x32_bf16 v[4:7], v[214:217], v[222:225], 0
	v_mfma_f32_16x16x32_bf16 v[0:3], v[214:217], v[230:233], 0
	v_mfma_f32_16x16x32_bf16 v[28:31], v[194:197], v[226:229], v[28:31]
	v_mfma_f32_16x16x32_bf16 v[24:27], v[194:197], v[234:237], v[24:27]
	v_mfma_f32_16x16x32_bf16 v[20:23], v[202:205], v[226:229], v[20:23]
	v_mfma_f32_16x16x32_bf16 v[16:19], v[202:205], v[234:237], v[16:19]
	v_mfma_f32_16x16x32_bf16 v[12:15], v[210:213], v[226:229], v[12:15]
	v_mfma_f32_16x16x32_bf16 v[8:11], v[210:213], v[234:237], v[8:11]
	v_mfma_f32_16x16x32_bf16 v[4:7], v[218:221], v[226:229], v[4:7]
	v_mfma_f32_16x16x32_bf16 v[0:3], v[218:221], v[234:237], v[0:3]
	s_setprio 0
	s_barrier
	ds_read_b128 v[156:159], v145
	ds_read_b128 v[166:169], v145 offset:1024
	ds_read_b128 v[170:173], v145 offset:2048
	ds_read_b128 v[186:189], v145 offset:3072
	v_readfirstlane_b32 s34, v132
	s_add_i32 s31, s29, 0x40100
	s_mov_b32 m0, s34
	v_readfirstlane_b32 s34, v131
	ds_read_b128 v[190:193], v143 offset:32768
	ds_read_b128 v[194:197], v143 offset:33792
	ds_read_b128 v[198:201], v142 offset:32768
	ds_read_b128 v[202:205], v142 offset:33792
	ds_read_b128 v[206:209], v141 offset:32768
	ds_read_b128 v[210:213], v141 offset:33792
	ds_read_b128 v[214:217], v140 offset:32768
	ds_read_b128 v[218:221], v140 offset:33792
	buffer_load_dwordx4 v32, s[4:7], s31 offen lds
	s_mov_b32 m0, s34
	s_nop 0
	buffer_load_dwordx4 v130, s[4:7], s31 offen lds
	s_waitcnt lgkmcnt(8)
	s_barrier
	s_setprio 1
	s_waitcnt lgkmcnt(7)
	v_mfma_f32_16x16x32_bf16 v[126:129], v[190:193], v[156:159], v[126:129]
	v_mfma_f32_16x16x32_bf16 v[122:125], v[190:193], v[170:173], v[122:125]
	s_waitcnt lgkmcnt(5)
	v_mfma_f32_16x16x32_bf16 v[118:121], v[198:201], v[156:159], v[118:121]
	v_mfma_f32_16x16x32_bf16 v[114:117], v[198:201], v[170:173], v[114:117]
	s_waitcnt lgkmcnt(3)
	v_mfma_f32_16x16x32_bf16 v[110:113], v[206:209], v[156:159], v[110:113]
	v_mfma_f32_16x16x32_bf16 v[106:109], v[206:209], v[170:173], v[106:109]
	s_waitcnt lgkmcnt(1)
	v_mfma_f32_16x16x32_bf16 v[102:105], v[214:217], v[156:159], v[102:105]
	v_mfma_f32_16x16x32_bf16 v[98:101], v[214:217], v[170:173], v[98:101]
	v_mfma_f32_16x16x32_bf16 v[126:129], v[194:197], v[166:169], v[126:129]
	v_mfma_f32_16x16x32_bf16 v[122:125], v[194:197], v[186:189], v[122:125]
	v_mfma_f32_16x16x32_bf16 v[118:121], v[202:205], v[166:169], v[118:121]
	v_mfma_f32_16x16x32_bf16 v[114:117], v[202:205], v[186:189], v[114:117]
	v_mfma_f32_16x16x32_bf16 v[110:113], v[210:213], v[166:169], v[110:113]
	v_mfma_f32_16x16x32_bf16 v[106:109], v[210:213], v[186:189], v[106:109]
	s_waitcnt lgkmcnt(0)
	v_mfma_f32_16x16x32_bf16 v[102:105], v[218:221], v[166:169], v[102:105]
	v_mfma_f32_16x16x32_bf16 v[98:101], v[218:221], v[186:189], v[98:101]
	s_setprio 0
	s_barrier
	v_readfirstlane_b32 s34, v146
	s_add_i32 s31, s30, 0x180
	s_mov_b32 m0, s34
	v_readfirstlane_b32 s34, v147
	ds_read_b128 v[222:225], v144
	ds_read_b128 v[226:229], v144 offset:1024
	ds_read_b128 v[230:233], v144 offset:2048
	ds_read_b128 v[234:237], v144 offset:3072
	buffer_load_dwordx4 v32, s[76:79], s31 offen lds
	s_mov_b32 m0, s34
	s_nop 0
	buffer_load_dwordx4 v130, s[76:79], s31 offen lds
	s_barrier
	s_setprio 1
	s_waitcnt lgkmcnt(3)
	v_mfma_f32_16x16x32_bf16 v[94:97], v[190:193], v[222:225], v[94:97]
	s_waitcnt lgkmcnt(1)
	v_mfma_f32_16x16x32_bf16 v[90:93], v[190:193], v[230:233], v[90:93]
	v_mfma_f32_16x16x32_bf16 v[86:89], v[198:201], v[222:225], v[86:89]
	v_mfma_f32_16x16x32_bf16 v[82:85], v[198:201], v[230:233], v[82:85]
	v_mfma_f32_16x16x32_bf16 v[78:81], v[206:209], v[222:225], v[78:81]
	v_mfma_f32_16x16x32_bf16 v[74:77], v[206:209], v[230:233], v[74:77]
	v_mfma_f32_16x16x32_bf16 v[70:73], v[214:217], v[222:225], v[70:73]
	v_mfma_f32_16x16x32_bf16 v[66:69], v[214:217], v[230:233], v[66:69]
	v_mfma_f32_16x16x32_bf16 v[94:97], v[194:197], v[226:229], v[94:97]
	s_waitcnt lgkmcnt(0)
	v_mfma_f32_16x16x32_bf16 v[90:93], v[194:197], v[234:237], v[90:93]
	v_mfma_f32_16x16x32_bf16 v[86:89], v[202:205], v[226:229], v[86:89]
	v_mfma_f32_16x16x32_bf16 v[82:85], v[202:205], v[234:237], v[82:85]
	v_mfma_f32_16x16x32_bf16 v[78:81], v[210:213], v[226:229], v[78:81]
	v_mfma_f32_16x16x32_bf16 v[74:77], v[210:213], v[234:237], v[74:77]
	v_mfma_f32_16x16x32_bf16 v[70:73], v[218:221], v[226:229], v[70:73]
	v_mfma_f32_16x16x32_bf16 v[66:69], v[218:221], v[234:237], v[66:69]
	s_setprio 0
	v_readfirstlane_b32 s31, v148
	s_addk_i32 s29, 0x180
	s_mov_b32 m0, s31
	v_readfirstlane_b32 s31, v150
	s_barrier
	ds_read_b128 v[190:193], v143 offset:49152
	ds_read_b128 v[194:197], v143 offset:50176
	ds_read_b128 v[198:201], v142 offset:49152
	ds_read_b128 v[202:205], v142 offset:50176
	ds_read_b128 v[206:209], v141 offset:49152
	ds_read_b128 v[210:213], v141 offset:50176
	ds_read_b128 v[214:217], v140 offset:49152
	ds_read_b128 v[218:221], v140 offset:50176
	buffer_load_dwordx4 v32, s[4:7], s29 offen lds
	s_mov_b32 m0, s31
	s_nop 0
	buffer_load_dwordx4 v130, s[4:7], s29 offen lds
	s_barrier
; #define STAGE(P, BASE, br, kt) do { int _so = ((br) * K + (kt) * BK) * 2; \
;     __builtin_amdgcn_raw_ptr_buffer_load_lds(rs_##BASE, (__attribute__((address_space(3))) void*)((char*)(P) + tx * 16), 16, voff0, _so, 0, 0); \
;     __builtin_amdgcn_raw_ptr_buffer_load_lds(rs_##BASE, (__attribute__((address_space(3))) void*)((char*)(P) + tx * 16 + 8192), 16, voff1, _so, 0, 0); } while (0)
; #define LDA(dst, b, h) _Pragma("unroll") for (int m = 0; m < 4; ++m) _Pragma("unroll") for (int k = 0; k < 2; ++k) \
;     dst[m][k] = *reinterpret_cast<const bf16x8*>((char*)SA(b, h) + lds_byte(wr * 64 + m * 16 + fr, k * 32 + fq * 8))
; #define LDB(dst, b, h) _Pragma("unroll") for (int n = 0; n < 2; ++n) _Pragma("unroll") for (int k = 0; k < 2; ++k) \
;     dst[n][k] = *reinterpret_cast<const bf16x8*>((char*)SB(b, h) + lds_byte(wc * 32 + n * 16 + fr, k * 32 + fq * 8))
; #define MMA(ai, bj, At, Bt_) do { __builtin_amdgcn_s_setprio(1); \
;     _Pragma("unroll") for (int m = 0; m < 4; ++m) _Pragma("unroll") for (int n = 0; n < 2; ++n) _Pragma("unroll") for (int k = 0; k < 2; ++k) \
;       acc[ai][bj][m][n] = __builtin_amdgcn_mfma_f32_16x16x32_bf16(At[m][k], Bt_[n][k], acc[ai][bj][m][n], 0, 0, 0); \
;     __builtin_amdgcn_s_setprio(0); } while (0)
; #define WAIT_V(n) asm volatile("s_waitcnt vmcnt(" #n ")" ::: "memory")
; #define WAIT_L(n) asm volatile("s_waitcnt lgkmcnt(" #n ")" ::: "memory")
; template <class Epi> ...
;     ...
;   for (int t = 0; t < nt - 2; t += 2) {
;     LDB(B0, 0, 0); SCHED; LDA(At, 0, 0); STAGE(SA(1, 1), A, brow + HALF, t + 1);
;     WAIT_L(8); BAR; WAIT_L(0); MMA(0, 0, At, B0); BAR; SCHED;
;     LDB(B1, 0, 1); STAGE(SB(0, 0), Bt, bcol, t + 2);
;     BAR; WAIT_L(0); MMA(0, 1, At, B1); BAR;
;     LDA(At, 0, 1); STAGE(SA(0, 0), A, brow, t + 2);
;     BAR; WAIT_L(0); MMA(1, 0, At, B0); BAR; SCHED;
;     STAGE(SB(0, 1), Bt, bcol + HALF, t + 2);
;     WAIT_V(6); BAR; MMA(1, 1, At, B1); BAR;
;     LDB(B0, 1, 0); SCHED; LDA(At, 1, 0); STAGE(SA(0, 1), A, brow + HALF, t + 2);
;     WAIT_L(8); BAR; WAIT_L(0); MMA(0, 0, At, B0); BAR; SCHED;
;     LDB(B1, 1, 1); STAGE(SB(1, 0), Bt, bcol, t + 3);
;     BAR; WAIT_L(0); MMA(0, 1, At, B1); BAR;
;     LDA(At, 1, 1); STAGE(SA(1, 0), A, brow, t + 3);
;     BAR; WAIT_L(0); MMA(1, 0, At, B0); BAR; SCHED;
;     STAGE(SB(1, 1), Bt, bcol + HALF, t + 3);
;     WAIT_V(6); BAR; MMA(1, 1, At, B1); BAR;
;   }
	s_setprio 1
	s_waitcnt lgkmcnt(7)
	v_mfma_f32_16x16x32_bf16 v[62:65], v[190:193], v[156:159], v[62:65]
	v_mfma_f32_16x16x32_bf16 v[58:61], v[190:193], v[170:173], v[58:61]
	s_waitcnt lgkmcnt(5)
	v_mfma_f32_16x16x32_bf16 v[54:57], v[198:201], v[156:159], v[54:57]
	v_mfma_f32_16x16x32_bf16 v[50:53], v[198:201], v[170:173], v[50:53]
	s_waitcnt lgkmcnt(3)
	v_mfma_f32_16x16x32_bf16 v[46:49], v[206:209], v[156:159], v[46:49]
	v_mfma_f32_16x16x32_bf16 v[42:45], v[206:209], v[170:173], v[42:45]
	s_waitcnt lgkmcnt(1)
	v_mfma_f32_16x16x32_bf16 v[38:41], v[214:217], v[156:159], v[38:41]
	v_mfma_f32_16x16x32_bf16 v[34:37], v[214:217], v[170:173], v[34:37]
	v_mfma_f32_16x16x32_bf16 v[62:65], v[194:197], v[166:169], v[62:65]
	v_mfma_f32_16x16x32_bf16 v[58:61], v[194:197], v[186:189], v[58:61]
	v_mfma_f32_16x16x32_bf16 v[54:57], v[202:205], v[166:169], v[54:57]
	v_mfma_f32_16x16x32_bf16 v[50:53], v[202:205], v[186:189], v[50:53]
	v_mfma_f32_16x16x32_bf16 v[46:49], v[210:213], v[166:169], v[46:49]
	v_mfma_f32_16x16x32_bf16 v[42:45], v[210:213], v[186:189], v[42:45]
	s_waitcnt lgkmcnt(0)
	v_mfma_f32_16x16x32_bf16 v[38:41], v[218:221], v[166:169], v[38:41]
	v_mfma_f32_16x16x32_bf16 v[34:37], v[218:221], v[186:189], v[34:37]
	s_setprio 0
	s_barrier
	v_readfirstlane_b32 s29, v153
	s_add_i32 s30, s30, 0x40180
	s_mov_b32 m0, s29
	v_readfirstlane_b32 s29, v154
	buffer_load_dwordx4 v32, s[76:79], s30 offen lds
	s_mov_b32 m0, s29
	s_nop 0
	buffer_load_dwordx4 v130, s[76:79], s30 offen lds
	s_waitcnt vmcnt(6)
	s_barrier
	s_setprio 1
	v_mfma_f32_16x16x32_bf16 v[28:31], v[190:193], v[222:225], v[28:31]
	v_mfma_f32_16x16x32_bf16 v[24:27], v[190:193], v[230:233], v[24:27]
	v_mfma_f32_16x16x32_bf16 v[20:23], v[198:201], v[222:225], v[20:23]
	v_mfma_f32_16x16x32_bf16 v[16:19], v[198:201], v[230:233], v[16:19]
	v_mfma_f32_16x16x32_bf16 v[12:15], v[206:209], v[222:225], v[12:15]
	v_mfma_f32_16x16x32_bf16 v[8:11], v[206:209], v[230:233], v[8:11]
	v_mfma_f32_16x16x32_bf16 v[4:7], v[214:217], v[222:225], v[4:7]
	v_mfma_f32_16x16x32_bf16 v[0:3], v[214:217], v[230:233], v[0:3]
	v_mfma_f32_16x16x32_bf16 v[28:31], v[194:197], v[226:229], v[28:31]
	v_mfma_f32_16x16x32_bf16 v[24:27], v[194:197], v[234:237], v[24:27]
	v_mfma_f32_16x16x32_bf16 v[20:23], v[202:205], v[226:229], v[20:23]
	v_mfma_f32_16x16x32_bf16 v[16:19], v[202:205], v[234:237], v[16:19]
	v_mfma_f32_16x16x32_bf16 v[12:15], v[210:213], v[226:229], v[12:15]
	v_mfma_f32_16x16x32_bf16 v[8:11], v[210:213], v[234:237], v[8:11]
	v_mfma_f32_16x16x32_bf16 v[4:7], v[218:221], v[226:229], v[4:7]
	v_mfma_f32_16x16x32_bf16 v[0:3], v[218:221], v[234:237], v[0:3]
	s_setprio 0
	s_add_i32 s27, s27, 2
	s_addk_i32 s28, 0x100
	s_cmp_lt_u32 s27, 12
	s_barrier
	s_cbranch_scc1 .LBB0_1682
	s_branch .Lpx3
.LBB0_1682:
	ds_read_b128 v[156:159], v155
	ds_read_b128 v[166:169], v155 offset:1024
	ds_read_b128 v[170:173], v155 offset:2048
	ds_read_b128 v[186:189], v155 offset:3072
	s_add_i32 s29, s19, s28
	v_readfirstlane_b32 s31, v152
	s_add_i32 s30, s29, 0x40080
	s_mov_b32 m0, s31
	v_readfirstlane_b32 s31, v151
	ds_read_b128 v[190:193], v143
	ds_read_b128 v[194:197], v143 offset:1024
	ds_read_b128 v[198:201], v142
	ds_read_b128 v[202:205], v142 offset:1024
	ds_read_b128 v[206:209], v141
	ds_read_b128 v[210:213], v141 offset:1024
	ds_read_b128 v[214:217], v140
	ds_read_b128 v[218:221], v140 offset:1024
	buffer_load_dwordx4 v32, s[4:7], s30 offen lds
	s_mov_b32 m0, s31
	s_nop 0
	buffer_load_dwordx4 v130, s[4:7], s30 offen lds
	s_waitcnt lgkmcnt(8)
	s_barrier
	s_setprio 1
	s_waitcnt lgkmcnt(7)
	v_mfma_f32_16x16x32_bf16 v[126:129], v[190:193], v[156:159], v[126:129]
	v_mfma_f32_16x16x32_bf16 v[122:125], v[190:193], v[170:173], v[122:125]
	s_waitcnt lgkmcnt(5)
	v_mfma_f32_16x16x32_bf16 v[118:121], v[198:201], v[156:159], v[118:121]
	v_mfma_f32_16x16x32_bf16 v[114:117], v[198:201], v[170:173], v[114:117]
	s_waitcnt lgkmcnt(3)
	v_mfma_f32_16x16x32_bf16 v[110:113], v[206:209], v[156:159], v[110:113]
	v_mfma_f32_16x16x32_bf16 v[106:109], v[206:209], v[170:173], v[106:109]
	s_waitcnt lgkmcnt(1)
	v_mfma_f32_16x16x32_bf16 v[102:105], v[214:217], v[156:159], v[102:105]
	v_mfma_f32_16x16x32_bf16 v[98:101], v[214:217], v[170:173], v[98:101]
	v_mfma_f32_16x16x32_bf16 v[126:129], v[194:197], v[166:169], v[126:129]
	v_mfma_f32_16x16x32_bf16 v[122:125], v[194:197], v[186:189], v[122:125]
	v_mfma_f32_16x16x32_bf16 v[118:121], v[202:205], v[166:169], v[118:121]
	v_mfma_f32_16x16x32_bf16 v[114:117], v[202:205], v[186:189], v[114:117]
	v_mfma_f32_16x16x32_bf16 v[110:113], v[210:213], v[166:169], v[110:113]
	v_mfma_f32_16x16x32_bf16 v[106:109], v[210:213], v[186:189], v[106:109]
	s_waitcnt lgkmcnt(0)
	v_mfma_f32_16x16x32_bf16 v[102:105], v[218:221], v[166:169], v[102:105]
	v_mfma_f32_16x16x32_bf16 v[98:101], v[218:221], v[186:189], v[98:101]
	s_setprio 0
	s_barrier
	s_add_i32 s30, s18, s28
	v_readfirstlane_b32 s34, v137
	s_add_i32 s31, s30, 0x100
	s_mov_b32 m0, s34
	v_readfirstlane_b32 s34, v139
	ds_read_b128 v[222:225], v149
	ds_read_b128 v[226:229], v149 offset:1024
	ds_read_b128 v[230:233], v149 offset:2048
	ds_read_b128 v[234:237], v149 offset:3072
	buffer_load_dwordx4 v32, s[76:79], s31 offen lds
	s_mov_b32 m0, s34
	s_nop 0
	buffer_load_dwordx4 v130, s[76:79], s31 offen lds
	s_barrier
; #define STAGE(P, BASE, br, kt) do { int _so = ((br) * K + (kt) * BK) * 2; \
;     __builtin_amdgcn_raw_ptr_buffer_load_lds(rs_##BASE, (__attribute__((address_space(3))) void*)((char*)(P) + tx * 16), 16, voff0, _so, 0, 0); \
;     __builtin_amdgcn_raw_ptr_buffer_load_lds(rs_##BASE, (__attribute__((address_space(3))) void*)((char*)(P) + tx * 16 + 8192), 16, voff1, _so, 0, 0); } while (0)
; #define LDA(dst, b, h) _Pragma("unroll") for (int m = 0; m < 4; ++m) _Pragma("unroll") for (int k = 0; k < 2; ++k) \
;     dst[m][k] = *reinterpret_cast<const bf16x8*>((char*)SA(b, h) + lds_byte(wr * 64 + m * 16 + fr, k * 32 + fq * 8))
; #define LDB(dst, b, h) _Pragma("unroll") for (int n = 0; n < 2; ++n) _Pragma("unroll") for (int k = 0; k < 2; ++k) \
;     dst[n][k] = *reinterpret_cast<const bf16x8*>((char*)SB(b, h) + lds_byte(wc * 32 + n * 16 + fr, k * 32 + fq * 8))
; #define MMA(ai, bj, At, Bt_) do { __builtin_amdgcn_s_setprio(1); \
;     _Pragma("unroll") for (int m = 0; m < 4; ++m) _Pragma("unroll") for (int n = 0; n < 2; ++n) _Pragma("unroll") for (int k = 0; k < 2; ++k) \
;       acc[ai][bj][m][n] = __builtin_amdgcn_mfma_f32_16x16x32_bf16(At[m][k], Bt_[n][k], acc[ai][bj][m][n], 0, 0, 0); \
;     __builtin_amdgcn_s_setprio(0); } while (0)
; #define WAIT_V(n) asm volatile("s_waitcnt vmcnt(" #n ")" ::: "memory")
; #define WAIT_L(n) asm volatile("s_waitcnt lgkmcnt(" #n ")" ::: "memory")
; template <class Epi> ...
;     ...
;   for (int t = 0; t < nt - 2; t += 2) {
;     LDB(B0, 0, 0); SCHED; LDA(At, 0, 0); STAGE(SA(1, 1), A, brow + HALF, t + 1);
;     WAIT_L(8); BAR; WAIT_L(0); MMA(0, 0, At, B0); BAR; SCHED;
;     LDB(B1, 0, 1); STAGE(SB(0, 0), Bt, bcol, t + 2);
;     BAR; WAIT_L(0); MMA(0, 1, At, B1); BAR;
;     LDA(At, 0, 1); STAGE(SA(0, 0), A, brow, t + 2);
;     BAR; WAIT_L(0); MMA(1, 0, At, B0); BAR; SCHED;
;     STAGE(SB(0, 1), Bt, bcol + HALF, t + 2);
;     WAIT_V(6); BAR; MMA(1, 1, At, B1); BAR;
;     LDB(B0, 1, 0); SCHED; LDA(At, 1, 0); STAGE(SA(0, 1), A, brow + HALF, t + 2);
;     WAIT_L(8); BAR; WAIT_L(0); MMA(0, 0, At, B0); BAR; SCHED;
;     LDB(B1, 1, 1); STAGE(SB(1, 0), Bt, bcol, t + 3);
;     BAR; WAIT_L(0); MMA(0, 1, At, B1); BAR;
;     LDA(At, 1, 1); STAGE(SA(1, 0), A, brow, t + 3);
;     BAR; WAIT_L(0); MMA(1, 0, At, B0); BAR; SCHED;
;     STAGE(SB(1, 1), Bt, bcol + HALF, t + 3);
;     WAIT_V(6); BAR; MMA(1, 1, At, B1); BAR;
;   }
	s_setprio 1
	s_waitcnt lgkmcnt(3)
	v_mfma_f32_16x16x32_bf16 v[94:97], v[190:193], v[222:225], v[94:97]
	s_waitcnt lgkmcnt(1)
	v_mfma_f32_16x16x32_bf16 v[90:93], v[190:193], v[230:233], v[90:93]
	v_mfma_f32_16x16x32_bf16 v[86:89], v[198:201], v[222:225], v[86:89]
	v_mfma_f32_16x16x32_bf16 v[82:85], v[198:201], v[230:233], v[82:85]
	v_mfma_f32_16x16x32_bf16 v[78:81], v[206:209], v[222:225], v[78:81]
	v_mfma_f32_16x16x32_bf16 v[74:77], v[206:209], v[230:233], v[74:77]
	v_mfma_f32_16x16x32_bf16 v[70:73], v[214:217], v[222:225], v[70:73]
	v_mfma_f32_16x16x32_bf16 v[66:69], v[214:217], v[230:233], v[66:69]
	v_mfma_f32_16x16x32_bf16 v[94:97], v[194:197], v[226:229], v[94:97]
	s_waitcnt lgkmcnt(0)
	v_mfma_f32_16x16x32_bf16 v[90:93], v[194:197], v[234:237], v[90:93]
	v_mfma_f32_16x16x32_bf16 v[86:89], v[202:205], v[226:229], v[86:89]
	v_mfma_f32_16x16x32_bf16 v[82:85], v[202:205], v[234:237], v[82:85]
	v_mfma_f32_16x16x32_bf16 v[78:81], v[210:213], v[226:229], v[78:81]
	v_mfma_f32_16x16x32_bf16 v[74:77], v[210:213], v[234:237], v[74:77]
	v_mfma_f32_16x16x32_bf16 v[70:73], v[218:221], v[226:229], v[70:73]
	v_mfma_f32_16x16x32_bf16 v[66:69], v[218:221], v[234:237], v[66:69]
	s_setprio 0
	v_readfirstlane_b32 s34, v136
	s_add_i32 s31, s29, 0x100
	s_mov_b32 m0, s34
	v_readfirstlane_b32 s34, v135
	s_barrier
	ds_read_b128 v[190:193], v143 offset:16384
	ds_read_b128 v[194:197], v143 offset:17408
	ds_read_b128 v[198:201], v142 offset:16384
	ds_read_b128 v[202:205], v142 offset:17408
	ds_read_b128 v[206:209], v141 offset:16384
	ds_read_b128 v[210:213], v141 offset:17408
	ds_read_b128 v[214:217], v140 offset:16384
	ds_read_b128 v[218:221], v140 offset:17408
	buffer_load_dwordx4 v32, s[4:7], s31 offen lds
	s_mov_b32 m0, s34
	s_nop 0
	buffer_load_dwordx4 v130, s[4:7], s31 offen lds
	s_barrier
	s_setprio 1
	s_waitcnt lgkmcnt(7)
	v_mfma_f32_16x16x32_bf16 v[62:65], v[190:193], v[156:159], v[62:65]
	v_mfma_f32_16x16x32_bf16 v[58:61], v[190:193], v[170:173], v[58:61]
	s_waitcnt lgkmcnt(5)
	v_mfma_f32_16x16x32_bf16 v[54:57], v[198:201], v[156:159], v[54:57]
	v_mfma_f32_16x16x32_bf16 v[50:53], v[198:201], v[170:173], v[50:53]
	s_waitcnt lgkmcnt(3)
	v_mfma_f32_16x16x32_bf16 v[46:49], v[206:209], v[156:159], v[46:49]
	v_mfma_f32_16x16x32_bf16 v[42:45], v[206:209], v[170:173], v[42:45]
	s_waitcnt lgkmcnt(1)
	v_mfma_f32_16x16x32_bf16 v[38:41], v[214:217], v[156:159], v[38:41]
	v_mfma_f32_16x16x32_bf16 v[34:37], v[214:217], v[170:173], v[34:37]
	v_mfma_f32_16x16x32_bf16 v[62:65], v[194:197], v[166:169], v[62:65]
	v_mfma_f32_16x16x32_bf16 v[58:61], v[194:197], v[186:189], v[58:61]
	v_mfma_f32_16x16x32_bf16 v[54:57], v[202:205], v[166:169], v[54:57]
	v_mfma_f32_16x16x32_bf16 v[50:53], v[202:205], v[186:189], v[50:53]
	v_mfma_f32_16x16x32_bf16 v[46:49], v[210:213], v[166:169], v[46:49]
	v_mfma_f32_16x16x32_bf16 v[42:45], v[210:213], v[186:189], v[42:45]
	s_waitcnt lgkmcnt(0)
	v_mfma_f32_16x16x32_bf16 v[38:41], v[218:221], v[166:169], v[38:41]
	v_mfma_f32_16x16x32_bf16 v[34:37], v[218:221], v[186:189], v[34:37]
	s_setprio 0
	s_barrier
	v_readfirstlane_b32 s34, v134
	s_add_i32 s31, s30, 0x40100
	s_mov_b32 m0, s34
	v_readfirstlane_b32 s34, v138
	buffer_load_dwordx4 v32, s[76:79], s31 offen lds
	s_mov_b32 m0, s34
	s_nop 0
	buffer_load_dwordx4 v130, s[76:79], s31 offen lds
	s_waitcnt vmcnt(6)
	s_barrier
	s_setprio 1
	v_mfma_f32_16x16x32_bf16 v[28:31], v[190:193], v[222:225], v[28:31]
	v_mfma_f32_16x16x32_bf16 v[24:27], v[190:193], v[230:233], v[24:27]
	v_mfma_f32_16x16x32_bf16 v[20:23], v[198:201], v[222:225], v[20:23]
	v_mfma_f32_16x16x32_bf16 v[16:19], v[198:201], v[230:233], v[16:19]
	v_mfma_f32_16x16x32_bf16 v[12:15], v[206:209], v[222:225], v[12:15]
	v_mfma_f32_16x16x32_bf16 v[8:11], v[206:209], v[230:233], v[8:11]
	v_mfma_f32_16x16x32_bf16 v[4:7], v[214:217], v[222:225], v[4:7]
	v_mfma_f32_16x16x32_bf16 v[0:3], v[214:217], v[230:233], v[0:3]
	v_mfma_f32_16x16x32_bf16 v[28:31], v[194:197], v[226:229], v[28:31]
	v_mfma_f32_16x16x32_bf16 v[24:27], v[194:197], v[234:237], v[24:27]
	v_mfma_f32_16x16x32_bf16 v[20:23], v[202:205], v[226:229], v[20:23]
	v_mfma_f32_16x16x32_bf16 v[16:19], v[202:205], v[234:237], v[16:19]
	v_mfma_f32_16x16x32_bf16 v[12:15], v[210:213], v[226:229], v[12:15]
	v_mfma_f32_16x16x32_bf16 v[8:11], v[210:213], v[234:237], v[8:11]
	v_mfma_f32_16x16x32_bf16 v[4:7], v[218:221], v[226:229], v[4:7]
	v_mfma_f32_16x16x32_bf16 v[0:3], v[218:221], v[234:237], v[0:3]
	s_setprio 0
	s_barrier
	ds_read_b128 v[156:159], v145
	ds_read_b128 v[166:169], v145 offset:1024
	ds_read_b128 v[170:173], v145 offset:2048
	ds_read_b128 v[186:189], v145 offset:3072
	v_readfirstlane_b32 s34, v132
	s_add_i32 s31, s29, 0x40100
	s_mov_b32 m0, s34
	v_readfirstlane_b32 s34, v131
	ds_read_b128 v[190:193], v143 offset:32768
	ds_read_b128 v[194:197], v143 offset:33792
	ds_read_b128 v[198:201], v142 offset:32768
	ds_read_b128 v[202:205], v142 offset:33792
	ds_read_b128 v[206:209], v141 offset:32768
	ds_read_b128 v[210:213], v141 offset:33792
	ds_read_b128 v[214:217], v140 offset:32768
	ds_read_b128 v[218:221], v140 offset:33792
	buffer_load_dwordx4 v32, s[4:7], s31 offen lds
	s_mov_b32 m0, s34
	s_nop 0
	buffer_load_dwordx4 v130, s[4:7], s31 offen lds
	s_waitcnt lgkmcnt(8)
	s_barrier
; #define STAGE(P, BASE, br, kt) do { int _so = ((br) * K + (kt) * BK) * 2; \
;     __builtin_amdgcn_raw_ptr_buffer_load_lds(rs_##BASE, (__attribute__((address_space(3))) void*)((char*)(P) + tx * 16), 16, voff0, _so, 0, 0); \
;     __builtin_amdgcn_raw_ptr_buffer_load_lds(rs_##BASE, (__attribute__((address_space(3))) void*)((char*)(P) + tx * 16 + 8192), 16, voff1, _so, 0, 0); } while (0)
; #define LDA(dst, b, h) _Pragma("unroll") for (int m = 0; m < 4; ++m) _Pragma("unroll") for (int k = 0; k < 2; ++k) \
;     dst[m][k] = *reinterpret_cast<const bf16x8*>((char*)SA(b, h) + lds_byte(wr * 64 + m * 16 + fr, k * 32 + fq * 8))
; #define LDB(dst, b, h) _Pragma("unroll") for (int n = 0; n < 2; ++n) _Pragma("unroll") for (int k = 0; k < 2; ++k) \
;     dst[n][k] = *reinterpret_cast<const bf16x8*>((char*)SB(b, h) + lds_byte(wc * 32 + n * 16 + fr, k * 32 + fq * 8))
; #define MMA(ai, bj, At, Bt_) do { __builtin_amdgcn_s_setprio(1); \
;     _Pragma("unroll") for (int m = 0; m < 4; ++m) _Pragma("unroll") for (int n = 0; n < 2; ++n) _Pragma("unroll") for (int k = 0; k < 2; ++k) \
;       acc[ai][bj][m][n] = __builtin_amdgcn_mfma_f32_16x16x32_bf16(At[m][k], Bt_[n][k], acc[ai][bj][m][n], 0, 0, 0); \
;     __builtin_amdgcn_s_setprio(0); } while (0)
; #define WAIT_V(n) asm volatile("s_waitcnt vmcnt(" #n ")" ::: "memory")
; #define WAIT_L(n) asm volatile("s_waitcnt lgkmcnt(" #n ")" ::: "memory")
; #define BAR __builtin_amdgcn_s_barrier()
; #define SCHED __builtin_amdgcn_sched_barrier(0)
; template <class Epi> ...
;     ...
;     LDB(B0, 1, 0); SCHED; LDA(At, 1, 0); STAGE(SA(0, 1), A, brow + HALF, t + 2);
;     WAIT_L(8); BAR; WAIT_L(0); MMA(0, 0, At, B0); BAR; SCHED;
;     LDB(B1, 1, 1); STAGE(SB(1, 0), Bt, bcol, t + 3);
;     BAR; WAIT_L(0); MMA(0, 1, At, B1); BAR;
;     LDA(At, 1, 1); STAGE(SA(1, 0), A, brow, t + 3);
;     BAR; WAIT_L(0); MMA(1, 0, At, B0); BAR; SCHED;
;     STAGE(SB(1, 1), Bt, bcol + HALF, t + 3);
;     WAIT_V(6); BAR; MMA(1, 1, At, B1); BAR;
;   }
	s_setprio 1
	s_waitcnt lgkmcnt(7)
	v_mfma_f32_16x16x32_bf16 v[126:129], v[190:193], v[156:159], v[126:129]
	v_mfma_f32_16x16x32_bf16 v[122:125], v[190:193], v[170:173], v[122:125]
	s_waitcnt lgkmcnt(5)
	v_mfma_f32_16x16x32_bf16 v[118:121], v[198:201], v[156:159], v[118:121]
	v_mfma_f32_16x16x32_bf16 v[114:117], v[198:201], v[170:173], v[114:117]
	s_waitcnt lgkmcnt(3)
	v_mfma_f32_16x16x32_bf16 v[110:113], v[206:209], v[156:159], v[110:113]
	v_mfma_f32_16x16x32_bf16 v[106:109], v[206:209], v[170:173], v[106:109]
	s_waitcnt lgkmcnt(1)
	v_mfma_f32_16x16x32_bf16 v[102:105], v[214:217], v[156:159], v[102:105]
	v_mfma_f32_16x16x32_bf16 v[98:101], v[214:217], v[170:173], v[98:101]
	v_mfma_f32_16x16x32_bf16 v[126:129], v[194:197], v[166:169], v[126:129]
	v_mfma_f32_16x16x32_bf16 v[122:125], v[194:197], v[186:189], v[122:125]
	v_mfma_f32_16x16x32_bf16 v[118:121], v[202:205], v[166:169], v[118:121]
	v_mfma_f32_16x16x32_bf16 v[114:117], v[202:205], v[186:189], v[114:117]
	v_mfma_f32_16x16x32_bf16 v[110:113], v[210:213], v[166:169], v[110:113]
	v_mfma_f32_16x16x32_bf16 v[106:109], v[210:213], v[186:189], v[106:109]
	s_waitcnt lgkmcnt(0)
	v_mfma_f32_16x16x32_bf16 v[102:105], v[218:221], v[166:169], v[102:105]
	v_mfma_f32_16x16x32_bf16 v[98:101], v[218:221], v[186:189], v[98:101]
	s_setprio 0
	s_barrier
	v_readfirstlane_b32 s34, v146
	s_add_i32 s31, s30, 0x180
	s_mov_b32 m0, s34
	v_readfirstlane_b32 s34, v147
	ds_read_b128 v[222:225], v144
	ds_read_b128 v[226:229], v144 offset:1024
	ds_read_b128 v[230:233], v144 offset:2048
	ds_read_b128 v[234:237], v144 offset:3072
	buffer_load_dwordx4 v32, s[76:79], s31 offen lds
	s_mov_b32 m0, s34
	s_nop 0
	buffer_load_dwordx4 v130, s[76:79], s31 offen lds
	s_barrier
	s_setprio 1
	s_waitcnt lgkmcnt(3)
	v_mfma_f32_16x16x32_bf16 v[94:97], v[190:193], v[222:225], v[94:97]
	s_waitcnt lgkmcnt(1)
	v_mfma_f32_16x16x32_bf16 v[90:93], v[190:193], v[230:233], v[90:93]
	v_mfma_f32_16x16x32_bf16 v[86:89], v[198:201], v[222:225], v[86:89]
	v_mfma_f32_16x16x32_bf16 v[82:85], v[198:201], v[230:233], v[82:85]
	v_mfma_f32_16x16x32_bf16 v[78:81], v[206:209], v[222:225], v[78:81]
	v_mfma_f32_16x16x32_bf16 v[74:77], v[206:209], v[230:233], v[74:77]
	v_mfma_f32_16x16x32_bf16 v[70:73], v[214:217], v[222:225], v[70:73]
	v_mfma_f32_16x16x32_bf16 v[66:69], v[214:217], v[230:233], v[66:69]
	v_mfma_f32_16x16x32_bf16 v[94:97], v[194:197], v[226:229], v[94:97]
	s_waitcnt lgkmcnt(0)
	v_mfma_f32_16x16x32_bf16 v[90:93], v[194:197], v[234:237], v[90:93]
	v_mfma_f32_16x16x32_bf16 v[86:89], v[202:205], v[226:229], v[86:89]
	v_mfma_f32_16x16x32_bf16 v[82:85], v[202:205], v[234:237], v[82:85]
	v_mfma_f32_16x16x32_bf16 v[78:81], v[210:213], v[226:229], v[78:81]
	v_mfma_f32_16x16x32_bf16 v[74:77], v[210:213], v[234:237], v[74:77]
	v_mfma_f32_16x16x32_bf16 v[70:73], v[218:221], v[226:229], v[70:73]
	v_mfma_f32_16x16x32_bf16 v[66:69], v[218:221], v[234:237], v[66:69]
	s_setprio 0
	v_readfirstlane_b32 s31, v148
	s_addk_i32 s29, 0x180
	s_mov_b32 m0, s31
	v_readfirstlane_b32 s31, v150
	s_barrier
	ds_read_b128 v[190:193], v143 offset:49152
	ds_read_b128 v[194:197], v143 offset:50176
	ds_read_b128 v[198:201], v142 offset:49152
	ds_read_b128 v[202:205], v142 offset:50176
	ds_read_b128 v[206:209], v141 offset:49152
	ds_read_b128 v[210:213], v141 offset:50176
	ds_read_b128 v[214:217], v140 offset:49152
	ds_read_b128 v[218:221], v140 offset:50176
	buffer_load_dwordx4 v32, s[4:7], s29 offen lds
	s_mov_b32 m0, s31
	s_nop 0
	buffer_load_dwordx4 v130, s[4:7], s29 offen lds
	s_barrier
	s_setprio 1
	s_waitcnt lgkmcnt(7)
	v_mfma_f32_16x16x32_bf16 v[62:65], v[190:193], v[156:159], v[62:65]
	v_mfma_f32_16x16x32_bf16 v[58:61], v[190:193], v[170:173], v[58:61]
	s_waitcnt lgkmcnt(5)
	v_mfma_f32_16x16x32_bf16 v[54:57], v[198:201], v[156:159], v[54:57]
	v_mfma_f32_16x16x32_bf16 v[50:53], v[198:201], v[170:173], v[50:53]
	s_waitcnt lgkmcnt(3)
	v_mfma_f32_16x16x32_bf16 v[46:49], v[206:209], v[156:159], v[46:49]
	v_mfma_f32_16x16x32_bf16 v[42:45], v[206:209], v[170:173], v[42:45]
	s_waitcnt lgkmcnt(1)
	v_mfma_f32_16x16x32_bf16 v[38:41], v[214:217], v[156:159], v[38:41]
	v_mfma_f32_16x16x32_bf16 v[34:37], v[214:217], v[170:173], v[34:37]
	v_mfma_f32_16x16x32_bf16 v[62:65], v[194:197], v[166:169], v[62:65]
	v_mfma_f32_16x16x32_bf16 v[58:61], v[194:197], v[186:189], v[58:61]
	v_mfma_f32_16x16x32_bf16 v[54:57], v[202:205], v[166:169], v[54:57]
	v_mfma_f32_16x16x32_bf16 v[50:53], v[202:205], v[186:189], v[50:53]
	v_mfma_f32_16x16x32_bf16 v[46:49], v[210:213], v[166:169], v[46:49]
	v_mfma_f32_16x16x32_bf16 v[42:45], v[210:213], v[186:189], v[42:45]
	s_waitcnt lgkmcnt(0)
	v_mfma_f32_16x16x32_bf16 v[38:41], v[218:221], v[166:169], v[38:41]
	v_mfma_f32_16x16x32_bf16 v[34:37], v[218:221], v[186:189], v[34:37]
	s_setprio 0
	s_barrier
	v_readfirstlane_b32 s29, v153
	s_add_i32 s30, s30, 0x40180
	s_mov_b32 m0, s29
	v_readfirstlane_b32 s29, v154
	buffer_load_dwordx4 v32, s[76:79], s30 offen lds
	s_mov_b32 m0, s29
	s_nop 0
	buffer_load_dwordx4 v130, s[76:79], s30 offen lds
	s_waitcnt vmcnt(6)
	s_barrier
	s_setprio 1
	v_mfma_f32_16x16x32_bf16 v[28:31], v[190:193], v[222:225], v[28:31]
	v_mfma_f32_16x16x32_bf16 v[24:27], v[190:193], v[230:233], v[24:27]
	v_mfma_f32_16x16x32_bf16 v[20:23], v[198:201], v[222:225], v[20:23]
	v_mfma_f32_16x16x32_bf16 v[16:19], v[198:201], v[230:233], v[16:19]
	v_mfma_f32_16x16x32_bf16 v[12:15], v[206:209], v[222:225], v[12:15]
	v_mfma_f32_16x16x32_bf16 v[8:11], v[206:209], v[230:233], v[8:11]
	v_mfma_f32_16x16x32_bf16 v[4:7], v[214:217], v[222:225], v[4:7]
	v_mfma_f32_16x16x32_bf16 v[0:3], v[214:217], v[230:233], v[0:3]
	v_mfma_f32_16x16x32_bf16 v[28:31], v[194:197], v[226:229], v[28:31]
	v_mfma_f32_16x16x32_bf16 v[24:27], v[194:197], v[234:237], v[24:27]
	v_mfma_f32_16x16x32_bf16 v[20:23], v[202:205], v[226:229], v[20:23]
	v_mfma_f32_16x16x32_bf16 v[16:19], v[202:205], v[234:237], v[16:19]
	v_mfma_f32_16x16x32_bf16 v[12:15], v[210:213], v[226:229], v[12:15]
	v_mfma_f32_16x16x32_bf16 v[8:11], v[210:213], v[234:237], v[8:11]
	v_mfma_f32_16x16x32_bf16 v[4:7], v[218:221], v[226:229], v[4:7]
	v_mfma_f32_16x16x32_bf16 v[0:3], v[218:221], v[234:237], v[0:3]
	s_setprio 0
	s_add_i32 s27, s27, 2
	s_addk_i32 s28, 0x100
	s_cmp_lt_u32 s27, 12
	s_barrier
	s_cbranch_scc1 .LBB0_1682
; #define STAGE(P, BASE, br, kt) do { int _so = ((br) * K + (kt) * BK) * 2; \
;     __builtin_amdgcn_raw_ptr_buffer_load_lds(rs_##BASE, (__attribute__((address_space(3))) void*)((char*)(P) + tx * 16), 16, voff0, _so, 0, 0); \
;     __builtin_amdgcn_raw_ptr_buffer_load_lds(rs_##BASE, (__attribute__((address_space(3))) void*)((char*)(P) + tx * 16 + 8192), 16, voff1, _so, 0, 0); } while (0)
; #define LDA(dst, b, h) _Pragma("unroll") for (int m = 0; m < 4; ++m) _Pragma("unroll") for (int k = 0; k < 2; ++k) \
;     dst[m][k] = *reinterpret_cast<const bf16x8*>((char*)SA(b, h) + lds_byte(wr * 64 + m * 16 + fr, k * 32 + fq * 8))
; #define LDB(dst, b, h) _Pragma("unroll") for (int n = 0; n < 2; ++n) _Pragma("unroll") for (int k = 0; k < 2; ++k) \
;     dst[n][k] = *reinterpret_cast<const bf16x8*>((char*)SB(b, h) + lds_byte(wc * 32 + n * 16 + fr, k * 32 + fq * 8))
; #define MMA(ai, bj, At, Bt_) do { __builtin_amdgcn_s_setprio(1); \
;     _Pragma("unroll") for (int m = 0; m < 4; ++m) _Pragma("unroll") for (int n = 0; n < 2; ++n) _Pragma("unroll") for (int k = 0; k < 2; ++k) \
;       acc[ai][bj][m][n] = __builtin_amdgcn_mfma_f32_16x16x32_bf16(At[m][k], Bt_[n][k], acc[ai][bj][m][n], 0, 0, 0); \
;     __builtin_amdgcn_s_setprio(0); } while (0)
; #define WAIT_V(n) asm volatile("s_waitcnt vmcnt(" #n ")" ::: "memory")
; #define WAIT_L(n) asm volatile("s_waitcnt lgkmcnt(" #n ")" ::: "memory")
; #define BAR __builtin_amdgcn_s_barrier()
; template <class Epi> ...
;     ...
;   { LDB(B0, 0, 0); LDA(At, 0, 0); STAGE(SA(1, 1), A, brow + HALF, nt - 1);
;     BAR; WAIT_L(0); MMA(0, 0, At, B0); BAR;
;     LDB(B1, 0, 1); BAR; WAIT_L(0); MMA(0, 1, At, B1); BAR;
;     LDA(At, 0, 1); WAIT_V(4); BAR; WAIT_L(0); MMA(1, 0, At, B0); MMA(1, 1, At, B1); BAR; }
;   { LDB(B0, 1, 0); LDA(At, 1, 0); WAIT_V(2); BAR; WAIT_L(0); MMA(0, 0, At, B0); BAR;
.Lpx3:
	v_readfirstlane_b32 s18, v152
	s_add_i32 s19, s19, 0x40780
	s_mov_b32 s6, s78
	s_mov_b32 s7, s79
	s_mov_b32 m0, s18
	v_readfirstlane_b32 s18, v151
	ds_read_b128 v[156:159], v155
	ds_read_b128 v[166:169], v155 offset:1024
	ds_read_b128 v[170:173], v155 offset:2048
	ds_read_b128 v[186:189], v155 offset:3072
	ds_read_b128 v[190:193], v143
	ds_read_b128 v[194:197], v143 offset:1024
	ds_read_b128 v[198:201], v142
	ds_read_b128 v[202:205], v142 offset:1024
	ds_read_b128 v[206:209], v141
	ds_read_b128 v[210:213], v141 offset:1024
	ds_read_b128 v[214:217], v140
	ds_read_b128 v[218:221], v140 offset:1024
	buffer_load_dwordx4 v32, s[4:7], s19 offen lds
	s_mov_b32 m0, s18
	s_nop 0
	buffer_load_dwordx4 v130, s[4:7], s19 offen lds
	s_barrier
	s_setprio 1
	s_waitcnt lgkmcnt(7)
	v_mfma_f32_16x16x32_bf16 v[126:129], v[190:193], v[156:159], v[126:129]
	v_mfma_f32_16x16x32_bf16 v[122:125], v[190:193], v[170:173], v[122:125]
	s_waitcnt lgkmcnt(5)
	v_mfma_f32_16x16x32_bf16 v[118:121], v[198:201], v[156:159], v[118:121]
	v_mfma_f32_16x16x32_bf16 v[114:117], v[198:201], v[170:173], v[114:117]
	s_waitcnt lgkmcnt(3)
	v_mfma_f32_16x16x32_bf16 v[110:113], v[206:209], v[156:159], v[110:113]
	v_mfma_f32_16x16x32_bf16 v[126:129], v[194:197], v[166:169], v[126:129]
	v_mfma_f32_16x16x32_bf16 v[122:125], v[194:197], v[186:189], v[122:125]
	v_mfma_f32_16x16x32_bf16 v[118:121], v[202:205], v[166:169], v[118:121]
	v_mfma_f32_16x16x32_bf16 v[114:117], v[202:205], v[186:189], v[114:117]
	s_waitcnt lgkmcnt(2)
	v_mfma_f32_16x16x32_bf16 v[110:113], v[210:213], v[166:169], v[110:113]
	v_mfma_f32_16x16x32_bf16 v[106:109], v[206:209], v[170:173], v[106:109]
	s_waitcnt lgkmcnt(1)
	v_mfma_f32_16x16x32_bf16 v[102:105], v[214:217], v[156:159], v[102:105]
	v_mfma_f32_16x16x32_bf16 v[98:101], v[214:217], v[170:173], v[98:101]
	v_mfma_f32_16x16x32_bf16 v[150:153], v[210:213], v[186:189], v[106:109]
	s_waitcnt lgkmcnt(0)
	v_mfma_f32_16x16x32_bf16 v[222:225], v[218:221], v[166:169], v[102:105]
	v_mfma_f32_16x16x32_bf16 v[226:229], v[218:221], v[186:189], v[98:101]
	s_setprio 0
	s_barrier
	s_nop 1
	ds_read_b128 v[98:101], v149
	ds_read_b128 v[102:105], v149 offset:1024
	ds_read_b128 v[106:109], v149 offset:2048
	ds_read_b128 v[146:149], v149 offset:3072
	s_barrier
	s_setprio 1
	s_waitcnt lgkmcnt(3)
	v_mfma_f32_16x16x32_bf16 v[94:97], v[190:193], v[98:101], v[94:97]
	s_waitcnt lgkmcnt(1)
	v_mfma_f32_16x16x32_bf16 v[90:93], v[190:193], v[106:109], v[90:93]
	v_mfma_f32_16x16x32_bf16 v[86:89], v[198:201], v[98:101], v[86:89]
	v_mfma_f32_16x16x32_bf16 v[82:85], v[198:201], v[106:109], v[82:85]
	v_mfma_f32_16x16x32_bf16 v[94:97], v[194:197], v[102:105], v[94:97]
	s_waitcnt lgkmcnt(0)
	v_mfma_f32_16x16x32_bf16 v[90:93], v[194:197], v[146:149], v[90:93]
	v_mfma_f32_16x16x32_bf16 v[86:89], v[202:205], v[102:105], v[86:89]
	v_mfma_f32_16x16x32_bf16 v[82:85], v[202:205], v[146:149], v[82:85]
	v_mfma_f32_16x16x32_bf16 v[78:81], v[206:209], v[98:101], v[78:81]
	v_mfma_f32_16x16x32_bf16 v[74:77], v[206:209], v[106:109], v[74:77]
	v_mfma_f32_16x16x32_bf16 v[70:73], v[214:217], v[98:101], v[70:73]
	v_mfma_f32_16x16x32_bf16 v[66:69], v[214:217], v[106:109], v[66:69]
	v_mfma_f32_16x16x32_bf16 v[190:193], v[210:213], v[102:105], v[78:81]
	v_mfma_f32_16x16x32_bf16 v[194:197], v[210:213], v[146:149], v[74:77]
	v_mfma_f32_16x16x32_bf16 v[198:201], v[218:221], v[102:105], v[70:73]
	v_mfma_f32_16x16x32_bf16 v[202:205], v[218:221], v[146:149], v[66:69]
	s_setprio 0
	s_barrier
	s_nop 1
	ds_read_b128 v[66:69], v143 offset:16384
	ds_read_b128 v[70:73], v143 offset:17408
	ds_read_b128 v[74:77], v142 offset:16384
	ds_read_b128 v[78:81], v142 offset:17408
	ds_read_b128 v[206:209], v141 offset:16384
	ds_read_b128 v[210:213], v141 offset:17408
	ds_read_b128 v[214:217], v140 offset:16384
	ds_read_b128 v[218:221], v140 offset:17408
	s_waitcnt vmcnt(4)
	s_barrier
	s_setprio 1
	s_waitcnt lgkmcnt(7)
	v_mfma_f32_16x16x32_bf16 v[62:65], v[66:69], v[156:159], v[62:65]
	v_mfma_f32_16x16x32_bf16 v[58:61], v[66:69], v[170:173], v[58:61]
	s_waitcnt lgkmcnt(5)
	v_mfma_f32_16x16x32_bf16 v[54:57], v[74:77], v[156:159], v[54:57]
	v_mfma_f32_16x16x32_bf16 v[50:53], v[74:77], v[170:173], v[50:53]
	v_mfma_f32_16x16x32_bf16 v[62:65], v[70:73], v[166:169], v[62:65]
	v_mfma_f32_16x16x32_bf16 v[58:61], v[70:73], v[186:189], v[58:61]
	s_waitcnt lgkmcnt(4)
	v_mfma_f32_16x16x32_bf16 v[54:57], v[78:81], v[166:169], v[54:57]
	v_mfma_f32_16x16x32_bf16 v[50:53], v[78:81], v[186:189], v[50:53]
	s_waitcnt lgkmcnt(3)
	v_mfma_f32_16x16x32_bf16 v[46:49], v[206:209], v[156:159], v[46:49]
	v_mfma_f32_16x16x32_bf16 v[42:45], v[206:209], v[170:173], v[42:45]
	s_waitcnt lgkmcnt(1)
	v_mfma_f32_16x16x32_bf16 v[38:41], v[214:217], v[156:159], v[38:41]
	v_mfma_f32_16x16x32_bf16 v[34:37], v[214:217], v[170:173], v[34:37]
	v_mfma_f32_16x16x32_bf16 v[230:233], v[210:213], v[166:169], v[46:49]
	v_mfma_f32_16x16x32_bf16 v[234:237], v[210:213], v[186:189], v[42:45]
	s_waitcnt lgkmcnt(0)
	v_mfma_f32_16x16x32_bf16 v[154:157], v[218:221], v[166:169], v[38:41]
	v_mfma_f32_16x16x32_bf16 v[158:161], v[218:221], v[186:189], v[34:37]
	s_setprio 0
	s_setprio 1
	v_mfma_f32_16x16x32_bf16 v[28:31], v[66:69], v[98:101], v[28:31]
	v_mfma_f32_16x16x32_bf16 v[24:27], v[66:69], v[106:109], v[24:27]
	v_mfma_f32_16x16x32_bf16 v[20:23], v[74:77], v[98:101], v[20:23]
	v_mfma_f32_16x16x32_bf16 v[12:15], v[206:209], v[98:101], v[12:15]
	v_mfma_f32_16x16x32_bf16 v[28:31], v[70:73], v[102:105], v[28:31]
	v_mfma_f32_16x16x32_bf16 v[24:27], v[70:73], v[146:149], v[24:27]
	v_mfma_f32_16x16x32_bf16 v[20:23], v[78:81], v[102:105], v[20:23]
	v_mfma_f32_16x16x32_bf16 v[16:19], v[74:77], v[106:109], v[16:19]
	v_mfma_f32_16x16x32_bf16 v[12:15], v[210:213], v[102:105], v[12:15]
	v_mfma_f32_16x16x32_bf16 v[8:11], v[206:209], v[106:109], v[8:11]
	v_mfma_f32_16x16x32_bf16 v[4:7], v[214:217], v[98:101], v[4:7]
	v_mfma_f32_16x16x32_bf16 v[0:3], v[214:217], v[106:109], v[0:3]
	v_mfma_f32_16x16x32_bf16 v[166:169], v[78:81], v[146:149], v[16:19]
	v_mfma_f32_16x16x32_bf16 v[170:173], v[210:213], v[146:149], v[8:11]
	v_mfma_f32_16x16x32_bf16 v[186:189], v[218:221], v[102:105], v[4:7]
	v_mfma_f32_16x16x32_bf16 v[146:149], v[218:221], v[146:149], v[0:3]
	s_setprio 0
	s_barrier
; #define LDA(dst, b, h) _Pragma("unroll") for (int m = 0; m < 4; ++m) _Pragma("unroll") for (int k = 0; k < 2; ++k) \
;     dst[m][k] = *reinterpret_cast<const bf16x8*>((char*)SA(b, h) + lds_byte(wr * 64 + m * 16 + fr, k * 32 + fq * 8))
; #define LDB(dst, b, h) _Pragma("unroll") for (int n = 0; n < 2; ++n) _Pragma("unroll") for (int k = 0; k < 2; ++k) \
;     dst[n][k] = *reinterpret_cast<const bf16x8*>((char*)SB(b, h) + lds_byte(wc * 32 + n * 16 + fr, k * 32 + fq * 8))
; #define MMA(ai, bj, At, Bt_) do { __builtin_amdgcn_s_setprio(1); \
;     _Pragma("unroll") for (int m = 0; m < 4; ++m) _Pragma("unroll") for (int n = 0; n < 2; ++n) _Pragma("unroll") for (int k = 0; k < 2; ++k) \
;       acc[ai][bj][m][n] = __builtin_amdgcn_mfma_f32_16x16x32_bf16(At[m][k], Bt_[n][k], acc[ai][bj][m][n], 0, 0, 0); \
;     __builtin_amdgcn_s_setprio(0); } while (0)
; #define WAIT_V(n) asm volatile("s_waitcnt vmcnt(" #n ")" ::: "memory")
; #define WAIT_L(n) asm volatile("s_waitcnt lgkmcnt(" #n ")" ::: "memory")
; #define BAR __builtin_amdgcn_s_barrier()
; template <class Epi> ...
;     ...
;   { LDB(B0, 1, 0); LDA(At, 1, 0); WAIT_V(2); BAR; WAIT_L(0); MMA(0, 0, At, B0); BAR;
;     LDB(B1, 1, 1); WAIT_V(0); BAR; WAIT_L(0); MMA(0, 1, At, B1); BAR;
;     LDA(At, 1, 1); BAR; WAIT_L(0); MMA(1, 0, At, B0); MMA(1, 1, At, B1); BAR; }
;   if (wr == 0) BAR;
	ds_read_b128 v[206:209], v145
	ds_read_b128 v[210:213], v145 offset:1024
	ds_read_b128 v[214:217], v145 offset:2048
	ds_read_b128 v[218:221], v145 offset:3072
	ds_read_b128 v[0:3], v143 offset:32768
	ds_read_b128 v[4:7], v143 offset:33792
	ds_read_b128 v[8:11], v142 offset:32768
	ds_read_b128 v[42:45], v142 offset:33792
	ds_read_b128 v[46:49], v141 offset:32768
	ds_read_b128 v[238:241], v141 offset:33792
	ds_read_b128 v[242:245], v140 offset:32768
	ds_read_b128 v[246:249], v140 offset:33792
	s_waitcnt vmcnt(2)
	s_barrier
	s_setprio 1
	s_waitcnt lgkmcnt(7)
	v_mfma_f32_16x16x32_bf16 v[16:19], v[0:3], v[206:209], v[126:129]
	s_waitcnt lgkmcnt(6)
	v_mfma_f32_16x16x32_bf16 v[98:101], v[4:7], v[210:213], v[16:19]
	v_mfma_f32_16x16x32_bf16 v[16:19], v[0:3], v[214:217], v[122:125]
	v_mfma_f32_16x16x32_bf16 v[66:69], v[4:7], v[218:221], v[16:19]
	s_waitcnt lgkmcnt(5)
	v_mfma_f32_16x16x32_bf16 v[16:19], v[8:11], v[206:209], v[118:121]
	s_waitcnt lgkmcnt(4)
	v_mfma_f32_16x16x32_bf16 v[102:105], v[42:45], v[210:213], v[16:19]
	v_mfma_f32_16x16x32_bf16 v[16:19], v[8:11], v[214:217], v[114:117]
	v_mfma_f32_16x16x32_bf16 v[70:73], v[42:45], v[218:221], v[16:19]
	s_waitcnt lgkmcnt(3)
	v_mfma_f32_16x16x32_bf16 v[16:19], v[46:49], v[206:209], v[110:113]
	s_waitcnt lgkmcnt(2)
	v_mfma_f32_16x16x32_bf16 v[106:109], v[238:241], v[210:213], v[16:19]
	v_mfma_f32_16x16x32_bf16 v[16:19], v[46:49], v[214:217], v[150:153]
	v_mfma_f32_16x16x32_bf16 v[74:77], v[238:241], v[218:221], v[16:19]
	s_waitcnt lgkmcnt(1)
	v_mfma_f32_16x16x32_bf16 v[16:19], v[242:245], v[206:209], v[222:225]
	s_waitcnt lgkmcnt(0)
	v_mfma_f32_16x16x32_bf16 v[110:113], v[246:249], v[210:213], v[16:19]
	v_mfma_f32_16x16x32_bf16 v[16:19], v[242:245], v[214:217], v[226:229]
	v_mfma_f32_16x16x32_bf16 v[78:81], v[246:249], v[218:221], v[16:19]
	s_setprio 0
	s_barrier
	ds_read_b128 v[150:153], v144
	ds_read_b128 v[222:225], v144 offset:1024
	ds_read_b128 v[226:229], v144 offset:2048
	ds_read_b128 v[250:253], v144 offset:3072
	s_waitcnt vmcnt(0)
	s_barrier
	s_setprio 1
	s_waitcnt lgkmcnt(3)
	v_mfma_f32_16x16x32_bf16 v[16:19], v[0:3], v[150:153], v[94:97]
	s_waitcnt lgkmcnt(1)
	v_mfma_f32_16x16x32_bf16 v[0:3], v[0:3], v[226:229], v[90:93]
	v_mfma_f32_16x16x32_bf16 v[34:37], v[4:7], v[222:225], v[16:19]
	s_waitcnt lgkmcnt(0)
	v_mfma_f32_16x16x32_bf16 v[16:19], v[4:7], v[250:253], v[0:3]
	v_mfma_f32_16x16x32_bf16 v[0:3], v[8:11], v[150:153], v[86:89]
	v_mfma_f32_16x16x32_bf16 v[38:41], v[42:45], v[222:225], v[0:3]
	v_mfma_f32_16x16x32_bf16 v[0:3], v[8:11], v[226:229], v[82:85]
	v_mfma_f32_16x16x32_bf16 v[8:11], v[42:45], v[250:253], v[0:3]
	v_mfma_f32_16x16x32_bf16 v[0:3], v[46:49], v[150:153], v[190:193]
	v_mfma_f32_16x16x32_bf16 v[42:45], v[238:241], v[222:225], v[0:3]
	v_mfma_f32_16x16x32_bf16 v[0:3], v[46:49], v[226:229], v[194:197]
	v_mfma_f32_16x16x32_bf16 v[4:7], v[238:241], v[250:253], v[0:3]
	v_mfma_f32_16x16x32_bf16 v[0:3], v[242:245], v[150:153], v[198:201]
	v_mfma_f32_16x16x32_bf16 v[46:49], v[246:249], v[222:225], v[0:3]
	v_mfma_f32_16x16x32_bf16 v[0:3], v[242:245], v[226:229], v[202:205]
	v_mfma_f32_16x16x32_bf16 v[0:3], v[246:249], v[250:253], v[0:3]
	s_setprio 0
	s_barrier
	ds_read_b128 v[190:193], v143 offset:49152
	ds_read_b128 v[194:197], v143 offset:50176
	ds_read_b128 v[198:201], v142 offset:49152
	ds_read_b128 v[142:145], v142 offset:50176
	ds_read_b128 v[202:205], v141 offset:49152
	ds_read_b128 v[238:241], v141 offset:50176
	ds_read_b128 v[242:245], v140 offset:49152
	ds_read_b128 v[246:249], v140 offset:50176
	s_barrier
	s_setprio 1
	s_waitcnt lgkmcnt(5)
	v_mfma_f32_16x16x32_bf16 v[50:53], v[198:201], v[214:217], v[50:53]
	s_waitcnt lgkmcnt(4)
	v_mfma_f32_16x16x32_bf16 v[86:89], v[142:145], v[218:221], v[50:53]
	s_waitcnt lgkmcnt(3)
	v_mfma_f32_16x16x32_bf16 v[50:53], v[202:205], v[206:209], v[230:233]
	s_waitcnt lgkmcnt(2)
	v_mfma_f32_16x16x32_bf16 v[122:125], v[238:241], v[210:213], v[50:53]
	v_mfma_f32_16x16x32_bf16 v[50:53], v[202:205], v[214:217], v[234:237]
	v_mfma_f32_16x16x32_bf16 v[90:93], v[238:241], v[218:221], v[50:53]
	s_waitcnt lgkmcnt(1)
	v_mfma_f32_16x16x32_bf16 v[50:53], v[242:245], v[206:209], v[154:157]
	v_mfma_f32_16x16x32_bf16 v[62:65], v[190:193], v[206:209], v[62:65]
	v_mfma_f32_16x16x32_bf16 v[58:61], v[190:193], v[214:217], v[58:61]
	v_mfma_f32_16x16x32_bf16 v[54:57], v[198:201], v[206:209], v[54:57]
	s_waitcnt lgkmcnt(0)
	v_mfma_f32_16x16x32_bf16 v[126:129], v[246:249], v[210:213], v[50:53]
	v_mfma_f32_16x16x32_bf16 v[50:53], v[242:245], v[214:217], v[158:161]
	v_mfma_f32_16x16x32_bf16 v[114:117], v[194:197], v[210:213], v[62:65]
	v_mfma_f32_16x16x32_bf16 v[82:85], v[194:197], v[218:221], v[58:61]
	v_mfma_f32_16x16x32_bf16 v[118:121], v[142:145], v[210:213], v[54:57]
	v_mfma_f32_16x16x32_bf16 v[94:97], v[246:249], v[218:221], v[50:53]
	s_setprio 0
	s_setprio 1
	v_mfma_f32_16x16x32_bf16 v[20:23], v[198:201], v[150:153], v[20:23]
	v_mfma_f32_16x16x32_bf16 v[12:15], v[202:205], v[150:153], v[12:15]
	v_mfma_f32_16x16x32_bf16 v[28:31], v[190:193], v[150:153], v[28:31]
	v_mfma_f32_16x16x32_bf16 v[24:27], v[190:193], v[226:229], v[24:27]
	v_mfma_f32_16x16x32_bf16 v[54:57], v[142:145], v[222:225], v[20:23]
	v_mfma_f32_16x16x32_bf16 v[20:23], v[198:201], v[226:229], v[166:169]
	v_mfma_f32_16x16x32_bf16 v[58:61], v[238:241], v[222:225], v[12:15]
	v_mfma_f32_16x16x32_bf16 v[12:15], v[202:205], v[226:229], v[170:173]
	v_mfma_f32_16x16x32_bf16 v[50:53], v[194:197], v[222:225], v[28:31]
	v_mfma_f32_16x16x32_bf16 v[28:31], v[194:197], v[250:253], v[24:27]
	v_mfma_f32_16x16x32_bf16 v[24:27], v[142:145], v[250:253], v[20:23]
	v_mfma_f32_16x16x32_bf16 v[20:23], v[238:241], v[250:253], v[12:15]
	v_mfma_f32_16x16x32_bf16 v[12:15], v[242:245], v[150:153], v[186:189]
	v_mfma_f32_16x16x32_bf16 v[62:65], v[246:249], v[222:225], v[12:15]
	v_mfma_f32_16x16x32_bf16 v[12:15], v[242:245], v[226:229], v[146:149]
	v_mfma_f32_16x16x32_bf16 v[12:15], v[246:249], v[250:253], v[12:15]
	s_setprio 0
	v_cmp_gt_u32_e32 vcc, s59, v133
	s_barrier
	s_and_saveexec_b64 s[4:5], vcc
	s_cbranch_execz .LBB0_1685
	s_barrier

; #define STAGE(P, BASE, br, kt) do { int _so = ((br) * K + (kt) * BK) * 2; \
;     __builtin_amdgcn_raw_ptr_buffer_load_lds(rs_##BASE, (__attribute__((address_space(3))) void*)((char*)(P) + tx * 16), 16, voff0, _so, 0, 0); \
;     __builtin_amdgcn_raw_ptr_buffer_load_lds(rs_##BASE, (__attribute__((address_space(3))) void*)((char*)(P) + tx * 16 + 8192), 16, voff1, _so, 0, 0); } while (0)
; #define LDA(dst, b, h) _Pragma("unroll") for (int m = 0; m < 4; ++m) _Pragma("unroll") for (int k = 0; k < 2; ++k) \
;     dst[m][k] = *reinterpret_cast<const bf16x8*>((char*)SA(b, h) + lds_byte(wr * 64 + m * 16 + fr, k * 32 + fq * 8))
; #define LDB(dst, b, h) _Pragma("unroll") for (int n = 0; n < 2; ++n) _Pragma("unroll") for (int k = 0; k < 2; ++k) \
;     dst[n][k] = *reinterpret_cast<const bf16x8*>((char*)SB(b, h) + lds_byte(wc * 32 + n * 16 + fr, k * 32 + fq * 8))
; #define MMA(ai, bj, At, Bt_) do { __builtin_amdgcn_s_setprio(1); \
;     _Pragma("unroll") for (int m = 0; m < 4; ++m) _Pragma("unroll") for (int n = 0; n < 2; ++n) _Pragma("unroll") for (int k = 0; k < 2; ++k) \
;       acc[ai][bj][m][n] = __builtin_amdgcn_mfma_f32_16x16x32_bf16(At[m][k], Bt_[n][k], acc[ai][bj][m][n], 0, 0, 0); \
;     __builtin_amdgcn_s_setprio(0); } while (0)
; #define WAIT_V(n) asm volatile("s_waitcnt vmcnt(" #n ")" ::: "memory")
; #define WAIT_L(n) asm volatile("s_waitcnt lgkmcnt(" #n ")" ::: "memory")
; #define BAR __builtin_amdgcn_s_barrier()
; #define SCHED __builtin_amdgcn_sched_barrier(0)
; template <class Epi> ...
;     ...
;   for (int t = 0; t < nt - 2; t += 2) {
;     LDB(B0, 0, 0); SCHED; LDA(At, 0, 0); STAGE(SA(1, 1), A, brow + HALF, t + 1);
;     WAIT_L(8); BAR; WAIT_L(0); MMA(0, 0, At, B0); BAR; SCHED;
;     LDB(B1, 0, 1); STAGE(SB(0, 0), Bt, bcol, t + 2);
;     BAR; WAIT_L(0); MMA(0, 1, At, B1); BAR;
;     LDA(At, 0, 1); STAGE(SA(0, 0), A, brow, t + 2);
;     BAR; WAIT_L(0); MMA(1, 0, At, B0); BAR; SCHED;
;     STAGE(SB(0, 1), Bt, bcol + HALF, t + 2);
;     WAIT_V(6); BAR; MMA(1, 1, At, B1); BAR;
.Lpk4:
	ds_read_b128 v[156:159], v155
	ds_read_b128 v[166:169], v155 offset:1024
	ds_read_b128 v[170:173], v155 offset:2048
	ds_read_b128 v[174:177], v155 offset:3072
	s_add_i32 s25, s17, s24
	v_readfirstlane_b32 s27, v152
	s_add_i32 s26, s25, 0x40080
	s_mov_b32 m0, s27
	v_readfirstlane_b32 s27, v151
	ds_read_b128 v[186:189], v143
	ds_read_b128 v[190:193], v143 offset:1024
	ds_read_b128 v[194:197], v142
	ds_read_b128 v[198:201], v142 offset:1024
	ds_read_b128 v[202:205], v141
	ds_read_b128 v[206:209], v141 offset:1024
	ds_read_b128 v[210:213], v140
	ds_read_b128 v[214:217], v140 offset:1024
	buffer_load_dwordx4 v32, s[8:11], s26 offen lds
	s_mov_b32 m0, s27
	s_nop 0
	buffer_load_dwordx4 v131, s[8:11], s26 offen lds
	s_waitcnt lgkmcnt(8)
	s_barrier
	s_setprio 1
	s_waitcnt lgkmcnt(7)
	v_mfma_f32_16x16x32_bf16 v[126:129], v[186:189], v[156:159], 0
	v_mfma_f32_16x16x32_bf16 v[122:125], v[186:189], v[170:173], 0
	s_waitcnt lgkmcnt(5)
	v_mfma_f32_16x16x32_bf16 v[118:121], v[194:197], v[156:159], 0
	v_mfma_f32_16x16x32_bf16 v[114:117], v[194:197], v[170:173], 0
	s_waitcnt lgkmcnt(3)
	v_mfma_f32_16x16x32_bf16 v[110:113], v[202:205], v[156:159], 0
	v_mfma_f32_16x16x32_bf16 v[106:109], v[202:205], v[170:173], 0
	s_waitcnt lgkmcnt(1)
	v_mfma_f32_16x16x32_bf16 v[102:105], v[210:213], v[156:159], 0
	v_mfma_f32_16x16x32_bf16 v[98:101], v[210:213], v[170:173], 0
	v_mfma_f32_16x16x32_bf16 v[126:129], v[190:193], v[166:169], v[126:129]
	v_mfma_f32_16x16x32_bf16 v[122:125], v[190:193], v[174:177], v[122:125]
	v_mfma_f32_16x16x32_bf16 v[118:121], v[198:201], v[166:169], v[118:121]
	v_mfma_f32_16x16x32_bf16 v[114:117], v[198:201], v[174:177], v[114:117]
	v_mfma_f32_16x16x32_bf16 v[110:113], v[206:209], v[166:169], v[110:113]
	v_mfma_f32_16x16x32_bf16 v[106:109], v[206:209], v[174:177], v[106:109]
	s_waitcnt lgkmcnt(0)
	v_mfma_f32_16x16x32_bf16 v[102:105], v[214:217], v[166:169], v[102:105]
	v_mfma_f32_16x16x32_bf16 v[98:101], v[214:217], v[174:177], v[98:101]
	s_setprio 0
	s_barrier
	s_add_i32 s26, s16, s24
	v_readfirstlane_b32 s28, v137
	s_add_i32 s27, s26, 0x100
	s_mov_b32 m0, s28
	v_readfirstlane_b32 s28, v139
	ds_read_b128 v[218:221], v149
	ds_read_b128 v[222:225], v149 offset:1024
	ds_read_b128 v[226:229], v149 offset:2048
	ds_read_b128 v[230:233], v149 offset:3072
	buffer_load_dwordx4 v32, s[76:79], s27 offen lds
	s_mov_b32 m0, s28
	s_nop 0
	buffer_load_dwordx4 v131, s[76:79], s27 offen lds
	s_barrier
	s_setprio 1
	s_waitcnt lgkmcnt(3)
	v_mfma_f32_16x16x32_bf16 v[94:97], v[186:189], v[218:221], 0
	s_waitcnt lgkmcnt(1)
	v_mfma_f32_16x16x32_bf16 v[90:93], v[186:189], v[226:229], 0
	v_mfma_f32_16x16x32_bf16 v[86:89], v[194:197], v[218:221], 0
	v_mfma_f32_16x16x32_bf16 v[82:85], v[194:197], v[226:229], 0
	v_mfma_f32_16x16x32_bf16 v[78:81], v[202:205], v[218:221], 0
	v_mfma_f32_16x16x32_bf16 v[74:77], v[202:205], v[226:229], 0
	v_mfma_f32_16x16x32_bf16 v[70:73], v[210:213], v[218:221], 0
	v_mfma_f32_16x16x32_bf16 v[66:69], v[210:213], v[226:229], 0
	v_mfma_f32_16x16x32_bf16 v[94:97], v[190:193], v[222:225], v[94:97]
	s_waitcnt lgkmcnt(0)
	v_mfma_f32_16x16x32_bf16 v[90:93], v[190:193], v[230:233], v[90:93]
	v_mfma_f32_16x16x32_bf16 v[86:89], v[198:201], v[222:225], v[86:89]
	v_mfma_f32_16x16x32_bf16 v[82:85], v[198:201], v[230:233], v[82:85]
	v_mfma_f32_16x16x32_bf16 v[78:81], v[206:209], v[222:225], v[78:81]
	v_mfma_f32_16x16x32_bf16 v[74:77], v[206:209], v[230:233], v[74:77]
	v_mfma_f32_16x16x32_bf16 v[70:73], v[214:217], v[222:225], v[70:73]
	v_mfma_f32_16x16x32_bf16 v[66:69], v[214:217], v[230:233], v[66:69]
	s_setprio 0
	v_readfirstlane_b32 s28, v136
	s_add_i32 s27, s25, 0x100
	s_mov_b32 m0, s28
	v_readfirstlane_b32 s28, v135
	s_barrier
	ds_read_b128 v[186:189], v143 offset:16384
	ds_read_b128 v[190:193], v143 offset:17408
	ds_read_b128 v[194:197], v142 offset:16384
	ds_read_b128 v[198:201], v142 offset:17408
	ds_read_b128 v[202:205], v141 offset:16384
	ds_read_b128 v[206:209], v141 offset:17408
	ds_read_b128 v[210:213], v140 offset:16384
	ds_read_b128 v[214:217], v140 offset:17408
	buffer_load_dwordx4 v32, s[8:11], s27 offen lds
	s_mov_b32 m0, s28
	s_nop 0
	buffer_load_dwordx4 v131, s[8:11], s27 offen lds
	s_barrier
	s_setprio 1
	s_waitcnt lgkmcnt(7)
	v_mfma_f32_16x16x32_bf16 v[62:65], v[186:189], v[156:159], 0
	v_mfma_f32_16x16x32_bf16 v[58:61], v[186:189], v[170:173], 0
	s_waitcnt lgkmcnt(5)
	v_mfma_f32_16x16x32_bf16 v[54:57], v[194:197], v[156:159], 0
	v_mfma_f32_16x16x32_bf16 v[50:53], v[194:197], v[170:173], 0
	s_waitcnt lgkmcnt(3)
	v_mfma_f32_16x16x32_bf16 v[46:49], v[202:205], v[156:159], 0
	v_mfma_f32_16x16x32_bf16 v[42:45], v[202:205], v[170:173], 0
	s_waitcnt lgkmcnt(1)
	v_mfma_f32_16x16x32_bf16 v[38:41], v[210:213], v[156:159], 0
	v_mfma_f32_16x16x32_bf16 v[34:37], v[210:213], v[170:173], 0
	v_mfma_f32_16x16x32_bf16 v[62:65], v[190:193], v[166:169], v[62:65]
	v_mfma_f32_16x16x32_bf16 v[58:61], v[190:193], v[174:177], v[58:61]
	v_mfma_f32_16x16x32_bf16 v[54:57], v[198:201], v[166:169], v[54:57]
	v_mfma_f32_16x16x32_bf16 v[50:53], v[198:201], v[174:177], v[50:53]
	v_mfma_f32_16x16x32_bf16 v[46:49], v[206:209], v[166:169], v[46:49]
	v_mfma_f32_16x16x32_bf16 v[42:45], v[206:209], v[174:177], v[42:45]
	s_waitcnt lgkmcnt(0)
	v_mfma_f32_16x16x32_bf16 v[38:41], v[214:217], v[166:169], v[38:41]
	v_mfma_f32_16x16x32_bf16 v[34:37], v[214:217], v[174:177], v[34:37]
	s_setprio 0
	s_barrier
	v_readfirstlane_b32 s28, v134
	s_add_i32 s27, s26, 0x40100
	s_mov_b32 m0, s28
	v_readfirstlane_b32 s28, v138
	buffer_load_dwordx4 v32, s[76:79], s27 offen lds
	s_mov_b32 m0, s28
	s_nop 0
	buffer_load_dwordx4 v131, s[76:79], s27 offen lds
	s_waitcnt vmcnt(6)
	s_barrier
; #define STAGE(P, BASE, br, kt) do { int _so = ((br) * K + (kt) * BK) * 2; \
;     __builtin_amdgcn_raw_ptr_buffer_load_lds(rs_##BASE, (__attribute__((address_space(3))) void*)((char*)(P) + tx * 16), 16, voff0, _so, 0, 0); \
;     __builtin_amdgcn_raw_ptr_buffer_load_lds(rs_##BASE, (__attribute__((address_space(3))) void*)((char*)(P) + tx * 16 + 8192), 16, voff1, _so, 0, 0); } while (0)
; #define LDA(dst, b, h) _Pragma("unroll") for (int m = 0; m < 4; ++m) _Pragma("unroll") for (int k = 0; k < 2; ++k) \
;     dst[m][k] = *reinterpret_cast<const bf16x8*>((char*)SA(b, h) + lds_byte(wr * 64 + m * 16 + fr, k * 32 + fq * 8))
; #define LDB(dst, b, h) _Pragma("unroll") for (int n = 0; n < 2; ++n) _Pragma("unroll") for (int k = 0; k < 2; ++k) \
;     dst[n][k] = *reinterpret_cast<const bf16x8*>((char*)SB(b, h) + lds_byte(wc * 32 + n * 16 + fr, k * 32 + fq * 8))
; #define MMA(ai, bj, At, Bt_) do { __builtin_amdgcn_s_setprio(1); \
;     _Pragma("unroll") for (int m = 0; m < 4; ++m) _Pragma("unroll") for (int n = 0; n < 2; ++n) _Pragma("unroll") for (int k = 0; k < 2; ++k) \
;       acc[ai][bj][m][n] = __builtin_amdgcn_mfma_f32_16x16x32_bf16(At[m][k], Bt_[n][k], acc[ai][bj][m][n], 0, 0, 0); \
;     __builtin_amdgcn_s_setprio(0); } while (0)
; #define WAIT_V(n) asm volatile("s_waitcnt vmcnt(" #n ")" ::: "memory")
; #define WAIT_L(n) asm volatile("s_waitcnt lgkmcnt(" #n ")" ::: "memory")
; #define BAR __builtin_amdgcn_s_barrier()
; #define SCHED __builtin_amdgcn_sched_barrier(0)
; template <class Epi> ...
;     ...
;     WAIT_V(6); BAR; MMA(1, 1, At, B1); BAR;
;     LDB(B0, 1, 0); SCHED; LDA(At, 1, 0); STAGE(SA(0, 1), A, brow + HALF, t + 2);
;     WAIT_L(8); BAR; WAIT_L(0); MMA(0, 0, At, B0); BAR; SCHED;
;     LDB(B1, 1, 1); STAGE(SB(1, 0), Bt, bcol, t + 3);
;     BAR; WAIT_L(0); MMA(0, 1, At, B1); BAR;
;     LDA(At, 1, 1); STAGE(SA(1, 0), A, brow, t + 3);
;     BAR; WAIT_L(0); MMA(1, 0, At, B0); BAR; SCHED;
;     STAGE(SB(1, 1), Bt, bcol + HALF, t + 3);
;     WAIT_V(6); BAR; MMA(1, 1, At, B1); BAR;
	s_setprio 1
	v_mfma_f32_16x16x32_bf16 v[28:31], v[186:189], v[218:221], 0
	v_mfma_f32_16x16x32_bf16 v[24:27], v[186:189], v[226:229], 0
	v_mfma_f32_16x16x32_bf16 v[20:23], v[194:197], v[218:221], 0
	v_mfma_f32_16x16x32_bf16 v[16:19], v[194:197], v[226:229], 0
	v_mfma_f32_16x16x32_bf16 v[12:15], v[202:205], v[218:221], 0
	v_mfma_f32_16x16x32_bf16 v[8:11], v[202:205], v[226:229], 0
	v_mfma_f32_16x16x32_bf16 v[4:7], v[210:213], v[218:221], 0
	v_mfma_f32_16x16x32_bf16 v[0:3], v[210:213], v[226:229], 0
	v_mfma_f32_16x16x32_bf16 v[28:31], v[190:193], v[222:225], v[28:31]
	v_mfma_f32_16x16x32_bf16 v[24:27], v[190:193], v[230:233], v[24:27]
	v_mfma_f32_16x16x32_bf16 v[20:23], v[198:201], v[222:225], v[20:23]
	v_mfma_f32_16x16x32_bf16 v[16:19], v[198:201], v[230:233], v[16:19]
	v_mfma_f32_16x16x32_bf16 v[12:15], v[206:209], v[222:225], v[12:15]
	v_mfma_f32_16x16x32_bf16 v[8:11], v[206:209], v[230:233], v[8:11]
	v_mfma_f32_16x16x32_bf16 v[4:7], v[214:217], v[222:225], v[4:7]
	v_mfma_f32_16x16x32_bf16 v[0:3], v[214:217], v[230:233], v[0:3]
	s_setprio 0
	s_barrier
	ds_read_b128 v[156:159], v145
	ds_read_b128 v[166:169], v145 offset:1024
	ds_read_b128 v[170:173], v145 offset:2048
	ds_read_b128 v[174:177], v145 offset:3072
	v_readfirstlane_b32 s28, v133
	s_add_i32 s27, s25, 0x40100
	s_mov_b32 m0, s28
	v_readfirstlane_b32 s28, v132
	ds_read_b128 v[186:189], v143 offset:32768
	ds_read_b128 v[190:193], v143 offset:33792
	ds_read_b128 v[194:197], v142 offset:32768
	ds_read_b128 v[198:201], v142 offset:33792
	ds_read_b128 v[202:205], v141 offset:32768
	ds_read_b128 v[206:209], v141 offset:33792
	ds_read_b128 v[210:213], v140 offset:32768
	ds_read_b128 v[214:217], v140 offset:33792
	buffer_load_dwordx4 v32, s[8:11], s27 offen lds
	s_mov_b32 m0, s28
	s_nop 0
	buffer_load_dwordx4 v131, s[8:11], s27 offen lds
	s_waitcnt lgkmcnt(8)
	s_barrier
	s_setprio 1
	s_waitcnt lgkmcnt(7)
	v_mfma_f32_16x16x32_bf16 v[126:129], v[186:189], v[156:159], v[126:129]
	v_mfma_f32_16x16x32_bf16 v[122:125], v[186:189], v[170:173], v[122:125]
	s_waitcnt lgkmcnt(5)
	v_mfma_f32_16x16x32_bf16 v[118:121], v[194:197], v[156:159], v[118:121]
	v_mfma_f32_16x16x32_bf16 v[114:117], v[194:197], v[170:173], v[114:117]
	s_waitcnt lgkmcnt(3)
	v_mfma_f32_16x16x32_bf16 v[110:113], v[202:205], v[156:159], v[110:113]
	v_mfma_f32_16x16x32_bf16 v[106:109], v[202:205], v[170:173], v[106:109]
	s_waitcnt lgkmcnt(1)
	v_mfma_f32_16x16x32_bf16 v[102:105], v[210:213], v[156:159], v[102:105]
	v_mfma_f32_16x16x32_bf16 v[98:101], v[210:213], v[170:173], v[98:101]
	v_mfma_f32_16x16x32_bf16 v[126:129], v[190:193], v[166:169], v[126:129]
	v_mfma_f32_16x16x32_bf16 v[122:125], v[190:193], v[174:177], v[122:125]
	v_mfma_f32_16x16x32_bf16 v[118:121], v[198:201], v[166:169], v[118:121]
	v_mfma_f32_16x16x32_bf16 v[114:117], v[198:201], v[174:177], v[114:117]
	v_mfma_f32_16x16x32_bf16 v[110:113], v[206:209], v[166:169], v[110:113]
	v_mfma_f32_16x16x32_bf16 v[106:109], v[206:209], v[174:177], v[106:109]
	s_waitcnt lgkmcnt(0)
	v_mfma_f32_16x16x32_bf16 v[102:105], v[214:217], v[166:169], v[102:105]
	v_mfma_f32_16x16x32_bf16 v[98:101], v[214:217], v[174:177], v[98:101]
	s_setprio 0
	s_barrier
	v_readfirstlane_b32 s28, v146
	s_add_i32 s27, s26, 0x180
	s_mov_b32 m0, s28
	v_readfirstlane_b32 s28, v147
	ds_read_b128 v[218:221], v144
	ds_read_b128 v[222:225], v144 offset:1024
	ds_read_b128 v[226:229], v144 offset:2048
	ds_read_b128 v[230:233], v144 offset:3072
	buffer_load_dwordx4 v32, s[76:79], s27 offen lds
	s_mov_b32 m0, s28
	s_nop 0
	buffer_load_dwordx4 v131, s[76:79], s27 offen lds
	s_barrier
	s_setprio 1
	s_waitcnt lgkmcnt(3)
	v_mfma_f32_16x16x32_bf16 v[94:97], v[186:189], v[218:221], v[94:97]
	s_waitcnt lgkmcnt(1)
	v_mfma_f32_16x16x32_bf16 v[90:93], v[186:189], v[226:229], v[90:93]
	v_mfma_f32_16x16x32_bf16 v[86:89], v[194:197], v[218:221], v[86:89]
	v_mfma_f32_16x16x32_bf16 v[82:85], v[194:197], v[226:229], v[82:85]
	v_mfma_f32_16x16x32_bf16 v[78:81], v[202:205], v[218:221], v[78:81]
	v_mfma_f32_16x16x32_bf16 v[74:77], v[202:205], v[226:229], v[74:77]
	v_mfma_f32_16x16x32_bf16 v[70:73], v[210:213], v[218:221], v[70:73]
	v_mfma_f32_16x16x32_bf16 v[66:69], v[210:213], v[226:229], v[66:69]
	v_mfma_f32_16x16x32_bf16 v[94:97], v[190:193], v[222:225], v[94:97]
	s_waitcnt lgkmcnt(0)
	v_mfma_f32_16x16x32_bf16 v[90:93], v[190:193], v[230:233], v[90:93]
	v_mfma_f32_16x16x32_bf16 v[86:89], v[198:201], v[222:225], v[86:89]
	v_mfma_f32_16x16x32_bf16 v[82:85], v[198:201], v[230:233], v[82:85]
	v_mfma_f32_16x16x32_bf16 v[78:81], v[206:209], v[222:225], v[78:81]
	v_mfma_f32_16x16x32_bf16 v[74:77], v[206:209], v[230:233], v[74:77]
	v_mfma_f32_16x16x32_bf16 v[70:73], v[214:217], v[222:225], v[70:73]
	v_mfma_f32_16x16x32_bf16 v[66:69], v[214:217], v[230:233], v[66:69]
	s_setprio 0
	v_readfirstlane_b32 s27, v148
	s_addk_i32 s25, 0x180
	s_mov_b32 m0, s27
	v_readfirstlane_b32 s27, v150
	s_barrier
	ds_read_b128 v[186:189], v143 offset:49152
	ds_read_b128 v[190:193], v143 offset:50176
	ds_read_b128 v[194:197], v142 offset:49152
	ds_read_b128 v[198:201], v142 offset:50176
	ds_read_b128 v[202:205], v141 offset:49152
	ds_read_b128 v[206:209], v141 offset:50176
	ds_read_b128 v[210:213], v140 offset:49152
	ds_read_b128 v[214:217], v140 offset:50176
	buffer_load_dwordx4 v32, s[8:11], s25 offen lds
	s_mov_b32 m0, s27
	s_nop 0
	buffer_load_dwordx4 v131, s[8:11], s25 offen lds
	s_barrier
; #define STAGE(P, BASE, br, kt) do { int _so = ((br) * K + (kt) * BK) * 2; \
;     __builtin_amdgcn_raw_ptr_buffer_load_lds(rs_##BASE, (__attribute__((address_space(3))) void*)((char*)(P) + tx * 16), 16, voff0, _so, 0, 0); \
;     __builtin_amdgcn_raw_ptr_buffer_load_lds(rs_##BASE, (__attribute__((address_space(3))) void*)((char*)(P) + tx * 16 + 8192), 16, voff1, _so, 0, 0); } while (0)
; #define LDA(dst, b, h) _Pragma("unroll") for (int m = 0; m < 4; ++m) _Pragma("unroll") for (int k = 0; k < 2; ++k) \
;     dst[m][k] = *reinterpret_cast<const bf16x8*>((char*)SA(b, h) + lds_byte(wr * 64 + m * 16 + fr, k * 32 + fq * 8))
; #define LDB(dst, b, h) _Pragma("unroll") for (int n = 0; n < 2; ++n) _Pragma("unroll") for (int k = 0; k < 2; ++k) \
;     dst[n][k] = *reinterpret_cast<const bf16x8*>((char*)SB(b, h) + lds_byte(wc * 32 + n * 16 + fr, k * 32 + fq * 8))
; #define MMA(ai, bj, At, Bt_) do { __builtin_amdgcn_s_setprio(1); \
;     _Pragma("unroll") for (int m = 0; m < 4; ++m) _Pragma("unroll") for (int n = 0; n < 2; ++n) _Pragma("unroll") for (int k = 0; k < 2; ++k) \
;       acc[ai][bj][m][n] = __builtin_amdgcn_mfma_f32_16x16x32_bf16(At[m][k], Bt_[n][k], acc[ai][bj][m][n], 0, 0, 0); \
;     __builtin_amdgcn_s_setprio(0); } while (0)
; #define WAIT_V(n) asm volatile("s_waitcnt vmcnt(" #n ")" ::: "memory")
; #define WAIT_L(n) asm volatile("s_waitcnt lgkmcnt(" #n ")" ::: "memory")
; #define BAR __builtin_amdgcn_s_barrier()
; #define SCHED __builtin_amdgcn_sched_barrier(0)
; template <class Epi> ...
;     ...
;   for (int t = 0; t < nt - 2; t += 2) {
;     LDB(B0, 0, 0); SCHED; LDA(At, 0, 0); STAGE(SA(1, 1), A, brow + HALF, t + 1);
;     WAIT_L(8); BAR; WAIT_L(0); MMA(0, 0, At, B0); BAR; SCHED;
;     LDB(B1, 0, 1); STAGE(SB(0, 0), Bt, bcol, t + 2);
;     BAR; WAIT_L(0); MMA(0, 1, At, B1); BAR;
;     ...
;     BAR; WAIT_L(0); MMA(1, 0, At, B0); BAR; SCHED;
;     STAGE(SB(1, 1), Bt, bcol + HALF, t + 3);
;     WAIT_V(6); BAR; MMA(1, 1, At, B1); BAR;
;   }
	s_setprio 1
	s_waitcnt lgkmcnt(7)
	v_mfma_f32_16x16x32_bf16 v[62:65], v[186:189], v[156:159], v[62:65]
	v_mfma_f32_16x16x32_bf16 v[58:61], v[186:189], v[170:173], v[58:61]
	s_waitcnt lgkmcnt(5)
	v_mfma_f32_16x16x32_bf16 v[54:57], v[194:197], v[156:159], v[54:57]
	v_mfma_f32_16x16x32_bf16 v[50:53], v[194:197], v[170:173], v[50:53]
	s_waitcnt lgkmcnt(3)
	v_mfma_f32_16x16x32_bf16 v[46:49], v[202:205], v[156:159], v[46:49]
	v_mfma_f32_16x16x32_bf16 v[42:45], v[202:205], v[170:173], v[42:45]
	s_waitcnt lgkmcnt(1)
	v_mfma_f32_16x16x32_bf16 v[38:41], v[210:213], v[156:159], v[38:41]
	v_mfma_f32_16x16x32_bf16 v[34:37], v[210:213], v[170:173], v[34:37]
	v_mfma_f32_16x16x32_bf16 v[62:65], v[190:193], v[166:169], v[62:65]
	v_mfma_f32_16x16x32_bf16 v[58:61], v[190:193], v[174:177], v[58:61]
	v_mfma_f32_16x16x32_bf16 v[54:57], v[198:201], v[166:169], v[54:57]
	v_mfma_f32_16x16x32_bf16 v[50:53], v[198:201], v[174:177], v[50:53]
	v_mfma_f32_16x16x32_bf16 v[46:49], v[206:209], v[166:169], v[46:49]
	v_mfma_f32_16x16x32_bf16 v[42:45], v[206:209], v[174:177], v[42:45]
	s_waitcnt lgkmcnt(0)
	v_mfma_f32_16x16x32_bf16 v[38:41], v[214:217], v[166:169], v[38:41]
	v_mfma_f32_16x16x32_bf16 v[34:37], v[214:217], v[174:177], v[34:37]
	s_setprio 0
	s_barrier
	v_readfirstlane_b32 s25, v153
	s_add_i32 s26, s26, 0x40180
	s_mov_b32 m0, s25
	v_readfirstlane_b32 s25, v154
	buffer_load_dwordx4 v32, s[76:79], s26 offen lds
	s_mov_b32 m0, s25
	s_nop 0
	buffer_load_dwordx4 v131, s[76:79], s26 offen lds
	s_waitcnt vmcnt(6)
	s_barrier
	s_setprio 1
	v_mfma_f32_16x16x32_bf16 v[28:31], v[186:189], v[218:221], v[28:31]
	v_mfma_f32_16x16x32_bf16 v[24:27], v[186:189], v[226:229], v[24:27]
	v_mfma_f32_16x16x32_bf16 v[20:23], v[194:197], v[218:221], v[20:23]
	v_mfma_f32_16x16x32_bf16 v[16:19], v[194:197], v[226:229], v[16:19]
	v_mfma_f32_16x16x32_bf16 v[12:15], v[202:205], v[218:221], v[12:15]
	v_mfma_f32_16x16x32_bf16 v[8:11], v[202:205], v[226:229], v[8:11]
	v_mfma_f32_16x16x32_bf16 v[4:7], v[210:213], v[218:221], v[4:7]
	v_mfma_f32_16x16x32_bf16 v[0:3], v[210:213], v[226:229], v[0:3]
	v_mfma_f32_16x16x32_bf16 v[28:31], v[190:193], v[222:225], v[28:31]
	v_mfma_f32_16x16x32_bf16 v[24:27], v[190:193], v[230:233], v[24:27]
	v_mfma_f32_16x16x32_bf16 v[20:23], v[198:201], v[222:225], v[20:23]
	v_mfma_f32_16x16x32_bf16 v[16:19], v[198:201], v[230:233], v[16:19]
	v_mfma_f32_16x16x32_bf16 v[12:15], v[206:209], v[222:225], v[12:15]
	v_mfma_f32_16x16x32_bf16 v[8:11], v[206:209], v[230:233], v[8:11]
	v_mfma_f32_16x16x32_bf16 v[4:7], v[214:217], v[222:225], v[4:7]
	v_mfma_f32_16x16x32_bf16 v[0:3], v[214:217], v[230:233], v[0:3]
	s_setprio 0
	s_add_i32 s23, s23, 2
	s_addk_i32 s24, 0x100
	s_cmp_lt_u32 s23, 12
	s_barrier
	s_cbranch_scc1 .LBB0_1927
	s_branch .Lpx4
.LBB0_1927:
	ds_read_b128 v[156:159], v155
	ds_read_b128 v[166:169], v155 offset:1024
	ds_read_b128 v[170:173], v155 offset:2048
	ds_read_b128 v[174:177], v155 offset:3072
	s_add_i32 s25, s17, s24
	v_readfirstlane_b32 s27, v152
	s_add_i32 s26, s25, 0x40080
	s_mov_b32 m0, s27
	v_readfirstlane_b32 s27, v151
	ds_read_b128 v[186:189], v143
	ds_read_b128 v[190:193], v143 offset:1024
	ds_read_b128 v[194:197], v142
	ds_read_b128 v[198:201], v142 offset:1024
	ds_read_b128 v[202:205], v141
	ds_read_b128 v[206:209], v141 offset:1024
	ds_read_b128 v[210:213], v140
	ds_read_b128 v[214:217], v140 offset:1024
	buffer_load_dwordx4 v32, s[8:11], s26 offen lds
	s_mov_b32 m0, s27
	s_nop 0
	buffer_load_dwordx4 v131, s[8:11], s26 offen lds
	s_waitcnt lgkmcnt(8)
	s_barrier
	s_setprio 1
	s_waitcnt lgkmcnt(7)
	v_mfma_f32_16x16x32_bf16 v[126:129], v[186:189], v[156:159], v[126:129]
	v_mfma_f32_16x16x32_bf16 v[122:125], v[186:189], v[170:173], v[122:125]
	s_waitcnt lgkmcnt(5)
	v_mfma_f32_16x16x32_bf16 v[118:121], v[194:197], v[156:159], v[118:121]
	v_mfma_f32_16x16x32_bf16 v[114:117], v[194:197], v[170:173], v[114:117]
	s_waitcnt lgkmcnt(3)
	v_mfma_f32_16x16x32_bf16 v[110:113], v[202:205], v[156:159], v[110:113]
	v_mfma_f32_16x16x32_bf16 v[106:109], v[202:205], v[170:173], v[106:109]
	s_waitcnt lgkmcnt(1)
	v_mfma_f32_16x16x32_bf16 v[102:105], v[210:213], v[156:159], v[102:105]
	v_mfma_f32_16x16x32_bf16 v[98:101], v[210:213], v[170:173], v[98:101]
	v_mfma_f32_16x16x32_bf16 v[126:129], v[190:193], v[166:169], v[126:129]
	v_mfma_f32_16x16x32_bf16 v[122:125], v[190:193], v[174:177], v[122:125]
	v_mfma_f32_16x16x32_bf16 v[118:121], v[198:201], v[166:169], v[118:121]
	v_mfma_f32_16x16x32_bf16 v[114:117], v[198:201], v[174:177], v[114:117]
	v_mfma_f32_16x16x32_bf16 v[110:113], v[206:209], v[166:169], v[110:113]
	v_mfma_f32_16x16x32_bf16 v[106:109], v[206:209], v[174:177], v[106:109]
	s_waitcnt lgkmcnt(0)
	v_mfma_f32_16x16x32_bf16 v[102:105], v[214:217], v[166:169], v[102:105]
	v_mfma_f32_16x16x32_bf16 v[98:101], v[214:217], v[174:177], v[98:101]
	s_setprio 0
	s_barrier
	s_add_i32 s26, s16, s24
	v_readfirstlane_b32 s28, v137
	s_add_i32 s27, s26, 0x100
	s_mov_b32 m0, s28
	v_readfirstlane_b32 s28, v139
	ds_read_b128 v[218:221], v149
	ds_read_b128 v[222:225], v149 offset:1024
	ds_read_b128 v[226:229], v149 offset:2048
	ds_read_b128 v[230:233], v149 offset:3072
	buffer_load_dwordx4 v32, s[76:79], s27 offen lds
	s_mov_b32 m0, s28
	s_nop 0
	buffer_load_dwordx4 v131, s[76:79], s27 offen lds
	s_barrier
; #define STAGE(P, BASE, br, kt) do { int _so = ((br) * K + (kt) * BK) * 2; \
;     __builtin_amdgcn_raw_ptr_buffer_load_lds(rs_##BASE, (__attribute__((address_space(3))) void*)((char*)(P) + tx * 16), 16, voff0, _so, 0, 0); \
;     __builtin_amdgcn_raw_ptr_buffer_load_lds(rs_##BASE, (__attribute__((address_space(3))) void*)((char*)(P) + tx * 16 + 8192), 16, voff1, _so, 0, 0); } while (0)
; #define LDA(dst, b, h) _Pragma("unroll") for (int m = 0; m < 4; ++m) _Pragma("unroll") for (int k = 0; k < 2; ++k) \
;     dst[m][k] = *reinterpret_cast<const bf16x8*>((char*)SA(b, h) + lds_byte(wr * 64 + m * 16 + fr, k * 32 + fq * 8))
; #define LDB(dst, b, h) _Pragma("unroll") for (int n = 0; n < 2; ++n) _Pragma("unroll") for (int k = 0; k < 2; ++k) \
;     dst[n][k] = *reinterpret_cast<const bf16x8*>((char*)SB(b, h) + lds_byte(wc * 32 + n * 16 + fr, k * 32 + fq * 8))
; #define MMA(ai, bj, At, Bt_) do { __builtin_amdgcn_s_setprio(1); \
;     _Pragma("unroll") for (int m = 0; m < 4; ++m) _Pragma("unroll") for (int n = 0; n < 2; ++n) _Pragma("unroll") for (int k = 0; k < 2; ++k) \
;       acc[ai][bj][m][n] = __builtin_amdgcn_mfma_f32_16x16x32_bf16(At[m][k], Bt_[n][k], acc[ai][bj][m][n], 0, 0, 0); \
;     __builtin_amdgcn_s_setprio(0); } while (0)
; #define WAIT_V(n) asm volatile("s_waitcnt vmcnt(" #n ")" ::: "memory")
; #define WAIT_L(n) asm volatile("s_waitcnt lgkmcnt(" #n ")" ::: "memory")
; #define BAR __builtin_amdgcn_s_barrier()
; #define SCHED __builtin_amdgcn_sched_barrier(0)
; template <class Epi> ...
;     ...
;     BAR; WAIT_L(0); MMA(0, 1, At, B1); BAR;
;     LDA(At, 0, 1); STAGE(SA(0, 0), A, brow, t + 2);
;     BAR; WAIT_L(0); MMA(1, 0, At, B0); BAR; SCHED;
;     STAGE(SB(0, 1), Bt, bcol + HALF, t + 2);
;     WAIT_V(6); BAR; MMA(1, 1, At, B1); BAR;
;     LDB(B0, 1, 0); SCHED; LDA(At, 1, 0); STAGE(SA(0, 1), A, brow + HALF, t + 2);
;     WAIT_L(8); BAR; WAIT_L(0); MMA(0, 0, At, B0); BAR; SCHED;
	s_setprio 1
	s_waitcnt lgkmcnt(3)
	v_mfma_f32_16x16x32_bf16 v[94:97], v[186:189], v[218:221], v[94:97]
	s_waitcnt lgkmcnt(1)
	v_mfma_f32_16x16x32_bf16 v[90:93], v[186:189], v[226:229], v[90:93]
	v_mfma_f32_16x16x32_bf16 v[86:89], v[194:197], v[218:221], v[86:89]
	v_mfma_f32_16x16x32_bf16 v[82:85], v[194:197], v[226:229], v[82:85]
	v_mfma_f32_16x16x32_bf16 v[78:81], v[202:205], v[218:221], v[78:81]
	v_mfma_f32_16x16x32_bf16 v[74:77], v[202:205], v[226:229], v[74:77]
	v_mfma_f32_16x16x32_bf16 v[70:73], v[210:213], v[218:221], v[70:73]
	v_mfma_f32_16x16x32_bf16 v[66:69], v[210:213], v[226:229], v[66:69]
	v_mfma_f32_16x16x32_bf16 v[94:97], v[190:193], v[222:225], v[94:97]
	s_waitcnt lgkmcnt(0)
	v_mfma_f32_16x16x32_bf16 v[90:93], v[190:193], v[230:233], v[90:93]
	v_mfma_f32_16x16x32_bf16 v[86:89], v[198:201], v[222:225], v[86:89]
	v_mfma_f32_16x16x32_bf16 v[82:85], v[198:201], v[230:233], v[82:85]
	v_mfma_f32_16x16x32_bf16 v[78:81], v[206:209], v[222:225], v[78:81]
	v_mfma_f32_16x16x32_bf16 v[74:77], v[206:209], v[230:233], v[74:77]
	v_mfma_f32_16x16x32_bf16 v[70:73], v[214:217], v[222:225], v[70:73]
	v_mfma_f32_16x16x32_bf16 v[66:69], v[214:217], v[230:233], v[66:69]
	s_setprio 0
	v_readfirstlane_b32 s28, v136
	s_add_i32 s27, s25, 0x100
	s_mov_b32 m0, s28
	v_readfirstlane_b32 s28, v135
	s_barrier
	ds_read_b128 v[186:189], v143 offset:16384
	ds_read_b128 v[190:193], v143 offset:17408
	ds_read_b128 v[194:197], v142 offset:16384
	ds_read_b128 v[198:201], v142 offset:17408
	ds_read_b128 v[202:205], v141 offset:16384
	ds_read_b128 v[206:209], v141 offset:17408
	ds_read_b128 v[210:213], v140 offset:16384
	ds_read_b128 v[214:217], v140 offset:17408
	buffer_load_dwordx4 v32, s[8:11], s27 offen lds
	s_mov_b32 m0, s28
	s_nop 0
	buffer_load_dwordx4 v131, s[8:11], s27 offen lds
	s_barrier
	s_setprio 1
	s_waitcnt lgkmcnt(7)
	v_mfma_f32_16x16x32_bf16 v[62:65], v[186:189], v[156:159], v[62:65]
	v_mfma_f32_16x16x32_bf16 v[58:61], v[186:189], v[170:173], v[58:61]
	s_waitcnt lgkmcnt(5)
	v_mfma_f32_16x16x32_bf16 v[54:57], v[194:197], v[156:159], v[54:57]
	v_mfma_f32_16x16x32_bf16 v[50:53], v[194:197], v[170:173], v[50:53]
	s_waitcnt lgkmcnt(3)
	v_mfma_f32_16x16x32_bf16 v[46:49], v[202:205], v[156:159], v[46:49]
	v_mfma_f32_16x16x32_bf16 v[42:45], v[202:205], v[170:173], v[42:45]
	s_waitcnt lgkmcnt(1)
	v_mfma_f32_16x16x32_bf16 v[38:41], v[210:213], v[156:159], v[38:41]
	v_mfma_f32_16x16x32_bf16 v[34:37], v[210:213], v[170:173], v[34:37]
	v_mfma_f32_16x16x32_bf16 v[62:65], v[190:193], v[166:169], v[62:65]
	v_mfma_f32_16x16x32_bf16 v[58:61], v[190:193], v[174:177], v[58:61]
	v_mfma_f32_16x16x32_bf16 v[54:57], v[198:201], v[166:169], v[54:57]
	v_mfma_f32_16x16x32_bf16 v[50:53], v[198:201], v[174:177], v[50:53]
	v_mfma_f32_16x16x32_bf16 v[46:49], v[206:209], v[166:169], v[46:49]
	v_mfma_f32_16x16x32_bf16 v[42:45], v[206:209], v[174:177], v[42:45]
	s_waitcnt lgkmcnt(0)
	v_mfma_f32_16x16x32_bf16 v[38:41], v[214:217], v[166:169], v[38:41]
	v_mfma_f32_16x16x32_bf16 v[34:37], v[214:217], v[174:177], v[34:37]
	s_setprio 0
	s_barrier
	v_readfirstlane_b32 s28, v134
	s_add_i32 s27, s26, 0x40100
	s_mov_b32 m0, s28
	v_readfirstlane_b32 s28, v138
	buffer_load_dwordx4 v32, s[76:79], s27 offen lds
	s_mov_b32 m0, s28
	s_nop 0
	buffer_load_dwordx4 v131, s[76:79], s27 offen lds
	s_waitcnt vmcnt(6)
	s_barrier
	s_setprio 1
	v_mfma_f32_16x16x32_bf16 v[28:31], v[186:189], v[218:221], v[28:31]
	v_mfma_f32_16x16x32_bf16 v[24:27], v[186:189], v[226:229], v[24:27]
	v_mfma_f32_16x16x32_bf16 v[20:23], v[194:197], v[218:221], v[20:23]
	v_mfma_f32_16x16x32_bf16 v[16:19], v[194:197], v[226:229], v[16:19]
	v_mfma_f32_16x16x32_bf16 v[12:15], v[202:205], v[218:221], v[12:15]
	v_mfma_f32_16x16x32_bf16 v[8:11], v[202:205], v[226:229], v[8:11]
	v_mfma_f32_16x16x32_bf16 v[4:7], v[210:213], v[218:221], v[4:7]
	v_mfma_f32_16x16x32_bf16 v[0:3], v[210:213], v[226:229], v[0:3]
	v_mfma_f32_16x16x32_bf16 v[28:31], v[190:193], v[222:225], v[28:31]
	v_mfma_f32_16x16x32_bf16 v[24:27], v[190:193], v[230:233], v[24:27]
	v_mfma_f32_16x16x32_bf16 v[20:23], v[198:201], v[222:225], v[20:23]
	v_mfma_f32_16x16x32_bf16 v[16:19], v[198:201], v[230:233], v[16:19]
	v_mfma_f32_16x16x32_bf16 v[12:15], v[206:209], v[222:225], v[12:15]
	v_mfma_f32_16x16x32_bf16 v[8:11], v[206:209], v[230:233], v[8:11]
	v_mfma_f32_16x16x32_bf16 v[4:7], v[214:217], v[222:225], v[4:7]
	v_mfma_f32_16x16x32_bf16 v[0:3], v[214:217], v[230:233], v[0:3]
	s_setprio 0
	s_barrier
	ds_read_b128 v[156:159], v145
	ds_read_b128 v[166:169], v145 offset:1024
	ds_read_b128 v[170:173], v145 offset:2048
	ds_read_b128 v[174:177], v145 offset:3072
	v_readfirstlane_b32 s28, v133
	s_add_i32 s27, s25, 0x40100
	s_mov_b32 m0, s28
	v_readfirstlane_b32 s28, v132
	ds_read_b128 v[186:189], v143 offset:32768
	ds_read_b128 v[190:193], v143 offset:33792
	ds_read_b128 v[194:197], v142 offset:32768
	ds_read_b128 v[198:201], v142 offset:33792
	ds_read_b128 v[202:205], v141 offset:32768
	ds_read_b128 v[206:209], v141 offset:33792
	ds_read_b128 v[210:213], v140 offset:32768
	ds_read_b128 v[214:217], v140 offset:33792
	buffer_load_dwordx4 v32, s[8:11], s27 offen lds
	s_mov_b32 m0, s28
	s_nop 0
	buffer_load_dwordx4 v131, s[8:11], s27 offen lds
	s_waitcnt lgkmcnt(8)
	s_barrier
; #define STAGE(P, BASE, br, kt) do { int _so = ((br) * K + (kt) * BK) * 2; \
;     __builtin_amdgcn_raw_ptr_buffer_load_lds(rs_##BASE, (__attribute__((address_space(3))) void*)((char*)(P) + tx * 16), 16, voff0, _so, 0, 0); \
;     __builtin_amdgcn_raw_ptr_buffer_load_lds(rs_##BASE, (__attribute__((address_space(3))) void*)((char*)(P) + tx * 16 + 8192), 16, voff1, _so, 0, 0); } while (0)
; #define LDA(dst, b, h) _Pragma("unroll") for (int m = 0; m < 4; ++m) _Pragma("unroll") for (int k = 0; k < 2; ++k) \
;     dst[m][k] = *reinterpret_cast<const bf16x8*>((char*)SA(b, h) + lds_byte(wr * 64 + m * 16 + fr, k * 32 + fq * 8))
; #define LDB(dst, b, h) _Pragma("unroll") for (int n = 0; n < 2; ++n) _Pragma("unroll") for (int k = 0; k < 2; ++k) \
;     dst[n][k] = *reinterpret_cast<const bf16x8*>((char*)SB(b, h) + lds_byte(wc * 32 + n * 16 + fr, k * 32 + fq * 8))
; #define MMA(ai, bj, At, Bt_) do { __builtin_amdgcn_s_setprio(1); \
;     _Pragma("unroll") for (int m = 0; m < 4; ++m) _Pragma("unroll") for (int n = 0; n < 2; ++n) _Pragma("unroll") for (int k = 0; k < 2; ++k) \
;       acc[ai][bj][m][n] = __builtin_amdgcn_mfma_f32_16x16x32_bf16(At[m][k], Bt_[n][k], acc[ai][bj][m][n], 0, 0, 0); \
;     __builtin_amdgcn_s_setprio(0); } while (0)
; #define WAIT_V(n) asm volatile("s_waitcnt vmcnt(" #n ")" ::: "memory")
; #define WAIT_L(n) asm volatile("s_waitcnt lgkmcnt(" #n ")" ::: "memory")
; #define BAR __builtin_amdgcn_s_barrier()
; #define SCHED __builtin_amdgcn_sched_barrier(0)
; template <class Epi> ...
;     ...
;     WAIT_L(8); BAR; WAIT_L(0); MMA(0, 0, At, B0); BAR; SCHED;
;     LDB(B1, 1, 1); STAGE(SB(1, 0), Bt, bcol, t + 3);
;     BAR; WAIT_L(0); MMA(0, 1, At, B1); BAR;
;     LDA(At, 1, 1); STAGE(SA(1, 0), A, brow, t + 3);
;     BAR; WAIT_L(0); MMA(1, 0, At, B0); BAR; SCHED;
;     STAGE(SB(1, 1), Bt, bcol + HALF, t + 3);
;     WAIT_V(6); BAR; MMA(1, 1, At, B1); BAR;
;   }
	s_setprio 1
	s_waitcnt lgkmcnt(7)
	v_mfma_f32_16x16x32_bf16 v[126:129], v[186:189], v[156:159], v[126:129]
	v_mfma_f32_16x16x32_bf16 v[122:125], v[186:189], v[170:173], v[122:125]
	s_waitcnt lgkmcnt(5)
	v_mfma_f32_16x16x32_bf16 v[118:121], v[194:197], v[156:159], v[118:121]
	v_mfma_f32_16x16x32_bf16 v[114:117], v[194:197], v[170:173], v[114:117]
	s_waitcnt lgkmcnt(3)
	v_mfma_f32_16x16x32_bf16 v[110:113], v[202:205], v[156:159], v[110:113]
	v_mfma_f32_16x16x32_bf16 v[106:109], v[202:205], v[170:173], v[106:109]
	s_waitcnt lgkmcnt(1)
	v_mfma_f32_16x16x32_bf16 v[102:105], v[210:213], v[156:159], v[102:105]
	v_mfma_f32_16x16x32_bf16 v[98:101], v[210:213], v[170:173], v[98:101]
	v_mfma_f32_16x16x32_bf16 v[126:129], v[190:193], v[166:169], v[126:129]
	v_mfma_f32_16x16x32_bf16 v[122:125], v[190:193], v[174:177], v[122:125]
	v_mfma_f32_16x16x32_bf16 v[118:121], v[198:201], v[166:169], v[118:121]
	v_mfma_f32_16x16x32_bf16 v[114:117], v[198:201], v[174:177], v[114:117]
	v_mfma_f32_16x16x32_bf16 v[110:113], v[206:209], v[166:169], v[110:113]
	v_mfma_f32_16x16x32_bf16 v[106:109], v[206:209], v[174:177], v[106:109]
	s_waitcnt lgkmcnt(0)
	v_mfma_f32_16x16x32_bf16 v[102:105], v[214:217], v[166:169], v[102:105]
	v_mfma_f32_16x16x32_bf16 v[98:101], v[214:217], v[174:177], v[98:101]
	s_setprio 0
	s_barrier
	v_readfirstlane_b32 s28, v146
	s_add_i32 s27, s26, 0x180
	s_mov_b32 m0, s28
	v_readfirstlane_b32 s28, v147
	ds_read_b128 v[218:221], v144
	ds_read_b128 v[222:225], v144 offset:1024
	ds_read_b128 v[226:229], v144 offset:2048
	ds_read_b128 v[230:233], v144 offset:3072
	buffer_load_dwordx4 v32, s[76:79], s27 offen lds
	s_mov_b32 m0, s28
	s_nop 0
	buffer_load_dwordx4 v131, s[76:79], s27 offen lds
	s_barrier
	s_setprio 1
	s_waitcnt lgkmcnt(3)
	v_mfma_f32_16x16x32_bf16 v[94:97], v[186:189], v[218:221], v[94:97]
	s_waitcnt lgkmcnt(1)
	v_mfma_f32_16x16x32_bf16 v[90:93], v[186:189], v[226:229], v[90:93]
	v_mfma_f32_16x16x32_bf16 v[86:89], v[194:197], v[218:221], v[86:89]
	v_mfma_f32_16x16x32_bf16 v[82:85], v[194:197], v[226:229], v[82:85]
	v_mfma_f32_16x16x32_bf16 v[78:81], v[202:205], v[218:221], v[78:81]
	v_mfma_f32_16x16x32_bf16 v[74:77], v[202:205], v[226:229], v[74:77]
	v_mfma_f32_16x16x32_bf16 v[70:73], v[210:213], v[218:221], v[70:73]
	v_mfma_f32_16x16x32_bf16 v[66:69], v[210:213], v[226:229], v[66:69]
	v_mfma_f32_16x16x32_bf16 v[94:97], v[190:193], v[222:225], v[94:97]
	s_waitcnt lgkmcnt(0)
	v_mfma_f32_16x16x32_bf16 v[90:93], v[190:193], v[230:233], v[90:93]
	v_mfma_f32_16x16x32_bf16 v[86:89], v[198:201], v[222:225], v[86:89]
	v_mfma_f32_16x16x32_bf16 v[82:85], v[198:201], v[230:233], v[82:85]
	v_mfma_f32_16x16x32_bf16 v[78:81], v[206:209], v[222:225], v[78:81]
	v_mfma_f32_16x16x32_bf16 v[74:77], v[206:209], v[230:233], v[74:77]
	v_mfma_f32_16x16x32_bf16 v[70:73], v[214:217], v[222:225], v[70:73]
	v_mfma_f32_16x16x32_bf16 v[66:69], v[214:217], v[230:233], v[66:69]
	s_setprio 0
	v_readfirstlane_b32 s27, v148
	s_addk_i32 s25, 0x180
	s_mov_b32 m0, s27
	v_readfirstlane_b32 s27, v150
	s_barrier
	ds_read_b128 v[186:189], v143 offset:49152
	ds_read_b128 v[190:193], v143 offset:50176
	ds_read_b128 v[194:197], v142 offset:49152
	ds_read_b128 v[198:201], v142 offset:50176
	ds_read_b128 v[202:205], v141 offset:49152
	ds_read_b128 v[206:209], v141 offset:50176
	ds_read_b128 v[210:213], v140 offset:49152
	ds_read_b128 v[214:217], v140 offset:50176
	buffer_load_dwordx4 v32, s[8:11], s25 offen lds
	s_mov_b32 m0, s27
	s_nop 0
	buffer_load_dwordx4 v131, s[8:11], s25 offen lds
	s_barrier
	s_setprio 1
	s_waitcnt lgkmcnt(7)
	v_mfma_f32_16x16x32_bf16 v[62:65], v[186:189], v[156:159], v[62:65]
	v_mfma_f32_16x16x32_bf16 v[58:61], v[186:189], v[170:173], v[58:61]
	s_waitcnt lgkmcnt(5)
	v_mfma_f32_16x16x32_bf16 v[54:57], v[194:197], v[156:159], v[54:57]
	v_mfma_f32_16x16x32_bf16 v[50:53], v[194:197], v[170:173], v[50:53]
	s_waitcnt lgkmcnt(3)
	v_mfma_f32_16x16x32_bf16 v[46:49], v[202:205], v[156:159], v[46:49]
	v_mfma_f32_16x16x32_bf16 v[42:45], v[202:205], v[170:173], v[42:45]
	s_waitcnt lgkmcnt(1)
	v_mfma_f32_16x16x32_bf16 v[38:41], v[210:213], v[156:159], v[38:41]
	v_mfma_f32_16x16x32_bf16 v[34:37], v[210:213], v[170:173], v[34:37]
	v_mfma_f32_16x16x32_bf16 v[62:65], v[190:193], v[166:169], v[62:65]
	v_mfma_f32_16x16x32_bf16 v[58:61], v[190:193], v[174:177], v[58:61]
	v_mfma_f32_16x16x32_bf16 v[54:57], v[198:201], v[166:169], v[54:57]
	v_mfma_f32_16x16x32_bf16 v[50:53], v[198:201], v[174:177], v[50:53]
	v_mfma_f32_16x16x32_bf16 v[46:49], v[206:209], v[166:169], v[46:49]
	v_mfma_f32_16x16x32_bf16 v[42:45], v[206:209], v[174:177], v[42:45]
	s_waitcnt lgkmcnt(0)
	v_mfma_f32_16x16x32_bf16 v[38:41], v[214:217], v[166:169], v[38:41]
	v_mfma_f32_16x16x32_bf16 v[34:37], v[214:217], v[174:177], v[34:37]
	s_setprio 0
	s_barrier
	v_readfirstlane_b32 s25, v153
	s_add_i32 s26, s26, 0x40180
	s_mov_b32 m0, s25
	v_readfirstlane_b32 s25, v154
	buffer_load_dwordx4 v32, s[76:79], s26 offen lds
	s_mov_b32 m0, s25
	s_nop 0
	buffer_load_dwordx4 v131, s[76:79], s26 offen lds
	s_waitcnt vmcnt(6)
	s_barrier
	s_setprio 1
	v_mfma_f32_16x16x32_bf16 v[28:31], v[186:189], v[218:221], v[28:31]
	v_mfma_f32_16x16x32_bf16 v[24:27], v[186:189], v[226:229], v[24:27]
	v_mfma_f32_16x16x32_bf16 v[20:23], v[194:197], v[218:221], v[20:23]
	v_mfma_f32_16x16x32_bf16 v[16:19], v[194:197], v[226:229], v[16:19]
	v_mfma_f32_16x16x32_bf16 v[12:15], v[202:205], v[218:221], v[12:15]
	v_mfma_f32_16x16x32_bf16 v[8:11], v[202:205], v[226:229], v[8:11]
	v_mfma_f32_16x16x32_bf16 v[4:7], v[210:213], v[218:221], v[4:7]
	v_mfma_f32_16x16x32_bf16 v[0:3], v[210:213], v[226:229], v[0:3]
	v_mfma_f32_16x16x32_bf16 v[28:31], v[190:193], v[222:225], v[28:31]
	v_mfma_f32_16x16x32_bf16 v[24:27], v[190:193], v[230:233], v[24:27]
	v_mfma_f32_16x16x32_bf16 v[20:23], v[198:201], v[222:225], v[20:23]
	v_mfma_f32_16x16x32_bf16 v[16:19], v[198:201], v[230:233], v[16:19]
	v_mfma_f32_16x16x32_bf16 v[12:15], v[206:209], v[222:225], v[12:15]
	v_mfma_f32_16x16x32_bf16 v[8:11], v[206:209], v[230:233], v[8:11]
	v_mfma_f32_16x16x32_bf16 v[4:7], v[214:217], v[222:225], v[4:7]
	v_mfma_f32_16x16x32_bf16 v[0:3], v[214:217], v[230:233], v[0:3]
	s_setprio 0
	s_add_i32 s23, s23, 2
	s_addk_i32 s24, 0x100
	s_cmp_lt_u32 s23, 12
	s_barrier
	s_cbranch_scc1 .LBB0_1927
; #define STAGE(P, BASE, br, kt) do { int _so = ((br) * K + (kt) * BK) * 2; \
;     __builtin_amdgcn_raw_ptr_buffer_load_lds(rs_##BASE, (__attribute__((address_space(3))) void*)((char*)(P) + tx * 16), 16, voff0, _so, 0, 0); \
;     __builtin_amdgcn_raw_ptr_buffer_load_lds(rs_##BASE, (__attribute__((address_space(3))) void*)((char*)(P) + tx * 16 + 8192), 16, voff1, _so, 0, 0); } while (0)
; #define LDA(dst, b, h) _Pragma("unroll") for (int m = 0; m < 4; ++m) _Pragma("unroll") for (int k = 0; k < 2; ++k) \
;     dst[m][k] = *reinterpret_cast<const bf16x8*>((char*)SA(b, h) + lds_byte(wr * 64 + m * 16 + fr, k * 32 + fq * 8))
; #define LDB(dst, b, h) _Pragma("unroll") for (int n = 0; n < 2; ++n) _Pragma("unroll") for (int k = 0; k < 2; ++k) \
;     dst[n][k] = *reinterpret_cast<const bf16x8*>((char*)SB(b, h) + lds_byte(wc * 32 + n * 16 + fr, k * 32 + fq * 8))
; #define MMA(ai, bj, At, Bt_) do { __builtin_amdgcn_s_setprio(1); \
;     _Pragma("unroll") for (int m = 0; m < 4; ++m) _Pragma("unroll") for (int n = 0; n < 2; ++n) _Pragma("unroll") for (int k = 0; k < 2; ++k) \
;       acc[ai][bj][m][n] = __builtin_amdgcn_mfma_f32_16x16x32_bf16(At[m][k], Bt_[n][k], acc[ai][bj][m][n], 0, 0, 0); \
;     __builtin_amdgcn_s_setprio(0); } while (0)
; #define WAIT_V(n) asm volatile("s_waitcnt vmcnt(" #n ")" ::: "memory")
; #define WAIT_L(n) asm volatile("s_waitcnt lgkmcnt(" #n ")" ::: "memory")
; #define BAR __builtin_amdgcn_s_barrier()
; template <class Epi> ...
;     ...
;   { LDB(B0, 0, 0); LDA(At, 0, 0); STAGE(SA(1, 1), A, brow + HALF, nt - 1);
;     BAR; WAIT_L(0); MMA(0, 0, At, B0); BAR;
;     LDB(B1, 0, 1); BAR; WAIT_L(0); MMA(0, 1, At, B1); BAR;
;     LDA(At, 0, 1); WAIT_V(4); BAR; WAIT_L(0); MMA(1, 0, At, B0); MMA(1, 1, At, B1); BAR; }
.Lpx4:
	s_or_b32 s16, s17, 0x40780
	v_readfirstlane_b32 s17, v152
	s_mov_b32 s10, s78
	s_mov_b32 s11, s79
	s_mov_b32 m0, s17
	v_readfirstlane_b32 s17, v151
	ds_read_b128 v[156:159], v155
	ds_read_b128 v[166:169], v155 offset:1024
	ds_read_b128 v[170:173], v155 offset:2048
	ds_read_b128 v[174:177], v155 offset:3072
	ds_read_b128 v[186:189], v143
	ds_read_b128 v[190:193], v143 offset:1024
	ds_read_b128 v[194:197], v142
	ds_read_b128 v[198:201], v142 offset:1024
	ds_read_b128 v[202:205], v141
	ds_read_b128 v[206:209], v141 offset:1024
	ds_read_b128 v[210:213], v140
	ds_read_b128 v[214:217], v140 offset:1024
	buffer_load_dwordx4 v32, s[8:11], s16 offen lds
	s_mov_b32 m0, s17
	s_nop 0
	buffer_load_dwordx4 v131, s[8:11], s16 offen lds
	s_barrier
	s_setprio 1
	s_waitcnt lgkmcnt(7)
	v_mfma_f32_16x16x32_bf16 v[126:129], v[186:189], v[156:159], v[126:129]
	v_mfma_f32_16x16x32_bf16 v[122:125], v[186:189], v[170:173], v[122:125]
	s_waitcnt lgkmcnt(5)
	v_mfma_f32_16x16x32_bf16 v[118:121], v[194:197], v[156:159], v[118:121]
	v_mfma_f32_16x16x32_bf16 v[114:117], v[194:197], v[170:173], v[114:117]
	s_waitcnt lgkmcnt(3)
	v_mfma_f32_16x16x32_bf16 v[110:113], v[202:205], v[156:159], v[110:113]
	v_mfma_f32_16x16x32_bf16 v[106:109], v[202:205], v[170:173], v[106:109]
	s_waitcnt lgkmcnt(1)
	v_mfma_f32_16x16x32_bf16 v[102:105], v[210:213], v[156:159], v[102:105]
	v_mfma_f32_16x16x32_bf16 v[98:101], v[210:213], v[170:173], v[98:101]
	v_mfma_f32_16x16x32_bf16 v[126:129], v[190:193], v[166:169], v[126:129]
	v_mfma_f32_16x16x32_bf16 v[122:125], v[190:193], v[174:177], v[122:125]
	v_mfma_f32_16x16x32_bf16 v[118:121], v[198:201], v[166:169], v[118:121]
	v_mfma_f32_16x16x32_bf16 v[114:117], v[198:201], v[174:177], v[114:117]
	v_mfma_f32_16x16x32_bf16 v[110:113], v[206:209], v[166:169], v[110:113]
	v_mfma_f32_16x16x32_bf16 v[106:109], v[206:209], v[174:177], v[106:109]
	s_waitcnt lgkmcnt(0)
	v_mfma_f32_16x16x32_bf16 v[102:105], v[214:217], v[166:169], v[102:105]
	v_mfma_f32_16x16x32_bf16 v[98:101], v[214:217], v[174:177], v[98:101]
	s_setprio 0
	s_barrier
	ds_read_b128 v[150:153], v149
	ds_read_b128 v[218:221], v149 offset:1024
	ds_read_b128 v[222:225], v149 offset:2048
	ds_read_b128 v[146:149], v149 offset:3072
	s_barrier
	s_setprio 1
	s_waitcnt lgkmcnt(3)
	v_mfma_f32_16x16x32_bf16 v[78:81], v[202:205], v[150:153], v[78:81]
	s_waitcnt lgkmcnt(1)
	v_mfma_f32_16x16x32_bf16 v[74:77], v[202:205], v[222:225], v[74:77]
	v_mfma_f32_16x16x32_bf16 v[70:73], v[210:213], v[150:153], v[70:73]
	v_mfma_f32_16x16x32_bf16 v[66:69], v[210:213], v[222:225], v[66:69]
	v_mfma_f32_16x16x32_bf16 v[94:97], v[186:189], v[150:153], v[94:97]
	v_mfma_f32_16x16x32_bf16 v[90:93], v[186:189], v[222:225], v[90:93]
	v_mfma_f32_16x16x32_bf16 v[86:89], v[194:197], v[150:153], v[86:89]
	v_mfma_f32_16x16x32_bf16 v[82:85], v[194:197], v[222:225], v[82:85]
	v_mfma_f32_16x16x32_bf16 v[78:81], v[206:209], v[218:221], v[78:81]
	s_waitcnt lgkmcnt(0)
	v_mfma_f32_16x16x32_bf16 v[74:77], v[206:209], v[146:149], v[74:77]
	v_mfma_f32_16x16x32_bf16 v[70:73], v[214:217], v[218:221], v[70:73]
	v_mfma_f32_16x16x32_bf16 v[66:69], v[214:217], v[146:149], v[66:69]
	v_mfma_f32_16x16x32_bf16 v[226:229], v[190:193], v[218:221], v[94:97]
	v_mfma_f32_16x16x32_bf16 v[186:189], v[190:193], v[146:149], v[90:93]
	v_mfma_f32_16x16x32_bf16 v[190:193], v[198:201], v[218:221], v[86:89]
	v_mfma_f32_16x16x32_bf16 v[194:197], v[198:201], v[146:149], v[82:85]
	s_setprio 0
	s_barrier
	s_nop 0
	ds_read_b128 v[82:85], v143 offset:16384
	ds_read_b128 v[86:89], v143 offset:17408
	ds_read_b128 v[90:93], v142 offset:16384
	ds_read_b128 v[94:97], v142 offset:17408
	ds_read_b128 v[198:201], v141 offset:16384
	ds_read_b128 v[202:205], v141 offset:17408
	ds_read_b128 v[206:209], v140 offset:16384
	ds_read_b128 v[210:213], v140 offset:17408
	s_waitcnt vmcnt(4)
	s_barrier
	s_setprio 1
	s_waitcnt lgkmcnt(3)
	v_mfma_f32_16x16x32_bf16 v[46:49], v[198:201], v[156:159], v[46:49]
	v_mfma_f32_16x16x32_bf16 v[42:45], v[198:201], v[170:173], v[42:45]
	s_waitcnt lgkmcnt(1)
	v_mfma_f32_16x16x32_bf16 v[38:41], v[206:209], v[156:159], v[38:41]
	v_mfma_f32_16x16x32_bf16 v[34:37], v[206:209], v[170:173], v[34:37]
	v_mfma_f32_16x16x32_bf16 v[62:65], v[82:85], v[156:159], v[62:65]
	v_mfma_f32_16x16x32_bf16 v[58:61], v[82:85], v[170:173], v[58:61]
	v_mfma_f32_16x16x32_bf16 v[54:57], v[90:93], v[156:159], v[54:57]
	v_mfma_f32_16x16x32_bf16 v[50:53], v[90:93], v[170:173], v[50:53]
	v_mfma_f32_16x16x32_bf16 v[46:49], v[202:205], v[166:169], v[46:49]
	v_mfma_f32_16x16x32_bf16 v[42:45], v[202:205], v[174:177], v[42:45]
	s_waitcnt lgkmcnt(0)
	v_mfma_f32_16x16x32_bf16 v[38:41], v[210:213], v[166:169], v[38:41]
	v_mfma_f32_16x16x32_bf16 v[34:37], v[210:213], v[174:177], v[34:37]
	v_mfma_f32_16x16x32_bf16 v[214:217], v[86:89], v[166:169], v[62:65]
	v_mfma_f32_16x16x32_bf16 v[230:233], v[86:89], v[174:177], v[58:61]
	v_mfma_f32_16x16x32_bf16 v[234:237], v[94:97], v[166:169], v[54:57]
	v_mfma_f32_16x16x32_bf16 v[238:241], v[94:97], v[174:177], v[50:53]
	s_setprio 0
	s_setprio 1
	v_mfma_f32_16x16x32_bf16 v[0:3], v[206:209], v[222:225], v[0:3]
	v_mfma_f32_16x16x32_bf16 v[28:31], v[82:85], v[150:153], v[28:31]
	v_mfma_f32_16x16x32_bf16 v[24:27], v[82:85], v[222:225], v[24:27]
	v_mfma_f32_16x16x32_bf16 v[20:23], v[90:93], v[150:153], v[20:23]
	v_mfma_f32_16x16x32_bf16 v[16:19], v[90:93], v[222:225], v[16:19]
	v_mfma_f32_16x16x32_bf16 v[12:15], v[198:201], v[150:153], v[12:15]
	v_mfma_f32_16x16x32_bf16 v[8:11], v[198:201], v[222:225], v[8:11]
	v_mfma_f32_16x16x32_bf16 v[4:7], v[206:209], v[150:153], v[4:7]
	v_mfma_f32_16x16x32_bf16 v[0:3], v[210:213], v[146:149], v[0:3]
	v_mfma_f32_16x16x32_bf16 v[154:157], v[86:89], v[218:221], v[28:31]
	v_mfma_f32_16x16x32_bf16 v[158:161], v[86:89], v[146:149], v[24:27]
	v_mfma_f32_16x16x32_bf16 v[166:169], v[94:97], v[218:221], v[20:23]
	v_mfma_f32_16x16x32_bf16 v[170:173], v[94:97], v[146:149], v[16:19]
	v_mfma_f32_16x16x32_bf16 v[174:177], v[202:205], v[218:221], v[12:15]
	v_mfma_f32_16x16x32_bf16 v[198:201], v[202:205], v[146:149], v[8:11]
	v_mfma_f32_16x16x32_bf16 v[150:153], v[210:213], v[218:221], v[4:7]
	s_setprio 0
	s_barrier
; #define LDA(dst, b, h) _Pragma("unroll") for (int m = 0; m < 4; ++m) _Pragma("unroll") for (int k = 0; k < 2; ++k) \
;     dst[m][k] = *reinterpret_cast<const bf16x8*>((char*)SA(b, h) + lds_byte(wr * 64 + m * 16 + fr, k * 32 + fq * 8))
; #define LDB(dst, b, h) _Pragma("unroll") for (int n = 0; n < 2; ++n) _Pragma("unroll") for (int k = 0; k < 2; ++k) \
;     dst[n][k] = *reinterpret_cast<const bf16x8*>((char*)SB(b, h) + lds_byte(wc * 32 + n * 16 + fr, k * 32 + fq * 8))
; #define MMA(ai, bj, At, Bt_) do { __builtin_amdgcn_s_setprio(1); \
;     _Pragma("unroll") for (int m = 0; m < 4; ++m) _Pragma("unroll") for (int n = 0; n < 2; ++n) _Pragma("unroll") for (int k = 0; k < 2; ++k) \
;       acc[ai][bj][m][n] = __builtin_amdgcn_mfma_f32_16x16x32_bf16(At[m][k], Bt_[n][k], acc[ai][bj][m][n], 0, 0, 0); \
;     __builtin_amdgcn_s_setprio(0); } while (0)
; #define WAIT_V(n) asm volatile("s_waitcnt vmcnt(" #n ")" ::: "memory")
; #define WAIT_L(n) asm volatile("s_waitcnt lgkmcnt(" #n ")" ::: "memory")
; #define BAR __builtin_amdgcn_s_barrier()
; template <class Epi> ...
;     ...
;   { LDB(B0, 1, 0); LDA(At, 1, 0); WAIT_V(2); BAR; WAIT_L(0); MMA(0, 0, At, B0); BAR;
;     LDB(B1, 1, 1); WAIT_V(0); BAR; WAIT_L(0); MMA(0, 1, At, B1); BAR;
;     LDA(At, 1, 1); BAR; WAIT_L(0); MMA(1, 0, At, B0); MMA(1, 1, At, B1); BAR; }
;   if (wr == 0) BAR;
	s_nop 0
	ds_read_b128 v[4:7], v145
	ds_read_b128 v[8:11], v145 offset:1024
	ds_read_b128 v[12:15], v145 offset:2048
	ds_read_b128 v[146:149], v145 offset:3072
	ds_read_b128 v[16:19], v143 offset:32768
	ds_read_b128 v[20:23], v143 offset:33792
	ds_read_b128 v[24:27], v142 offset:32768
	ds_read_b128 v[50:53], v142 offset:33792
	ds_read_b128 v[202:205], v141 offset:32768
	ds_read_b128 v[206:209], v141 offset:33792
	ds_read_b128 v[210:213], v140 offset:32768
	ds_read_b128 v[218:221], v140 offset:33792
	s_waitcnt vmcnt(2)
	s_barrier
	s_setprio 1
	s_waitcnt lgkmcnt(7)
	v_mfma_f32_16x16x32_bf16 v[28:31], v[16:19], v[4:7], v[126:129]
	s_waitcnt lgkmcnt(6)
	v_mfma_f32_16x16x32_bf16 v[126:129], v[20:23], v[8:11], v[28:31]
	v_mfma_f32_16x16x32_bf16 v[28:31], v[16:19], v[12:15], v[122:125]
	v_mfma_f32_16x16x32_bf16 v[94:97], v[20:23], v[146:149], v[28:31]
	s_waitcnt lgkmcnt(5)
	v_mfma_f32_16x16x32_bf16 v[28:31], v[24:27], v[4:7], v[118:121]
	s_waitcnt lgkmcnt(4)
	v_mfma_f32_16x16x32_bf16 v[122:125], v[50:53], v[8:11], v[28:31]
	v_mfma_f32_16x16x32_bf16 v[28:31], v[24:27], v[12:15], v[114:117]
	v_mfma_f32_16x16x32_bf16 v[90:93], v[50:53], v[146:149], v[28:31]
	s_waitcnt lgkmcnt(3)
	v_mfma_f32_16x16x32_bf16 v[28:31], v[202:205], v[4:7], v[110:113]
	s_waitcnt lgkmcnt(2)
	v_mfma_f32_16x16x32_bf16 v[118:121], v[206:209], v[8:11], v[28:31]
	v_mfma_f32_16x16x32_bf16 v[28:31], v[202:205], v[12:15], v[106:109]
	v_mfma_f32_16x16x32_bf16 v[86:89], v[206:209], v[146:149], v[28:31]
	s_waitcnt lgkmcnt(1)
	v_mfma_f32_16x16x32_bf16 v[28:31], v[210:213], v[4:7], v[102:105]
	s_waitcnt lgkmcnt(0)
	v_mfma_f32_16x16x32_bf16 v[114:117], v[218:221], v[8:11], v[28:31]
	v_mfma_f32_16x16x32_bf16 v[28:31], v[210:213], v[12:15], v[98:101]
	v_mfma_f32_16x16x32_bf16 v[82:85], v[218:221], v[146:149], v[28:31]
	s_setprio 0
	s_barrier
	ds_read_b128 v[222:225], v144
	ds_read_b128 v[242:245], v144 offset:1024
	ds_read_b128 v[246:249], v144 offset:2048
	ds_read_b128 v[250:253], v144 offset:3072
	s_waitcnt vmcnt(0)
	s_barrier
	s_setprio 1
	s_waitcnt lgkmcnt(3)
	v_mfma_f32_16x16x32_bf16 v[28:31], v[16:19], v[222:225], v[226:229]
	s_waitcnt lgkmcnt(1)
	v_mfma_f32_16x16x32_bf16 v[16:19], v[16:19], v[246:249], v[186:189]
	v_mfma_f32_16x16x32_bf16 v[62:65], v[20:23], v[242:245], v[28:31]
	s_waitcnt lgkmcnt(0)
	v_mfma_f32_16x16x32_bf16 v[28:31], v[20:23], v[250:253], v[16:19]
	v_mfma_f32_16x16x32_bf16 v[16:19], v[24:27], v[222:225], v[190:193]
	v_mfma_f32_16x16x32_bf16 v[58:61], v[50:53], v[242:245], v[16:19]
	v_mfma_f32_16x16x32_bf16 v[16:19], v[24:27], v[246:249], v[194:197]
	v_mfma_f32_16x16x32_bf16 v[24:27], v[50:53], v[250:253], v[16:19]
	v_mfma_f32_16x16x32_bf16 v[16:19], v[202:205], v[222:225], v[78:81]
	v_mfma_f32_16x16x32_bf16 v[54:57], v[206:209], v[242:245], v[16:19]
	v_mfma_f32_16x16x32_bf16 v[16:19], v[202:205], v[246:249], v[74:77]
	v_mfma_f32_16x16x32_bf16 v[20:23], v[206:209], v[250:253], v[16:19]
	v_mfma_f32_16x16x32_bf16 v[16:19], v[210:213], v[222:225], v[70:73]
	v_mfma_f32_16x16x32_bf16 v[50:53], v[218:221], v[242:245], v[16:19]
	v_mfma_f32_16x16x32_bf16 v[16:19], v[210:213], v[246:249], v[66:69]
	v_mfma_f32_16x16x32_bf16 v[16:19], v[218:221], v[250:253], v[16:19]
	s_setprio 0
	s_barrier
	ds_read_b128 v[186:189], v143 offset:49152
	ds_read_b128 v[190:193], v143 offset:50176
	ds_read_b128 v[194:197], v142 offset:49152
	ds_read_b128 v[142:145], v142 offset:50176
	ds_read_b128 v[202:205], v141 offset:49152
	ds_read_b128 v[206:209], v141 offset:50176
	ds_read_b128 v[210:213], v140 offset:49152
	ds_read_b128 v[218:221], v140 offset:50176
	s_barrier
	s_setprio 1
	s_waitcnt lgkmcnt(7)
	v_mfma_f32_16x16x32_bf16 v[66:69], v[186:189], v[4:7], v[214:217]
	s_waitcnt lgkmcnt(6)
	v_mfma_f32_16x16x32_bf16 v[110:113], v[190:193], v[8:11], v[66:69]
	v_mfma_f32_16x16x32_bf16 v[66:69], v[186:189], v[12:15], v[230:233]
	v_mfma_f32_16x16x32_bf16 v[78:81], v[190:193], v[146:149], v[66:69]
	s_waitcnt lgkmcnt(5)
	v_mfma_f32_16x16x32_bf16 v[66:69], v[194:197], v[4:7], v[234:237]
	s_waitcnt lgkmcnt(3)
	v_mfma_f32_16x16x32_bf16 v[46:49], v[202:205], v[4:7], v[46:49]
	s_waitcnt lgkmcnt(1)
	v_mfma_f32_16x16x32_bf16 v[4:7], v[210:213], v[4:7], v[38:41]
	v_mfma_f32_16x16x32_bf16 v[106:109], v[142:145], v[8:11], v[66:69]
	v_mfma_f32_16x16x32_bf16 v[66:69], v[194:197], v[12:15], v[238:241]
	v_mfma_f32_16x16x32_bf16 v[42:45], v[202:205], v[12:15], v[42:45]
	s_waitcnt lgkmcnt(0)
	v_mfma_f32_16x16x32_bf16 v[98:101], v[218:221], v[8:11], v[4:7]
	v_mfma_f32_16x16x32_bf16 v[4:7], v[210:213], v[12:15], v[34:37]
	v_mfma_f32_16x16x32_bf16 v[74:77], v[142:145], v[146:149], v[66:69]
	v_mfma_f32_16x16x32_bf16 v[102:105], v[206:209], v[8:11], v[46:49]
	v_mfma_f32_16x16x32_bf16 v[70:73], v[206:209], v[146:149], v[42:45]
	v_mfma_f32_16x16x32_bf16 v[66:69], v[218:221], v[146:149], v[4:7]
	s_setprio 0
	s_setprio 1
	v_mfma_f32_16x16x32_bf16 v[4:7], v[186:189], v[222:225], v[154:157]
	v_mfma_f32_16x16x32_bf16 v[46:49], v[190:193], v[242:245], v[4:7]
	v_mfma_f32_16x16x32_bf16 v[4:7], v[186:189], v[246:249], v[158:161]
	v_mfma_f32_16x16x32_bf16 v[12:15], v[190:193], v[250:253], v[4:7]
	v_mfma_f32_16x16x32_bf16 v[4:7], v[194:197], v[222:225], v[166:169]
	v_mfma_f32_16x16x32_bf16 v[42:45], v[142:145], v[242:245], v[4:7]
	v_mfma_f32_16x16x32_bf16 v[4:7], v[194:197], v[246:249], v[170:173]
	v_mfma_f32_16x16x32_bf16 v[8:11], v[142:145], v[250:253], v[4:7]
	v_mfma_f32_16x16x32_bf16 v[4:7], v[202:205], v[222:225], v[174:177]
	v_mfma_f32_16x16x32_bf16 v[38:41], v[206:209], v[242:245], v[4:7]
	v_mfma_f32_16x16x32_bf16 v[4:7], v[202:205], v[246:249], v[198:201]
	v_mfma_f32_16x16x32_bf16 v[34:37], v[210:213], v[222:225], v[150:153]
	v_mfma_f32_16x16x32_bf16 v[0:3], v[210:213], v[246:249], v[0:3]
	v_mfma_f32_16x16x32_bf16 v[4:7], v[206:209], v[250:253], v[4:7]
	v_mfma_f32_16x16x32_bf16 v[34:37], v[218:221], v[242:245], v[34:37]
	v_mfma_f32_16x16x32_bf16 v[0:3], v[218:221], v[250:253], v[0:3]
	s_setprio 0
	v_cmp_gt_u32_e32 vcc, s59, v130
	s_barrier
	s_and_saveexec_b64 s[10:11], vcc
	s_cbranch_execz .LBB0_1930
	s_barrier

; #define STAGE(P, BASE, br, kt) do { int _so = ((br) * K + (kt) * BK) * 2; \
;     __builtin_amdgcn_raw_ptr_buffer_load_lds(rs_##BASE, (__attribute__((address_space(3))) void*)((char*)(P) + tx * 16), 16, voff0, _so, 0, 0); \
;     __builtin_amdgcn_raw_ptr_buffer_load_lds(rs_##BASE, (__attribute__((address_space(3))) void*)((char*)(P) + tx * 16 + 8192), 16, voff1, _so, 0, 0); } while (0)
; #define LDA(dst, b, h) _Pragma("unroll") for (int m = 0; m < 4; ++m) _Pragma("unroll") for (int k = 0; k < 2; ++k) \
;     dst[m][k] = *reinterpret_cast<const bf16x8*>((char*)SA(b, h) + lds_byte(wr * 64 + m * 16 + fr, k * 32 + fq * 8))
; #define LDB(dst, b, h) _Pragma("unroll") for (int n = 0; n < 2; ++n) _Pragma("unroll") for (int k = 0; k < 2; ++k) \
;     dst[n][k] = *reinterpret_cast<const bf16x8*>((char*)SB(b, h) + lds_byte(wc * 32 + n * 16 + fr, k * 32 + fq * 8))
; #define MMA(ai, bj, At, Bt_) do { __builtin_amdgcn_s_setprio(1); \
;     _Pragma("unroll") for (int m = 0; m < 4; ++m) _Pragma("unroll") for (int n = 0; n < 2; ++n) _Pragma("unroll") for (int k = 0; k < 2; ++k) \
;       acc[ai][bj][m][n] = __builtin_amdgcn_mfma_f32_16x16x32_bf16(At[m][k], Bt_[n][k], acc[ai][bj][m][n], 0, 0, 0); \
;     __builtin_amdgcn_s_setprio(0); } while (0)
; #define WAIT_V(n) asm volatile("s_waitcnt vmcnt(" #n ")" ::: "memory")
; #define WAIT_L(n) asm volatile("s_waitcnt lgkmcnt(" #n ")" ::: "memory")
; #define BAR __builtin_amdgcn_s_barrier()
; template <class Epi> ...
;     ...
;   { LDB(B0, 0, 0); LDA(At, 0, 0); STAGE(SA(1, 1), A, brow + HALF, nt - 1);
;     BAR; WAIT_L(0); MMA(0, 0, At, B0); BAR;
;     LDB(B1, 0, 1); BAR; WAIT_L(0); MMA(0, 1, At, B1); BAR;
;     LDA(At, 0, 1); WAIT_V(4); BAR; WAIT_L(0); MMA(1, 0, At, B0); MMA(1, 1, At, B1); BAR; }
.Lpx5:
	s_or_b32 s16, s17, 0x40780
	v_readfirstlane_b32 s17, v152
	s_mov_b32 s10, s78
	s_mov_b32 s11, s79
	s_mov_b32 m0, s17
	v_readfirstlane_b32 s17, v151
	ds_read_b128 v[156:159], v155
	ds_read_b128 v[166:169], v155 offset:1024
	ds_read_b128 v[170:173], v155 offset:2048
	ds_read_b128 v[174:177], v155 offset:3072
	ds_read_b128 v[186:189], v143
	ds_read_b128 v[190:193], v143 offset:1024
	ds_read_b128 v[194:197], v142
	ds_read_b128 v[198:201], v142 offset:1024
	ds_read_b128 v[202:205], v141
	ds_read_b128 v[206:209], v141 offset:1024
	ds_read_b128 v[210:213], v140
	ds_read_b128 v[214:217], v140 offset:1024
	buffer_load_dwordx4 v32, s[8:11], s16 offen lds
	s_mov_b32 m0, s17
	s_nop 0
	buffer_load_dwordx4 v131, s[8:11], s16 offen lds
	s_barrier
	s_setprio 1
	s_waitcnt lgkmcnt(7)
	v_mfma_f32_16x16x32_bf16 v[126:129], v[186:189], v[156:159], v[126:129]
	v_mfma_f32_16x16x32_bf16 v[122:125], v[186:189], v[170:173], v[122:125]
	s_waitcnt lgkmcnt(5)
	v_mfma_f32_16x16x32_bf16 v[118:121], v[194:197], v[156:159], v[118:121]
	v_mfma_f32_16x16x32_bf16 v[114:117], v[194:197], v[170:173], v[114:117]
	v_mfma_f32_16x16x32_bf16 v[126:129], v[190:193], v[166:169], v[126:129]
	v_mfma_f32_16x16x32_bf16 v[122:125], v[190:193], v[174:177], v[122:125]
	s_waitcnt lgkmcnt(4)
	v_mfma_f32_16x16x32_bf16 v[118:121], v[198:201], v[166:169], v[118:121]
	v_mfma_f32_16x16x32_bf16 v[114:117], v[198:201], v[174:177], v[114:117]
	s_waitcnt lgkmcnt(3)
	v_mfma_f32_16x16x32_bf16 v[110:113], v[202:205], v[156:159], v[110:113]
	v_mfma_f32_16x16x32_bf16 v[106:109], v[202:205], v[170:173], v[106:109]
	s_waitcnt lgkmcnt(1)
	v_mfma_f32_16x16x32_bf16 v[102:105], v[210:213], v[156:159], v[102:105]
	v_mfma_f32_16x16x32_bf16 v[98:101], v[210:213], v[170:173], v[98:101]
	v_mfma_f32_16x16x32_bf16 v[150:153], v[206:209], v[166:169], v[110:113]
	v_mfma_f32_16x16x32_bf16 v[218:221], v[206:209], v[174:177], v[106:109]
	s_waitcnt lgkmcnt(0)
	v_mfma_f32_16x16x32_bf16 v[222:225], v[214:217], v[166:169], v[102:105]
	v_mfma_f32_16x16x32_bf16 v[226:229], v[214:217], v[174:177], v[98:101]
	s_setprio 0
	s_barrier
	s_nop 0
	ds_read_b128 v[98:101], v149
	ds_read_b128 v[102:105], v149 offset:1024
	ds_read_b128 v[106:109], v149 offset:2048
	ds_read_b128 v[110:113], v149 offset:3072
	s_barrier
	s_setprio 1
	s_waitcnt lgkmcnt(3)
	v_mfma_f32_16x16x32_bf16 v[94:97], v[186:189], v[98:101], v[94:97]
	s_waitcnt lgkmcnt(1)
	v_mfma_f32_16x16x32_bf16 v[90:93], v[186:189], v[106:109], v[90:93]
	v_mfma_f32_16x16x32_bf16 v[86:89], v[194:197], v[98:101], v[86:89]
	v_mfma_f32_16x16x32_bf16 v[82:85], v[194:197], v[106:109], v[82:85]
	v_mfma_f32_16x16x32_bf16 v[94:97], v[190:193], v[102:105], v[94:97]
	s_waitcnt lgkmcnt(0)
	v_mfma_f32_16x16x32_bf16 v[90:93], v[190:193], v[110:113], v[90:93]
	v_mfma_f32_16x16x32_bf16 v[86:89], v[198:201], v[102:105], v[86:89]
	v_mfma_f32_16x16x32_bf16 v[82:85], v[198:201], v[110:113], v[82:85]
	v_mfma_f32_16x16x32_bf16 v[78:81], v[202:205], v[98:101], v[78:81]
	v_mfma_f32_16x16x32_bf16 v[74:77], v[202:205], v[106:109], v[74:77]
	v_mfma_f32_16x16x32_bf16 v[70:73], v[210:213], v[98:101], v[70:73]
	v_mfma_f32_16x16x32_bf16 v[66:69], v[210:213], v[106:109], v[66:69]
	v_mfma_f32_16x16x32_bf16 v[146:149], v[206:209], v[102:105], v[78:81]
	v_mfma_f32_16x16x32_bf16 v[186:189], v[206:209], v[110:113], v[74:77]
	v_mfma_f32_16x16x32_bf16 v[190:193], v[214:217], v[102:105], v[70:73]
	v_mfma_f32_16x16x32_bf16 v[194:197], v[214:217], v[110:113], v[66:69]
	s_setprio 0
	s_barrier
	s_nop 1
	ds_read_b128 v[66:69], v143 offset:16384
	ds_read_b128 v[70:73], v143 offset:17408
	ds_read_b128 v[74:77], v142 offset:16384
	ds_read_b128 v[78:81], v142 offset:17408
	ds_read_b128 v[198:201], v141 offset:16384
	ds_read_b128 v[202:205], v141 offset:17408
	ds_read_b128 v[206:209], v140 offset:16384
	ds_read_b128 v[210:213], v140 offset:17408
	s_waitcnt vmcnt(4)
	s_barrier
	s_setprio 1
	s_waitcnt lgkmcnt(7)
	v_mfma_f32_16x16x32_bf16 v[62:65], v[66:69], v[156:159], v[62:65]
	v_mfma_f32_16x16x32_bf16 v[58:61], v[66:69], v[170:173], v[58:61]
	s_waitcnt lgkmcnt(5)
	v_mfma_f32_16x16x32_bf16 v[54:57], v[74:77], v[156:159], v[54:57]
	v_mfma_f32_16x16x32_bf16 v[50:53], v[74:77], v[170:173], v[50:53]
	v_mfma_f32_16x16x32_bf16 v[62:65], v[70:73], v[166:169], v[62:65]
	v_mfma_f32_16x16x32_bf16 v[58:61], v[70:73], v[174:177], v[58:61]
	s_waitcnt lgkmcnt(4)
	v_mfma_f32_16x16x32_bf16 v[54:57], v[78:81], v[166:169], v[54:57]
	v_mfma_f32_16x16x32_bf16 v[50:53], v[78:81], v[174:177], v[50:53]
	s_waitcnt lgkmcnt(3)
	v_mfma_f32_16x16x32_bf16 v[46:49], v[198:201], v[156:159], v[46:49]
	v_mfma_f32_16x16x32_bf16 v[42:45], v[198:201], v[170:173], v[42:45]
	s_waitcnt lgkmcnt(1)
	v_mfma_f32_16x16x32_bf16 v[38:41], v[206:209], v[156:159], v[38:41]
	v_mfma_f32_16x16x32_bf16 v[34:37], v[206:209], v[170:173], v[34:37]
	v_mfma_f32_16x16x32_bf16 v[214:217], v[202:205], v[166:169], v[46:49]
	v_mfma_f32_16x16x32_bf16 v[230:233], v[202:205], v[174:177], v[42:45]
	s_waitcnt lgkmcnt(0)
	v_mfma_f32_16x16x32_bf16 v[154:157], v[210:213], v[166:169], v[38:41]
	v_mfma_f32_16x16x32_bf16 v[158:161], v[210:213], v[174:177], v[34:37]
	s_setprio 0
	s_setprio 1
	v_mfma_f32_16x16x32_bf16 v[28:31], v[66:69], v[98:101], v[28:31]
	v_mfma_f32_16x16x32_bf16 v[24:27], v[66:69], v[106:109], v[24:27]
	v_mfma_f32_16x16x32_bf16 v[20:23], v[74:77], v[98:101], v[20:23]
	v_mfma_f32_16x16x32_bf16 v[16:19], v[74:77], v[106:109], v[16:19]
	v_mfma_f32_16x16x32_bf16 v[28:31], v[70:73], v[102:105], v[28:31]
	v_mfma_f32_16x16x32_bf16 v[24:27], v[70:73], v[110:113], v[24:27]
	v_mfma_f32_16x16x32_bf16 v[20:23], v[78:81], v[102:105], v[20:23]
	v_mfma_f32_16x16x32_bf16 v[16:19], v[78:81], v[110:113], v[16:19]
	v_mfma_f32_16x16x32_bf16 v[12:15], v[198:201], v[98:101], v[12:15]
	v_mfma_f32_16x16x32_bf16 v[8:11], v[198:201], v[106:109], v[8:11]
	v_mfma_f32_16x16x32_bf16 v[4:7], v[206:209], v[98:101], v[4:7]
	v_mfma_f32_16x16x32_bf16 v[0:3], v[206:209], v[106:109], v[0:3]
	v_mfma_f32_16x16x32_bf16 v[166:169], v[202:205], v[102:105], v[12:15]
	v_mfma_f32_16x16x32_bf16 v[170:173], v[202:205], v[110:113], v[8:11]
	v_mfma_f32_16x16x32_bf16 v[174:177], v[210:213], v[102:105], v[4:7]
	v_mfma_f32_16x16x32_bf16 v[198:201], v[210:213], v[110:113], v[0:3]
	s_setprio 0
	s_barrier
; #define LDA(dst, b, h) _Pragma("unroll") for (int m = 0; m < 4; ++m) _Pragma("unroll") for (int k = 0; k < 2; ++k) \
;     dst[m][k] = *reinterpret_cast<const bf16x8*>((char*)SA(b, h) + lds_byte(wr * 64 + m * 16 + fr, k * 32 + fq * 8))
; #define LDB(dst, b, h) _Pragma("unroll") for (int n = 0; n < 2; ++n) _Pragma("unroll") for (int k = 0; k < 2; ++k) \
;     dst[n][k] = *reinterpret_cast<const bf16x8*>((char*)SB(b, h) + lds_byte(wc * 32 + n * 16 + fr, k * 32 + fq * 8))
; #define MMA(ai, bj, At, Bt_) do { __builtin_amdgcn_s_setprio(1); \
;     _Pragma("unroll") for (int m = 0; m < 4; ++m) _Pragma("unroll") for (int n = 0; n < 2; ++n) _Pragma("unroll") for (int k = 0; k < 2; ++k) \
;       acc[ai][bj][m][n] = __builtin_amdgcn_mfma_f32_16x16x32_bf16(At[m][k], Bt_[n][k], acc[ai][bj][m][n], 0, 0, 0); \
;     __builtin_amdgcn_s_setprio(0); } while (0)
; #define WAIT_V(n) asm volatile("s_waitcnt vmcnt(" #n ")" ::: "memory")
; #define WAIT_L(n) asm volatile("s_waitcnt lgkmcnt(" #n ")" ::: "memory")
; #define BAR __builtin_amdgcn_s_barrier()
; template <class Epi> ...
;     ...
;   { LDB(B0, 1, 0); LDA(At, 1, 0); WAIT_V(2); BAR; WAIT_L(0); MMA(0, 0, At, B0); BAR;
;     LDB(B1, 1, 1); WAIT_V(0); BAR; WAIT_L(0); MMA(0, 1, At, B1); BAR;
;     LDA(At, 1, 1); BAR; WAIT_L(0); MMA(1, 0, At, B0); MMA(1, 1, At, B1); BAR; }
;   if (wr == 0) BAR;
	ds_read_b128 v[202:205], v145
	ds_read_b128 v[206:209], v145 offset:1024
	ds_read_b128 v[210:213], v145 offset:2048
	ds_read_b128 v[234:237], v145 offset:3072
	ds_read_b128 v[0:3], v143 offset:32768
	ds_read_b128 v[4:7], v143 offset:33792
	ds_read_b128 v[8:11], v142 offset:32768
	ds_read_b128 v[34:37], v142 offset:33792
	ds_read_b128 v[238:241], v141 offset:32768
	ds_read_b128 v[242:245], v141 offset:33792
	ds_read_b128 v[246:249], v140 offset:32768
	ds_read_b128 v[250:253], v140 offset:33792
	s_waitcnt vmcnt(2)
	s_barrier
	s_setprio 1
	s_waitcnt lgkmcnt(7)
	v_mfma_f32_16x16x32_bf16 v[12:15], v[0:3], v[202:205], v[126:129]
	s_waitcnt lgkmcnt(6)
	v_mfma_f32_16x16x32_bf16 v[110:113], v[4:7], v[206:209], v[12:15]
	v_mfma_f32_16x16x32_bf16 v[12:15], v[0:3], v[210:213], v[122:125]
	v_mfma_f32_16x16x32_bf16 v[78:81], v[4:7], v[234:237], v[12:15]
	s_waitcnt lgkmcnt(5)
	v_mfma_f32_16x16x32_bf16 v[12:15], v[8:11], v[202:205], v[118:121]
	s_waitcnt lgkmcnt(4)
	v_mfma_f32_16x16x32_bf16 v[106:109], v[34:37], v[206:209], v[12:15]
	v_mfma_f32_16x16x32_bf16 v[12:15], v[8:11], v[210:213], v[114:117]
	v_mfma_f32_16x16x32_bf16 v[74:77], v[34:37], v[234:237], v[12:15]
	s_waitcnt lgkmcnt(3)
	v_mfma_f32_16x16x32_bf16 v[12:15], v[238:241], v[202:205], v[150:153]
	s_waitcnt lgkmcnt(2)
	v_mfma_f32_16x16x32_bf16 v[102:105], v[242:245], v[206:209], v[12:15]
	v_mfma_f32_16x16x32_bf16 v[12:15], v[238:241], v[210:213], v[218:221]
	v_mfma_f32_16x16x32_bf16 v[70:73], v[242:245], v[234:237], v[12:15]
	s_waitcnt lgkmcnt(1)
	v_mfma_f32_16x16x32_bf16 v[12:15], v[246:249], v[202:205], v[222:225]
	s_waitcnt lgkmcnt(0)
	v_mfma_f32_16x16x32_bf16 v[98:101], v[250:253], v[206:209], v[12:15]
	v_mfma_f32_16x16x32_bf16 v[12:15], v[246:249], v[210:213], v[226:229]
	v_mfma_f32_16x16x32_bf16 v[66:69], v[250:253], v[234:237], v[12:15]
	s_setprio 0
	s_barrier
	ds_read_b128 v[150:153], v144
	ds_read_b128 v[218:221], v144 offset:1024
	ds_read_b128 v[222:225], v144 offset:2048
	ds_read_b128 v[226:229], v144 offset:3072
	s_waitcnt vmcnt(0)
	s_barrier
	s_setprio 1
	s_waitcnt lgkmcnt(3)
	v_mfma_f32_16x16x32_bf16 v[12:15], v[0:3], v[150:153], v[94:97]
	s_waitcnt lgkmcnt(1)
	v_mfma_f32_16x16x32_bf16 v[0:3], v[0:3], v[222:225], v[90:93]
	v_mfma_f32_16x16x32_bf16 v[46:49], v[4:7], v[218:221], v[12:15]
	s_waitcnt lgkmcnt(0)
	v_mfma_f32_16x16x32_bf16 v[12:15], v[4:7], v[226:229], v[0:3]
	v_mfma_f32_16x16x32_bf16 v[0:3], v[8:11], v[150:153], v[86:89]
	v_mfma_f32_16x16x32_bf16 v[42:45], v[34:37], v[218:221], v[0:3]
	v_mfma_f32_16x16x32_bf16 v[0:3], v[8:11], v[222:225], v[82:85]
	v_mfma_f32_16x16x32_bf16 v[8:11], v[34:37], v[226:229], v[0:3]
	v_mfma_f32_16x16x32_bf16 v[0:3], v[238:241], v[150:153], v[146:149]
	v_mfma_f32_16x16x32_bf16 v[38:41], v[242:245], v[218:221], v[0:3]
	v_mfma_f32_16x16x32_bf16 v[0:3], v[238:241], v[222:225], v[186:189]
	v_mfma_f32_16x16x32_bf16 v[4:7], v[242:245], v[226:229], v[0:3]
	v_mfma_f32_16x16x32_bf16 v[0:3], v[246:249], v[150:153], v[190:193]
	v_mfma_f32_16x16x32_bf16 v[34:37], v[250:253], v[218:221], v[0:3]
	v_mfma_f32_16x16x32_bf16 v[0:3], v[246:249], v[222:225], v[194:197]
	v_mfma_f32_16x16x32_bf16 v[0:3], v[250:253], v[226:229], v[0:3]
	s_setprio 0
	s_barrier
	ds_read_b128 v[144:147], v143 offset:49152
	ds_read_b128 v[186:189], v143 offset:50176
	ds_read_b128 v[190:193], v142 offset:49152
	ds_read_b128 v[194:197], v142 offset:50176
	ds_read_b128 v[238:241], v141 offset:49152
	ds_read_b128 v[242:245], v141 offset:50176
	ds_read_b128 v[246:249], v140 offset:49152
	ds_read_b128 v[140:143], v140 offset:50176
	s_barrier
	s_setprio 1
	s_waitcnt lgkmcnt(5)
	v_mfma_f32_16x16x32_bf16 v[50:53], v[190:193], v[210:213], v[50:53]
	s_waitcnt lgkmcnt(4)
	v_mfma_f32_16x16x32_bf16 v[90:93], v[194:197], v[234:237], v[50:53]
	s_waitcnt lgkmcnt(3)
	v_mfma_f32_16x16x32_bf16 v[50:53], v[238:241], v[202:205], v[214:217]
	s_waitcnt lgkmcnt(2)
	v_mfma_f32_16x16x32_bf16 v[118:121], v[242:245], v[206:209], v[50:53]
	v_mfma_f32_16x16x32_bf16 v[50:53], v[238:241], v[210:213], v[230:233]
	v_mfma_f32_16x16x32_bf16 v[86:89], v[242:245], v[234:237], v[50:53]
	s_waitcnt lgkmcnt(1)
	v_mfma_f32_16x16x32_bf16 v[50:53], v[246:249], v[202:205], v[154:157]
	v_mfma_f32_16x16x32_bf16 v[62:65], v[144:147], v[202:205], v[62:65]
	v_mfma_f32_16x16x32_bf16 v[58:61], v[144:147], v[210:213], v[58:61]
	v_mfma_f32_16x16x32_bf16 v[54:57], v[190:193], v[202:205], v[54:57]
	s_waitcnt lgkmcnt(0)
	v_mfma_f32_16x16x32_bf16 v[114:117], v[140:143], v[206:209], v[50:53]
	v_mfma_f32_16x16x32_bf16 v[50:53], v[246:249], v[210:213], v[158:161]
	v_mfma_f32_16x16x32_bf16 v[126:129], v[186:189], v[206:209], v[62:65]
	v_mfma_f32_16x16x32_bf16 v[94:97], v[186:189], v[234:237], v[58:61]
	v_mfma_f32_16x16x32_bf16 v[122:125], v[194:197], v[206:209], v[54:57]
	v_mfma_f32_16x16x32_bf16 v[82:85], v[140:143], v[234:237], v[50:53]
	s_setprio 0
	s_setprio 1
	v_mfma_f32_16x16x32_bf16 v[28:31], v[144:147], v[150:153], v[28:31]
	v_mfma_f32_16x16x32_bf16 v[24:27], v[144:147], v[222:225], v[24:27]
	v_mfma_f32_16x16x32_bf16 v[16:19], v[190:193], v[222:225], v[16:19]
	v_mfma_f32_16x16x32_bf16 v[62:65], v[186:189], v[218:221], v[28:31]
	v_mfma_f32_16x16x32_bf16 v[28:31], v[186:189], v[226:229], v[24:27]
	v_mfma_f32_16x16x32_bf16 v[24:27], v[194:197], v[226:229], v[16:19]
	v_mfma_f32_16x16x32_bf16 v[16:19], v[238:241], v[150:153], v[166:169]
	v_mfma_f32_16x16x32_bf16 v[20:23], v[190:193], v[150:153], v[20:23]
	v_mfma_f32_16x16x32_bf16 v[54:57], v[242:245], v[218:221], v[16:19]
	v_mfma_f32_16x16x32_bf16 v[16:19], v[238:241], v[222:225], v[170:173]
	v_mfma_f32_16x16x32_bf16 v[58:61], v[194:197], v[218:221], v[20:23]
	v_mfma_f32_16x16x32_bf16 v[20:23], v[242:245], v[226:229], v[16:19]
	v_mfma_f32_16x16x32_bf16 v[16:19], v[246:249], v[150:153], v[174:177]
	v_mfma_f32_16x16x32_bf16 v[50:53], v[140:143], v[218:221], v[16:19]
	v_mfma_f32_16x16x32_bf16 v[16:19], v[246:249], v[222:225], v[198:201]
	v_mfma_f32_16x16x32_bf16 v[16:19], v[140:143], v[226:229], v[16:19]
	s_setprio 0
	v_cmp_gt_u32_e32 vcc, s59, v130
	s_barrier
	s_and_saveexec_b64 s[10:11], vcc
	s_cbranch_execz .LBB0_2021
	s_barrier

; #define STAGE(P, BASE, br, kt) do { int _so = ((br) * K + (kt) * BK) * 2; \
;     __builtin_amdgcn_raw_ptr_buffer_load_lds(rs_##BASE, (__attribute__((address_space(3))) void*)((char*)(P) + tx * 16), 16, voff0, _so, 0, 0); \
;     __builtin_amdgcn_raw_ptr_buffer_load_lds(rs_##BASE, (__attribute__((address_space(3))) void*)((char*)(P) + tx * 16 + 8192), 16, voff1, _so, 0, 0); } while (0)
; #define LDA(dst, b, h) _Pragma("unroll") for (int m = 0; m < 4; ++m) _Pragma("unroll") for (int k = 0; k < 2; ++k) \
;     dst[m][k] = *reinterpret_cast<const bf16x8*>((char*)SA(b, h) + lds_byte(wr * 64 + m * 16 + fr, k * 32 + fq * 8))
; #define LDB(dst, b, h) _Pragma("unroll") for (int n = 0; n < 2; ++n) _Pragma("unroll") for (int k = 0; k < 2; ++k) \
;     dst[n][k] = *reinterpret_cast<const bf16x8*>((char*)SB(b, h) + lds_byte(wc * 32 + n * 16 + fr, k * 32 + fq * 8))
; #define MMA(ai, bj, At, Bt_) do { __builtin_amdgcn_s_setprio(1); \
;     _Pragma("unroll") for (int m = 0; m < 4; ++m) _Pragma("unroll") for (int n = 0; n < 2; ++n) _Pragma("unroll") for (int k = 0; k < 2; ++k) \
;       acc[ai][bj][m][n] = __builtin_amdgcn_mfma_f32_16x16x32_bf16(At[m][k], Bt_[n][k], acc[ai][bj][m][n], 0, 0, 0); \
;     __builtin_amdgcn_s_setprio(0); } while (0)
; #define WAIT_V(n) asm volatile("s_waitcnt vmcnt(" #n ")" ::: "memory")
; #define WAIT_L(n) asm volatile("s_waitcnt lgkmcnt(" #n ")" ::: "memory")
; #define BAR __builtin_amdgcn_s_barrier()
; template <class Epi> ...
;     ...
;   { LDB(B0, 0, 0); LDA(At, 0, 0); STAGE(SA(1, 1), A, brow + HALF, nt - 1);
;     BAR; WAIT_L(0); MMA(0, 0, At, B0); BAR;
;     LDB(B1, 0, 1); BAR; WAIT_L(0); MMA(0, 1, At, B1); BAR;
;     LDA(At, 0, 1); WAIT_V(4); BAR; WAIT_L(0); MMA(1, 0, At, B0); MMA(1, 1, At, B1); BAR; }
.Lpx7:
	s_or_b32 s16, s17, 0x40780
	v_readfirstlane_b32 s17, v152
	s_mov_b32 s10, s78
	s_mov_b32 s11, s79
	s_mov_b32 m0, s17
	v_readfirstlane_b32 s17, v151
	ds_read_b128 v[156:159], v155
	ds_read_b128 v[166:169], v155 offset:1024
	ds_read_b128 v[170:173], v155 offset:2048
	ds_read_b128 v[174:177], v155 offset:3072
	ds_read_b128 v[186:189], v143
	ds_read_b128 v[190:193], v143 offset:1024
	ds_read_b128 v[194:197], v142
	ds_read_b128 v[198:201], v142 offset:1024
	ds_read_b128 v[202:205], v141
	ds_read_b128 v[206:209], v141 offset:1024
	ds_read_b128 v[210:213], v140
	ds_read_b128 v[214:217], v140 offset:1024
	buffer_load_dwordx4 v32, s[8:11], s16 offen lds
	s_mov_b32 m0, s17
	s_nop 0
	buffer_load_dwordx4 v131, s[8:11], s16 offen lds
	s_barrier
	s_setprio 1
	s_waitcnt lgkmcnt(7)
	v_mfma_f32_16x16x32_bf16 v[126:129], v[186:189], v[156:159], v[126:129]
	s_waitcnt lgkmcnt(5)
	v_mfma_f32_16x16x32_bf16 v[118:121], v[194:197], v[156:159], v[118:121]
	s_waitcnt lgkmcnt(3)
	v_mfma_f32_16x16x32_bf16 v[110:113], v[202:205], v[156:159], v[110:113]
	v_mfma_f32_16x16x32_bf16 v[106:109], v[202:205], v[170:173], v[106:109]
	s_waitcnt lgkmcnt(1)
	v_mfma_f32_16x16x32_bf16 v[102:105], v[210:213], v[156:159], v[102:105]
	v_mfma_f32_16x16x32_bf16 v[126:129], v[190:193], v[166:169], v[126:129]
	v_mfma_f32_16x16x32_bf16 v[122:125], v[186:189], v[170:173], v[122:125]
	v_mfma_f32_16x16x32_bf16 v[118:121], v[198:201], v[166:169], v[118:121]
	v_mfma_f32_16x16x32_bf16 v[114:117], v[194:197], v[170:173], v[114:117]
	v_mfma_f32_16x16x32_bf16 v[110:113], v[206:209], v[166:169], v[110:113]
	v_mfma_f32_16x16x32_bf16 v[106:109], v[206:209], v[174:177], v[106:109]
	s_waitcnt lgkmcnt(0)
	v_mfma_f32_16x16x32_bf16 v[102:105], v[214:217], v[166:169], v[102:105]
	v_mfma_f32_16x16x32_bf16 v[98:101], v[210:213], v[170:173], v[98:101]
	v_mfma_f32_16x16x32_bf16 v[150:153], v[190:193], v[174:177], v[122:125]
	v_mfma_f32_16x16x32_bf16 v[218:221], v[198:201], v[174:177], v[114:117]
	v_mfma_f32_16x16x32_bf16 v[222:225], v[214:217], v[174:177], v[98:101]
	s_setprio 0
	s_barrier
	s_nop 2
	ds_read_b128 v[98:101], v149
	ds_read_b128 v[114:117], v149 offset:1024
	ds_read_b128 v[122:125], v149 offset:2048
	ds_read_b128 v[146:149], v149 offset:3072
	s_barrier
	s_setprio 1
	s_waitcnt lgkmcnt(3)
	v_mfma_f32_16x16x32_bf16 v[94:97], v[186:189], v[98:101], v[94:97]
	s_waitcnt lgkmcnt(1)
	v_mfma_f32_16x16x32_bf16 v[82:85], v[194:197], v[122:125], v[82:85]
	v_mfma_f32_16x16x32_bf16 v[78:81], v[202:205], v[98:101], v[78:81]
	v_mfma_f32_16x16x32_bf16 v[70:73], v[210:213], v[98:101], v[70:73]
	v_mfma_f32_16x16x32_bf16 v[94:97], v[190:193], v[114:117], v[94:97]
	v_mfma_f32_16x16x32_bf16 v[90:93], v[186:189], v[122:125], v[90:93]
	v_mfma_f32_16x16x32_bf16 v[86:89], v[194:197], v[98:101], v[86:89]
	s_waitcnt lgkmcnt(0)
	v_mfma_f32_16x16x32_bf16 v[82:85], v[198:201], v[146:149], v[82:85]
	v_mfma_f32_16x16x32_bf16 v[78:81], v[206:209], v[114:117], v[78:81]
	v_mfma_f32_16x16x32_bf16 v[74:77], v[202:205], v[122:125], v[74:77]
	v_mfma_f32_16x16x32_bf16 v[70:73], v[214:217], v[114:117], v[70:73]
	v_mfma_f32_16x16x32_bf16 v[66:69], v[210:213], v[122:125], v[66:69]
	v_mfma_f32_16x16x32_bf16 v[186:189], v[190:193], v[146:149], v[90:93]
	v_mfma_f32_16x16x32_bf16 v[190:193], v[198:201], v[114:117], v[86:89]
	v_mfma_f32_16x16x32_bf16 v[194:197], v[206:209], v[146:149], v[74:77]
	v_mfma_f32_16x16x32_bf16 v[198:201], v[214:217], v[146:149], v[66:69]
	s_setprio 0
	s_barrier
	s_nop 1
	ds_read_b128 v[66:69], v143 offset:16384
	ds_read_b128 v[74:77], v143 offset:17408
	ds_read_b128 v[86:89], v142 offset:16384
	ds_read_b128 v[90:93], v142 offset:17408
	ds_read_b128 v[202:205], v141 offset:16384
	ds_read_b128 v[206:209], v141 offset:17408
	ds_read_b128 v[210:213], v140 offset:16384
	ds_read_b128 v[214:217], v140 offset:17408
	s_waitcnt vmcnt(4)
	s_barrier
	s_setprio 1
	s_waitcnt lgkmcnt(7)
	v_mfma_f32_16x16x32_bf16 v[58:61], v[66:69], v[170:173], v[58:61]
	s_waitcnt lgkmcnt(5)
	v_mfma_f32_16x16x32_bf16 v[54:57], v[86:89], v[156:159], v[54:57]
	s_waitcnt lgkmcnt(3)
	v_mfma_f32_16x16x32_bf16 v[46:49], v[202:205], v[156:159], v[46:49]
	s_waitcnt lgkmcnt(1)
	v_mfma_f32_16x16x32_bf16 v[38:41], v[210:213], v[156:159], v[38:41]
	v_mfma_f32_16x16x32_bf16 v[62:65], v[66:69], v[156:159], v[62:65]
	v_mfma_f32_16x16x32_bf16 v[58:61], v[74:77], v[174:177], v[58:61]
	v_mfma_f32_16x16x32_bf16 v[54:57], v[90:93], v[166:169], v[54:57]
	v_mfma_f32_16x16x32_bf16 v[50:53], v[86:89], v[170:173], v[50:53]
	v_mfma_f32_16x16x32_bf16 v[46:49], v[206:209], v[166:169], v[46:49]
	v_mfma_f32_16x16x32_bf16 v[42:45], v[202:205], v[170:173], v[42:45]
	s_waitcnt lgkmcnt(0)
	v_mfma_f32_16x16x32_bf16 v[38:41], v[214:217], v[166:169], v[38:41]
	v_mfma_f32_16x16x32_bf16 v[34:37], v[210:213], v[170:173], v[34:37]
	v_mfma_f32_16x16x32_bf16 v[226:229], v[74:77], v[166:169], v[62:65]
	v_mfma_f32_16x16x32_bf16 v[230:233], v[90:93], v[174:177], v[50:53]
	v_mfma_f32_16x16x32_bf16 v[234:237], v[206:209], v[174:177], v[42:45]
	v_mfma_f32_16x16x32_bf16 v[154:157], v[214:217], v[174:177], v[34:37]
	s_setprio 0
	s_setprio 1
	v_mfma_f32_16x16x32_bf16 v[28:31], v[66:69], v[98:101], v[28:31]
	v_mfma_f32_16x16x32_bf16 v[20:23], v[86:89], v[98:101], v[20:23]
	v_mfma_f32_16x16x32_bf16 v[12:15], v[202:205], v[98:101], v[12:15]
	v_mfma_f32_16x16x32_bf16 v[4:7], v[210:213], v[98:101], v[4:7]
	v_mfma_f32_16x16x32_bf16 v[28:31], v[74:77], v[114:117], v[28:31]
	v_mfma_f32_16x16x32_bf16 v[24:27], v[66:69], v[122:125], v[24:27]
	v_mfma_f32_16x16x32_bf16 v[20:23], v[90:93], v[114:117], v[20:23]
	v_mfma_f32_16x16x32_bf16 v[16:19], v[86:89], v[122:125], v[16:19]
	v_mfma_f32_16x16x32_bf16 v[12:15], v[206:209], v[114:117], v[12:15]
	v_mfma_f32_16x16x32_bf16 v[8:11], v[202:205], v[122:125], v[8:11]
	v_mfma_f32_16x16x32_bf16 v[4:7], v[214:217], v[114:117], v[4:7]
	v_mfma_f32_16x16x32_bf16 v[0:3], v[210:213], v[122:125], v[0:3]
	v_mfma_f32_16x16x32_bf16 v[158:161], v[74:77], v[146:149], v[24:27]
	v_mfma_f32_16x16x32_bf16 v[166:169], v[90:93], v[146:149], v[16:19]
	v_mfma_f32_16x16x32_bf16 v[170:173], v[206:209], v[146:149], v[8:11]
	v_mfma_f32_16x16x32_bf16 v[146:149], v[214:217], v[146:149], v[0:3]
	s_setprio 0
	s_barrier
; #define LDA(dst, b, h) _Pragma("unroll") for (int m = 0; m < 4; ++m) _Pragma("unroll") for (int k = 0; k < 2; ++k) \
;     dst[m][k] = *reinterpret_cast<const bf16x8*>((char*)SA(b, h) + lds_byte(wr * 64 + m * 16 + fr, k * 32 + fq * 8))
; #define LDB(dst, b, h) _Pragma("unroll") for (int n = 0; n < 2; ++n) _Pragma("unroll") for (int k = 0; k < 2; ++k) \
;     dst[n][k] = *reinterpret_cast<const bf16x8*>((char*)SB(b, h) + lds_byte(wc * 32 + n * 16 + fr, k * 32 + fq * 8))
; #define MMA(ai, bj, At, Bt_) do { __builtin_amdgcn_s_setprio(1); \
;     _Pragma("unroll") for (int m = 0; m < 4; ++m) _Pragma("unroll") for (int n = 0; n < 2; ++n) _Pragma("unroll") for (int k = 0; k < 2; ++k) \
;       acc[ai][bj][m][n] = __builtin_amdgcn_mfma_f32_16x16x32_bf16(At[m][k], Bt_[n][k], acc[ai][bj][m][n], 0, 0, 0); \
;     __builtin_amdgcn_s_setprio(0); } while (0)
; #define WAIT_V(n) asm volatile("s_waitcnt vmcnt(" #n ")" ::: "memory")
; #define WAIT_L(n) asm volatile("s_waitcnt lgkmcnt(" #n ")" ::: "memory")
; #define BAR __builtin_amdgcn_s_barrier()
; template <class Epi> ...
;     ...
;   { LDB(B0, 1, 0); LDA(At, 1, 0); WAIT_V(2); BAR; WAIT_L(0); MMA(0, 0, At, B0); BAR;
;     LDB(B1, 1, 1); WAIT_V(0); BAR; WAIT_L(0); MMA(0, 1, At, B1); BAR;
;     LDA(At, 1, 1); BAR; WAIT_L(0); MMA(1, 0, At, B0); MMA(1, 1, At, B1); BAR; }
;   if (wr == 0) BAR;
	ds_read_b128 v[174:177], v145
	ds_read_b128 v[202:205], v145 offset:1024
	ds_read_b128 v[206:209], v145 offset:2048
	ds_read_b128 v[210:213], v145 offset:3072
	ds_read_b128 v[0:3], v143 offset:32768
	ds_read_b128 v[8:11], v143 offset:33792
	ds_read_b128 v[16:19], v142 offset:32768
	ds_read_b128 v[34:37], v142 offset:33792
	ds_read_b128 v[214:217], v141 offset:32768
	ds_read_b128 v[238:241], v141 offset:33792
	ds_read_b128 v[242:245], v140 offset:32768
	ds_read_b128 v[246:249], v140 offset:33792
	s_waitcnt vmcnt(2)
	s_barrier
	s_setprio 1
	s_waitcnt lgkmcnt(7)
	v_mfma_f32_16x16x32_bf16 v[24:27], v[0:3], v[174:177], v[126:129]
	s_waitcnt lgkmcnt(6)
	v_mfma_f32_16x16x32_bf16 v[122:125], v[8:11], v[202:205], v[24:27]
	v_mfma_f32_16x16x32_bf16 v[24:27], v[0:3], v[206:209], v[150:153]
	v_mfma_f32_16x16x32_bf16 v[90:93], v[8:11], v[210:213], v[24:27]
	s_waitcnt lgkmcnt(5)
	v_mfma_f32_16x16x32_bf16 v[24:27], v[16:19], v[174:177], v[118:121]
	s_waitcnt lgkmcnt(4)
	v_mfma_f32_16x16x32_bf16 v[114:117], v[34:37], v[202:205], v[24:27]
	v_mfma_f32_16x16x32_bf16 v[24:27], v[16:19], v[206:209], v[218:221]
	v_mfma_f32_16x16x32_bf16 v[86:89], v[34:37], v[210:213], v[24:27]
	s_waitcnt lgkmcnt(3)
	v_mfma_f32_16x16x32_bf16 v[24:27], v[214:217], v[174:177], v[110:113]
	s_waitcnt lgkmcnt(2)
	v_mfma_f32_16x16x32_bf16 v[110:113], v[238:241], v[202:205], v[24:27]
	v_mfma_f32_16x16x32_bf16 v[24:27], v[214:217], v[206:209], v[106:109]
	v_mfma_f32_16x16x32_bf16 v[74:77], v[238:241], v[210:213], v[24:27]
	s_waitcnt lgkmcnt(1)
	v_mfma_f32_16x16x32_bf16 v[24:27], v[242:245], v[174:177], v[102:105]
	s_waitcnt lgkmcnt(0)
	v_mfma_f32_16x16x32_bf16 v[98:101], v[246:249], v[202:205], v[24:27]
	v_mfma_f32_16x16x32_bf16 v[24:27], v[242:245], v[206:209], v[222:225]
	v_mfma_f32_16x16x32_bf16 v[66:69], v[246:249], v[210:213], v[24:27]
	s_setprio 0
	s_barrier
	ds_read_b128 v[150:153], v144
	ds_read_b128 v[218:221], v144 offset:1024
	ds_read_b128 v[222:225], v144 offset:2048
	ds_read_b128 v[250:253], v144 offset:3072
	s_waitcnt vmcnt(0)
	s_barrier
	s_setprio 1
	s_waitcnt lgkmcnt(3)
	v_mfma_f32_16x16x32_bf16 v[24:27], v[0:3], v[150:153], v[94:97]
	s_waitcnt lgkmcnt(1)
	v_mfma_f32_16x16x32_bf16 v[0:3], v[0:3], v[222:225], v[186:189]
	v_mfma_f32_16x16x32_bf16 v[62:65], v[8:11], v[218:221], v[24:27]
	s_waitcnt lgkmcnt(0)
	v_mfma_f32_16x16x32_bf16 v[24:27], v[8:11], v[250:253], v[0:3]
	v_mfma_f32_16x16x32_bf16 v[0:3], v[16:19], v[150:153], v[190:193]
	v_mfma_f32_16x16x32_bf16 v[50:53], v[34:37], v[218:221], v[0:3]
	v_mfma_f32_16x16x32_bf16 v[0:3], v[16:19], v[222:225], v[82:85]
	v_mfma_f32_16x16x32_bf16 v[16:19], v[34:37], v[250:253], v[0:3]
	v_mfma_f32_16x16x32_bf16 v[0:3], v[214:217], v[150:153], v[78:81]
	v_mfma_f32_16x16x32_bf16 v[42:45], v[238:241], v[218:221], v[0:3]
	v_mfma_f32_16x16x32_bf16 v[0:3], v[214:217], v[222:225], v[194:197]
	v_mfma_f32_16x16x32_bf16 v[8:11], v[238:241], v[250:253], v[0:3]
	v_mfma_f32_16x16x32_bf16 v[0:3], v[242:245], v[150:153], v[70:73]
	v_mfma_f32_16x16x32_bf16 v[34:37], v[246:249], v[218:221], v[0:3]
	v_mfma_f32_16x16x32_bf16 v[0:3], v[242:245], v[222:225], v[198:201]
	v_mfma_f32_16x16x32_bf16 v[0:3], v[246:249], v[250:253], v[0:3]
	s_setprio 0
	s_barrier
	ds_read_b128 v[186:189], v143 offset:49152
	ds_read_b128 v[190:193], v143 offset:50176
	ds_read_b128 v[194:197], v142 offset:49152
	ds_read_b128 v[142:145], v142 offset:50176
	ds_read_b128 v[198:201], v141 offset:49152
	ds_read_b128 v[214:217], v141 offset:50176
	ds_read_b128 v[238:241], v140 offset:49152
	ds_read_b128 v[242:245], v140 offset:50176
	s_barrier
	s_setprio 1
	s_waitcnt lgkmcnt(5)
	v_mfma_f32_16x16x32_bf16 v[54:57], v[194:197], v[174:177], v[54:57]
	s_waitcnt lgkmcnt(3)
	v_mfma_f32_16x16x32_bf16 v[46:49], v[198:201], v[174:177], v[46:49]
	s_waitcnt lgkmcnt(1)
	v_mfma_f32_16x16x32_bf16 v[38:41], v[238:241], v[174:177], v[38:41]
	v_mfma_f32_16x16x32_bf16 v[70:73], v[186:189], v[174:177], v[226:229]
	v_mfma_f32_16x16x32_bf16 v[58:61], v[186:189], v[206:209], v[58:61]
	v_mfma_f32_16x16x32_bf16 v[118:121], v[142:145], v[202:205], v[54:57]
	v_mfma_f32_16x16x32_bf16 v[54:57], v[194:197], v[206:209], v[230:233]
	v_mfma_f32_16x16x32_bf16 v[106:109], v[214:217], v[202:205], v[46:49]
	v_mfma_f32_16x16x32_bf16 v[46:49], v[198:201], v[206:209], v[234:237]
	s_waitcnt lgkmcnt(0)
	v_mfma_f32_16x16x32_bf16 v[102:105], v[242:245], v[202:205], v[38:41]
	v_mfma_f32_16x16x32_bf16 v[38:41], v[238:241], v[206:209], v[154:157]
	v_mfma_f32_16x16x32_bf16 v[126:129], v[190:193], v[202:205], v[70:73]
	v_mfma_f32_16x16x32_bf16 v[94:97], v[190:193], v[210:213], v[58:61]
	v_mfma_f32_16x16x32_bf16 v[82:85], v[142:145], v[210:213], v[54:57]
	v_mfma_f32_16x16x32_bf16 v[78:81], v[214:217], v[210:213], v[46:49]
	v_mfma_f32_16x16x32_bf16 v[70:73], v[242:245], v[210:213], v[38:41]
	s_setprio 0
	s_setprio 1
	v_mfma_f32_16x16x32_bf16 v[28:31], v[186:189], v[150:153], v[28:31]
	v_mfma_f32_16x16x32_bf16 v[20:23], v[194:197], v[150:153], v[20:23]
	v_mfma_f32_16x16x32_bf16 v[12:15], v[198:201], v[150:153], v[12:15]
	v_mfma_f32_16x16x32_bf16 v[4:7], v[238:241], v[150:153], v[4:7]
	v_mfma_f32_16x16x32_bf16 v[58:61], v[190:193], v[218:221], v[28:31]
	v_mfma_f32_16x16x32_bf16 v[28:31], v[186:189], v[222:225], v[158:161]
	v_mfma_f32_16x16x32_bf16 v[54:57], v[142:145], v[218:221], v[20:23]
	v_mfma_f32_16x16x32_bf16 v[20:23], v[194:197], v[222:225], v[166:169]
	v_mfma_f32_16x16x32_bf16 v[46:49], v[214:217], v[218:221], v[12:15]
	v_mfma_f32_16x16x32_bf16 v[12:15], v[198:201], v[222:225], v[170:173]
	v_mfma_f32_16x16x32_bf16 v[38:41], v[242:245], v[218:221], v[4:7]
	v_mfma_f32_16x16x32_bf16 v[4:7], v[238:241], v[222:225], v[146:149]
	v_mfma_f32_16x16x32_bf16 v[28:31], v[190:193], v[250:253], v[28:31]
	v_mfma_f32_16x16x32_bf16 v[20:23], v[142:145], v[250:253], v[20:23]
	v_mfma_f32_16x16x32_bf16 v[12:15], v[214:217], v[250:253], v[12:15]
	v_mfma_f32_16x16x32_bf16 v[4:7], v[242:245], v[250:253], v[4:7]
	s_setprio 0
	v_cmp_gt_u32_e32 vcc, s59, v130
	s_barrier
	s_and_saveexec_b64 s[10:11], vcc
	s_cbranch_execz .LBB0_2256
	s_barrier

; #define STAGE(P, BASE, br, kt) do { int _so = ((br) * K + (kt) * BK) * 2; \
;     __builtin_amdgcn_raw_ptr_buffer_load_lds(rs_##BASE, (__attribute__((address_space(3))) void*)((char*)(P) + tx * 16), 16, voff0, _so, 0, 0); \
;     __builtin_amdgcn_raw_ptr_buffer_load_lds(rs_##BASE, (__attribute__((address_space(3))) void*)((char*)(P) + tx * 16 + 8192), 16, voff1, _so, 0, 0); } while (0)
; #define LDA(dst, b, h) _Pragma("unroll") for (int m = 0; m < 4; ++m) _Pragma("unroll") for (int k = 0; k < 2; ++k) \
;     dst[m][k] = *reinterpret_cast<const bf16x8*>((char*)SA(b, h) + lds_byte(wr * 64 + m * 16 + fr, k * 32 + fq * 8))
; #define LDB(dst, b, h) _Pragma("unroll") for (int n = 0; n < 2; ++n) _Pragma("unroll") for (int k = 0; k < 2; ++k) \
;     dst[n][k] = *reinterpret_cast<const bf16x8*>((char*)SB(b, h) + lds_byte(wc * 32 + n * 16 + fr, k * 32 + fq * 8))
; #define MMA(ai, bj, At, Bt_) do { __builtin_amdgcn_s_setprio(1); \
;     _Pragma("unroll") for (int m = 0; m < 4; ++m) _Pragma("unroll") for (int n = 0; n < 2; ++n) _Pragma("unroll") for (int k = 0; k < 2; ++k) \
;       acc[ai][bj][m][n] = __builtin_amdgcn_mfma_f32_16x16x32_bf16(At[m][k], Bt_[n][k], acc[ai][bj][m][n], 0, 0, 0); \
;     __builtin_amdgcn_s_setprio(0); } while (0)
; #define WAIT_V(n) asm volatile("s_waitcnt vmcnt(" #n ")" ::: "memory")
; #define WAIT_L(n) asm volatile("s_waitcnt lgkmcnt(" #n ")" ::: "memory")
; #define BAR __builtin_amdgcn_s_barrier()
; #define SCHED __builtin_amdgcn_sched_barrier(0)
; template <class Epi> ...
;     ...
;   for (int t = 0; t < nt - 2; t += 2) {
;     LDB(B0, 0, 0); SCHED; LDA(At, 0, 0); STAGE(SA(1, 1), A, brow + HALF, t + 1);
;     WAIT_L(8); BAR; WAIT_L(0); MMA(0, 0, At, B0); BAR; SCHED;
;     LDB(B1, 0, 1); STAGE(SB(0, 0), Bt, bcol, t + 2);
;     BAR; WAIT_L(0); MMA(0, 1, At, B1); BAR;
;     LDA(At, 0, 1); STAGE(SA(0, 0), A, brow, t + 2);
;     BAR; WAIT_L(0); MMA(1, 0, At, B0); BAR; SCHED;
;     STAGE(SB(0, 1), Bt, bcol + HALF, t + 2);
;     WAIT_V(6); BAR; MMA(1, 1, At, B1); BAR;
.Lpk8:
	ds_read_b128 v[156:159], v155
	ds_read_b128 v[166:169], v155 offset:1024
	ds_read_b128 v[170:173], v155 offset:2048
	ds_read_b128 v[174:177], v155 offset:3072
	s_add_i32 s23, s21, s15
	v_readfirstlane_b32 s25, v152
	s_add_i32 s24, s23, 0xb0080
	s_mov_b32 m0, s25
	v_readfirstlane_b32 s25, v151
	ds_read_b128 v[186:189], v143
	ds_read_b128 v[190:193], v143 offset:1024
	ds_read_b128 v[194:197], v142
	ds_read_b128 v[198:201], v142 offset:1024
	ds_read_b128 v[202:205], v141
	ds_read_b128 v[206:209], v141 offset:1024
	ds_read_b128 v[210:213], v140
	ds_read_b128 v[214:217], v140 offset:1024
	buffer_load_dwordx4 v32, s[4:7], s24 offen lds
	s_mov_b32 m0, s25
	s_nop 0
	buffer_load_dwordx4 v131, s[4:7], s24 offen lds
	s_waitcnt lgkmcnt(8)
	s_barrier
	s_setprio 1
	s_waitcnt lgkmcnt(7)
	v_mfma_f32_16x16x32_bf16 v[126:129], v[186:189], v[156:159], 0
	v_mfma_f32_16x16x32_bf16 v[122:125], v[186:189], v[170:173], 0
	s_waitcnt lgkmcnt(5)
	v_mfma_f32_16x16x32_bf16 v[118:121], v[194:197], v[156:159], 0
	v_mfma_f32_16x16x32_bf16 v[114:117], v[194:197], v[170:173], 0
	s_waitcnt lgkmcnt(3)
	v_mfma_f32_16x16x32_bf16 v[110:113], v[202:205], v[156:159], 0
	v_mfma_f32_16x16x32_bf16 v[106:109], v[202:205], v[170:173], 0
	s_waitcnt lgkmcnt(1)
	v_mfma_f32_16x16x32_bf16 v[102:105], v[210:213], v[156:159], 0
	v_mfma_f32_16x16x32_bf16 v[98:101], v[210:213], v[170:173], 0
	v_mfma_f32_16x16x32_bf16 v[126:129], v[190:193], v[166:169], v[126:129]
	v_mfma_f32_16x16x32_bf16 v[122:125], v[190:193], v[174:177], v[122:125]
	v_mfma_f32_16x16x32_bf16 v[118:121], v[198:201], v[166:169], v[118:121]
	v_mfma_f32_16x16x32_bf16 v[114:117], v[198:201], v[174:177], v[114:117]
	v_mfma_f32_16x16x32_bf16 v[110:113], v[206:209], v[166:169], v[110:113]
	v_mfma_f32_16x16x32_bf16 v[106:109], v[206:209], v[174:177], v[106:109]
	s_waitcnt lgkmcnt(0)
	v_mfma_f32_16x16x32_bf16 v[102:105], v[214:217], v[166:169], v[102:105]
	v_mfma_f32_16x16x32_bf16 v[98:101], v[214:217], v[174:177], v[98:101]
	s_setprio 0
	s_barrier
	s_add_i32 s24, s22, s15
	v_readfirstlane_b32 s26, v137
	s_add_i32 s25, s24, 0x100
	s_mov_b32 m0, s26
	v_readfirstlane_b32 s26, v139
	ds_read_b128 v[218:221], v149
	ds_read_b128 v[222:225], v149 offset:1024
	ds_read_b128 v[226:229], v149 offset:2048
	ds_read_b128 v[230:233], v149 offset:3072
	buffer_load_dwordx4 v32, s[76:79], s25 offen lds
	s_mov_b32 m0, s26
	s_nop 0
	buffer_load_dwordx4 v131, s[76:79], s25 offen lds
	s_barrier
	s_setprio 1
	s_waitcnt lgkmcnt(3)
	v_mfma_f32_16x16x32_bf16 v[94:97], v[186:189], v[218:221], 0
	s_waitcnt lgkmcnt(1)
	v_mfma_f32_16x16x32_bf16 v[90:93], v[186:189], v[226:229], 0
	v_mfma_f32_16x16x32_bf16 v[86:89], v[194:197], v[218:221], 0
	v_mfma_f32_16x16x32_bf16 v[82:85], v[194:197], v[226:229], 0
	v_mfma_f32_16x16x32_bf16 v[78:81], v[202:205], v[218:221], 0
	v_mfma_f32_16x16x32_bf16 v[74:77], v[202:205], v[226:229], 0
	v_mfma_f32_16x16x32_bf16 v[70:73], v[210:213], v[218:221], 0
	v_mfma_f32_16x16x32_bf16 v[66:69], v[210:213], v[226:229], 0
	v_mfma_f32_16x16x32_bf16 v[94:97], v[190:193], v[222:225], v[94:97]
	s_waitcnt lgkmcnt(0)
	v_mfma_f32_16x16x32_bf16 v[90:93], v[190:193], v[230:233], v[90:93]
	v_mfma_f32_16x16x32_bf16 v[86:89], v[198:201], v[222:225], v[86:89]
	v_mfma_f32_16x16x32_bf16 v[82:85], v[198:201], v[230:233], v[82:85]
	v_mfma_f32_16x16x32_bf16 v[78:81], v[206:209], v[222:225], v[78:81]
	v_mfma_f32_16x16x32_bf16 v[74:77], v[206:209], v[230:233], v[74:77]
	v_mfma_f32_16x16x32_bf16 v[70:73], v[214:217], v[222:225], v[70:73]
	v_mfma_f32_16x16x32_bf16 v[66:69], v[214:217], v[230:233], v[66:69]
	s_setprio 0
	v_readfirstlane_b32 s26, v136
	s_add_i32 s25, s23, 0x100
	s_mov_b32 m0, s26
	v_readfirstlane_b32 s26, v135
	s_barrier
	ds_read_b128 v[186:189], v143 offset:16384
	ds_read_b128 v[190:193], v143 offset:17408
	ds_read_b128 v[194:197], v142 offset:16384
	ds_read_b128 v[198:201], v142 offset:17408
	ds_read_b128 v[202:205], v141 offset:16384
	ds_read_b128 v[206:209], v141 offset:17408
	ds_read_b128 v[210:213], v140 offset:16384
	ds_read_b128 v[214:217], v140 offset:17408
	buffer_load_dwordx4 v32, s[4:7], s25 offen lds
	s_mov_b32 m0, s26
	s_nop 0
	buffer_load_dwordx4 v131, s[4:7], s25 offen lds
	s_barrier
	s_setprio 1
	s_waitcnt lgkmcnt(7)
	v_mfma_f32_16x16x32_bf16 v[62:65], v[186:189], v[156:159], 0
	v_mfma_f32_16x16x32_bf16 v[58:61], v[186:189], v[170:173], 0
	s_waitcnt lgkmcnt(5)
	v_mfma_f32_16x16x32_bf16 v[54:57], v[194:197], v[156:159], 0
	v_mfma_f32_16x16x32_bf16 v[50:53], v[194:197], v[170:173], 0
	s_waitcnt lgkmcnt(3)
	v_mfma_f32_16x16x32_bf16 v[46:49], v[202:205], v[156:159], 0
	v_mfma_f32_16x16x32_bf16 v[42:45], v[202:205], v[170:173], 0
	s_waitcnt lgkmcnt(1)
	v_mfma_f32_16x16x32_bf16 v[38:41], v[210:213], v[156:159], 0
	v_mfma_f32_16x16x32_bf16 v[34:37], v[210:213], v[170:173], 0
	v_mfma_f32_16x16x32_bf16 v[62:65], v[190:193], v[166:169], v[62:65]
	v_mfma_f32_16x16x32_bf16 v[58:61], v[190:193], v[174:177], v[58:61]
	v_mfma_f32_16x16x32_bf16 v[54:57], v[198:201], v[166:169], v[54:57]
	v_mfma_f32_16x16x32_bf16 v[50:53], v[198:201], v[174:177], v[50:53]
	v_mfma_f32_16x16x32_bf16 v[46:49], v[206:209], v[166:169], v[46:49]
	v_mfma_f32_16x16x32_bf16 v[42:45], v[206:209], v[174:177], v[42:45]
	s_waitcnt lgkmcnt(0)
	v_mfma_f32_16x16x32_bf16 v[38:41], v[214:217], v[166:169], v[38:41]
	v_mfma_f32_16x16x32_bf16 v[34:37], v[214:217], v[174:177], v[34:37]
	s_setprio 0
	s_barrier
	v_readfirstlane_b32 s26, v134
	s_add_i32 s25, s24, 0xb0100
	s_mov_b32 m0, s26
	v_readfirstlane_b32 s26, v138
	buffer_load_dwordx4 v32, s[76:79], s25 offen lds
	s_mov_b32 m0, s26
	s_nop 0
	buffer_load_dwordx4 v131, s[76:79], s25 offen lds
	s_waitcnt vmcnt(6)
	s_barrier
; #define STAGE(P, BASE, br, kt) do { int _so = ((br) * K + (kt) * BK) * 2; \
;     __builtin_amdgcn_raw_ptr_buffer_load_lds(rs_##BASE, (__attribute__((address_space(3))) void*)((char*)(P) + tx * 16), 16, voff0, _so, 0, 0); \
;     __builtin_amdgcn_raw_ptr_buffer_load_lds(rs_##BASE, (__attribute__((address_space(3))) void*)((char*)(P) + tx * 16 + 8192), 16, voff1, _so, 0, 0); } while (0)
; #define LDA(dst, b, h) _Pragma("unroll") for (int m = 0; m < 4; ++m) _Pragma("unroll") for (int k = 0; k < 2; ++k) \
;     dst[m][k] = *reinterpret_cast<const bf16x8*>((char*)SA(b, h) + lds_byte(wr * 64 + m * 16 + fr, k * 32 + fq * 8))
; #define LDB(dst, b, h) _Pragma("unroll") for (int n = 0; n < 2; ++n) _Pragma("unroll") for (int k = 0; k < 2; ++k) \
;     dst[n][k] = *reinterpret_cast<const bf16x8*>((char*)SB(b, h) + lds_byte(wc * 32 + n * 16 + fr, k * 32 + fq * 8))
; #define MMA(ai, bj, At, Bt_) do { __builtin_amdgcn_s_setprio(1); \
;     _Pragma("unroll") for (int m = 0; m < 4; ++m) _Pragma("unroll") for (int n = 0; n < 2; ++n) _Pragma("unroll") for (int k = 0; k < 2; ++k) \
;       acc[ai][bj][m][n] = __builtin_amdgcn_mfma_f32_16x16x32_bf16(At[m][k], Bt_[n][k], acc[ai][bj][m][n], 0, 0, 0); \
;     __builtin_amdgcn_s_setprio(0); } while (0)
; #define WAIT_V(n) asm volatile("s_waitcnt vmcnt(" #n ")" ::: "memory")
; #define WAIT_L(n) asm volatile("s_waitcnt lgkmcnt(" #n ")" ::: "memory")
; #define BAR __builtin_amdgcn_s_barrier()
; #define SCHED __builtin_amdgcn_sched_barrier(0)
; template <class Epi> ...
;     ...
;     WAIT_V(6); BAR; MMA(1, 1, At, B1); BAR;
;     LDB(B0, 1, 0); SCHED; LDA(At, 1, 0); STAGE(SA(0, 1), A, brow + HALF, t + 2);
;     WAIT_L(8); BAR; WAIT_L(0); MMA(0, 0, At, B0); BAR; SCHED;
;     LDB(B1, 1, 1); STAGE(SB(1, 0), Bt, bcol, t + 3);
;     BAR; WAIT_L(0); MMA(0, 1, At, B1); BAR;
;     LDA(At, 1, 1); STAGE(SA(1, 0), A, brow, t + 3);
;     BAR; WAIT_L(0); MMA(1, 0, At, B0); BAR; SCHED;
;     STAGE(SB(1, 1), Bt, bcol + HALF, t + 3);
;     WAIT_V(6); BAR; MMA(1, 1, At, B1); BAR;
	s_setprio 1
	v_mfma_f32_16x16x32_bf16 v[28:31], v[186:189], v[218:221], 0
	v_mfma_f32_16x16x32_bf16 v[24:27], v[186:189], v[226:229], 0
	v_mfma_f32_16x16x32_bf16 v[20:23], v[194:197], v[218:221], 0
	v_mfma_f32_16x16x32_bf16 v[16:19], v[194:197], v[226:229], 0
	v_mfma_f32_16x16x32_bf16 v[12:15], v[202:205], v[218:221], 0
	v_mfma_f32_16x16x32_bf16 v[8:11], v[202:205], v[226:229], 0
	v_mfma_f32_16x16x32_bf16 v[4:7], v[210:213], v[218:221], 0
	v_mfma_f32_16x16x32_bf16 v[0:3], v[210:213], v[226:229], 0
	v_mfma_f32_16x16x32_bf16 v[28:31], v[190:193], v[222:225], v[28:31]
	v_mfma_f32_16x16x32_bf16 v[24:27], v[190:193], v[230:233], v[24:27]
	v_mfma_f32_16x16x32_bf16 v[20:23], v[198:201], v[222:225], v[20:23]
	v_mfma_f32_16x16x32_bf16 v[16:19], v[198:201], v[230:233], v[16:19]
	v_mfma_f32_16x16x32_bf16 v[12:15], v[206:209], v[222:225], v[12:15]
	v_mfma_f32_16x16x32_bf16 v[8:11], v[206:209], v[230:233], v[8:11]
	v_mfma_f32_16x16x32_bf16 v[4:7], v[214:217], v[222:225], v[4:7]
	v_mfma_f32_16x16x32_bf16 v[0:3], v[214:217], v[230:233], v[0:3]
	s_setprio 0
	s_barrier
	ds_read_b128 v[156:159], v145
	ds_read_b128 v[166:169], v145 offset:1024
	ds_read_b128 v[170:173], v145 offset:2048
	ds_read_b128 v[174:177], v145 offset:3072
	v_readfirstlane_b32 s26, v133
	s_add_i32 s25, s23, 0xb0100
	s_mov_b32 m0, s26
	v_readfirstlane_b32 s26, v132
	ds_read_b128 v[186:189], v143 offset:32768
	ds_read_b128 v[190:193], v143 offset:33792
	ds_read_b128 v[194:197], v142 offset:32768
	ds_read_b128 v[198:201], v142 offset:33792
	ds_read_b128 v[202:205], v141 offset:32768
	ds_read_b128 v[206:209], v141 offset:33792
	ds_read_b128 v[210:213], v140 offset:32768
	ds_read_b128 v[214:217], v140 offset:33792
	buffer_load_dwordx4 v32, s[4:7], s25 offen lds
	s_mov_b32 m0, s26
	s_nop 0
	buffer_load_dwordx4 v131, s[4:7], s25 offen lds
	s_waitcnt lgkmcnt(8)
	s_barrier
	s_setprio 1
	s_waitcnt lgkmcnt(7)
	v_mfma_f32_16x16x32_bf16 v[126:129], v[186:189], v[156:159], v[126:129]
	v_mfma_f32_16x16x32_bf16 v[122:125], v[186:189], v[170:173], v[122:125]
	s_waitcnt lgkmcnt(5)
	v_mfma_f32_16x16x32_bf16 v[118:121], v[194:197], v[156:159], v[118:121]
	v_mfma_f32_16x16x32_bf16 v[114:117], v[194:197], v[170:173], v[114:117]
	s_waitcnt lgkmcnt(3)
	v_mfma_f32_16x16x32_bf16 v[110:113], v[202:205], v[156:159], v[110:113]
	v_mfma_f32_16x16x32_bf16 v[106:109], v[202:205], v[170:173], v[106:109]
	s_waitcnt lgkmcnt(1)
	v_mfma_f32_16x16x32_bf16 v[102:105], v[210:213], v[156:159], v[102:105]
	v_mfma_f32_16x16x32_bf16 v[98:101], v[210:213], v[170:173], v[98:101]
	v_mfma_f32_16x16x32_bf16 v[126:129], v[190:193], v[166:169], v[126:129]
	v_mfma_f32_16x16x32_bf16 v[122:125], v[190:193], v[174:177], v[122:125]
	v_mfma_f32_16x16x32_bf16 v[118:121], v[198:201], v[166:169], v[118:121]
	v_mfma_f32_16x16x32_bf16 v[114:117], v[198:201], v[174:177], v[114:117]
	v_mfma_f32_16x16x32_bf16 v[110:113], v[206:209], v[166:169], v[110:113]
	v_mfma_f32_16x16x32_bf16 v[106:109], v[206:209], v[174:177], v[106:109]
	s_waitcnt lgkmcnt(0)
	v_mfma_f32_16x16x32_bf16 v[102:105], v[214:217], v[166:169], v[102:105]
	v_mfma_f32_16x16x32_bf16 v[98:101], v[214:217], v[174:177], v[98:101]
	s_setprio 0
	s_barrier
	v_readfirstlane_b32 s26, v146
	s_add_i32 s25, s24, 0x180
	s_mov_b32 m0, s26
	v_readfirstlane_b32 s26, v147
	ds_read_b128 v[218:221], v144
	ds_read_b128 v[222:225], v144 offset:1024
	ds_read_b128 v[226:229], v144 offset:2048
	ds_read_b128 v[230:233], v144 offset:3072
	buffer_load_dwordx4 v32, s[76:79], s25 offen lds
	s_mov_b32 m0, s26
	s_nop 0
	buffer_load_dwordx4 v131, s[76:79], s25 offen lds
	s_barrier
	s_setprio 1
	s_waitcnt lgkmcnt(3)
	v_mfma_f32_16x16x32_bf16 v[94:97], v[186:189], v[218:221], v[94:97]
	s_waitcnt lgkmcnt(1)
	v_mfma_f32_16x16x32_bf16 v[90:93], v[186:189], v[226:229], v[90:93]
	v_mfma_f32_16x16x32_bf16 v[86:89], v[194:197], v[218:221], v[86:89]
	v_mfma_f32_16x16x32_bf16 v[82:85], v[194:197], v[226:229], v[82:85]
	v_mfma_f32_16x16x32_bf16 v[78:81], v[202:205], v[218:221], v[78:81]
	v_mfma_f32_16x16x32_bf16 v[74:77], v[202:205], v[226:229], v[74:77]
	v_mfma_f32_16x16x32_bf16 v[70:73], v[210:213], v[218:221], v[70:73]
	v_mfma_f32_16x16x32_bf16 v[66:69], v[210:213], v[226:229], v[66:69]
	v_mfma_f32_16x16x32_bf16 v[94:97], v[190:193], v[222:225], v[94:97]
	s_waitcnt lgkmcnt(0)
	v_mfma_f32_16x16x32_bf16 v[90:93], v[190:193], v[230:233], v[90:93]
	v_mfma_f32_16x16x32_bf16 v[86:89], v[198:201], v[222:225], v[86:89]
	v_mfma_f32_16x16x32_bf16 v[82:85], v[198:201], v[230:233], v[82:85]
	v_mfma_f32_16x16x32_bf16 v[78:81], v[206:209], v[222:225], v[78:81]
	v_mfma_f32_16x16x32_bf16 v[74:77], v[206:209], v[230:233], v[74:77]
	v_mfma_f32_16x16x32_bf16 v[70:73], v[214:217], v[222:225], v[70:73]
	v_mfma_f32_16x16x32_bf16 v[66:69], v[214:217], v[230:233], v[66:69]
	s_setprio 0
	v_readfirstlane_b32 s25, v148
	s_addk_i32 s23, 0x180
	s_mov_b32 m0, s25
	v_readfirstlane_b32 s25, v150
	s_barrier
	ds_read_b128 v[186:189], v143 offset:49152
	ds_read_b128 v[190:193], v143 offset:50176
	ds_read_b128 v[194:197], v142 offset:49152
	ds_read_b128 v[198:201], v142 offset:50176
	ds_read_b128 v[202:205], v141 offset:49152
	ds_read_b128 v[206:209], v141 offset:50176
	ds_read_b128 v[210:213], v140 offset:49152
	ds_read_b128 v[214:217], v140 offset:50176
	buffer_load_dwordx4 v32, s[4:7], s23 offen lds
	s_mov_b32 m0, s25
	s_nop 0
	buffer_load_dwordx4 v131, s[4:7], s23 offen lds
	s_barrier
; #define STAGE(P, BASE, br, kt) do { int _so = ((br) * K + (kt) * BK) * 2; \
;     __builtin_amdgcn_raw_ptr_buffer_load_lds(rs_##BASE, (__attribute__((address_space(3))) void*)((char*)(P) + tx * 16), 16, voff0, _so, 0, 0); \
;     __builtin_amdgcn_raw_ptr_buffer_load_lds(rs_##BASE, (__attribute__((address_space(3))) void*)((char*)(P) + tx * 16 + 8192), 16, voff1, _so, 0, 0); } while (0)
; #define LDA(dst, b, h) _Pragma("unroll") for (int m = 0; m < 4; ++m) _Pragma("unroll") for (int k = 0; k < 2; ++k) \
;     dst[m][k] = *reinterpret_cast<const bf16x8*>((char*)SA(b, h) + lds_byte(wr * 64 + m * 16 + fr, k * 32 + fq * 8))
; #define LDB(dst, b, h) _Pragma("unroll") for (int n = 0; n < 2; ++n) _Pragma("unroll") for (int k = 0; k < 2; ++k) \
;     dst[n][k] = *reinterpret_cast<const bf16x8*>((char*)SB(b, h) + lds_byte(wc * 32 + n * 16 + fr, k * 32 + fq * 8))
; #define MMA(ai, bj, At, Bt_) do { __builtin_amdgcn_s_setprio(1); \
;     _Pragma("unroll") for (int m = 0; m < 4; ++m) _Pragma("unroll") for (int n = 0; n < 2; ++n) _Pragma("unroll") for (int k = 0; k < 2; ++k) \
;       acc[ai][bj][m][n] = __builtin_amdgcn_mfma_f32_16x16x32_bf16(At[m][k], Bt_[n][k], acc[ai][bj][m][n], 0, 0, 0); \
;     __builtin_amdgcn_s_setprio(0); } while (0)
; #define WAIT_V(n) asm volatile("s_waitcnt vmcnt(" #n ")" ::: "memory")
; #define WAIT_L(n) asm volatile("s_waitcnt lgkmcnt(" #n ")" ::: "memory")
; #define BAR __builtin_amdgcn_s_barrier()
; #define SCHED __builtin_amdgcn_sched_barrier(0)
; template <class Epi> ...
;     ...
;   for (int t = 0; t < nt - 2; t += 2) {
;     LDB(B0, 0, 0); SCHED; LDA(At, 0, 0); STAGE(SA(1, 1), A, brow + HALF, t + 1);
;     WAIT_L(8); BAR; WAIT_L(0); MMA(0, 0, At, B0); BAR; SCHED;
;     LDB(B1, 0, 1); STAGE(SB(0, 0), Bt, bcol, t + 2);
;     BAR; WAIT_L(0); MMA(0, 1, At, B1); BAR;
;     ...
;     BAR; WAIT_L(0); MMA(1, 0, At, B0); BAR; SCHED;
;     STAGE(SB(1, 1), Bt, bcol + HALF, t + 3);
;     WAIT_V(6); BAR; MMA(1, 1, At, B1); BAR;
;   }
	s_setprio 1
	s_waitcnt lgkmcnt(7)
	v_mfma_f32_16x16x32_bf16 v[62:65], v[186:189], v[156:159], v[62:65]
	v_mfma_f32_16x16x32_bf16 v[58:61], v[186:189], v[170:173], v[58:61]
	s_waitcnt lgkmcnt(5)
	v_mfma_f32_16x16x32_bf16 v[54:57], v[194:197], v[156:159], v[54:57]
	v_mfma_f32_16x16x32_bf16 v[50:53], v[194:197], v[170:173], v[50:53]
	s_waitcnt lgkmcnt(3)
	v_mfma_f32_16x16x32_bf16 v[46:49], v[202:205], v[156:159], v[46:49]
	v_mfma_f32_16x16x32_bf16 v[42:45], v[202:205], v[170:173], v[42:45]
	s_waitcnt lgkmcnt(1)
	v_mfma_f32_16x16x32_bf16 v[38:41], v[210:213], v[156:159], v[38:41]
	v_mfma_f32_16x16x32_bf16 v[34:37], v[210:213], v[170:173], v[34:37]
	v_mfma_f32_16x16x32_bf16 v[62:65], v[190:193], v[166:169], v[62:65]
	v_mfma_f32_16x16x32_bf16 v[58:61], v[190:193], v[174:177], v[58:61]
	v_mfma_f32_16x16x32_bf16 v[54:57], v[198:201], v[166:169], v[54:57]
	v_mfma_f32_16x16x32_bf16 v[50:53], v[198:201], v[174:177], v[50:53]
	v_mfma_f32_16x16x32_bf16 v[46:49], v[206:209], v[166:169], v[46:49]
	v_mfma_f32_16x16x32_bf16 v[42:45], v[206:209], v[174:177], v[42:45]
	s_waitcnt lgkmcnt(0)
	v_mfma_f32_16x16x32_bf16 v[38:41], v[214:217], v[166:169], v[38:41]
	v_mfma_f32_16x16x32_bf16 v[34:37], v[214:217], v[174:177], v[34:37]
	s_setprio 0
	s_barrier
	v_readfirstlane_b32 s23, v153
	s_add_i32 s24, s24, 0xb0180
	s_mov_b32 m0, s23
	v_readfirstlane_b32 s23, v154
	buffer_load_dwordx4 v32, s[76:79], s24 offen lds
	s_mov_b32 m0, s23
	s_nop 0
	buffer_load_dwordx4 v131, s[76:79], s24 offen lds
	s_waitcnt vmcnt(6)
	s_barrier
	s_setprio 1
	v_mfma_f32_16x16x32_bf16 v[28:31], v[186:189], v[218:221], v[28:31]
	v_mfma_f32_16x16x32_bf16 v[24:27], v[186:189], v[226:229], v[24:27]
	v_mfma_f32_16x16x32_bf16 v[20:23], v[194:197], v[218:221], v[20:23]
	v_mfma_f32_16x16x32_bf16 v[16:19], v[194:197], v[226:229], v[16:19]
	v_mfma_f32_16x16x32_bf16 v[12:15], v[202:205], v[218:221], v[12:15]
	v_mfma_f32_16x16x32_bf16 v[8:11], v[202:205], v[226:229], v[8:11]
	v_mfma_f32_16x16x32_bf16 v[4:7], v[210:213], v[218:221], v[4:7]
	v_mfma_f32_16x16x32_bf16 v[0:3], v[210:213], v[226:229], v[0:3]
	v_mfma_f32_16x16x32_bf16 v[28:31], v[190:193], v[222:225], v[28:31]
	v_mfma_f32_16x16x32_bf16 v[24:27], v[190:193], v[230:233], v[24:27]
	v_mfma_f32_16x16x32_bf16 v[20:23], v[198:201], v[222:225], v[20:23]
	v_mfma_f32_16x16x32_bf16 v[16:19], v[198:201], v[230:233], v[16:19]
	v_mfma_f32_16x16x32_bf16 v[12:15], v[206:209], v[222:225], v[12:15]
	v_mfma_f32_16x16x32_bf16 v[8:11], v[206:209], v[230:233], v[8:11]
	v_mfma_f32_16x16x32_bf16 v[4:7], v[214:217], v[222:225], v[4:7]
	v_mfma_f32_16x16x32_bf16 v[0:3], v[214:217], v[230:233], v[0:3]
	s_setprio 0
	s_add_i32 s14, s14, 2
	s_addk_i32 s15, 0x100
	s_cmp_lt_u32 s14, 40
	s_barrier
	s_cbranch_scc1 .LBB0_2336
	s_branch .Lpx8
.LBB0_2336:
	ds_read_b128 v[156:159], v155
	ds_read_b128 v[166:169], v155 offset:1024
	ds_read_b128 v[170:173], v155 offset:2048
	ds_read_b128 v[174:177], v155 offset:3072
	s_add_i32 s23, s21, s15
	v_readfirstlane_b32 s25, v152
	s_add_i32 s24, s23, 0xb0080
	s_mov_b32 m0, s25
	v_readfirstlane_b32 s25, v151
	ds_read_b128 v[186:189], v143
	ds_read_b128 v[190:193], v143 offset:1024
	ds_read_b128 v[194:197], v142
	ds_read_b128 v[198:201], v142 offset:1024
	ds_read_b128 v[202:205], v141
	ds_read_b128 v[206:209], v141 offset:1024
	ds_read_b128 v[210:213], v140
	ds_read_b128 v[214:217], v140 offset:1024
	buffer_load_dwordx4 v32, s[4:7], s24 offen lds
	s_mov_b32 m0, s25
	s_nop 0
	buffer_load_dwordx4 v131, s[4:7], s24 offen lds
	s_waitcnt lgkmcnt(8)
	s_barrier
	s_setprio 1
	s_waitcnt lgkmcnt(7)
	v_mfma_f32_16x16x32_bf16 v[126:129], v[186:189], v[156:159], v[126:129]
	v_mfma_f32_16x16x32_bf16 v[122:125], v[186:189], v[170:173], v[122:125]
	s_waitcnt lgkmcnt(5)
	v_mfma_f32_16x16x32_bf16 v[118:121], v[194:197], v[156:159], v[118:121]
	v_mfma_f32_16x16x32_bf16 v[114:117], v[194:197], v[170:173], v[114:117]
	s_waitcnt lgkmcnt(3)
	v_mfma_f32_16x16x32_bf16 v[110:113], v[202:205], v[156:159], v[110:113]
	v_mfma_f32_16x16x32_bf16 v[106:109], v[202:205], v[170:173], v[106:109]
	s_waitcnt lgkmcnt(1)
	v_mfma_f32_16x16x32_bf16 v[102:105], v[210:213], v[156:159], v[102:105]
	v_mfma_f32_16x16x32_bf16 v[98:101], v[210:213], v[170:173], v[98:101]
	v_mfma_f32_16x16x32_bf16 v[126:129], v[190:193], v[166:169], v[126:129]
	v_mfma_f32_16x16x32_bf16 v[122:125], v[190:193], v[174:177], v[122:125]
	v_mfma_f32_16x16x32_bf16 v[118:121], v[198:201], v[166:169], v[118:121]
	v_mfma_f32_16x16x32_bf16 v[114:117], v[198:201], v[174:177], v[114:117]
	v_mfma_f32_16x16x32_bf16 v[110:113], v[206:209], v[166:169], v[110:113]
	v_mfma_f32_16x16x32_bf16 v[106:109], v[206:209], v[174:177], v[106:109]
	s_waitcnt lgkmcnt(0)
	v_mfma_f32_16x16x32_bf16 v[102:105], v[214:217], v[166:169], v[102:105]
	v_mfma_f32_16x16x32_bf16 v[98:101], v[214:217], v[174:177], v[98:101]
	s_setprio 0
	s_barrier
	s_add_i32 s24, s22, s15
	v_readfirstlane_b32 s26, v137
	s_add_i32 s25, s24, 0x100
	s_mov_b32 m0, s26
	v_readfirstlane_b32 s26, v139
	ds_read_b128 v[218:221], v149
	ds_read_b128 v[222:225], v149 offset:1024
	ds_read_b128 v[226:229], v149 offset:2048
	ds_read_b128 v[230:233], v149 offset:3072
	buffer_load_dwordx4 v32, s[76:79], s25 offen lds
	s_mov_b32 m0, s26
	s_nop 0
	buffer_load_dwordx4 v131, s[76:79], s25 offen lds
	s_barrier
; #define STAGE(P, BASE, br, kt) do { int _so = ((br) * K + (kt) * BK) * 2; \
;     __builtin_amdgcn_raw_ptr_buffer_load_lds(rs_##BASE, (__attribute__((address_space(3))) void*)((char*)(P) + tx * 16), 16, voff0, _so, 0, 0); \
;     __builtin_amdgcn_raw_ptr_buffer_load_lds(rs_##BASE, (__attribute__((address_space(3))) void*)((char*)(P) + tx * 16 + 8192), 16, voff1, _so, 0, 0); } while (0)
; #define LDA(dst, b, h) _Pragma("unroll") for (int m = 0; m < 4; ++m) _Pragma("unroll") for (int k = 0; k < 2; ++k) \
;     dst[m][k] = *reinterpret_cast<const bf16x8*>((char*)SA(b, h) + lds_byte(wr * 64 + m * 16 + fr, k * 32 + fq * 8))
; #define LDB(dst, b, h) _Pragma("unroll") for (int n = 0; n < 2; ++n) _Pragma("unroll") for (int k = 0; k < 2; ++k) \
;     dst[n][k] = *reinterpret_cast<const bf16x8*>((char*)SB(b, h) + lds_byte(wc * 32 + n * 16 + fr, k * 32 + fq * 8))
; #define MMA(ai, bj, At, Bt_) do { __builtin_amdgcn_s_setprio(1); \
;     _Pragma("unroll") for (int m = 0; m < 4; ++m) _Pragma("unroll") for (int n = 0; n < 2; ++n) _Pragma("unroll") for (int k = 0; k < 2; ++k) \
;       acc[ai][bj][m][n] = __builtin_amdgcn_mfma_f32_16x16x32_bf16(At[m][k], Bt_[n][k], acc[ai][bj][m][n], 0, 0, 0); \
;     __builtin_amdgcn_s_setprio(0); } while (0)
; #define WAIT_V(n) asm volatile("s_waitcnt vmcnt(" #n ")" ::: "memory")
; #define WAIT_L(n) asm volatile("s_waitcnt lgkmcnt(" #n ")" ::: "memory")
; #define BAR __builtin_amdgcn_s_barrier()
; #define SCHED __builtin_amdgcn_sched_barrier(0)
; template <class Epi> ...
;     ...
;     BAR; WAIT_L(0); MMA(0, 1, At, B1); BAR;
;     LDA(At, 0, 1); STAGE(SA(0, 0), A, brow, t + 2);
;     BAR; WAIT_L(0); MMA(1, 0, At, B0); BAR; SCHED;
;     STAGE(SB(0, 1), Bt, bcol + HALF, t + 2);
;     WAIT_V(6); BAR; MMA(1, 1, At, B1); BAR;
;     LDB(B0, 1, 0); SCHED; LDA(At, 1, 0); STAGE(SA(0, 1), A, brow + HALF, t + 2);
;     WAIT_L(8); BAR; WAIT_L(0); MMA(0, 0, At, B0); BAR; SCHED;
	s_setprio 1
	s_waitcnt lgkmcnt(3)
	v_mfma_f32_16x16x32_bf16 v[94:97], v[186:189], v[218:221], v[94:97]
	s_waitcnt lgkmcnt(1)
	v_mfma_f32_16x16x32_bf16 v[90:93], v[186:189], v[226:229], v[90:93]
	v_mfma_f32_16x16x32_bf16 v[86:89], v[194:197], v[218:221], v[86:89]
	v_mfma_f32_16x16x32_bf16 v[82:85], v[194:197], v[226:229], v[82:85]
	v_mfma_f32_16x16x32_bf16 v[78:81], v[202:205], v[218:221], v[78:81]
	v_mfma_f32_16x16x32_bf16 v[74:77], v[202:205], v[226:229], v[74:77]
	v_mfma_f32_16x16x32_bf16 v[70:73], v[210:213], v[218:221], v[70:73]
	v_mfma_f32_16x16x32_bf16 v[66:69], v[210:213], v[226:229], v[66:69]
	v_mfma_f32_16x16x32_bf16 v[94:97], v[190:193], v[222:225], v[94:97]
	s_waitcnt lgkmcnt(0)
	v_mfma_f32_16x16x32_bf16 v[90:93], v[190:193], v[230:233], v[90:93]
	v_mfma_f32_16x16x32_bf16 v[86:89], v[198:201], v[222:225], v[86:89]
	v_mfma_f32_16x16x32_bf16 v[82:85], v[198:201], v[230:233], v[82:85]
	v_mfma_f32_16x16x32_bf16 v[78:81], v[206:209], v[222:225], v[78:81]
	v_mfma_f32_16x16x32_bf16 v[74:77], v[206:209], v[230:233], v[74:77]
	v_mfma_f32_16x16x32_bf16 v[70:73], v[214:217], v[222:225], v[70:73]
	v_mfma_f32_16x16x32_bf16 v[66:69], v[214:217], v[230:233], v[66:69]
	s_setprio 0
	v_readfirstlane_b32 s26, v136
	s_add_i32 s25, s23, 0x100
	s_mov_b32 m0, s26
	v_readfirstlane_b32 s26, v135
	s_barrier
	ds_read_b128 v[186:189], v143 offset:16384
	ds_read_b128 v[190:193], v143 offset:17408
	ds_read_b128 v[194:197], v142 offset:16384
	ds_read_b128 v[198:201], v142 offset:17408
	ds_read_b128 v[202:205], v141 offset:16384
	ds_read_b128 v[206:209], v141 offset:17408
	ds_read_b128 v[210:213], v140 offset:16384
	ds_read_b128 v[214:217], v140 offset:17408
	buffer_load_dwordx4 v32, s[4:7], s25 offen lds
	s_mov_b32 m0, s26
	s_nop 0
	buffer_load_dwordx4 v131, s[4:7], s25 offen lds
	s_barrier
	s_setprio 1
	s_waitcnt lgkmcnt(7)
	v_mfma_f32_16x16x32_bf16 v[62:65], v[186:189], v[156:159], v[62:65]
	v_mfma_f32_16x16x32_bf16 v[58:61], v[186:189], v[170:173], v[58:61]
	s_waitcnt lgkmcnt(5)
	v_mfma_f32_16x16x32_bf16 v[54:57], v[194:197], v[156:159], v[54:57]
	v_mfma_f32_16x16x32_bf16 v[50:53], v[194:197], v[170:173], v[50:53]
	s_waitcnt lgkmcnt(3)
	v_mfma_f32_16x16x32_bf16 v[46:49], v[202:205], v[156:159], v[46:49]
	v_mfma_f32_16x16x32_bf16 v[42:45], v[202:205], v[170:173], v[42:45]
	s_waitcnt lgkmcnt(1)
	v_mfma_f32_16x16x32_bf16 v[38:41], v[210:213], v[156:159], v[38:41]
	v_mfma_f32_16x16x32_bf16 v[34:37], v[210:213], v[170:173], v[34:37]
	v_mfma_f32_16x16x32_bf16 v[62:65], v[190:193], v[166:169], v[62:65]
	v_mfma_f32_16x16x32_bf16 v[58:61], v[190:193], v[174:177], v[58:61]
	v_mfma_f32_16x16x32_bf16 v[54:57], v[198:201], v[166:169], v[54:57]
	v_mfma_f32_16x16x32_bf16 v[50:53], v[198:201], v[174:177], v[50:53]
	v_mfma_f32_16x16x32_bf16 v[46:49], v[206:209], v[166:169], v[46:49]
	v_mfma_f32_16x16x32_bf16 v[42:45], v[206:209], v[174:177], v[42:45]
	s_waitcnt lgkmcnt(0)
	v_mfma_f32_16x16x32_bf16 v[38:41], v[214:217], v[166:169], v[38:41]
	v_mfma_f32_16x16x32_bf16 v[34:37], v[214:217], v[174:177], v[34:37]
	s_setprio 0
	s_barrier
	v_readfirstlane_b32 s26, v134
	s_add_i32 s25, s24, 0xb0100
	s_mov_b32 m0, s26
	v_readfirstlane_b32 s26, v138
	buffer_load_dwordx4 v32, s[76:79], s25 offen lds
	s_mov_b32 m0, s26
	s_nop 0
	buffer_load_dwordx4 v131, s[76:79], s25 offen lds
	s_waitcnt vmcnt(6)
	s_barrier
	s_setprio 1
	v_mfma_f32_16x16x32_bf16 v[28:31], v[186:189], v[218:221], v[28:31]
	v_mfma_f32_16x16x32_bf16 v[24:27], v[186:189], v[226:229], v[24:27]
	v_mfma_f32_16x16x32_bf16 v[20:23], v[194:197], v[218:221], v[20:23]
	v_mfma_f32_16x16x32_bf16 v[16:19], v[194:197], v[226:229], v[16:19]
	v_mfma_f32_16x16x32_bf16 v[12:15], v[202:205], v[218:221], v[12:15]
	v_mfma_f32_16x16x32_bf16 v[8:11], v[202:205], v[226:229], v[8:11]
	v_mfma_f32_16x16x32_bf16 v[4:7], v[210:213], v[218:221], v[4:7]
	v_mfma_f32_16x16x32_bf16 v[0:3], v[210:213], v[226:229], v[0:3]
	v_mfma_f32_16x16x32_bf16 v[28:31], v[190:193], v[222:225], v[28:31]
	v_mfma_f32_16x16x32_bf16 v[24:27], v[190:193], v[230:233], v[24:27]
	v_mfma_f32_16x16x32_bf16 v[20:23], v[198:201], v[222:225], v[20:23]
	v_mfma_f32_16x16x32_bf16 v[16:19], v[198:201], v[230:233], v[16:19]
	v_mfma_f32_16x16x32_bf16 v[12:15], v[206:209], v[222:225], v[12:15]
	v_mfma_f32_16x16x32_bf16 v[8:11], v[206:209], v[230:233], v[8:11]
	v_mfma_f32_16x16x32_bf16 v[4:7], v[214:217], v[222:225], v[4:7]
	v_mfma_f32_16x16x32_bf16 v[0:3], v[214:217], v[230:233], v[0:3]
	s_setprio 0
	s_barrier
	ds_read_b128 v[156:159], v145
	ds_read_b128 v[166:169], v145 offset:1024
	ds_read_b128 v[170:173], v145 offset:2048
	ds_read_b128 v[174:177], v145 offset:3072
	v_readfirstlane_b32 s26, v133
	s_add_i32 s25, s23, 0xb0100
	s_mov_b32 m0, s26
	v_readfirstlane_b32 s26, v132
	ds_read_b128 v[186:189], v143 offset:32768
	ds_read_b128 v[190:193], v143 offset:33792
	ds_read_b128 v[194:197], v142 offset:32768
	ds_read_b128 v[198:201], v142 offset:33792
	ds_read_b128 v[202:205], v141 offset:32768
	ds_read_b128 v[206:209], v141 offset:33792
	ds_read_b128 v[210:213], v140 offset:32768
	ds_read_b128 v[214:217], v140 offset:33792
	buffer_load_dwordx4 v32, s[4:7], s25 offen lds
	s_mov_b32 m0, s26
	s_nop 0
	buffer_load_dwordx4 v131, s[4:7], s25 offen lds
	s_waitcnt lgkmcnt(8)
	s_barrier
; #define STAGE(P, BASE, br, kt) do { int _so = ((br) * K + (kt) * BK) * 2; \
;     __builtin_amdgcn_raw_ptr_buffer_load_lds(rs_##BASE, (__attribute__((address_space(3))) void*)((char*)(P) + tx * 16), 16, voff0, _so, 0, 0); \
;     __builtin_amdgcn_raw_ptr_buffer_load_lds(rs_##BASE, (__attribute__((address_space(3))) void*)((char*)(P) + tx * 16 + 8192), 16, voff1, _so, 0, 0); } while (0)
; #define LDA(dst, b, h) _Pragma("unroll") for (int m = 0; m < 4; ++m) _Pragma("unroll") for (int k = 0; k < 2; ++k) \
;     dst[m][k] = *reinterpret_cast<const bf16x8*>((char*)SA(b, h) + lds_byte(wr * 64 + m * 16 + fr, k * 32 + fq * 8))
; #define LDB(dst, b, h) _Pragma("unroll") for (int n = 0; n < 2; ++n) _Pragma("unroll") for (int k = 0; k < 2; ++k) \
;     dst[n][k] = *reinterpret_cast<const bf16x8*>((char*)SB(b, h) + lds_byte(wc * 32 + n * 16 + fr, k * 32 + fq * 8))
; #define MMA(ai, bj, At, Bt_) do { __builtin_amdgcn_s_setprio(1); \
;     _Pragma("unroll") for (int m = 0; m < 4; ++m) _Pragma("unroll") for (int n = 0; n < 2; ++n) _Pragma("unroll") for (int k = 0; k < 2; ++k) \
;       acc[ai][bj][m][n] = __builtin_amdgcn_mfma_f32_16x16x32_bf16(At[m][k], Bt_[n][k], acc[ai][bj][m][n], 0, 0, 0); \
;     __builtin_amdgcn_s_setprio(0); } while (0)
; #define WAIT_V(n) asm volatile("s_waitcnt vmcnt(" #n ")" ::: "memory")
; #define WAIT_L(n) asm volatile("s_waitcnt lgkmcnt(" #n ")" ::: "memory")
; #define BAR __builtin_amdgcn_s_barrier()
; #define SCHED __builtin_amdgcn_sched_barrier(0)
; template <class Epi> ...
;     ...
;     WAIT_L(8); BAR; WAIT_L(0); MMA(0, 0, At, B0); BAR; SCHED;
;     LDB(B1, 1, 1); STAGE(SB(1, 0), Bt, bcol, t + 3);
;     BAR; WAIT_L(0); MMA(0, 1, At, B1); BAR;
;     LDA(At, 1, 1); STAGE(SA(1, 0), A, brow, t + 3);
;     BAR; WAIT_L(0); MMA(1, 0, At, B0); BAR; SCHED;
;     STAGE(SB(1, 1), Bt, bcol + HALF, t + 3);
;     WAIT_V(6); BAR; MMA(1, 1, At, B1); BAR;
;   }
	s_setprio 1
	s_waitcnt lgkmcnt(7)
	v_mfma_f32_16x16x32_bf16 v[126:129], v[186:189], v[156:159], v[126:129]
	v_mfma_f32_16x16x32_bf16 v[122:125], v[186:189], v[170:173], v[122:125]
	s_waitcnt lgkmcnt(5)
	v_mfma_f32_16x16x32_bf16 v[118:121], v[194:197], v[156:159], v[118:121]
	v_mfma_f32_16x16x32_bf16 v[114:117], v[194:197], v[170:173], v[114:117]
	s_waitcnt lgkmcnt(3)
	v_mfma_f32_16x16x32_bf16 v[110:113], v[202:205], v[156:159], v[110:113]
	v_mfma_f32_16x16x32_bf16 v[106:109], v[202:205], v[170:173], v[106:109]
	s_waitcnt lgkmcnt(1)
	v_mfma_f32_16x16x32_bf16 v[102:105], v[210:213], v[156:159], v[102:105]
	v_mfma_f32_16x16x32_bf16 v[98:101], v[210:213], v[170:173], v[98:101]
	v_mfma_f32_16x16x32_bf16 v[126:129], v[190:193], v[166:169], v[126:129]
	v_mfma_f32_16x16x32_bf16 v[122:125], v[190:193], v[174:177], v[122:125]
	v_mfma_f32_16x16x32_bf16 v[118:121], v[198:201], v[166:169], v[118:121]
	v_mfma_f32_16x16x32_bf16 v[114:117], v[198:201], v[174:177], v[114:117]
	v_mfma_f32_16x16x32_bf16 v[110:113], v[206:209], v[166:169], v[110:113]
	v_mfma_f32_16x16x32_bf16 v[106:109], v[206:209], v[174:177], v[106:109]
	s_waitcnt lgkmcnt(0)
	v_mfma_f32_16x16x32_bf16 v[102:105], v[214:217], v[166:169], v[102:105]
	v_mfma_f32_16x16x32_bf16 v[98:101], v[214:217], v[174:177], v[98:101]
	s_setprio 0
	s_barrier
	v_readfirstlane_b32 s26, v146
	s_add_i32 s25, s24, 0x180
	s_mov_b32 m0, s26
	v_readfirstlane_b32 s26, v147
	ds_read_b128 v[218:221], v144
	ds_read_b128 v[222:225], v144 offset:1024
	ds_read_b128 v[226:229], v144 offset:2048
	ds_read_b128 v[230:233], v144 offset:3072
	buffer_load_dwordx4 v32, s[76:79], s25 offen lds
	s_mov_b32 m0, s26
	s_nop 0
	buffer_load_dwordx4 v131, s[76:79], s25 offen lds
	s_barrier
	s_setprio 1
	s_waitcnt lgkmcnt(3)
	v_mfma_f32_16x16x32_bf16 v[94:97], v[186:189], v[218:221], v[94:97]
	s_waitcnt lgkmcnt(1)
	v_mfma_f32_16x16x32_bf16 v[90:93], v[186:189], v[226:229], v[90:93]
	v_mfma_f32_16x16x32_bf16 v[86:89], v[194:197], v[218:221], v[86:89]
	v_mfma_f32_16x16x32_bf16 v[82:85], v[194:197], v[226:229], v[82:85]
	v_mfma_f32_16x16x32_bf16 v[78:81], v[202:205], v[218:221], v[78:81]
	v_mfma_f32_16x16x32_bf16 v[74:77], v[202:205], v[226:229], v[74:77]
	v_mfma_f32_16x16x32_bf16 v[70:73], v[210:213], v[218:221], v[70:73]
	v_mfma_f32_16x16x32_bf16 v[66:69], v[210:213], v[226:229], v[66:69]
	v_mfma_f32_16x16x32_bf16 v[94:97], v[190:193], v[222:225], v[94:97]
	s_waitcnt lgkmcnt(0)
	v_mfma_f32_16x16x32_bf16 v[90:93], v[190:193], v[230:233], v[90:93]
	v_mfma_f32_16x16x32_bf16 v[86:89], v[198:201], v[222:225], v[86:89]
	v_mfma_f32_16x16x32_bf16 v[82:85], v[198:201], v[230:233], v[82:85]
	v_mfma_f32_16x16x32_bf16 v[78:81], v[206:209], v[222:225], v[78:81]
	v_mfma_f32_16x16x32_bf16 v[74:77], v[206:209], v[230:233], v[74:77]
	v_mfma_f32_16x16x32_bf16 v[70:73], v[214:217], v[222:225], v[70:73]
	v_mfma_f32_16x16x32_bf16 v[66:69], v[214:217], v[230:233], v[66:69]
	s_setprio 0
	v_readfirstlane_b32 s25, v148
	s_addk_i32 s23, 0x180
	s_mov_b32 m0, s25
	v_readfirstlane_b32 s25, v150
	s_barrier
	ds_read_b128 v[186:189], v143 offset:49152
	ds_read_b128 v[190:193], v143 offset:50176
	ds_read_b128 v[194:197], v142 offset:49152
	ds_read_b128 v[198:201], v142 offset:50176
	ds_read_b128 v[202:205], v141 offset:49152
	ds_read_b128 v[206:209], v141 offset:50176
	ds_read_b128 v[210:213], v140 offset:49152
	ds_read_b128 v[214:217], v140 offset:50176
	buffer_load_dwordx4 v32, s[4:7], s23 offen lds
	s_mov_b32 m0, s25
	s_nop 0
	buffer_load_dwordx4 v131, s[4:7], s23 offen lds
	s_barrier
	s_setprio 1
	s_waitcnt lgkmcnt(7)
	v_mfma_f32_16x16x32_bf16 v[62:65], v[186:189], v[156:159], v[62:65]
	v_mfma_f32_16x16x32_bf16 v[58:61], v[186:189], v[170:173], v[58:61]
	s_waitcnt lgkmcnt(5)
	v_mfma_f32_16x16x32_bf16 v[54:57], v[194:197], v[156:159], v[54:57]
	v_mfma_f32_16x16x32_bf16 v[50:53], v[194:197], v[170:173], v[50:53]
	s_waitcnt lgkmcnt(3)
	v_mfma_f32_16x16x32_bf16 v[46:49], v[202:205], v[156:159], v[46:49]
	v_mfma_f32_16x16x32_bf16 v[42:45], v[202:205], v[170:173], v[42:45]
	s_waitcnt lgkmcnt(1)
	v_mfma_f32_16x16x32_bf16 v[38:41], v[210:213], v[156:159], v[38:41]
	v_mfma_f32_16x16x32_bf16 v[34:37], v[210:213], v[170:173], v[34:37]
	v_mfma_f32_16x16x32_bf16 v[62:65], v[190:193], v[166:169], v[62:65]
	v_mfma_f32_16x16x32_bf16 v[58:61], v[190:193], v[174:177], v[58:61]
	v_mfma_f32_16x16x32_bf16 v[54:57], v[198:201], v[166:169], v[54:57]
	v_mfma_f32_16x16x32_bf16 v[50:53], v[198:201], v[174:177], v[50:53]
	v_mfma_f32_16x16x32_bf16 v[46:49], v[206:209], v[166:169], v[46:49]
	v_mfma_f32_16x16x32_bf16 v[42:45], v[206:209], v[174:177], v[42:45]
	s_waitcnt lgkmcnt(0)
	v_mfma_f32_16x16x32_bf16 v[38:41], v[214:217], v[166:169], v[38:41]
	v_mfma_f32_16x16x32_bf16 v[34:37], v[214:217], v[174:177], v[34:37]
	s_setprio 0
	s_barrier
	v_readfirstlane_b32 s23, v153
	s_add_i32 s24, s24, 0xb0180
	s_mov_b32 m0, s23
	v_readfirstlane_b32 s23, v154
	buffer_load_dwordx4 v32, s[76:79], s24 offen lds
	s_mov_b32 m0, s23
	s_nop 0
	buffer_load_dwordx4 v131, s[76:79], s24 offen lds
	s_waitcnt vmcnt(6)
	s_barrier
	s_setprio 1
	v_mfma_f32_16x16x32_bf16 v[28:31], v[186:189], v[218:221], v[28:31]
	v_mfma_f32_16x16x32_bf16 v[24:27], v[186:189], v[226:229], v[24:27]
	v_mfma_f32_16x16x32_bf16 v[20:23], v[194:197], v[218:221], v[20:23]
	v_mfma_f32_16x16x32_bf16 v[16:19], v[194:197], v[226:229], v[16:19]
	v_mfma_f32_16x16x32_bf16 v[12:15], v[202:205], v[218:221], v[12:15]
	v_mfma_f32_16x16x32_bf16 v[8:11], v[202:205], v[226:229], v[8:11]
	v_mfma_f32_16x16x32_bf16 v[4:7], v[210:213], v[218:221], v[4:7]
	v_mfma_f32_16x16x32_bf16 v[0:3], v[210:213], v[226:229], v[0:3]
	v_mfma_f32_16x16x32_bf16 v[28:31], v[190:193], v[222:225], v[28:31]
	v_mfma_f32_16x16x32_bf16 v[24:27], v[190:193], v[230:233], v[24:27]
	v_mfma_f32_16x16x32_bf16 v[20:23], v[198:201], v[222:225], v[20:23]
	v_mfma_f32_16x16x32_bf16 v[16:19], v[198:201], v[230:233], v[16:19]
	v_mfma_f32_16x16x32_bf16 v[12:15], v[206:209], v[222:225], v[12:15]
	v_mfma_f32_16x16x32_bf16 v[8:11], v[206:209], v[230:233], v[8:11]
	v_mfma_f32_16x16x32_bf16 v[4:7], v[214:217], v[222:225], v[4:7]
	v_mfma_f32_16x16x32_bf16 v[0:3], v[214:217], v[230:233], v[0:3]
	s_setprio 0
	s_add_i32 s14, s14, 2
	s_addk_i32 s15, 0x100
	s_cmp_lt_u32 s14, 40
	s_barrier
	s_cbranch_scc1 .LBB0_2336
; #define STAGE(P, BASE, br, kt) do { int _so = ((br) * K + (kt) * BK) * 2; \
;     __builtin_amdgcn_raw_ptr_buffer_load_lds(rs_##BASE, (__attribute__((address_space(3))) void*)((char*)(P) + tx * 16), 16, voff0, _so, 0, 0); \
;     __builtin_amdgcn_raw_ptr_buffer_load_lds(rs_##BASE, (__attribute__((address_space(3))) void*)((char*)(P) + tx * 16 + 8192), 16, voff1, _so, 0, 0); } while (0)
; #define LDA(dst, b, h) _Pragma("unroll") for (int m = 0; m < 4; ++m) _Pragma("unroll") for (int k = 0; k < 2; ++k) \
;     dst[m][k] = *reinterpret_cast<const bf16x8*>((char*)SA(b, h) + lds_byte(wr * 64 + m * 16 + fr, k * 32 + fq * 8))
; #define LDB(dst, b, h) _Pragma("unroll") for (int n = 0; n < 2; ++n) _Pragma("unroll") for (int k = 0; k < 2; ++k) \
;     dst[n][k] = *reinterpret_cast<const bf16x8*>((char*)SB(b, h) + lds_byte(wc * 32 + n * 16 + fr, k * 32 + fq * 8))
; #define MMA(ai, bj, At, Bt_) do { __builtin_amdgcn_s_setprio(1); \
;     _Pragma("unroll") for (int m = 0; m < 4; ++m) _Pragma("unroll") for (int n = 0; n < 2; ++n) _Pragma("unroll") for (int k = 0; k < 2; ++k) \
;       acc[ai][bj][m][n] = __builtin_amdgcn_mfma_f32_16x16x32_bf16(At[m][k], Bt_[n][k], acc[ai][bj][m][n], 0, 0, 0); \
;     __builtin_amdgcn_s_setprio(0); } while (0)
; #define WAIT_V(n) asm volatile("s_waitcnt vmcnt(" #n ")" ::: "memory")
; #define WAIT_L(n) asm volatile("s_waitcnt lgkmcnt(" #n ")" ::: "memory")
; #define BAR __builtin_amdgcn_s_barrier()
; template <class Epi> ...
;     ...
;   { LDB(B0, 0, 0); LDA(At, 0, 0); STAGE(SA(1, 1), A, brow + HALF, nt - 1);
;     BAR; WAIT_L(0); MMA(0, 0, At, B0); BAR;
;     LDB(B1, 0, 1); BAR; WAIT_L(0); MMA(0, 1, At, B1); BAR;
;     LDA(At, 0, 1); WAIT_V(4); BAR; WAIT_L(0); MMA(1, 0, At, B0); MMA(1, 1, At, B1); BAR; }
.Lpx8:
	v_readfirstlane_b32 s14, v152
	s_add_i32 s21, s21, 0xb1580
	s_mov_b32 s6, s78
	s_mov_b32 s7, s79
	s_mov_b32 m0, s14
	v_readfirstlane_b32 s14, v151
	ds_read_b128 v[156:159], v155
	ds_read_b128 v[166:169], v155 offset:1024
	ds_read_b128 v[170:173], v155 offset:2048
	ds_read_b128 v[174:177], v155 offset:3072
	ds_read_b128 v[186:189], v143
	ds_read_b128 v[190:193], v143 offset:1024
	ds_read_b128 v[194:197], v142
	ds_read_b128 v[198:201], v142 offset:1024
	ds_read_b128 v[202:205], v141
	ds_read_b128 v[206:209], v141 offset:1024
	ds_read_b128 v[210:213], v140
	ds_read_b128 v[214:217], v140 offset:1024
	buffer_load_dwordx4 v32, s[4:7], s21 offen lds
	s_mov_b32 m0, s14
	s_nop 0
	buffer_load_dwordx4 v131, s[4:7], s21 offen lds
	s_barrier
	s_setprio 1
	s_waitcnt lgkmcnt(7)
	v_mfma_f32_16x16x32_bf16 v[126:129], v[186:189], v[156:159], v[126:129]
	v_mfma_f32_16x16x32_bf16 v[122:125], v[186:189], v[170:173], v[122:125]
	s_waitcnt lgkmcnt(5)
	v_mfma_f32_16x16x32_bf16 v[118:121], v[194:197], v[156:159], v[118:121]
	v_mfma_f32_16x16x32_bf16 v[114:117], v[194:197], v[170:173], v[114:117]
	s_waitcnt lgkmcnt(3)
	v_mfma_f32_16x16x32_bf16 v[110:113], v[202:205], v[156:159], v[110:113]
	v_mfma_f32_16x16x32_bf16 v[106:109], v[202:205], v[170:173], v[106:109]
	s_waitcnt lgkmcnt(1)
	v_mfma_f32_16x16x32_bf16 v[102:105], v[210:213], v[156:159], v[102:105]
	v_mfma_f32_16x16x32_bf16 v[98:101], v[210:213], v[170:173], v[98:101]
	v_mfma_f32_16x16x32_bf16 v[126:129], v[190:193], v[166:169], v[126:129]
	v_mfma_f32_16x16x32_bf16 v[122:125], v[190:193], v[174:177], v[122:125]
	v_mfma_f32_16x16x32_bf16 v[118:121], v[198:201], v[166:169], v[118:121]
	v_mfma_f32_16x16x32_bf16 v[114:117], v[198:201], v[174:177], v[114:117]
	v_mfma_f32_16x16x32_bf16 v[110:113], v[206:209], v[166:169], v[110:113]
	v_mfma_f32_16x16x32_bf16 v[106:109], v[206:209], v[174:177], v[106:109]
	s_waitcnt lgkmcnt(0)
	v_mfma_f32_16x16x32_bf16 v[102:105], v[214:217], v[166:169], v[102:105]
	v_mfma_f32_16x16x32_bf16 v[98:101], v[214:217], v[174:177], v[98:101]
	s_setprio 0
	s_barrier
	ds_read_b128 v[150:153], v149
	ds_read_b128 v[218:221], v149 offset:1024
	ds_read_b128 v[222:225], v149 offset:2048
	ds_read_b128 v[146:149], v149 offset:3072
	s_barrier
	s_setprio 1
	s_waitcnt lgkmcnt(3)
	v_mfma_f32_16x16x32_bf16 v[78:81], v[202:205], v[150:153], v[78:81]
	s_waitcnt lgkmcnt(1)
	v_mfma_f32_16x16x32_bf16 v[74:77], v[202:205], v[222:225], v[74:77]
	v_mfma_f32_16x16x32_bf16 v[70:73], v[210:213], v[150:153], v[70:73]
	v_mfma_f32_16x16x32_bf16 v[66:69], v[210:213], v[222:225], v[66:69]
	v_mfma_f32_16x16x32_bf16 v[94:97], v[186:189], v[150:153], v[94:97]
	v_mfma_f32_16x16x32_bf16 v[90:93], v[186:189], v[222:225], v[90:93]
	v_mfma_f32_16x16x32_bf16 v[86:89], v[194:197], v[150:153], v[86:89]
	v_mfma_f32_16x16x32_bf16 v[82:85], v[194:197], v[222:225], v[82:85]
	v_mfma_f32_16x16x32_bf16 v[78:81], v[206:209], v[218:221], v[78:81]
	s_waitcnt lgkmcnt(0)
	v_mfma_f32_16x16x32_bf16 v[74:77], v[206:209], v[146:149], v[74:77]
	v_mfma_f32_16x16x32_bf16 v[70:73], v[214:217], v[218:221], v[70:73]
	v_mfma_f32_16x16x32_bf16 v[66:69], v[214:217], v[146:149], v[66:69]
	v_mfma_f32_16x16x32_bf16 v[226:229], v[190:193], v[218:221], v[94:97]
	v_mfma_f32_16x16x32_bf16 v[186:189], v[190:193], v[146:149], v[90:93]
	v_mfma_f32_16x16x32_bf16 v[190:193], v[198:201], v[218:221], v[86:89]
	v_mfma_f32_16x16x32_bf16 v[194:197], v[198:201], v[146:149], v[82:85]
	s_setprio 0
	s_barrier
	s_nop 0
	ds_read_b128 v[82:85], v143 offset:16384
	ds_read_b128 v[86:89], v143 offset:17408
	ds_read_b128 v[90:93], v142 offset:16384
	ds_read_b128 v[94:97], v142 offset:17408
	ds_read_b128 v[198:201], v141 offset:16384
	ds_read_b128 v[202:205], v141 offset:17408
	ds_read_b128 v[206:209], v140 offset:16384
	ds_read_b128 v[210:213], v140 offset:17408
	s_waitcnt vmcnt(4)
	s_barrier
	s_setprio 1
	s_waitcnt lgkmcnt(3)
	v_mfma_f32_16x16x32_bf16 v[46:49], v[198:201], v[156:159], v[46:49]
	v_mfma_f32_16x16x32_bf16 v[42:45], v[198:201], v[170:173], v[42:45]
	s_waitcnt lgkmcnt(1)
	v_mfma_f32_16x16x32_bf16 v[38:41], v[206:209], v[156:159], v[38:41]
	v_mfma_f32_16x16x32_bf16 v[34:37], v[206:209], v[170:173], v[34:37]
	v_mfma_f32_16x16x32_bf16 v[62:65], v[82:85], v[156:159], v[62:65]
	v_mfma_f32_16x16x32_bf16 v[58:61], v[82:85], v[170:173], v[58:61]
	v_mfma_f32_16x16x32_bf16 v[54:57], v[90:93], v[156:159], v[54:57]
	v_mfma_f32_16x16x32_bf16 v[50:53], v[90:93], v[170:173], v[50:53]
	v_mfma_f32_16x16x32_bf16 v[46:49], v[202:205], v[166:169], v[46:49]
	v_mfma_f32_16x16x32_bf16 v[42:45], v[202:205], v[174:177], v[42:45]
	s_waitcnt lgkmcnt(0)
	v_mfma_f32_16x16x32_bf16 v[38:41], v[210:213], v[166:169], v[38:41]
	v_mfma_f32_16x16x32_bf16 v[34:37], v[210:213], v[174:177], v[34:37]
	v_mfma_f32_16x16x32_bf16 v[214:217], v[86:89], v[166:169], v[62:65]
	v_mfma_f32_16x16x32_bf16 v[230:233], v[86:89], v[174:177], v[58:61]
	v_mfma_f32_16x16x32_bf16 v[234:237], v[94:97], v[166:169], v[54:57]
	v_mfma_f32_16x16x32_bf16 v[238:241], v[94:97], v[174:177], v[50:53]
	s_setprio 0
	s_setprio 1
	v_mfma_f32_16x16x32_bf16 v[0:3], v[206:209], v[222:225], v[0:3]
	v_mfma_f32_16x16x32_bf16 v[28:31], v[82:85], v[150:153], v[28:31]
	v_mfma_f32_16x16x32_bf16 v[24:27], v[82:85], v[222:225], v[24:27]
	v_mfma_f32_16x16x32_bf16 v[20:23], v[90:93], v[150:153], v[20:23]
	v_mfma_f32_16x16x32_bf16 v[16:19], v[90:93], v[222:225], v[16:19]
	v_mfma_f32_16x16x32_bf16 v[12:15], v[198:201], v[150:153], v[12:15]
	v_mfma_f32_16x16x32_bf16 v[8:11], v[198:201], v[222:225], v[8:11]
	v_mfma_f32_16x16x32_bf16 v[4:7], v[206:209], v[150:153], v[4:7]
	v_mfma_f32_16x16x32_bf16 v[0:3], v[210:213], v[146:149], v[0:3]
	v_mfma_f32_16x16x32_bf16 v[154:157], v[86:89], v[218:221], v[28:31]
	v_mfma_f32_16x16x32_bf16 v[158:161], v[86:89], v[146:149], v[24:27]
	v_mfma_f32_16x16x32_bf16 v[166:169], v[94:97], v[218:221], v[20:23]
	v_mfma_f32_16x16x32_bf16 v[170:173], v[94:97], v[146:149], v[16:19]
	v_mfma_f32_16x16x32_bf16 v[174:177], v[202:205], v[218:221], v[12:15]
	v_mfma_f32_16x16x32_bf16 v[198:201], v[202:205], v[146:149], v[8:11]
	v_mfma_f32_16x16x32_bf16 v[150:153], v[210:213], v[218:221], v[4:7]
	s_setprio 0
	s_barrier
; #define LDA(dst, b, h) _Pragma("unroll") for (int m = 0; m < 4; ++m) _Pragma("unroll") for (int k = 0; k < 2; ++k) \
;     dst[m][k] = *reinterpret_cast<const bf16x8*>((char*)SA(b, h) + lds_byte(wr * 64 + m * 16 + fr, k * 32 + fq * 8))
; #define LDB(dst, b, h) _Pragma("unroll") for (int n = 0; n < 2; ++n) _Pragma("unroll") for (int k = 0; k < 2; ++k) \
;     dst[n][k] = *reinterpret_cast<const bf16x8*>((char*)SB(b, h) + lds_byte(wc * 32 + n * 16 + fr, k * 32 + fq * 8))
; #define MMA(ai, bj, At, Bt_) do { __builtin_amdgcn_s_setprio(1); \
;     _Pragma("unroll") for (int m = 0; m < 4; ++m) _Pragma("unroll") for (int n = 0; n < 2; ++n) _Pragma("unroll") for (int k = 0; k < 2; ++k) \
;       acc[ai][bj][m][n] = __builtin_amdgcn_mfma_f32_16x16x32_bf16(At[m][k], Bt_[n][k], acc[ai][bj][m][n], 0, 0, 0); \
;     __builtin_amdgcn_s_setprio(0); } while (0)
; #define WAIT_V(n) asm volatile("s_waitcnt vmcnt(" #n ")" ::: "memory")
; #define WAIT_L(n) asm volatile("s_waitcnt lgkmcnt(" #n ")" ::: "memory")
; #define BAR __builtin_amdgcn_s_barrier()
; template <class Epi> ...
;     ...
;   { LDB(B0, 1, 0); LDA(At, 1, 0); WAIT_V(2); BAR; WAIT_L(0); MMA(0, 0, At, B0); BAR;
;     LDB(B1, 1, 1); WAIT_V(0); BAR; WAIT_L(0); MMA(0, 1, At, B1); BAR;
;     LDA(At, 1, 1); BAR; WAIT_L(0); MMA(1, 0, At, B0); MMA(1, 1, At, B1); BAR; }
;   if (wr == 0) BAR;
	s_nop 0
	ds_read_b128 v[4:7], v145
	ds_read_b128 v[8:11], v145 offset:1024
	ds_read_b128 v[12:15], v145 offset:2048
	ds_read_b128 v[146:149], v145 offset:3072
	ds_read_b128 v[16:19], v143 offset:32768
	ds_read_b128 v[20:23], v143 offset:33792
	ds_read_b128 v[24:27], v142 offset:32768
	ds_read_b128 v[50:53], v142 offset:33792
	ds_read_b128 v[202:205], v141 offset:32768
	ds_read_b128 v[206:209], v141 offset:33792
	ds_read_b128 v[210:213], v140 offset:32768
	ds_read_b128 v[218:221], v140 offset:33792
	s_waitcnt vmcnt(2)
	s_barrier
	s_setprio 1
	s_waitcnt lgkmcnt(7)
	v_mfma_f32_16x16x32_bf16 v[28:31], v[16:19], v[4:7], v[126:129]
	s_waitcnt lgkmcnt(6)
	v_mfma_f32_16x16x32_bf16 v[126:129], v[20:23], v[8:11], v[28:31]
	v_mfma_f32_16x16x32_bf16 v[28:31], v[16:19], v[12:15], v[122:125]
	v_mfma_f32_16x16x32_bf16 v[94:97], v[20:23], v[146:149], v[28:31]
	s_waitcnt lgkmcnt(5)
	v_mfma_f32_16x16x32_bf16 v[28:31], v[24:27], v[4:7], v[118:121]
	s_waitcnt lgkmcnt(4)
	v_mfma_f32_16x16x32_bf16 v[122:125], v[50:53], v[8:11], v[28:31]
	v_mfma_f32_16x16x32_bf16 v[28:31], v[24:27], v[12:15], v[114:117]
	v_mfma_f32_16x16x32_bf16 v[90:93], v[50:53], v[146:149], v[28:31]
	s_waitcnt lgkmcnt(3)
	v_mfma_f32_16x16x32_bf16 v[28:31], v[202:205], v[4:7], v[110:113]
	s_waitcnt lgkmcnt(2)
	v_mfma_f32_16x16x32_bf16 v[118:121], v[206:209], v[8:11], v[28:31]
	v_mfma_f32_16x16x32_bf16 v[28:31], v[202:205], v[12:15], v[106:109]
	v_mfma_f32_16x16x32_bf16 v[86:89], v[206:209], v[146:149], v[28:31]
	s_waitcnt lgkmcnt(1)
	v_mfma_f32_16x16x32_bf16 v[28:31], v[210:213], v[4:7], v[102:105]
	s_waitcnt lgkmcnt(0)
	v_mfma_f32_16x16x32_bf16 v[114:117], v[218:221], v[8:11], v[28:31]
	v_mfma_f32_16x16x32_bf16 v[28:31], v[210:213], v[12:15], v[98:101]
	v_mfma_f32_16x16x32_bf16 v[82:85], v[218:221], v[146:149], v[28:31]
	s_setprio 0
	s_barrier
	ds_read_b128 v[222:225], v144
	ds_read_b128 v[242:245], v144 offset:1024
	ds_read_b128 v[246:249], v144 offset:2048
	ds_read_b128 v[250:253], v144 offset:3072
	s_waitcnt vmcnt(0)
	s_barrier
	s_setprio 1
	s_waitcnt lgkmcnt(3)
	v_mfma_f32_16x16x32_bf16 v[28:31], v[16:19], v[222:225], v[226:229]
	s_waitcnt lgkmcnt(1)
	v_mfma_f32_16x16x32_bf16 v[16:19], v[16:19], v[246:249], v[186:189]
	v_mfma_f32_16x16x32_bf16 v[62:65], v[20:23], v[242:245], v[28:31]
	s_waitcnt lgkmcnt(0)
	v_mfma_f32_16x16x32_bf16 v[28:31], v[20:23], v[250:253], v[16:19]
	v_mfma_f32_16x16x32_bf16 v[16:19], v[24:27], v[222:225], v[190:193]
	v_mfma_f32_16x16x32_bf16 v[58:61], v[50:53], v[242:245], v[16:19]
	v_mfma_f32_16x16x32_bf16 v[16:19], v[24:27], v[246:249], v[194:197]
	v_mfma_f32_16x16x32_bf16 v[24:27], v[50:53], v[250:253], v[16:19]
	v_mfma_f32_16x16x32_bf16 v[16:19], v[202:205], v[222:225], v[78:81]
	v_mfma_f32_16x16x32_bf16 v[54:57], v[206:209], v[242:245], v[16:19]
	v_mfma_f32_16x16x32_bf16 v[16:19], v[202:205], v[246:249], v[74:77]
	v_mfma_f32_16x16x32_bf16 v[20:23], v[206:209], v[250:253], v[16:19]
	v_mfma_f32_16x16x32_bf16 v[16:19], v[210:213], v[222:225], v[70:73]
	v_mfma_f32_16x16x32_bf16 v[50:53], v[218:221], v[242:245], v[16:19]
	v_mfma_f32_16x16x32_bf16 v[16:19], v[210:213], v[246:249], v[66:69]
	v_mfma_f32_16x16x32_bf16 v[16:19], v[218:221], v[250:253], v[16:19]
	s_setprio 0
	s_barrier
	ds_read_b128 v[186:189], v143 offset:49152
	ds_read_b128 v[190:193], v143 offset:50176
	ds_read_b128 v[194:197], v142 offset:49152
	ds_read_b128 v[142:145], v142 offset:50176
	ds_read_b128 v[202:205], v141 offset:49152
	ds_read_b128 v[206:209], v141 offset:50176
	ds_read_b128 v[210:213], v140 offset:49152
	ds_read_b128 v[218:221], v140 offset:50176
	s_barrier
	s_setprio 1
	s_waitcnt lgkmcnt(7)
	v_mfma_f32_16x16x32_bf16 v[66:69], v[186:189], v[4:7], v[214:217]
	s_waitcnt lgkmcnt(6)
	v_mfma_f32_16x16x32_bf16 v[110:113], v[190:193], v[8:11], v[66:69]
	v_mfma_f32_16x16x32_bf16 v[66:69], v[186:189], v[12:15], v[230:233]
	v_mfma_f32_16x16x32_bf16 v[78:81], v[190:193], v[146:149], v[66:69]
	s_waitcnt lgkmcnt(5)
	v_mfma_f32_16x16x32_bf16 v[66:69], v[194:197], v[4:7], v[234:237]
	s_waitcnt lgkmcnt(3)
	v_mfma_f32_16x16x32_bf16 v[46:49], v[202:205], v[4:7], v[46:49]
	s_waitcnt lgkmcnt(1)
	v_mfma_f32_16x16x32_bf16 v[4:7], v[210:213], v[4:7], v[38:41]
	v_mfma_f32_16x16x32_bf16 v[106:109], v[142:145], v[8:11], v[66:69]
	v_mfma_f32_16x16x32_bf16 v[66:69], v[194:197], v[12:15], v[238:241]
	v_mfma_f32_16x16x32_bf16 v[42:45], v[202:205], v[12:15], v[42:45]
	s_waitcnt lgkmcnt(0)
	v_mfma_f32_16x16x32_bf16 v[98:101], v[218:221], v[8:11], v[4:7]
	v_mfma_f32_16x16x32_bf16 v[4:7], v[210:213], v[12:15], v[34:37]
	v_mfma_f32_16x16x32_bf16 v[74:77], v[142:145], v[146:149], v[66:69]
	v_mfma_f32_16x16x32_bf16 v[102:105], v[206:209], v[8:11], v[46:49]
	v_mfma_f32_16x16x32_bf16 v[70:73], v[206:209], v[146:149], v[42:45]
	v_mfma_f32_16x16x32_bf16 v[66:69], v[218:221], v[146:149], v[4:7]
	s_setprio 0
	s_setprio 1
	v_mfma_f32_16x16x32_bf16 v[4:7], v[186:189], v[222:225], v[154:157]
	v_mfma_f32_16x16x32_bf16 v[46:49], v[190:193], v[242:245], v[4:7]
	v_mfma_f32_16x16x32_bf16 v[4:7], v[186:189], v[246:249], v[158:161]
	v_mfma_f32_16x16x32_bf16 v[12:15], v[190:193], v[250:253], v[4:7]
	v_mfma_f32_16x16x32_bf16 v[4:7], v[194:197], v[222:225], v[166:169]
	v_mfma_f32_16x16x32_bf16 v[42:45], v[142:145], v[242:245], v[4:7]
	v_mfma_f32_16x16x32_bf16 v[4:7], v[194:197], v[246:249], v[170:173]
	v_mfma_f32_16x16x32_bf16 v[8:11], v[142:145], v[250:253], v[4:7]
	v_mfma_f32_16x16x32_bf16 v[4:7], v[202:205], v[222:225], v[174:177]
	v_mfma_f32_16x16x32_bf16 v[38:41], v[206:209], v[242:245], v[4:7]
	v_mfma_f32_16x16x32_bf16 v[4:7], v[202:205], v[246:249], v[198:201]
	v_mfma_f32_16x16x32_bf16 v[34:37], v[210:213], v[222:225], v[150:153]
	v_mfma_f32_16x16x32_bf16 v[0:3], v[210:213], v[246:249], v[0:3]
	v_mfma_f32_16x16x32_bf16 v[4:7], v[206:209], v[250:253], v[4:7]
	v_mfma_f32_16x16x32_bf16 v[34:37], v[218:221], v[242:245], v[34:37]
	v_mfma_f32_16x16x32_bf16 v[0:3], v[218:221], v[250:253], v[0:3]
	s_setprio 0
	v_cmp_gt_u32_e32 vcc, s59, v130
	s_barrier
	s_and_saveexec_b64 s[6:7], vcc
	s_cbranch_execz .LBB0_2339
	s_barrier
